# fast f32 division in epilogues + P9 chain/epilogue software pipeline + K8 head-major layout + GEMM LDS-DMA staging rebalanced 4/4 per load segment (vmcnt 8/6)
# speedup vs baseline: 1.0041x; 1.0041x over previous
; #define PG8_STAGE(bufoff, gbase, voff) do { _Pragma("unroll") for (int _i = 0; _i < 2; ++_i) \
;         __builtin_amdgcn_global_load_lds((const unsigned*)((const char*)(gbase) + (voff)[_i]), (PG8_LAS unsigned*)(lds + (bufoff) + ldsw + _i * 8192), 16, 0, 0); } while (0)
; #define PG8_LDA(dst, b, h) do { _Pragma("unroll") for (int m = 0; m < 4; ++m) _Pragma("unroll") for (int k = 0; k < 2; ++k) dst[m][k] = *(const PG8_LAS bf16x8*)(lds + PG8_SA(b, h) + aoff + m * 2048 + k * 1024); } while (0)
; #define PG8_LDB(dst, b, h) do { _Pragma("unroll") for (int n = 0; n < 2; ++n) _Pragma("unroll") for (int k = 0; k < 2; ++k) dst[n][k] = *(const PG8_LAS bf16x8*)(lds + PG8_SB(b, h) + boff + n * 2048 + k * 1024); } while (0)
; #define PG8_MMA(ai, bj, At, Bt) do { __builtin_amdgcn_s_setprio(1); _Pragma("unroll") for (int m = 0; m < 4; ++m) _Pragma("unroll") for (int n = 0; n < 2; ++n) _Pragma("unroll") for (int k = 0; k < 2; ++k) \
;         acc[ai][bj][m][n] = __builtin_amdgcn_mfma_f32_16x16x32_bf16(Bt[n][k], At[m][k], acc[ai][bj][m][n], 0, 0, 0); __builtin_amdgcn_s_setprio(0); } while (0)
; #define PG8_WAIT_V(n) asm volatile("s_waitcnt vmcnt(" #n ")" ::: "memory")
; #define PG8_WAIT_L(n) asm volatile("s_waitcnt lgkmcnt(" #n ")" ::: "memory")
; #define PG8_BAR __builtin_amdgcn_s_barrier()
; #define PG8_SCHED __builtin_amdgcn_sched_barrier(0)
; template <class Epi, class Sched, bool ALIGN_EPI = false, bool SP2 = false>
; __device__ __forceinline__ void gemm_phase(PG8_LAS unsigned char* lds, const Gemm g, const Sched& S, const Epi& E, const int wid  ) {
;     ...
;             const bool last = (t == nt - 2);
;             const char* a1 = cA + (size_t)(t + 1) * kstep;
;             const char* a2 = last ? nA : cA + (size_t)(t + 2) * kstep; const char* b2 = last ? nB : cB + (size_t)(t + 2) * kstep;
;             const char* a3 = a2 + kstep; const char* b3 = b2 + kstep;
;             if (last && has_next) S.a_ready(nxt);
;             if constexpr (SP2) {
;             PG8_LDB(B0, 0, 0); PG8_LDB(B1, 0, 1); PG8_SCHED; PG8_LDA(At, 0, 0); PG8_STAGE(PG8_SA(1, 1), a1 + hstep, voffA);
;             PG8_WAIT_V(8); PG8_WAIT_L(0); PG8_BAR; PG8_MMA(0, 0, At, B0); PG8_MMA(0, 1, At, B1); PG8_BAR; PG8_SCHED;
;             PG8_LDA(At, 0, 1); PG8_STAGE(PG8_SB(0, 0), b2, voffB); PG8_STAGE(PG8_SB(0, 1), b2 + hstep, voffB); PG8_STAGE(PG8_SA(0, 0), a2, voffA);
.LBB0_230:
	s_add_u32 s100, s10, 0xfff80000
	s_addc_u32 s101, s11, -1
	ds_read_b128 v[68:71], v185
	ds_read_b128 v[76:79], v185 offset:1024
	ds_read_b128 v[80:83], v185 offset:2048
	ds_read_b128 v[88:91], v185 offset:3072
	ds_read_b128 v[160:163], v186
	ds_read_b128 v[164:167], v186 offset:1024
	ds_read_b128 v[168:171], v186 offset:2048
	ds_read_b128 v[190:193], v186 offset:3072
	s_add_u32 s47, s10, 0xfff80080
	s_addc_u32 s52, s11, -1
	s_cmp_eq_u32 s45, 28
	s_cselect_b32 s55, s7, s52
	s_cselect_b32 s54, s9, s47
	s_cselect_b32 s53, s30, s35
	s_cselect_b32 s52, s31, s34
	v_lshl_add_u64 v[228:229], s[100:101], 0, v[152:153]
	s_mov_b32 m0, s62
	v_lshl_add_u64 v[230:231], s[100:101], 0, v[154:155]
	global_load_lds_dwordx4 v[228:229], off
	s_mov_b32 m0, s63
	s_nop 0
	global_load_lds_dwordx4 v[230:231], off
	v_lshl_add_u64 v[172:173], s[10:11], 0, v[152:153]
	s_add_i32 m0, s37, 0xc000
	ds_read_b128 v[194:197], v187
	ds_read_b128 v[198:201], v187 offset:1024
	ds_read_b128 v[202:205], v187 offset:2048
	ds_read_b128 v[206:209], v187 offset:3072
	ds_read_b128 v[210:213], v187 offset:4096
	ds_read_b128 v[214:217], v187 offset:5120
	ds_read_b128 v[218:221], v187 offset:6144
	ds_read_b128 v[222:225], v187 offset:7168
	global_load_lds_dwordx4 v[172:173], off
	v_lshl_add_u64 v[172:173], s[10:11], 0, v[154:155]
	s_add_i32 m0, s37, 0xe000
	s_nop 0
	global_load_lds_dwordx4 v[172:173], off
	s_waitcnt vmcnt(8)
	s_waitcnt lgkmcnt(0)
	s_barrier
	s_setprio 1
	s_waitcnt lgkmcnt(0)
	v_mfma_f32_16x16x32_bf16 v[140:143], v[68:71], v[194:197], v[140:143]
	v_mfma_f32_16x16x32_bf16 v[136:139], v[80:83], v[194:197], v[136:139]
	v_mfma_f32_16x16x32_bf16 v[124:127], v[68:71], v[202:205], v[124:127]
	v_mfma_f32_16x16x32_bf16 v[120:123], v[80:83], v[202:205], v[120:123]
	v_mfma_f32_16x16x32_bf16 v[108:111], v[68:71], v[210:213], v[108:111]
	v_mfma_f32_16x16x32_bf16 v[104:107], v[80:83], v[210:213], v[104:107]
	v_mfma_f32_16x16x32_bf16 v[92:95], v[68:71], v[218:221], v[92:95]
	v_mfma_f32_16x16x32_bf16 v[84:87], v[80:83], v[218:221], v[84:87]
	v_mfma_f32_16x16x32_bf16 v[140:143], v[76:79], v[198:201], v[140:143]
	v_mfma_f32_16x16x32_bf16 v[136:139], v[88:91], v[198:201], v[136:139]
	v_mfma_f32_16x16x32_bf16 v[124:127], v[76:79], v[206:209], v[124:127]
	v_mfma_f32_16x16x32_bf16 v[120:123], v[88:91], v[206:209], v[120:123]
	v_mfma_f32_16x16x32_bf16 v[108:111], v[76:79], v[214:217], v[108:111]
	v_mfma_f32_16x16x32_bf16 v[104:107], v[88:91], v[214:217], v[104:107]
	v_mfma_f32_16x16x32_bf16 v[92:95], v[76:79], v[222:225], v[92:95]
	v_mfma_f32_16x16x32_bf16 v[84:87], v[88:91], v[222:225], v[84:87]
	s_setprio 0
	s_setprio 1
	v_mfma_f32_16x16x32_bf16 v[132:135], v[160:163], v[194:197], v[132:135]
	v_mfma_f32_16x16x32_bf16 v[128:131], v[168:171], v[194:197], v[128:131]
	v_mfma_f32_16x16x32_bf16 v[116:119], v[160:163], v[202:205], v[116:119]
	v_mfma_f32_16x16x32_bf16 v[112:115], v[168:171], v[202:205], v[112:115]
	v_mfma_f32_16x16x32_bf16 v[100:103], v[160:163], v[210:213], v[100:103]
	v_mfma_f32_16x16x32_bf16 v[96:99], v[168:171], v[210:213], v[96:99]
	v_mfma_f32_16x16x32_bf16 v[72:75], v[160:163], v[218:221], v[72:75]
	v_mfma_f32_16x16x32_bf16 v[64:67], v[168:171], v[218:221], v[64:67]
	v_mfma_f32_16x16x32_bf16 v[132:135], v[164:167], v[198:201], v[132:135]
	v_mfma_f32_16x16x32_bf16 v[128:131], v[190:193], v[198:201], v[128:131]
	v_mfma_f32_16x16x32_bf16 v[116:119], v[164:167], v[206:209], v[116:119]
	v_mfma_f32_16x16x32_bf16 v[112:115], v[190:193], v[206:209], v[112:115]
	v_mfma_f32_16x16x32_bf16 v[100:103], v[164:167], v[214:217], v[100:103]
	v_mfma_f32_16x16x32_bf16 v[96:99], v[190:193], v[214:217], v[96:99]
	v_mfma_f32_16x16x32_bf16 v[72:75], v[164:167], v[222:225], v[72:75]
	v_mfma_f32_16x16x32_bf16 v[64:67], v[190:193], v[222:225], v[64:67]
	s_setprio 0
	s_barrier
	s_add_i32 s47, s66, s29
	v_lshl_add_u64 v[172:173], s[52:53], 0, v[146:147]
	s_mov_b32 m0, s47
	ds_read_b128 v[194:197], v187 offset:16384
	ds_read_b128 v[198:201], v187 offset:17408
	ds_read_b128 v[202:205], v187 offset:18432
	ds_read_b128 v[206:209], v187 offset:19456
	ds_read_b128 v[210:213], v187 offset:20480
	ds_read_b128 v[214:217], v187 offset:21504
	ds_read_b128 v[218:221], v187 offset:22528
	ds_read_b128 v[222:225], v187 offset:23552
	global_load_lds_dwordx4 v[172:173], off
	s_add_i32 m0, s47, 0x2000
	s_add_u32 s72, s52, 0x80000
	v_lshl_add_u64 v[226:227], s[52:53], 0, v[150:151]
	s_addc_u32 s73, s53, 0
	s_add_i32 s47, s67, s29
	global_load_lds_dwordx4 v[226:227], off
	v_lshl_add_u64 v[228:229], s[72:73], 0, v[146:147]
	s_mov_b32 m0, s47
	s_nop 0
	global_load_lds_dwordx4 v[228:229], off
	v_lshl_add_u64 v[228:229], s[72:73], 0, v[150:151]
	s_add_i32 m0, s47, 0x2000
	s_nop 0
	global_load_lds_dwordx4 v[228:229], off
	s_waitcnt vmcnt(6)
	s_waitcnt lgkmcnt(0)
	s_barrier
; #define PG8_STAGE(bufoff, gbase, voff) do { _Pragma("unroll") for (int _i = 0; _i < 2; ++_i) \
;         __builtin_amdgcn_global_load_lds((const unsigned*)((const char*)(gbase) + (voff)[_i]), (PG8_LAS unsigned*)(lds + (bufoff) + ldsw + _i * 8192), 16, 0, 0); } while (0)
; #define PG8_LDA(dst, b, h) do { _Pragma("unroll") for (int m = 0; m < 4; ++m) _Pragma("unroll") for (int k = 0; k < 2; ++k) dst[m][k] = *(const PG8_LAS bf16x8*)(lds + PG8_SA(b, h) + aoff + m * 2048 + k * 1024); } while (0)
; #define PG8_LDB(dst, b, h) do { _Pragma("unroll") for (int n = 0; n < 2; ++n) _Pragma("unroll") for (int k = 0; k < 2; ++k) dst[n][k] = *(const PG8_LAS bf16x8*)(lds + PG8_SB(b, h) + boff + n * 2048 + k * 1024); } while (0)
; #define PG8_MMA(ai, bj, At, Bt) do { __builtin_amdgcn_s_setprio(1); _Pragma("unroll") for (int m = 0; m < 4; ++m) _Pragma("unroll") for (int n = 0; n < 2; ++n) _Pragma("unroll") for (int k = 0; k < 2; ++k) \
;         acc[ai][bj][m][n] = __builtin_amdgcn_mfma_f32_16x16x32_bf16(Bt[n][k], At[m][k], acc[ai][bj][m][n], 0, 0, 0); __builtin_amdgcn_s_setprio(0); } while (0)
; #define PG8_WAIT_V(n) asm volatile("s_waitcnt vmcnt(" #n ")" ::: "memory")
; #define PG8_WAIT_L(n) asm volatile("s_waitcnt lgkmcnt(" #n ")" ::: "memory")
; #define PG8_BAR __builtin_amdgcn_s_barrier()
; #define PG8_SCHED __builtin_amdgcn_sched_barrier(0)
; template <class Epi, class Sched, bool ALIGN_EPI = false, bool SP2 = false>
; __device__ __forceinline__ void gemm_phase(PG8_LAS unsigned char* lds, const Gemm g, const Sched& S, const Epi& E, const int wid  ) {
;     ...
;             PG8_LDA(At, 0, 1); PG8_STAGE(PG8_SB(0, 0), b2, voffB); PG8_STAGE(PG8_SB(0, 1), b2 + hstep, voffB); PG8_STAGE(PG8_SA(0, 0), a2, voffA);
;             PG8_WAIT_V(8); PG8_WAIT_L(0); PG8_BAR; PG8_MMA(1, 0, At, B0); PG8_MMA(1, 1, At, B1); PG8_BAR; PG8_SCHED;
;             PG8_LDB(B0, 1, 0); PG8_LDB(B1, 1, 1); PG8_SCHED; PG8_LDA(At, 1, 0); PG8_STAGE(PG8_SA(0, 1), a2 + hstep, voffA);
	s_setprio 1
	s_waitcnt lgkmcnt(0)
	v_mfma_f32_16x16x32_bf16 v[60:63], v[68:71], v[194:197], v[60:63]
	v_mfma_f32_16x16x32_bf16 v[56:59], v[80:83], v[194:197], v[56:59]
	v_mfma_f32_16x16x32_bf16 v[44:47], v[68:71], v[202:205], v[44:47]
	v_mfma_f32_16x16x32_bf16 v[40:43], v[80:83], v[202:205], v[40:43]
	v_mfma_f32_16x16x32_bf16 v[28:31], v[68:71], v[210:213], v[28:31]
	v_mfma_f32_16x16x32_bf16 v[24:27], v[80:83], v[210:213], v[24:27]
	v_mfma_f32_16x16x32_bf16 v[12:15], v[68:71], v[218:221], v[12:15]
	v_mfma_f32_16x16x32_bf16 v[8:11], v[80:83], v[218:221], v[8:11]
	v_mfma_f32_16x16x32_bf16 v[60:63], v[76:79], v[198:201], v[60:63]
	v_mfma_f32_16x16x32_bf16 v[56:59], v[88:91], v[198:201], v[56:59]
	v_mfma_f32_16x16x32_bf16 v[44:47], v[76:79], v[206:209], v[44:47]
	v_mfma_f32_16x16x32_bf16 v[40:43], v[88:91], v[206:209], v[40:43]
	v_mfma_f32_16x16x32_bf16 v[28:31], v[76:79], v[214:217], v[28:31]
	v_mfma_f32_16x16x32_bf16 v[24:27], v[88:91], v[214:217], v[24:27]
	v_mfma_f32_16x16x32_bf16 v[12:15], v[76:79], v[222:225], v[12:15]
	v_mfma_f32_16x16x32_bf16 v[8:11], v[88:91], v[222:225], v[8:11]
	s_setprio 0
	s_setprio 1
	v_mfma_f32_16x16x32_bf16 v[52:55], v[160:163], v[194:197], v[52:55]
	v_mfma_f32_16x16x32_bf16 v[48:51], v[168:171], v[194:197], v[48:51]
	v_mfma_f32_16x16x32_bf16 v[36:39], v[160:163], v[202:205], v[36:39]
	v_mfma_f32_16x16x32_bf16 v[32:35], v[168:171], v[202:205], v[32:35]
	v_mfma_f32_16x16x32_bf16 v[20:23], v[160:163], v[210:213], v[20:23]
	v_mfma_f32_16x16x32_bf16 v[16:19], v[168:171], v[210:213], v[16:19]
	v_mfma_f32_16x16x32_bf16 v[4:7], v[160:163], v[218:221], v[4:7]
	v_mfma_f32_16x16x32_bf16 v[0:3], v[168:171], v[218:221], v[0:3]
	v_mfma_f32_16x16x32_bf16 v[52:55], v[164:167], v[198:201], v[52:55]
	v_mfma_f32_16x16x32_bf16 v[48:51], v[190:193], v[198:201], v[48:51]
	v_mfma_f32_16x16x32_bf16 v[36:39], v[164:167], v[206:209], v[36:39]
	v_mfma_f32_16x16x32_bf16 v[32:35], v[190:193], v[206:209], v[32:35]
	v_mfma_f32_16x16x32_bf16 v[20:23], v[164:167], v[214:217], v[20:23]
	v_mfma_f32_16x16x32_bf16 v[16:19], v[190:193], v[214:217], v[16:19]
	v_mfma_f32_16x16x32_bf16 v[4:7], v[164:167], v[222:225], v[4:7]
	v_mfma_f32_16x16x32_bf16 v[0:3], v[190:193], v[222:225], v[0:3]
	s_setprio 0
	s_barrier
	s_add_i32 s47, 0, 0x18000
	s_add_i32 s72, 0, 0x1c000
	v_add_u32_e32 v88, s47, v176
	v_add_u32_e32 v190, s72, v176
	ds_read_b128 v[68:71], v88
	ds_read_b128 v[76:79], v88 offset:1024
	ds_read_b128 v[80:83], v88 offset:2048
	ds_read_b128 v[88:91], v88 offset:3072
	ds_read_b128 v[160:163], v190
	ds_read_b128 v[164:167], v190 offset:1024
	ds_read_b128 v[168:171], v190 offset:2048
	ds_read_b128 v[190:193], v190 offset:3072
	v_lshl_add_u64 v[228:229], s[54:55], 0, v[144:145]
	s_mov_b32 m0, s37
	v_lshl_add_u64 v[230:231], s[54:55], 0, v[148:149]
	global_load_lds_dwordx4 v[228:229], off
	s_mov_b32 m0, s56
	s_nop 0
	global_load_lds_dwordx4 v[230:231], off
	s_add_u32 s54, s54, 0x80000
	s_addc_u32 s55, s55, 0
	s_mov_b32 m0, s57
	v_lshl_add_u64 v[232:233], s[54:55], 0, v[144:145]
	ds_read_b128 v[194:197], v187 offset:32768
	ds_read_b128 v[198:201], v187 offset:33792
	ds_read_b128 v[202:205], v187 offset:34816
	ds_read_b128 v[206:209], v187 offset:35840
	ds_read_b128 v[210:213], v187 offset:36864
	ds_read_b128 v[214:217], v187 offset:37888
	ds_read_b128 v[218:221], v187 offset:38912
	ds_read_b128 v[222:225], v187 offset:39936
	global_load_lds_dwordx4 v[232:233], off
	v_lshl_add_u64 v[232:233], s[54:55], 0, v[148:149]
	s_mov_b32 m0, s58
	s_nop 0
	global_load_lds_dwordx4 v[232:233], off
	s_waitcnt vmcnt(8)
	s_waitcnt lgkmcnt(0)
	s_barrier
; #define PG8_STAGE(bufoff, gbase, voff) do { _Pragma("unroll") for (int _i = 0; _i < 2; ++_i) \
;         __builtin_amdgcn_global_load_lds((const unsigned*)((const char*)(gbase) + (voff)[_i]), (PG8_LAS unsigned*)(lds + (bufoff) + ldsw + _i * 8192), 16, 0, 0); } while (0)
; #define PG8_LDA(dst, b, h) do { _Pragma("unroll") for (int m = 0; m < 4; ++m) _Pragma("unroll") for (int k = 0; k < 2; ++k) dst[m][k] = *(const PG8_LAS bf16x8*)(lds + PG8_SA(b, h) + aoff + m * 2048 + k * 1024); } while (0)
; #define PG8_LDB(dst, b, h) do { _Pragma("unroll") for (int n = 0; n < 2; ++n) _Pragma("unroll") for (int k = 0; k < 2; ++k) dst[n][k] = *(const PG8_LAS bf16x8*)(lds + PG8_SB(b, h) + boff + n * 2048 + k * 1024); } while (0)
; #define PG8_MMA(ai, bj, At, Bt) do { __builtin_amdgcn_s_setprio(1); _Pragma("unroll") for (int m = 0; m < 4; ++m) _Pragma("unroll") for (int n = 0; n < 2; ++n) _Pragma("unroll") for (int k = 0; k < 2; ++k) \
;         acc[ai][bj][m][n] = __builtin_amdgcn_mfma_f32_16x16x32_bf16(Bt[n][k], At[m][k], acc[ai][bj][m][n], 0, 0, 0); __builtin_amdgcn_s_setprio(0); } while (0)
; #define PG8_WAIT_V(n) asm volatile("s_waitcnt vmcnt(" #n ")" ::: "memory")
; #define PG8_WAIT_L(n) asm volatile("s_waitcnt lgkmcnt(" #n ")" ::: "memory")
; #define PG8_BAR __builtin_amdgcn_s_barrier()
; #define PG8_SCHED __builtin_amdgcn_sched_barrier(0)
; template <class Epi, class Sched, bool ALIGN_EPI = false, bool SP2 = false>
; __device__ __forceinline__ void gemm_phase(PG8_LAS unsigned char* lds, const Gemm g, const Sched& S, const Epi& E, const int wid  ) {
;     ...
;             PG8_LDB(B0, 1, 0); PG8_LDB(B1, 1, 1); PG8_SCHED; PG8_LDA(At, 1, 0); PG8_STAGE(PG8_SA(0, 1), a2 + hstep, voffA);
;             PG8_WAIT_V(8); PG8_WAIT_L(0); PG8_BAR; PG8_MMA(0, 0, At, B0); PG8_MMA(0, 1, At, B1); PG8_BAR; PG8_SCHED;
;             PG8_LDA(At, 1, 1); PG8_STAGE(PG8_SB(1, 0), b3, voffB); PG8_STAGE(PG8_SB(1, 1), b3 + hstep, voffB); PG8_STAGE(PG8_SA(1, 0), a3, voffA);
;             PG8_WAIT_V(8); PG8_WAIT_L(0); PG8_BAR; PG8_MMA(1, 0, At, B0); PG8_MMA(1, 1, At, B1); PG8_BAR; PG8_SCHED;
	s_setprio 1
	s_waitcnt lgkmcnt(0)
	v_mfma_f32_16x16x32_bf16 v[140:143], v[68:71], v[194:197], v[140:143]
	v_mfma_f32_16x16x32_bf16 v[136:139], v[80:83], v[194:197], v[136:139]
	v_mfma_f32_16x16x32_bf16 v[124:127], v[68:71], v[202:205], v[124:127]
	v_mfma_f32_16x16x32_bf16 v[120:123], v[80:83], v[202:205], v[120:123]
	v_mfma_f32_16x16x32_bf16 v[108:111], v[68:71], v[210:213], v[108:111]
	v_mfma_f32_16x16x32_bf16 v[104:107], v[80:83], v[210:213], v[104:107]
	v_mfma_f32_16x16x32_bf16 v[92:95], v[68:71], v[218:221], v[92:95]
	v_mfma_f32_16x16x32_bf16 v[84:87], v[80:83], v[218:221], v[84:87]
	v_mfma_f32_16x16x32_bf16 v[140:143], v[76:79], v[198:201], v[140:143]
	v_mfma_f32_16x16x32_bf16 v[136:139], v[88:91], v[198:201], v[136:139]
	v_mfma_f32_16x16x32_bf16 v[124:127], v[76:79], v[206:209], v[124:127]
	v_mfma_f32_16x16x32_bf16 v[120:123], v[88:91], v[206:209], v[120:123]
	v_mfma_f32_16x16x32_bf16 v[108:111], v[76:79], v[214:217], v[108:111]
	v_mfma_f32_16x16x32_bf16 v[104:107], v[88:91], v[214:217], v[104:107]
	v_mfma_f32_16x16x32_bf16 v[92:95], v[76:79], v[222:225], v[92:95]
	v_mfma_f32_16x16x32_bf16 v[84:87], v[88:91], v[222:225], v[84:87]
	s_setprio 0
	s_setprio 1
	v_mfma_f32_16x16x32_bf16 v[132:135], v[160:163], v[194:197], v[132:135]
	v_mfma_f32_16x16x32_bf16 v[128:131], v[168:171], v[194:197], v[128:131]
	v_mfma_f32_16x16x32_bf16 v[116:119], v[160:163], v[202:205], v[116:119]
	v_mfma_f32_16x16x32_bf16 v[112:115], v[168:171], v[202:205], v[112:115]
	v_mfma_f32_16x16x32_bf16 v[100:103], v[160:163], v[210:213], v[100:103]
	v_mfma_f32_16x16x32_bf16 v[96:99], v[168:171], v[210:213], v[96:99]
	v_mfma_f32_16x16x32_bf16 v[72:75], v[160:163], v[218:221], v[72:75]
	v_mfma_f32_16x16x32_bf16 v[64:67], v[168:171], v[218:221], v[64:67]
	v_mfma_f32_16x16x32_bf16 v[132:135], v[164:167], v[198:201], v[132:135]
	v_mfma_f32_16x16x32_bf16 v[128:131], v[190:193], v[198:201], v[128:131]
	v_mfma_f32_16x16x32_bf16 v[116:119], v[164:167], v[206:209], v[116:119]
	v_mfma_f32_16x16x32_bf16 v[112:115], v[190:193], v[206:209], v[112:115]
	v_mfma_f32_16x16x32_bf16 v[100:103], v[164:167], v[214:217], v[100:103]
	v_mfma_f32_16x16x32_bf16 v[96:99], v[190:193], v[214:217], v[96:99]
	v_mfma_f32_16x16x32_bf16 v[72:75], v[164:167], v[222:225], v[72:75]
	v_mfma_f32_16x16x32_bf16 v[64:67], v[190:193], v[222:225], v[64:67]
	s_setprio 0
	s_barrier
	s_add_i32 s47, s47, s29
	v_lshl_add_u64 v[172:173], v[172:173], 0, s[38:39]
	s_mov_b32 m0, s47
	ds_read_b128 v[194:197], v187 offset:49152
	ds_read_b128 v[198:201], v187 offset:50176
	ds_read_b128 v[202:205], v187 offset:51200
	ds_read_b128 v[206:209], v187 offset:52224
	ds_read_b128 v[210:213], v187 offset:53248
	ds_read_b128 v[214:217], v187 offset:54272
	ds_read_b128 v[218:221], v187 offset:55296
	ds_read_b128 v[222:225], v187 offset:56320
	global_load_lds_dwordx4 v[172:173], off
	s_add_i32 m0, s47, 0x2000
	s_add_u32 s52, s52, 0x80080
	v_lshl_add_u64 v[172:173], v[226:227], 0, s[38:39]
	s_addc_u32 s53, s53, 0
	s_add_i32 s47, s72, s29
	global_load_lds_dwordx4 v[172:173], off
	v_lshl_add_u64 v[172:173], s[52:53], 0, v[146:147]
	s_mov_b32 m0, s47
	s_nop 0
	global_load_lds_dwordx4 v[172:173], off
	v_lshl_add_u64 v[172:173], s[52:53], 0, v[150:151]
	s_add_i32 m0, s47, 0x2000
	s_nop 0
	global_load_lds_dwordx4 v[172:173], off
	s_waitcnt vmcnt(6)
	s_waitcnt lgkmcnt(0)
	s_barrier
	s_setprio 1
	s_waitcnt lgkmcnt(0)
	v_mfma_f32_16x16x32_bf16 v[60:63], v[68:71], v[194:197], v[60:63]
	v_mfma_f32_16x16x32_bf16 v[56:59], v[80:83], v[194:197], v[56:59]
	v_mfma_f32_16x16x32_bf16 v[44:47], v[68:71], v[202:205], v[44:47]
	v_mfma_f32_16x16x32_bf16 v[40:43], v[80:83], v[202:205], v[40:43]
	v_mfma_f32_16x16x32_bf16 v[28:31], v[68:71], v[210:213], v[28:31]
	v_mfma_f32_16x16x32_bf16 v[24:27], v[80:83], v[210:213], v[24:27]
	v_mfma_f32_16x16x32_bf16 v[12:15], v[68:71], v[218:221], v[12:15]
	v_mfma_f32_16x16x32_bf16 v[8:11], v[80:83], v[218:221], v[8:11]
	v_mfma_f32_16x16x32_bf16 v[60:63], v[76:79], v[198:201], v[60:63]
	v_mfma_f32_16x16x32_bf16 v[56:59], v[88:91], v[198:201], v[56:59]
	v_mfma_f32_16x16x32_bf16 v[44:47], v[76:79], v[206:209], v[44:47]
	v_mfma_f32_16x16x32_bf16 v[40:43], v[88:91], v[206:209], v[40:43]
	v_mfma_f32_16x16x32_bf16 v[28:31], v[76:79], v[214:217], v[28:31]
	v_mfma_f32_16x16x32_bf16 v[24:27], v[88:91], v[214:217], v[24:27]
	v_mfma_f32_16x16x32_bf16 v[12:15], v[76:79], v[222:225], v[12:15]
	v_mfma_f32_16x16x32_bf16 v[8:11], v[88:91], v[222:225], v[8:11]
	s_setprio 0
	s_setprio 1
	v_mfma_f32_16x16x32_bf16 v[52:55], v[160:163], v[194:197], v[52:55]
	v_mfma_f32_16x16x32_bf16 v[48:51], v[168:171], v[194:197], v[48:51]
	v_mfma_f32_16x16x32_bf16 v[36:39], v[160:163], v[202:205], v[36:39]
	v_mfma_f32_16x16x32_bf16 v[32:35], v[168:171], v[202:205], v[32:35]
	v_mfma_f32_16x16x32_bf16 v[20:23], v[160:163], v[210:213], v[20:23]
	v_mfma_f32_16x16x32_bf16 v[16:19], v[168:171], v[210:213], v[16:19]
	v_mfma_f32_16x16x32_bf16 v[4:7], v[160:163], v[218:221], v[4:7]
	v_mfma_f32_16x16x32_bf16 v[0:3], v[168:171], v[218:221], v[0:3]
	v_mfma_f32_16x16x32_bf16 v[52:55], v[164:167], v[198:201], v[52:55]
	v_mfma_f32_16x16x32_bf16 v[48:51], v[190:193], v[198:201], v[48:51]
	v_mfma_f32_16x16x32_bf16 v[36:39], v[164:167], v[206:209], v[36:39]
	v_mfma_f32_16x16x32_bf16 v[32:35], v[190:193], v[206:209], v[32:35]
	v_mfma_f32_16x16x32_bf16 v[20:23], v[164:167], v[214:217], v[20:23]
	v_mfma_f32_16x16x32_bf16 v[16:19], v[190:193], v[214:217], v[16:19]
	v_mfma_f32_16x16x32_bf16 v[4:7], v[164:167], v[222:225], v[4:7]
	v_mfma_f32_16x16x32_bf16 v[0:3], v[190:193], v[222:225], v[0:3]
	s_setprio 0
	s_barrier
	s_add_i32 s45, s45, 2
	s_add_u32 s10, s10, 0x100
	s_addc_u32 s11, s11, 0
	s_add_u32 s34, s34, 0x100
	s_addc_u32 s35, s35, 0
	s_cmp_gt_u32 s45, 29
	s_cbranch_scc0 .LBB0_230
	s_and_b64 vcc, exec, s[40:41]
	s_cbranch_vccz .LBB0_233
	s_barrier

; #define PG8_STAGE(bufoff, gbase, voff) do { _Pragma("unroll") for (int _i = 0; _i < 2; ++_i) \
;         __builtin_amdgcn_global_load_lds((const unsigned*)((const char*)(gbase) + (voff)[_i]), (PG8_LAS unsigned*)(lds + (bufoff) + ldsw + _i * 8192), 16, 0, 0); } while (0)
; #define PG8_LDA(dst, b, h) do { _Pragma("unroll") for (int m = 0; m < 4; ++m) _Pragma("unroll") for (int k = 0; k < 2; ++k) dst[m][k] = *(const PG8_LAS bf16x8*)(lds + PG8_SA(b, h) + aoff + m * 2048 + k * 1024); } while (0)
; #define PG8_LDB(dst, b, h) do { _Pragma("unroll") for (int n = 0; n < 2; ++n) _Pragma("unroll") for (int k = 0; k < 2; ++k) dst[n][k] = *(const PG8_LAS bf16x8*)(lds + PG8_SB(b, h) + boff + n * 2048 + k * 1024); } while (0)
; #define PG8_MMA(ai, bj, At, Bt) do { __builtin_amdgcn_s_setprio(1); _Pragma("unroll") for (int m = 0; m < 4; ++m) _Pragma("unroll") for (int n = 0; n < 2; ++n) _Pragma("unroll") for (int k = 0; k < 2; ++k) \
;         acc[ai][bj][m][n] = __builtin_amdgcn_mfma_f32_16x16x32_bf16(Bt[n][k], At[m][k], acc[ai][bj][m][n], 0, 0, 0); __builtin_amdgcn_s_setprio(0); } while (0)
; #define PG8_WAIT_V(n) asm volatile("s_waitcnt vmcnt(" #n ")" ::: "memory")
; #define PG8_WAIT_L(n) asm volatile("s_waitcnt lgkmcnt(" #n ")" ::: "memory")
; #define PG8_BAR __builtin_amdgcn_s_barrier()
; #define PG8_SCHED __builtin_amdgcn_sched_barrier(0)
; template <class Epi, class Sched, bool ALIGN_EPI = false, bool SP2 = false>
; __device__ __forceinline__ void gemm_phase(PG8_LAS unsigned char* lds, const Gemm g, const Sched& S, const Epi& E, const int wid  ) {
;     ...
;             const bool last = (t == nt - 2);
;             const char* a1 = cA + (size_t)(t + 1) * kstep;
;             const char* a2 = last ? nA : cA + (size_t)(t + 2) * kstep; const char* b2 = last ? nB : cB + (size_t)(t + 2) * kstep;
;             const char* a3 = a2 + kstep; const char* b3 = b2 + kstep;
;             if (last && has_next) S.a_ready(nxt);
;             if constexpr (SP2) {
;             PG8_LDB(B0, 0, 0); PG8_LDB(B1, 0, 1); PG8_SCHED; PG8_LDA(At, 0, 0); PG8_STAGE(PG8_SA(1, 1), a1 + hstep, voffA);
;             PG8_WAIT_V(8); PG8_WAIT_L(0); PG8_BAR; PG8_MMA(0, 0, At, B0); PG8_MMA(0, 1, At, B1); PG8_BAR; PG8_SCHED;
;             PG8_LDA(At, 0, 1); PG8_STAGE(PG8_SB(0, 0), b2, voffB); PG8_STAGE(PG8_SB(0, 1), b2 + hstep, voffB); PG8_STAGE(PG8_SA(0, 0), a2, voffA);
.LBB0_549:
	s_add_u32 s100, s56, 0xfff80000
	s_addc_u32 s101, s57, -1
	ds_read_b128 v[64:67], v236
	ds_read_b128 v[68:71], v236 offset:1024
	ds_read_b128 v[80:83], v236 offset:2048
	ds_read_b128 v[84:87], v236 offset:3072
	ds_read_b128 v[144:147], v237
	ds_read_b128 v[148:151], v237 offset:1024
	ds_read_b128 v[152:155], v237 offset:2048
	ds_read_b128 v[156:159], v237 offset:3072
	s_add_u32 s58, s56, 0xfff80080
	s_addc_u32 s59, s57, -1
	s_cmp_eq_u32 s72, 28
	s_cselect_b32 s61, s9, s59
	s_cselect_b32 s60, s49, s58
	s_cselect_b32 s59, s47, s71
	s_cselect_b32 s58, s55, s70
	v_lshl_add_u64 v[196:197], s[100:101], 0, v[208:209]
	s_mov_b32 m0, s64
	v_lshl_add_u64 v[198:199], s[100:101], 0, v[210:211]
	global_load_lds_dwordx4 v[196:197], off
	s_mov_b32 m0, s65
	s_nop 0
	global_load_lds_dwordx4 v[198:199], off
	v_lshl_add_u64 v[192:193], s[56:57], 0, v[208:209]
	s_add_i32 m0, s34, 0xc000
	ds_read_b128 v[160:163], v238
	ds_read_b128 v[164:167], v238 offset:1024
	ds_read_b128 v[168:171], v238 offset:2048
	ds_read_b128 v[172:175], v238 offset:3072
	ds_read_b128 v[176:179], v238 offset:4096
	ds_read_b128 v[180:183], v238 offset:5120
	ds_read_b128 v[184:187], v238 offset:6144
	ds_read_b128 v[188:191], v238 offset:7168
	global_load_lds_dwordx4 v[192:193], off
	v_lshl_add_u64 v[192:193], s[56:57], 0, v[210:211]
	s_add_i32 m0, s34, 0xe000
	s_nop 0
	global_load_lds_dwordx4 v[192:193], off
	s_waitcnt vmcnt(8)
	s_waitcnt lgkmcnt(0)
	s_barrier
	s_setprio 1
	s_waitcnt lgkmcnt(0)
	v_mfma_f32_16x16x32_bf16 v[140:143], v[64:67], v[160:163], v[140:143]
	v_mfma_f32_16x16x32_bf16 v[136:139], v[80:83], v[160:163], v[136:139]
	v_mfma_f32_16x16x32_bf16 v[124:127], v[64:67], v[168:171], v[124:127]
	v_mfma_f32_16x16x32_bf16 v[120:123], v[80:83], v[168:171], v[120:123]
	v_mfma_f32_16x16x32_bf16 v[108:111], v[64:67], v[176:179], v[108:111]
	v_mfma_f32_16x16x32_bf16 v[104:107], v[80:83], v[176:179], v[104:107]
	v_mfma_f32_16x16x32_bf16 v[92:95], v[64:67], v[184:187], v[92:95]
	v_mfma_f32_16x16x32_bf16 v[88:91], v[80:83], v[184:187], v[88:91]
	v_mfma_f32_16x16x32_bf16 v[140:143], v[68:71], v[164:167], v[140:143]
	v_mfma_f32_16x16x32_bf16 v[136:139], v[84:87], v[164:167], v[136:139]
	v_mfma_f32_16x16x32_bf16 v[124:127], v[68:71], v[172:175], v[124:127]
	v_mfma_f32_16x16x32_bf16 v[120:123], v[84:87], v[172:175], v[120:123]
	v_mfma_f32_16x16x32_bf16 v[108:111], v[68:71], v[180:183], v[108:111]
	v_mfma_f32_16x16x32_bf16 v[104:107], v[84:87], v[180:183], v[104:107]
	v_mfma_f32_16x16x32_bf16 v[92:95], v[68:71], v[188:191], v[92:95]
	v_mfma_f32_16x16x32_bf16 v[88:91], v[84:87], v[188:191], v[88:91]
	s_setprio 0
	s_setprio 1
	v_mfma_f32_16x16x32_bf16 v[132:135], v[144:147], v[160:163], v[132:135]
	v_mfma_f32_16x16x32_bf16 v[128:131], v[152:155], v[160:163], v[128:131]
	v_mfma_f32_16x16x32_bf16 v[116:119], v[144:147], v[168:171], v[116:119]
	v_mfma_f32_16x16x32_bf16 v[112:115], v[152:155], v[168:171], v[112:115]
	v_mfma_f32_16x16x32_bf16 v[100:103], v[144:147], v[176:179], v[100:103]
	v_mfma_f32_16x16x32_bf16 v[96:99], v[152:155], v[176:179], v[96:99]
	v_mfma_f32_16x16x32_bf16 v[76:79], v[144:147], v[184:187], v[76:79]
	v_mfma_f32_16x16x32_bf16 v[72:75], v[152:155], v[184:187], v[72:75]
	v_mfma_f32_16x16x32_bf16 v[132:135], v[148:151], v[164:167], v[132:135]
	v_mfma_f32_16x16x32_bf16 v[128:131], v[156:159], v[164:167], v[128:131]
	v_mfma_f32_16x16x32_bf16 v[116:119], v[148:151], v[172:175], v[116:119]
	v_mfma_f32_16x16x32_bf16 v[112:115], v[156:159], v[172:175], v[112:115]
	v_mfma_f32_16x16x32_bf16 v[100:103], v[148:151], v[180:183], v[100:103]
	v_mfma_f32_16x16x32_bf16 v[96:99], v[156:159], v[180:183], v[96:99]
	v_mfma_f32_16x16x32_bf16 v[76:79], v[148:151], v[188:191], v[76:79]
	v_mfma_f32_16x16x32_bf16 v[72:75], v[156:159], v[188:191], v[72:75]
	s_setprio 0
	s_barrier
	s_add_i32 s73, s68, s31
	v_lshl_add_u64 v[192:193], s[58:59], 0, v[202:203]
	s_mov_b32 m0, s73
	ds_read_b128 v[160:163], v238 offset:16384
	ds_read_b128 v[164:167], v238 offset:17408
	ds_read_b128 v[168:171], v238 offset:18432
	ds_read_b128 v[172:175], v238 offset:19456
	ds_read_b128 v[176:179], v238 offset:20480
	ds_read_b128 v[180:183], v238 offset:21504
	ds_read_b128 v[184:187], v238 offset:22528
	ds_read_b128 v[188:191], v238 offset:23552
	global_load_lds_dwordx4 v[192:193], off
	s_add_i32 m0, s73, 0x2000
	s_add_u32 s74, s58, 0x80000
	v_lshl_add_u64 v[194:195], s[58:59], 0, v[206:207]
	s_addc_u32 s75, s59, 0
	s_add_i32 s73, s69, s31
	global_load_lds_dwordx4 v[194:195], off
	v_lshl_add_u64 v[196:197], s[74:75], 0, v[202:203]
	s_mov_b32 m0, s73
	s_nop 0
	global_load_lds_dwordx4 v[196:197], off
	v_lshl_add_u64 v[196:197], s[74:75], 0, v[206:207]
	s_add_i32 m0, s73, 0x2000
	s_nop 0
	global_load_lds_dwordx4 v[196:197], off
	s_waitcnt vmcnt(6)
	s_waitcnt lgkmcnt(0)
	s_barrier
; #define PG8_STAGE(bufoff, gbase, voff) do { _Pragma("unroll") for (int _i = 0; _i < 2; ++_i) \
;         __builtin_amdgcn_global_load_lds((const unsigned*)((const char*)(gbase) + (voff)[_i]), (PG8_LAS unsigned*)(lds + (bufoff) + ldsw + _i * 8192), 16, 0, 0); } while (0)
; #define PG8_LDA(dst, b, h) do { _Pragma("unroll") for (int m = 0; m < 4; ++m) _Pragma("unroll") for (int k = 0; k < 2; ++k) dst[m][k] = *(const PG8_LAS bf16x8*)(lds + PG8_SA(b, h) + aoff + m * 2048 + k * 1024); } while (0)
; #define PG8_LDB(dst, b, h) do { _Pragma("unroll") for (int n = 0; n < 2; ++n) _Pragma("unroll") for (int k = 0; k < 2; ++k) dst[n][k] = *(const PG8_LAS bf16x8*)(lds + PG8_SB(b, h) + boff + n * 2048 + k * 1024); } while (0)
; #define PG8_MMA(ai, bj, At, Bt) do { __builtin_amdgcn_s_setprio(1); _Pragma("unroll") for (int m = 0; m < 4; ++m) _Pragma("unroll") for (int n = 0; n < 2; ++n) _Pragma("unroll") for (int k = 0; k < 2; ++k) \
;         acc[ai][bj][m][n] = __builtin_amdgcn_mfma_f32_16x16x32_bf16(Bt[n][k], At[m][k], acc[ai][bj][m][n], 0, 0, 0); __builtin_amdgcn_s_setprio(0); } while (0)
; #define PG8_WAIT_V(n) asm volatile("s_waitcnt vmcnt(" #n ")" ::: "memory")
; #define PG8_WAIT_L(n) asm volatile("s_waitcnt lgkmcnt(" #n ")" ::: "memory")
; #define PG8_BAR __builtin_amdgcn_s_barrier()
; #define PG8_SCHED __builtin_amdgcn_sched_barrier(0)
; template <class Epi, class Sched, bool ALIGN_EPI = false, bool SP2 = false>
; __device__ __forceinline__ void gemm_phase(PG8_LAS unsigned char* lds, const Gemm g, const Sched& S, const Epi& E, const int wid  ) {
;     ...
;             PG8_LDA(At, 0, 1); PG8_STAGE(PG8_SB(0, 0), b2, voffB); PG8_STAGE(PG8_SB(0, 1), b2 + hstep, voffB); PG8_STAGE(PG8_SA(0, 0), a2, voffA);
;             PG8_WAIT_V(8); PG8_WAIT_L(0); PG8_BAR; PG8_MMA(1, 0, At, B0); PG8_MMA(1, 1, At, B1); PG8_BAR; PG8_SCHED;
;             PG8_LDB(B0, 1, 0); PG8_LDB(B1, 1, 1); PG8_SCHED; PG8_LDA(At, 1, 0); PG8_STAGE(PG8_SA(0, 1), a2 + hstep, voffA);
	s_setprio 1
	s_waitcnt lgkmcnt(0)
	v_mfma_f32_16x16x32_bf16 v[60:63], v[64:67], v[160:163], v[60:63]
	v_mfma_f32_16x16x32_bf16 v[56:59], v[80:83], v[160:163], v[56:59]
	v_mfma_f32_16x16x32_bf16 v[44:47], v[64:67], v[168:171], v[44:47]
	v_mfma_f32_16x16x32_bf16 v[40:43], v[80:83], v[168:171], v[40:43]
	v_mfma_f32_16x16x32_bf16 v[28:31], v[64:67], v[176:179], v[28:31]
	v_mfma_f32_16x16x32_bf16 v[24:27], v[80:83], v[176:179], v[24:27]
	v_mfma_f32_16x16x32_bf16 v[12:15], v[64:67], v[184:187], v[12:15]
	v_mfma_f32_16x16x32_bf16 v[8:11], v[80:83], v[184:187], v[8:11]
	v_mfma_f32_16x16x32_bf16 v[60:63], v[68:71], v[164:167], v[60:63]
	v_mfma_f32_16x16x32_bf16 v[56:59], v[84:87], v[164:167], v[56:59]
	v_mfma_f32_16x16x32_bf16 v[44:47], v[68:71], v[172:175], v[44:47]
	v_mfma_f32_16x16x32_bf16 v[40:43], v[84:87], v[172:175], v[40:43]
	v_mfma_f32_16x16x32_bf16 v[28:31], v[68:71], v[180:183], v[28:31]
	v_mfma_f32_16x16x32_bf16 v[24:27], v[84:87], v[180:183], v[24:27]
	v_mfma_f32_16x16x32_bf16 v[12:15], v[68:71], v[188:191], v[12:15]
	v_mfma_f32_16x16x32_bf16 v[8:11], v[84:87], v[188:191], v[8:11]
	s_setprio 0
	s_setprio 1
	v_mfma_f32_16x16x32_bf16 v[52:55], v[144:147], v[160:163], v[52:55]
	v_mfma_f32_16x16x32_bf16 v[48:51], v[152:155], v[160:163], v[48:51]
	v_mfma_f32_16x16x32_bf16 v[36:39], v[144:147], v[168:171], v[36:39]
	v_mfma_f32_16x16x32_bf16 v[32:35], v[152:155], v[168:171], v[32:35]
	v_mfma_f32_16x16x32_bf16 v[20:23], v[144:147], v[176:179], v[20:23]
	v_mfma_f32_16x16x32_bf16 v[16:19], v[152:155], v[176:179], v[16:19]
	v_mfma_f32_16x16x32_bf16 v[4:7], v[144:147], v[184:187], v[4:7]
	v_mfma_f32_16x16x32_bf16 v[0:3], v[152:155], v[184:187], v[0:3]
	v_mfma_f32_16x16x32_bf16 v[52:55], v[148:151], v[164:167], v[52:55]
	v_mfma_f32_16x16x32_bf16 v[48:51], v[156:159], v[164:167], v[48:51]
	v_mfma_f32_16x16x32_bf16 v[36:39], v[148:151], v[172:175], v[36:39]
	v_mfma_f32_16x16x32_bf16 v[32:35], v[156:159], v[172:175], v[32:35]
	v_mfma_f32_16x16x32_bf16 v[20:23], v[148:151], v[180:183], v[20:23]
	v_mfma_f32_16x16x32_bf16 v[16:19], v[156:159], v[180:183], v[16:19]
	v_mfma_f32_16x16x32_bf16 v[4:7], v[148:151], v[188:191], v[4:7]
	v_mfma_f32_16x16x32_bf16 v[0:3], v[156:159], v[188:191], v[0:3]
	s_setprio 0
	s_barrier
	s_add_i32 s73, 0, 0x18000
	s_add_i32 s74, 0, 0x1c000
	v_add_u32_e32 v84, s73, v234
	v_add_u32_e32 v156, s74, v234
	ds_read_b128 v[64:67], v84
	ds_read_b128 v[68:71], v84 offset:1024
	ds_read_b128 v[80:83], v84 offset:2048
	ds_read_b128 v[84:87], v84 offset:3072
	ds_read_b128 v[144:147], v156
	ds_read_b128 v[148:151], v156 offset:1024
	ds_read_b128 v[152:155], v156 offset:2048
	ds_read_b128 v[156:159], v156 offset:3072
	v_lshl_add_u64 v[196:197], s[60:61], 0, v[200:201]
	s_mov_b32 m0, s34
	v_lshl_add_u64 v[198:199], s[60:61], 0, v[204:205]
	global_load_lds_dwordx4 v[196:197], off
	s_mov_b32 m0, s35
	s_nop 0
	global_load_lds_dwordx4 v[198:199], off
	s_add_u32 s60, s60, 0x80000
	s_addc_u32 s61, s61, 0
	s_mov_b32 m0, s37
	v_lshl_add_u64 v[216:217], s[60:61], 0, v[200:201]
	ds_read_b128 v[160:163], v238 offset:32768
	ds_read_b128 v[164:167], v238 offset:33792
	ds_read_b128 v[168:171], v238 offset:34816
	ds_read_b128 v[172:175], v238 offset:35840
	ds_read_b128 v[176:179], v238 offset:36864
	ds_read_b128 v[180:183], v238 offset:37888
	ds_read_b128 v[184:187], v238 offset:38912
	ds_read_b128 v[188:191], v238 offset:39936
	global_load_lds_dwordx4 v[216:217], off
	v_lshl_add_u64 v[216:217], s[60:61], 0, v[204:205]
	s_mov_b32 m0, s62
	s_nop 0
	global_load_lds_dwordx4 v[216:217], off
	s_waitcnt vmcnt(8)
	s_waitcnt lgkmcnt(0)
	s_barrier
; #define PG8_STAGE(bufoff, gbase, voff) do { _Pragma("unroll") for (int _i = 0; _i < 2; ++_i) \
;         __builtin_amdgcn_global_load_lds((const unsigned*)((const char*)(gbase) + (voff)[_i]), (PG8_LAS unsigned*)(lds + (bufoff) + ldsw + _i * 8192), 16, 0, 0); } while (0)
; #define PG8_LDA(dst, b, h) do { _Pragma("unroll") for (int m = 0; m < 4; ++m) _Pragma("unroll") for (int k = 0; k < 2; ++k) dst[m][k] = *(const PG8_LAS bf16x8*)(lds + PG8_SA(b, h) + aoff + m * 2048 + k * 1024); } while (0)
; #define PG8_LDB(dst, b, h) do { _Pragma("unroll") for (int n = 0; n < 2; ++n) _Pragma("unroll") for (int k = 0; k < 2; ++k) dst[n][k] = *(const PG8_LAS bf16x8*)(lds + PG8_SB(b, h) + boff + n * 2048 + k * 1024); } while (0)
; #define PG8_MMA(ai, bj, At, Bt) do { __builtin_amdgcn_s_setprio(1); _Pragma("unroll") for (int m = 0; m < 4; ++m) _Pragma("unroll") for (int n = 0; n < 2; ++n) _Pragma("unroll") for (int k = 0; k < 2; ++k) \
;         acc[ai][bj][m][n] = __builtin_amdgcn_mfma_f32_16x16x32_bf16(Bt[n][k], At[m][k], acc[ai][bj][m][n], 0, 0, 0); __builtin_amdgcn_s_setprio(0); } while (0)
; #define PG8_WAIT_V(n) asm volatile("s_waitcnt vmcnt(" #n ")" ::: "memory")
; #define PG8_WAIT_L(n) asm volatile("s_waitcnt lgkmcnt(" #n ")" ::: "memory")
; #define PG8_BAR __builtin_amdgcn_s_barrier()
; #define PG8_SCHED __builtin_amdgcn_sched_barrier(0)
; template <class Epi, class Sched, bool ALIGN_EPI = false, bool SP2 = false>
; __device__ __forceinline__ void gemm_phase(PG8_LAS unsigned char* lds, const Gemm g, const Sched& S, const Epi& E, const int wid  ) {
;     ...
;             PG8_LDB(B0, 1, 0); PG8_LDB(B1, 1, 1); PG8_SCHED; PG8_LDA(At, 1, 0); PG8_STAGE(PG8_SA(0, 1), a2 + hstep, voffA);
;             PG8_WAIT_V(8); PG8_WAIT_L(0); PG8_BAR; PG8_MMA(0, 0, At, B0); PG8_MMA(0, 1, At, B1); PG8_BAR; PG8_SCHED;
;             PG8_LDA(At, 1, 1); PG8_STAGE(PG8_SB(1, 0), b3, voffB); PG8_STAGE(PG8_SB(1, 1), b3 + hstep, voffB); PG8_STAGE(PG8_SA(1, 0), a3, voffA);
;             PG8_WAIT_V(8); PG8_WAIT_L(0); PG8_BAR; PG8_MMA(1, 0, At, B0); PG8_MMA(1, 1, At, B1); PG8_BAR; PG8_SCHED;
	s_setprio 1
	s_waitcnt lgkmcnt(0)
	v_mfma_f32_16x16x32_bf16 v[140:143], v[64:67], v[160:163], v[140:143]
	v_mfma_f32_16x16x32_bf16 v[136:139], v[80:83], v[160:163], v[136:139]
	v_mfma_f32_16x16x32_bf16 v[124:127], v[64:67], v[168:171], v[124:127]
	v_mfma_f32_16x16x32_bf16 v[120:123], v[80:83], v[168:171], v[120:123]
	v_mfma_f32_16x16x32_bf16 v[108:111], v[64:67], v[176:179], v[108:111]
	v_mfma_f32_16x16x32_bf16 v[104:107], v[80:83], v[176:179], v[104:107]
	v_mfma_f32_16x16x32_bf16 v[92:95], v[64:67], v[184:187], v[92:95]
	v_mfma_f32_16x16x32_bf16 v[88:91], v[80:83], v[184:187], v[88:91]
	v_mfma_f32_16x16x32_bf16 v[140:143], v[68:71], v[164:167], v[140:143]
	v_mfma_f32_16x16x32_bf16 v[136:139], v[84:87], v[164:167], v[136:139]
	v_mfma_f32_16x16x32_bf16 v[124:127], v[68:71], v[172:175], v[124:127]
	v_mfma_f32_16x16x32_bf16 v[120:123], v[84:87], v[172:175], v[120:123]
	v_mfma_f32_16x16x32_bf16 v[108:111], v[68:71], v[180:183], v[108:111]
	v_mfma_f32_16x16x32_bf16 v[104:107], v[84:87], v[180:183], v[104:107]
	v_mfma_f32_16x16x32_bf16 v[92:95], v[68:71], v[188:191], v[92:95]
	v_mfma_f32_16x16x32_bf16 v[88:91], v[84:87], v[188:191], v[88:91]
	s_setprio 0
	s_setprio 1
	v_mfma_f32_16x16x32_bf16 v[132:135], v[144:147], v[160:163], v[132:135]
	v_mfma_f32_16x16x32_bf16 v[128:131], v[152:155], v[160:163], v[128:131]
	v_mfma_f32_16x16x32_bf16 v[116:119], v[144:147], v[168:171], v[116:119]
	v_mfma_f32_16x16x32_bf16 v[112:115], v[152:155], v[168:171], v[112:115]
	v_mfma_f32_16x16x32_bf16 v[100:103], v[144:147], v[176:179], v[100:103]
	v_mfma_f32_16x16x32_bf16 v[96:99], v[152:155], v[176:179], v[96:99]
	v_mfma_f32_16x16x32_bf16 v[76:79], v[144:147], v[184:187], v[76:79]
	v_mfma_f32_16x16x32_bf16 v[72:75], v[152:155], v[184:187], v[72:75]
	v_mfma_f32_16x16x32_bf16 v[132:135], v[148:151], v[164:167], v[132:135]
	v_mfma_f32_16x16x32_bf16 v[128:131], v[156:159], v[164:167], v[128:131]
	v_mfma_f32_16x16x32_bf16 v[116:119], v[148:151], v[172:175], v[116:119]
	v_mfma_f32_16x16x32_bf16 v[112:115], v[156:159], v[172:175], v[112:115]
	v_mfma_f32_16x16x32_bf16 v[100:103], v[148:151], v[180:183], v[100:103]
	v_mfma_f32_16x16x32_bf16 v[96:99], v[156:159], v[180:183], v[96:99]
	v_mfma_f32_16x16x32_bf16 v[76:79], v[148:151], v[188:191], v[76:79]
	v_mfma_f32_16x16x32_bf16 v[72:75], v[156:159], v[188:191], v[72:75]
	s_setprio 0
	s_barrier
	s_add_i32 s60, s73, s31
	v_lshl_add_u64 v[192:193], v[192:193], 0, s[40:41]
	s_mov_b32 m0, s60
	ds_read_b128 v[160:163], v238 offset:49152
	ds_read_b128 v[164:167], v238 offset:50176
	ds_read_b128 v[168:171], v238 offset:51200
	ds_read_b128 v[172:175], v238 offset:52224
	ds_read_b128 v[176:179], v238 offset:53248
	ds_read_b128 v[180:183], v238 offset:54272
	ds_read_b128 v[184:187], v238 offset:55296
	ds_read_b128 v[188:191], v238 offset:56320
	global_load_lds_dwordx4 v[192:193], off
	s_add_i32 m0, s60, 0x2000
	s_add_u32 s58, s58, 0x80080
	v_lshl_add_u64 v[192:193], v[194:195], 0, s[40:41]
	s_addc_u32 s59, s59, 0
	s_add_i32 s60, s74, s31
	global_load_lds_dwordx4 v[192:193], off
	v_lshl_add_u64 v[192:193], s[58:59], 0, v[202:203]
	s_mov_b32 m0, s60
	s_nop 0
	global_load_lds_dwordx4 v[192:193], off
	v_lshl_add_u64 v[192:193], s[58:59], 0, v[206:207]
	s_add_i32 m0, s60, 0x2000
	s_nop 0
	global_load_lds_dwordx4 v[192:193], off
	s_waitcnt vmcnt(6)
	s_waitcnt lgkmcnt(0)
	s_barrier
	s_setprio 1
	s_waitcnt lgkmcnt(0)
	v_mfma_f32_16x16x32_bf16 v[60:63], v[64:67], v[160:163], v[60:63]
	v_mfma_f32_16x16x32_bf16 v[56:59], v[80:83], v[160:163], v[56:59]
	v_mfma_f32_16x16x32_bf16 v[44:47], v[64:67], v[168:171], v[44:47]
	v_mfma_f32_16x16x32_bf16 v[40:43], v[80:83], v[168:171], v[40:43]
	v_mfma_f32_16x16x32_bf16 v[28:31], v[64:67], v[176:179], v[28:31]
	v_mfma_f32_16x16x32_bf16 v[24:27], v[80:83], v[176:179], v[24:27]
	v_mfma_f32_16x16x32_bf16 v[12:15], v[64:67], v[184:187], v[12:15]
	v_mfma_f32_16x16x32_bf16 v[8:11], v[80:83], v[184:187], v[8:11]
	v_mfma_f32_16x16x32_bf16 v[60:63], v[68:71], v[164:167], v[60:63]
	v_mfma_f32_16x16x32_bf16 v[56:59], v[84:87], v[164:167], v[56:59]
	v_mfma_f32_16x16x32_bf16 v[44:47], v[68:71], v[172:175], v[44:47]
	v_mfma_f32_16x16x32_bf16 v[40:43], v[84:87], v[172:175], v[40:43]
	v_mfma_f32_16x16x32_bf16 v[28:31], v[68:71], v[180:183], v[28:31]
	v_mfma_f32_16x16x32_bf16 v[24:27], v[84:87], v[180:183], v[24:27]
	v_mfma_f32_16x16x32_bf16 v[12:15], v[68:71], v[188:191], v[12:15]
	v_mfma_f32_16x16x32_bf16 v[8:11], v[84:87], v[188:191], v[8:11]
	s_setprio 0
	s_setprio 1
	v_mfma_f32_16x16x32_bf16 v[52:55], v[144:147], v[160:163], v[52:55]
	v_mfma_f32_16x16x32_bf16 v[48:51], v[152:155], v[160:163], v[48:51]
	v_mfma_f32_16x16x32_bf16 v[36:39], v[144:147], v[168:171], v[36:39]
	v_mfma_f32_16x16x32_bf16 v[32:35], v[152:155], v[168:171], v[32:35]
	v_mfma_f32_16x16x32_bf16 v[20:23], v[144:147], v[176:179], v[20:23]
	v_mfma_f32_16x16x32_bf16 v[16:19], v[152:155], v[176:179], v[16:19]
	v_mfma_f32_16x16x32_bf16 v[4:7], v[144:147], v[184:187], v[4:7]
	v_mfma_f32_16x16x32_bf16 v[0:3], v[152:155], v[184:187], v[0:3]
	v_mfma_f32_16x16x32_bf16 v[52:55], v[148:151], v[164:167], v[52:55]
	v_mfma_f32_16x16x32_bf16 v[48:51], v[156:159], v[164:167], v[48:51]
	v_mfma_f32_16x16x32_bf16 v[36:39], v[148:151], v[172:175], v[36:39]
	v_mfma_f32_16x16x32_bf16 v[32:35], v[156:159], v[172:175], v[32:35]
	v_mfma_f32_16x16x32_bf16 v[20:23], v[148:151], v[180:183], v[20:23]
	v_mfma_f32_16x16x32_bf16 v[16:19], v[156:159], v[180:183], v[16:19]
	v_mfma_f32_16x16x32_bf16 v[4:7], v[148:151], v[188:191], v[4:7]
	v_mfma_f32_16x16x32_bf16 v[0:3], v[156:159], v[188:191], v[0:3]
	s_setprio 0
	s_barrier
	s_add_i32 s72, s72, 2
	s_add_u32 s56, s56, 0x100
	s_addc_u32 s57, s57, 0
	s_add_u32 s70, s70, 0x100
	s_addc_u32 s71, s71, 0
	s_cmp_gt_u32 s72, 29
	s_cbranch_scc0 .LBB0_549
	s_and_b64 vcc, exec, s[42:43]
	s_cbranch_vccz .LBB0_552
	s_barrier

; #define PG8_STAGE(bufoff, gbase, voff) do { _Pragma("unroll") for (int _i = 0; _i < 2; ++_i) \
;         __builtin_amdgcn_global_load_lds((const unsigned*)((const char*)(gbase) + (voff)[_i]), (PG8_LAS unsigned*)(lds + (bufoff) + ldsw + _i * 8192), 16, 0, 0); } while (0)
; #define PG8_LDA(dst, b, h) do { _Pragma("unroll") for (int m = 0; m < 4; ++m) _Pragma("unroll") for (int k = 0; k < 2; ++k) dst[m][k] = *(const PG8_LAS bf16x8*)(lds + PG8_SA(b, h) + aoff + m * 2048 + k * 1024); } while (0)
; #define PG8_LDB(dst, b, h) do { _Pragma("unroll") for (int n = 0; n < 2; ++n) _Pragma("unroll") for (int k = 0; k < 2; ++k) dst[n][k] = *(const PG8_LAS bf16x8*)(lds + PG8_SB(b, h) + boff + n * 2048 + k * 1024); } while (0)
; #define PG8_MMA(ai, bj, At, Bt) do { __builtin_amdgcn_s_setprio(1); _Pragma("unroll") for (int m = 0; m < 4; ++m) _Pragma("unroll") for (int n = 0; n < 2; ++n) _Pragma("unroll") for (int k = 0; k < 2; ++k) \
;         acc[ai][bj][m][n] = __builtin_amdgcn_mfma_f32_16x16x32_bf16(Bt[n][k], At[m][k], acc[ai][bj][m][n], 0, 0, 0); __builtin_amdgcn_s_setprio(0); } while (0)
; #define PG8_WAIT_V(n) asm volatile("s_waitcnt vmcnt(" #n ")" ::: "memory")
; #define PG8_WAIT_L(n) asm volatile("s_waitcnt lgkmcnt(" #n ")" ::: "memory")
; #define PG8_BAR __builtin_amdgcn_s_barrier()
; #define PG8_SCHED __builtin_amdgcn_sched_barrier(0)
; template <class Epi, class Sched, bool ALIGN_EPI = false, bool SP2 = false>
; __device__ __forceinline__ void gemm_phase(PG8_LAS unsigned char* lds, const Gemm g, const Sched& S, const Epi& E, const int wid  ) {
;     ...
;             const bool last = (t == nt - 2);
;             const char* a1 = cA + (size_t)(t + 1) * kstep;
;             const char* a2 = last ? nA : cA + (size_t)(t + 2) * kstep; const char* b2 = last ? nB : cB + (size_t)(t + 2) * kstep;
;             const char* a3 = a2 + kstep; const char* b3 = b2 + kstep;
;             if (last && has_next) S.a_ready(nxt);
;             if constexpr (SP2) {
;             PG8_LDB(B0, 0, 0); PG8_LDB(B1, 0, 1); PG8_SCHED; PG8_LDA(At, 0, 0); PG8_STAGE(PG8_SA(1, 1), a1 + hstep, voffA);
;             PG8_WAIT_V(8); PG8_WAIT_L(0); PG8_BAR; PG8_MMA(0, 0, At, B0); PG8_MMA(0, 1, At, B1); PG8_BAR; PG8_SCHED;
;             PG8_LDA(At, 0, 1); PG8_STAGE(PG8_SB(0, 0), b2, voffB); PG8_STAGE(PG8_SB(0, 1), b2 + hstep, voffB); PG8_STAGE(PG8_SA(0, 0), a2, voffA);
.LBB0_687:
	s_add_u32 s100, s8, 0xfff80000
	s_addc_u32 s101, s9, -1
	ds_read_b128 v[144:147], v153
	ds_read_b128 v[158:161], v153 offset:1024
	ds_read_b128 v[162:165], v153 offset:2048
	ds_read_b128 v[166:169], v153 offset:3072
	ds_read_b128 v[170:173], v154
	ds_read_b128 v[174:177], v154 offset:1024
	ds_read_b128 v[178:181], v154 offset:2048
	ds_read_b128 v[182:185], v154 offset:3072
	s_add_u32 s10, s8, 0xfff80080
	s_addc_u32 s11, s9, -1
	s_cmp_eq_u32 s67, 28
	s_cselect_b32 s13, s14, s11
	s_cselect_b32 s12, s15, s10
	s_cselect_b32 s11, s47, s66
	s_cselect_b32 s10, s49, s65
	v_lshl_add_u64 v[222:223], s[100:101], 0, v[136:137]
	s_mov_b32 m0, s58
	v_lshl_add_u64 v[224:225], s[100:101], 0, v[138:139]
	global_load_lds_dwordx4 v[222:223], off
	s_mov_b32 m0, s59
	s_nop 0
	global_load_lds_dwordx4 v[224:225], off
	v_lshl_add_u64 v[218:219], s[8:9], 0, v[136:137]
	s_add_i32 m0, s37, 0xc000
	ds_read_b128 v[186:189], v155
	ds_read_b128 v[190:193], v155 offset:1024
	ds_read_b128 v[194:197], v155 offset:2048
	ds_read_b128 v[198:201], v155 offset:3072
	ds_read_b128 v[202:205], v155 offset:4096
	ds_read_b128 v[206:209], v155 offset:5120
	ds_read_b128 v[210:213], v155 offset:6144
	ds_read_b128 v[214:217], v155 offset:7168
	global_load_lds_dwordx4 v[218:219], off
	v_lshl_add_u64 v[218:219], s[8:9], 0, v[138:139]
	s_add_i32 m0, s37, 0xe000
	s_nop 0
	global_load_lds_dwordx4 v[218:219], off
	s_waitcnt vmcnt(8)
	s_waitcnt lgkmcnt(0)
	s_barrier
	s_setprio 1
	s_waitcnt lgkmcnt(0)
	v_mfma_f32_16x16x32_bf16 v[124:127], v[144:147], v[186:189], v[124:127]
	v_mfma_f32_16x16x32_bf16 v[120:123], v[162:165], v[186:189], v[120:123]
	v_mfma_f32_16x16x32_bf16 v[108:111], v[144:147], v[194:197], v[108:111]
	v_mfma_f32_16x16x32_bf16 v[104:107], v[162:165], v[194:197], v[104:107]
	v_mfma_f32_16x16x32_bf16 v[92:95], v[144:147], v[202:205], v[92:95]
	v_mfma_f32_16x16x32_bf16 v[88:91], v[162:165], v[202:205], v[88:91]
	v_mfma_f32_16x16x32_bf16 v[76:79], v[144:147], v[210:213], v[76:79]
	v_mfma_f32_16x16x32_bf16 v[72:75], v[162:165], v[210:213], v[72:75]
	v_mfma_f32_16x16x32_bf16 v[124:127], v[158:161], v[190:193], v[124:127]
	v_mfma_f32_16x16x32_bf16 v[120:123], v[166:169], v[190:193], v[120:123]
	v_mfma_f32_16x16x32_bf16 v[108:111], v[158:161], v[198:201], v[108:111]
	v_mfma_f32_16x16x32_bf16 v[104:107], v[166:169], v[198:201], v[104:107]
	v_mfma_f32_16x16x32_bf16 v[92:95], v[158:161], v[206:209], v[92:95]
	v_mfma_f32_16x16x32_bf16 v[88:91], v[166:169], v[206:209], v[88:91]
	v_mfma_f32_16x16x32_bf16 v[76:79], v[158:161], v[214:217], v[76:79]
	v_mfma_f32_16x16x32_bf16 v[72:75], v[166:169], v[214:217], v[72:75]
	s_setprio 0
	s_setprio 1
	v_mfma_f32_16x16x32_bf16 v[116:119], v[170:173], v[186:189], v[116:119]
	v_mfma_f32_16x16x32_bf16 v[112:115], v[178:181], v[186:189], v[112:115]
	v_mfma_f32_16x16x32_bf16 v[100:103], v[170:173], v[194:197], v[100:103]
	v_mfma_f32_16x16x32_bf16 v[96:99], v[178:181], v[194:197], v[96:99]
	v_mfma_f32_16x16x32_bf16 v[84:87], v[170:173], v[202:205], v[84:87]
	v_mfma_f32_16x16x32_bf16 v[80:83], v[178:181], v[202:205], v[80:83]
	v_mfma_f32_16x16x32_bf16 v[68:71], v[170:173], v[210:213], v[68:71]
	v_mfma_f32_16x16x32_bf16 v[64:67], v[178:181], v[210:213], v[64:67]
	v_mfma_f32_16x16x32_bf16 v[116:119], v[174:177], v[190:193], v[116:119]
	v_mfma_f32_16x16x32_bf16 v[112:115], v[182:185], v[190:193], v[112:115]
	v_mfma_f32_16x16x32_bf16 v[100:103], v[174:177], v[198:201], v[100:103]
	v_mfma_f32_16x16x32_bf16 v[96:99], v[182:185], v[198:201], v[96:99]
	v_mfma_f32_16x16x32_bf16 v[84:87], v[174:177], v[206:209], v[84:87]
	v_mfma_f32_16x16x32_bf16 v[80:83], v[182:185], v[206:209], v[80:83]
	v_mfma_f32_16x16x32_bf16 v[68:71], v[174:177], v[214:217], v[68:71]
	v_mfma_f32_16x16x32_bf16 v[64:67], v[182:185], v[214:217], v[64:67]
	s_setprio 0
	s_barrier
	s_add_i32 s68, s61, s31
	v_lshl_add_u64 v[218:219], s[10:11], 0, v[132:133]
	s_mov_b32 m0, s68
	ds_read_b128 v[186:189], v155 offset:16384
	ds_read_b128 v[190:193], v155 offset:17408
	ds_read_b128 v[194:197], v155 offset:18432
	ds_read_b128 v[198:201], v155 offset:19456
	ds_read_b128 v[202:205], v155 offset:20480
	ds_read_b128 v[206:209], v155 offset:21504
	ds_read_b128 v[210:213], v155 offset:22528
	ds_read_b128 v[214:217], v155 offset:23552
	global_load_lds_dwordx4 v[218:219], off
	s_add_i32 m0, s68, 0x2000
	s_add_u32 s68, s10, 0x80000
	v_lshl_add_u64 v[220:221], s[10:11], 0, v[128:129]
	s_addc_u32 s69, s11, 0
	s_add_i32 s70, s62, s31
	global_load_lds_dwordx4 v[220:221], off
	v_lshl_add_u64 v[222:223], s[68:69], 0, v[132:133]
	s_mov_b32 m0, s70
	s_nop 0
	global_load_lds_dwordx4 v[222:223], off
	v_lshl_add_u64 v[222:223], s[68:69], 0, v[128:129]
	s_add_i32 m0, s70, 0x2000
	s_nop 0
	global_load_lds_dwordx4 v[222:223], off
	s_waitcnt vmcnt(6)
	s_waitcnt lgkmcnt(0)
	s_barrier
; #define PG8_STAGE(bufoff, gbase, voff) do { _Pragma("unroll") for (int _i = 0; _i < 2; ++_i) \
;         __builtin_amdgcn_global_load_lds((const unsigned*)((const char*)(gbase) + (voff)[_i]), (PG8_LAS unsigned*)(lds + (bufoff) + ldsw + _i * 8192), 16, 0, 0); } while (0)
; #define PG8_LDA(dst, b, h) do { _Pragma("unroll") for (int m = 0; m < 4; ++m) _Pragma("unroll") for (int k = 0; k < 2; ++k) dst[m][k] = *(const PG8_LAS bf16x8*)(lds + PG8_SA(b, h) + aoff + m * 2048 + k * 1024); } while (0)
; #define PG8_LDB(dst, b, h) do { _Pragma("unroll") for (int n = 0; n < 2; ++n) _Pragma("unroll") for (int k = 0; k < 2; ++k) dst[n][k] = *(const PG8_LAS bf16x8*)(lds + PG8_SB(b, h) + boff + n * 2048 + k * 1024); } while (0)
; #define PG8_MMA(ai, bj, At, Bt) do { __builtin_amdgcn_s_setprio(1); _Pragma("unroll") for (int m = 0; m < 4; ++m) _Pragma("unroll") for (int n = 0; n < 2; ++n) _Pragma("unroll") for (int k = 0; k < 2; ++k) \
;         acc[ai][bj][m][n] = __builtin_amdgcn_mfma_f32_16x16x32_bf16(Bt[n][k], At[m][k], acc[ai][bj][m][n], 0, 0, 0); __builtin_amdgcn_s_setprio(0); } while (0)
; #define PG8_WAIT_V(n) asm volatile("s_waitcnt vmcnt(" #n ")" ::: "memory")
; #define PG8_WAIT_L(n) asm volatile("s_waitcnt lgkmcnt(" #n ")" ::: "memory")
; #define PG8_BAR __builtin_amdgcn_s_barrier()
; #define PG8_SCHED __builtin_amdgcn_sched_barrier(0)
; template <class Epi, class Sched, bool ALIGN_EPI = false, bool SP2 = false>
; __device__ __forceinline__ void gemm_phase(PG8_LAS unsigned char* lds, const Gemm g, const Sched& S, const Epi& E, const int wid  ) {
;     ...
;             PG8_LDA(At, 0, 1); PG8_STAGE(PG8_SB(0, 0), b2, voffB); PG8_STAGE(PG8_SB(0, 1), b2 + hstep, voffB); PG8_STAGE(PG8_SA(0, 0), a2, voffA);
;             PG8_WAIT_V(8); PG8_WAIT_L(0); PG8_BAR; PG8_MMA(1, 0, At, B0); PG8_MMA(1, 1, At, B1); PG8_BAR; PG8_SCHED;
;             PG8_LDB(B0, 1, 0); PG8_LDB(B1, 1, 1); PG8_SCHED; PG8_LDA(At, 1, 0); PG8_STAGE(PG8_SA(0, 1), a2 + hstep, voffA);
	s_setprio 1
	s_waitcnt lgkmcnt(0)
	v_mfma_f32_16x16x32_bf16 v[60:63], v[144:147], v[186:189], v[60:63]
	v_mfma_f32_16x16x32_bf16 v[56:59], v[162:165], v[186:189], v[56:59]
	v_mfma_f32_16x16x32_bf16 v[44:47], v[144:147], v[194:197], v[44:47]
	v_mfma_f32_16x16x32_bf16 v[40:43], v[162:165], v[194:197], v[40:43]
	v_mfma_f32_16x16x32_bf16 v[28:31], v[144:147], v[202:205], v[28:31]
	v_mfma_f32_16x16x32_bf16 v[24:27], v[162:165], v[202:205], v[24:27]
	v_mfma_f32_16x16x32_bf16 v[12:15], v[144:147], v[210:213], v[12:15]
	v_mfma_f32_16x16x32_bf16 v[8:11], v[162:165], v[210:213], v[8:11]
	v_mfma_f32_16x16x32_bf16 v[60:63], v[158:161], v[190:193], v[60:63]
	v_mfma_f32_16x16x32_bf16 v[56:59], v[166:169], v[190:193], v[56:59]
	v_mfma_f32_16x16x32_bf16 v[44:47], v[158:161], v[198:201], v[44:47]
	v_mfma_f32_16x16x32_bf16 v[40:43], v[166:169], v[198:201], v[40:43]
	v_mfma_f32_16x16x32_bf16 v[28:31], v[158:161], v[206:209], v[28:31]
	v_mfma_f32_16x16x32_bf16 v[24:27], v[166:169], v[206:209], v[24:27]
	v_mfma_f32_16x16x32_bf16 v[12:15], v[158:161], v[214:217], v[12:15]
	v_mfma_f32_16x16x32_bf16 v[8:11], v[166:169], v[214:217], v[8:11]
	s_setprio 0
	s_setprio 1
	v_mfma_f32_16x16x32_bf16 v[52:55], v[170:173], v[186:189], v[52:55]
	v_mfma_f32_16x16x32_bf16 v[48:51], v[178:181], v[186:189], v[48:51]
	v_mfma_f32_16x16x32_bf16 v[36:39], v[170:173], v[194:197], v[36:39]
	v_mfma_f32_16x16x32_bf16 v[32:35], v[178:181], v[194:197], v[32:35]
	v_mfma_f32_16x16x32_bf16 v[20:23], v[170:173], v[202:205], v[20:23]
	v_mfma_f32_16x16x32_bf16 v[16:19], v[178:181], v[202:205], v[16:19]
	v_mfma_f32_16x16x32_bf16 v[4:7], v[170:173], v[210:213], v[4:7]
	v_mfma_f32_16x16x32_bf16 v[0:3], v[178:181], v[210:213], v[0:3]
	v_mfma_f32_16x16x32_bf16 v[52:55], v[174:177], v[190:193], v[52:55]
	v_mfma_f32_16x16x32_bf16 v[48:51], v[182:185], v[190:193], v[48:51]
	v_mfma_f32_16x16x32_bf16 v[36:39], v[174:177], v[198:201], v[36:39]
	v_mfma_f32_16x16x32_bf16 v[32:35], v[182:185], v[198:201], v[32:35]
	v_mfma_f32_16x16x32_bf16 v[20:23], v[174:177], v[206:209], v[20:23]
	v_mfma_f32_16x16x32_bf16 v[16:19], v[182:185], v[206:209], v[16:19]
	v_mfma_f32_16x16x32_bf16 v[4:7], v[174:177], v[214:217], v[4:7]
	v_mfma_f32_16x16x32_bf16 v[0:3], v[182:185], v[214:217], v[0:3]
	s_setprio 0
	s_barrier
	s_add_i32 s68, 0, 0x18000
	v_add_u32_e32 v148, s68, v151
	s_add_i32 s69, 0, 0x1c000
	ds_read_b128 v[144:147], v148
	ds_read_b128 v[158:161], v148 offset:1024
	ds_read_b128 v[162:165], v148 offset:2048
	ds_read_b128 v[166:169], v148 offset:3072
	v_add_u32_e32 v148, s69, v151
	ds_read_b128 v[170:173], v148
	ds_read_b128 v[174:177], v148 offset:1024
	ds_read_b128 v[178:181], v148 offset:2048
	ds_read_b128 v[182:185], v148 offset:3072
	v_lshl_add_u64 v[222:223], s[12:13], 0, v[134:135]
	s_mov_b32 m0, s37
	v_lshl_add_u64 v[224:225], s[12:13], 0, v[130:131]
	global_load_lds_dwordx4 v[222:223], off
	s_mov_b32 m0, s54
	s_nop 0
	global_load_lds_dwordx4 v[224:225], off
	s_add_u32 s12, s12, 0x80000
	s_addc_u32 s13, s13, 0
	s_mov_b32 m0, s55
	v_lshl_add_u64 v[226:227], s[12:13], 0, v[134:135]
	ds_read_b128 v[186:189], v155 offset:32768
	ds_read_b128 v[190:193], v155 offset:33792
	ds_read_b128 v[194:197], v155 offset:34816
	ds_read_b128 v[198:201], v155 offset:35840
	ds_read_b128 v[202:205], v155 offset:36864
	ds_read_b128 v[206:209], v155 offset:37888
	ds_read_b128 v[210:213], v155 offset:38912
	ds_read_b128 v[214:217], v155 offset:39936
	global_load_lds_dwordx4 v[226:227], off
	v_lshl_add_u64 v[226:227], s[12:13], 0, v[130:131]
	s_mov_b32 m0, s56
	s_nop 0
	global_load_lds_dwordx4 v[226:227], off
	s_waitcnt vmcnt(8)
	s_waitcnt lgkmcnt(0)
	s_barrier
; #define PG8_STAGE(bufoff, gbase, voff) do { _Pragma("unroll") for (int _i = 0; _i < 2; ++_i) \
;         __builtin_amdgcn_global_load_lds((const unsigned*)((const char*)(gbase) + (voff)[_i]), (PG8_LAS unsigned*)(lds + (bufoff) + ldsw + _i * 8192), 16, 0, 0); } while (0)
; #define PG8_LDA(dst, b, h) do { _Pragma("unroll") for (int m = 0; m < 4; ++m) _Pragma("unroll") for (int k = 0; k < 2; ++k) dst[m][k] = *(const PG8_LAS bf16x8*)(lds + PG8_SA(b, h) + aoff + m * 2048 + k * 1024); } while (0)
; #define PG8_LDB(dst, b, h) do { _Pragma("unroll") for (int n = 0; n < 2; ++n) _Pragma("unroll") for (int k = 0; k < 2; ++k) dst[n][k] = *(const PG8_LAS bf16x8*)(lds + PG8_SB(b, h) + boff + n * 2048 + k * 1024); } while (0)
; #define PG8_MMA(ai, bj, At, Bt) do { __builtin_amdgcn_s_setprio(1); _Pragma("unroll") for (int m = 0; m < 4; ++m) _Pragma("unroll") for (int n = 0; n < 2; ++n) _Pragma("unroll") for (int k = 0; k < 2; ++k) \
;         acc[ai][bj][m][n] = __builtin_amdgcn_mfma_f32_16x16x32_bf16(Bt[n][k], At[m][k], acc[ai][bj][m][n], 0, 0, 0); __builtin_amdgcn_s_setprio(0); } while (0)
; #define PG8_WAIT_V(n) asm volatile("s_waitcnt vmcnt(" #n ")" ::: "memory")
; #define PG8_WAIT_L(n) asm volatile("s_waitcnt lgkmcnt(" #n ")" ::: "memory")
; #define PG8_BAR __builtin_amdgcn_s_barrier()
; #define PG8_SCHED __builtin_amdgcn_sched_barrier(0)
; template <class Epi, class Sched, bool ALIGN_EPI = false, bool SP2 = false>
; __device__ __forceinline__ void gemm_phase(PG8_LAS unsigned char* lds, const Gemm g, const Sched& S, const Epi& E, const int wid  ) {
;     ...
;             PG8_LDB(B0, 1, 0); PG8_LDB(B1, 1, 1); PG8_SCHED; PG8_LDA(At, 1, 0); PG8_STAGE(PG8_SA(0, 1), a2 + hstep, voffA);
;             PG8_WAIT_V(8); PG8_WAIT_L(0); PG8_BAR; PG8_MMA(0, 0, At, B0); PG8_MMA(0, 1, At, B1); PG8_BAR; PG8_SCHED;
;             PG8_LDA(At, 1, 1); PG8_STAGE(PG8_SB(1, 0), b3, voffB); PG8_STAGE(PG8_SB(1, 1), b3 + hstep, voffB); PG8_STAGE(PG8_SA(1, 0), a3, voffA);
;             PG8_WAIT_V(8); PG8_WAIT_L(0); PG8_BAR; PG8_MMA(1, 0, At, B0); PG8_MMA(1, 1, At, B1); PG8_BAR; PG8_SCHED;
	s_setprio 1
	s_waitcnt lgkmcnt(0)
	v_mfma_f32_16x16x32_bf16 v[124:127], v[144:147], v[186:189], v[124:127]
	v_mfma_f32_16x16x32_bf16 v[120:123], v[162:165], v[186:189], v[120:123]
	v_mfma_f32_16x16x32_bf16 v[108:111], v[144:147], v[194:197], v[108:111]
	v_mfma_f32_16x16x32_bf16 v[104:107], v[162:165], v[194:197], v[104:107]
	v_mfma_f32_16x16x32_bf16 v[92:95], v[144:147], v[202:205], v[92:95]
	v_mfma_f32_16x16x32_bf16 v[88:91], v[162:165], v[202:205], v[88:91]
	v_mfma_f32_16x16x32_bf16 v[76:79], v[144:147], v[210:213], v[76:79]
	v_mfma_f32_16x16x32_bf16 v[72:75], v[162:165], v[210:213], v[72:75]
	v_mfma_f32_16x16x32_bf16 v[124:127], v[158:161], v[190:193], v[124:127]
	v_mfma_f32_16x16x32_bf16 v[120:123], v[166:169], v[190:193], v[120:123]
	v_mfma_f32_16x16x32_bf16 v[108:111], v[158:161], v[198:201], v[108:111]
	v_mfma_f32_16x16x32_bf16 v[104:107], v[166:169], v[198:201], v[104:107]
	v_mfma_f32_16x16x32_bf16 v[92:95], v[158:161], v[206:209], v[92:95]
	v_mfma_f32_16x16x32_bf16 v[88:91], v[166:169], v[206:209], v[88:91]
	v_mfma_f32_16x16x32_bf16 v[76:79], v[158:161], v[214:217], v[76:79]
	v_mfma_f32_16x16x32_bf16 v[72:75], v[166:169], v[214:217], v[72:75]
	s_setprio 0
	s_setprio 1
	v_mfma_f32_16x16x32_bf16 v[116:119], v[170:173], v[186:189], v[116:119]
	v_mfma_f32_16x16x32_bf16 v[112:115], v[178:181], v[186:189], v[112:115]
	v_mfma_f32_16x16x32_bf16 v[100:103], v[170:173], v[194:197], v[100:103]
	v_mfma_f32_16x16x32_bf16 v[96:99], v[178:181], v[194:197], v[96:99]
	v_mfma_f32_16x16x32_bf16 v[84:87], v[170:173], v[202:205], v[84:87]
	v_mfma_f32_16x16x32_bf16 v[80:83], v[178:181], v[202:205], v[80:83]
	v_mfma_f32_16x16x32_bf16 v[68:71], v[170:173], v[210:213], v[68:71]
	v_mfma_f32_16x16x32_bf16 v[64:67], v[178:181], v[210:213], v[64:67]
	v_mfma_f32_16x16x32_bf16 v[116:119], v[174:177], v[190:193], v[116:119]
	v_mfma_f32_16x16x32_bf16 v[112:115], v[182:185], v[190:193], v[112:115]
	v_mfma_f32_16x16x32_bf16 v[100:103], v[174:177], v[198:201], v[100:103]
	v_mfma_f32_16x16x32_bf16 v[96:99], v[182:185], v[198:201], v[96:99]
	v_mfma_f32_16x16x32_bf16 v[84:87], v[174:177], v[206:209], v[84:87]
	v_mfma_f32_16x16x32_bf16 v[80:83], v[182:185], v[206:209], v[80:83]
	v_mfma_f32_16x16x32_bf16 v[68:71], v[174:177], v[214:217], v[68:71]
	v_mfma_f32_16x16x32_bf16 v[64:67], v[182:185], v[214:217], v[64:67]
	s_setprio 0
	s_barrier
	s_add_i32 s12, s68, s31
	v_lshl_add_u64 v[218:219], v[218:219], 0, s[42:43]
	s_mov_b32 m0, s12
	ds_read_b128 v[186:189], v155 offset:49152
	ds_read_b128 v[190:193], v155 offset:50176
	ds_read_b128 v[194:197], v155 offset:51200
	ds_read_b128 v[198:201], v155 offset:52224
	ds_read_b128 v[202:205], v155 offset:53248
	ds_read_b128 v[206:209], v155 offset:54272
	ds_read_b128 v[210:213], v155 offset:55296
	ds_read_b128 v[214:217], v155 offset:56320
	global_load_lds_dwordx4 v[218:219], off
	s_add_i32 m0, s12, 0x2000
	s_add_u32 s10, s10, 0x80080
	v_lshl_add_u64 v[218:219], v[220:221], 0, s[42:43]
	s_addc_u32 s11, s11, 0
	s_add_i32 s12, s69, s31
	global_load_lds_dwordx4 v[218:219], off
	v_lshl_add_u64 v[218:219], s[10:11], 0, v[132:133]
	s_mov_b32 m0, s12
	s_nop 0
	global_load_lds_dwordx4 v[218:219], off
	v_lshl_add_u64 v[218:219], s[10:11], 0, v[128:129]
	s_add_i32 m0, s12, 0x2000
	s_nop 0
	global_load_lds_dwordx4 v[218:219], off
	s_waitcnt vmcnt(6)
	s_waitcnt lgkmcnt(0)
	s_barrier
	s_setprio 1
	s_waitcnt lgkmcnt(0)
	v_mfma_f32_16x16x32_bf16 v[60:63], v[144:147], v[186:189], v[60:63]
	v_mfma_f32_16x16x32_bf16 v[56:59], v[162:165], v[186:189], v[56:59]
	v_mfma_f32_16x16x32_bf16 v[44:47], v[144:147], v[194:197], v[44:47]
	v_mfma_f32_16x16x32_bf16 v[40:43], v[162:165], v[194:197], v[40:43]
	v_mfma_f32_16x16x32_bf16 v[28:31], v[144:147], v[202:205], v[28:31]
	v_mfma_f32_16x16x32_bf16 v[24:27], v[162:165], v[202:205], v[24:27]
	v_mfma_f32_16x16x32_bf16 v[12:15], v[144:147], v[210:213], v[12:15]
	v_mfma_f32_16x16x32_bf16 v[8:11], v[162:165], v[210:213], v[8:11]
	v_mfma_f32_16x16x32_bf16 v[60:63], v[158:161], v[190:193], v[60:63]
	v_mfma_f32_16x16x32_bf16 v[56:59], v[166:169], v[190:193], v[56:59]
	v_mfma_f32_16x16x32_bf16 v[44:47], v[158:161], v[198:201], v[44:47]
	v_mfma_f32_16x16x32_bf16 v[40:43], v[166:169], v[198:201], v[40:43]
	v_mfma_f32_16x16x32_bf16 v[28:31], v[158:161], v[206:209], v[28:31]
	v_mfma_f32_16x16x32_bf16 v[24:27], v[166:169], v[206:209], v[24:27]
	v_mfma_f32_16x16x32_bf16 v[12:15], v[158:161], v[214:217], v[12:15]
	v_mfma_f32_16x16x32_bf16 v[8:11], v[166:169], v[214:217], v[8:11]
	s_setprio 0
	s_setprio 1
	v_mfma_f32_16x16x32_bf16 v[52:55], v[170:173], v[186:189], v[52:55]
	v_mfma_f32_16x16x32_bf16 v[48:51], v[178:181], v[186:189], v[48:51]
	v_mfma_f32_16x16x32_bf16 v[36:39], v[170:173], v[194:197], v[36:39]
	v_mfma_f32_16x16x32_bf16 v[32:35], v[178:181], v[194:197], v[32:35]
	v_mfma_f32_16x16x32_bf16 v[20:23], v[170:173], v[202:205], v[20:23]
	v_mfma_f32_16x16x32_bf16 v[16:19], v[178:181], v[202:205], v[16:19]
	v_mfma_f32_16x16x32_bf16 v[4:7], v[170:173], v[210:213], v[4:7]
	v_mfma_f32_16x16x32_bf16 v[0:3], v[178:181], v[210:213], v[0:3]
	v_mfma_f32_16x16x32_bf16 v[52:55], v[174:177], v[190:193], v[52:55]
	v_mfma_f32_16x16x32_bf16 v[48:51], v[182:185], v[190:193], v[48:51]
	v_mfma_f32_16x16x32_bf16 v[36:39], v[174:177], v[198:201], v[36:39]
	v_mfma_f32_16x16x32_bf16 v[32:35], v[182:185], v[198:201], v[32:35]
	v_mfma_f32_16x16x32_bf16 v[20:23], v[174:177], v[206:209], v[20:23]
	v_mfma_f32_16x16x32_bf16 v[16:19], v[182:185], v[206:209], v[16:19]
	v_mfma_f32_16x16x32_bf16 v[4:7], v[174:177], v[214:217], v[4:7]
	v_mfma_f32_16x16x32_bf16 v[0:3], v[182:185], v[214:217], v[0:3]
	s_setprio 0
	s_barrier
	s_add_i32 s67, s67, 2
	s_add_u32 s8, s8, 0x100
	s_addc_u32 s9, s9, 0
	s_add_u32 s65, s65, 0x100
	s_addc_u32 s66, s66, 0
	s_cmp_gt_u32 s67, 29
	s_cbranch_scc0 .LBB0_687
	s_and_b64 vcc, exec, s[44:45]
	s_cbranch_vccz .LBB0_690
	s_barrier

; #define PG8_STAGE(bufoff, gbase, voff) do { _Pragma("unroll") for (int _i = 0; _i < 2; ++_i) \
;         __builtin_amdgcn_global_load_lds((const unsigned*)((const char*)(gbase) + (voff)[_i]), (PG8_LAS unsigned*)(lds + (bufoff) + ldsw + _i * 8192), 16, 0, 0); } while (0)
; #define PG8_LDA(dst, b, h) do { _Pragma("unroll") for (int m = 0; m < 4; ++m) _Pragma("unroll") for (int k = 0; k < 2; ++k) dst[m][k] = *(const PG8_LAS bf16x8*)(lds + PG8_SA(b, h) + aoff + m * 2048 + k * 1024); } while (0)
; #define PG8_LDB(dst, b, h) do { _Pragma("unroll") for (int n = 0; n < 2; ++n) _Pragma("unroll") for (int k = 0; k < 2; ++k) dst[n][k] = *(const PG8_LAS bf16x8*)(lds + PG8_SB(b, h) + boff + n * 2048 + k * 1024); } while (0)
; #define PG8_MMA(ai, bj, At, Bt) do { __builtin_amdgcn_s_setprio(1); _Pragma("unroll") for (int m = 0; m < 4; ++m) _Pragma("unroll") for (int n = 0; n < 2; ++n) _Pragma("unroll") for (int k = 0; k < 2; ++k) \
;         acc[ai][bj][m][n] = __builtin_amdgcn_mfma_f32_16x16x32_bf16(Bt[n][k], At[m][k], acc[ai][bj][m][n], 0, 0, 0); __builtin_amdgcn_s_setprio(0); } while (0)
; #define PG8_WAIT_V(n) asm volatile("s_waitcnt vmcnt(" #n ")" ::: "memory")
; #define PG8_WAIT_L(n) asm volatile("s_waitcnt lgkmcnt(" #n ")" ::: "memory")
; #define PG8_BAR __builtin_amdgcn_s_barrier()
; #define PG8_SCHED __builtin_amdgcn_sched_barrier(0)
; template <class Epi, class Sched, bool ALIGN_EPI = false, bool SP2 = false>
; __device__ __forceinline__ void gemm_phase(PG8_LAS unsigned char* lds, const Gemm g, const Sched& S, const Epi& E, const int wid  ) {
;     ...
;             const bool last = (t == nt - 2);
;             const char* a1 = cA + (size_t)(t + 1) * kstep;
;             const char* a2 = last ? nA : cA + (size_t)(t + 2) * kstep; const char* b2 = last ? nB : cB + (size_t)(t + 2) * kstep;
;             const char* a3 = a2 + kstep; const char* b3 = b2 + kstep;
;             if (last && has_next) S.a_ready(nxt);
;             if constexpr (SP2) {
;             PG8_LDB(B0, 0, 0); PG8_LDB(B1, 0, 1); PG8_SCHED; PG8_LDA(At, 0, 0); PG8_STAGE(PG8_SA(1, 1), a1 + hstep, voffA);
;             PG8_WAIT_V(8); PG8_WAIT_L(0); PG8_BAR; PG8_MMA(0, 0, At, B0); PG8_MMA(0, 1, At, B1); PG8_BAR; PG8_SCHED;
;             PG8_LDA(At, 0, 1); PG8_STAGE(PG8_SB(0, 0), b2, voffB); PG8_STAGE(PG8_SB(0, 1), b2 + hstep, voffB); PG8_STAGE(PG8_SA(0, 0), a2, voffA);
.LBB0_780:
	s_add_u32 s100, s46, 0xffea0000
	s_addc_u32 s101, s47, -1
	ds_read_b128 v[72:75], v200
	ds_read_b128 v[76:79], v200 offset:1024
	ds_read_b128 v[88:91], v200 offset:2048
	ds_read_b128 v[92:95], v200 offset:3072
	ds_read_b128 v[144:147], v201
	ds_read_b128 v[148:151], v201 offset:1024
	ds_read_b128 v[152:155], v201 offset:2048
	ds_read_b128 v[156:159], v201 offset:3072
	s_add_u32 s48, s46, 0x100
	s_addc_u32 s49, s47, 0
	s_cmpk_eq_i32 s68, 0x54
	s_cselect_b32 s53, s9, s49
	s_cselect_b32 s52, s8, s48
	s_cselect_b32 s51, s45, s67
	s_cselect_b32 s50, s44, s66
	v_lshl_add_u64 v[220:221], s[100:101], 0, v[176:177]
	s_mov_b32 m0, s56
	v_lshl_add_u64 v[222:223], s[100:101], 0, v[178:179]
	global_load_lds_dwordx4 v[220:221], off
	s_mov_b32 m0, s57
	s_nop 0
	global_load_lds_dwordx4 v[222:223], off
	v_lshl_add_u64 v[216:217], s[46:47], 0, v[176:177]
	s_add_i32 m0, s34, 0xc000
	ds_read_b128 v[160:163], v202
	ds_read_b128 v[164:167], v202 offset:1024
	ds_read_b128 v[184:187], v202 offset:2048
	ds_read_b128 v[188:191], v202 offset:3072
	ds_read_b128 v[192:195], v202 offset:4096
	ds_read_b128 v[204:207], v202 offset:5120
	ds_read_b128 v[208:211], v202 offset:6144
	ds_read_b128 v[212:215], v202 offset:7168
	global_load_lds_dwordx4 v[216:217], off
	v_lshl_add_u64 v[216:217], s[46:47], 0, v[178:179]
	s_add_i32 m0, s34, 0xe000
	s_nop 0
	global_load_lds_dwordx4 v[216:217], off
	s_waitcnt vmcnt(8)
	s_waitcnt lgkmcnt(0)
	s_barrier
	s_setprio 1
	s_waitcnt lgkmcnt(0)
	v_mfma_f32_16x16x32_bf16 v[140:143], v[72:75], v[160:163], v[140:143]
	v_mfma_f32_16x16x32_bf16 v[136:139], v[88:91], v[160:163], v[136:139]
	v_mfma_f32_16x16x32_bf16 v[124:127], v[72:75], v[184:187], v[124:127]
	v_mfma_f32_16x16x32_bf16 v[120:123], v[88:91], v[184:187], v[120:123]
	v_mfma_f32_16x16x32_bf16 v[108:111], v[72:75], v[192:195], v[108:111]
	v_mfma_f32_16x16x32_bf16 v[104:107], v[88:91], v[192:195], v[104:107]
	v_mfma_f32_16x16x32_bf16 v[84:87], v[72:75], v[208:211], v[84:87]
	v_mfma_f32_16x16x32_bf16 v[80:83], v[88:91], v[208:211], v[80:83]
	v_mfma_f32_16x16x32_bf16 v[140:143], v[76:79], v[164:167], v[140:143]
	v_mfma_f32_16x16x32_bf16 v[136:139], v[92:95], v[164:167], v[136:139]
	v_mfma_f32_16x16x32_bf16 v[124:127], v[76:79], v[188:191], v[124:127]
	v_mfma_f32_16x16x32_bf16 v[120:123], v[92:95], v[188:191], v[120:123]
	v_mfma_f32_16x16x32_bf16 v[108:111], v[76:79], v[204:207], v[108:111]
	v_mfma_f32_16x16x32_bf16 v[104:107], v[92:95], v[204:207], v[104:107]
	v_mfma_f32_16x16x32_bf16 v[84:87], v[76:79], v[212:215], v[84:87]
	v_mfma_f32_16x16x32_bf16 v[80:83], v[92:95], v[212:215], v[80:83]
	s_setprio 0
	s_setprio 1
	v_mfma_f32_16x16x32_bf16 v[132:135], v[144:147], v[160:163], v[132:135]
	v_mfma_f32_16x16x32_bf16 v[128:131], v[152:155], v[160:163], v[128:131]
	v_mfma_f32_16x16x32_bf16 v[116:119], v[144:147], v[184:187], v[116:119]
	v_mfma_f32_16x16x32_bf16 v[112:115], v[152:155], v[184:187], v[112:115]
	v_mfma_f32_16x16x32_bf16 v[100:103], v[144:147], v[192:195], v[100:103]
	v_mfma_f32_16x16x32_bf16 v[96:99], v[152:155], v[192:195], v[96:99]
	v_mfma_f32_16x16x32_bf16 v[68:71], v[144:147], v[208:211], v[68:71]
	v_mfma_f32_16x16x32_bf16 v[64:67], v[152:155], v[208:211], v[64:67]
	v_mfma_f32_16x16x32_bf16 v[132:135], v[148:151], v[164:167], v[132:135]
	v_mfma_f32_16x16x32_bf16 v[128:131], v[156:159], v[164:167], v[128:131]
	v_mfma_f32_16x16x32_bf16 v[116:119], v[148:151], v[188:191], v[116:119]
	v_mfma_f32_16x16x32_bf16 v[112:115], v[156:159], v[188:191], v[112:115]
	v_mfma_f32_16x16x32_bf16 v[100:103], v[148:151], v[204:207], v[100:103]
	v_mfma_f32_16x16x32_bf16 v[96:99], v[156:159], v[204:207], v[96:99]
	v_mfma_f32_16x16x32_bf16 v[68:71], v[148:151], v[212:215], v[68:71]
	v_mfma_f32_16x16x32_bf16 v[64:67], v[156:159], v[212:215], v[64:67]
	s_setprio 0
	s_barrier
	s_add_i32 s46, s60, s31
	v_lshl_add_u64 v[216:217], s[50:51], 0, v[170:171]
	s_mov_b32 m0, s46
	ds_read_b128 v[160:163], v202 offset:16384
	ds_read_b128 v[164:167], v202 offset:17408
	ds_read_b128 v[184:187], v202 offset:18432
	ds_read_b128 v[188:191], v202 offset:19456
	ds_read_b128 v[192:195], v202 offset:20480
	ds_read_b128 v[204:207], v202 offset:21504
	ds_read_b128 v[208:211], v202 offset:22528
	ds_read_b128 v[212:215], v202 offset:23552
	global_load_lds_dwordx4 v[216:217], off
	s_add_i32 m0, s46, 0x2000
	s_add_u32 s46, s50, 0x160000
	v_lshl_add_u64 v[218:219], s[50:51], 0, v[174:175]
	s_addc_u32 s47, s51, 0
	s_add_i32 s69, s61, s31
	global_load_lds_dwordx4 v[218:219], off
	v_lshl_add_u64 v[220:221], s[46:47], 0, v[170:171]
	s_mov_b32 m0, s69
	s_nop 0
	global_load_lds_dwordx4 v[220:221], off
	v_lshl_add_u64 v[220:221], s[46:47], 0, v[174:175]
	s_add_i32 m0, s69, 0x2000
	s_nop 0
	global_load_lds_dwordx4 v[220:221], off
	s_waitcnt vmcnt(6)
	s_waitcnt lgkmcnt(0)
	s_barrier
; #define PG8_STAGE(bufoff, gbase, voff) do { _Pragma("unroll") for (int _i = 0; _i < 2; ++_i) \
;         __builtin_amdgcn_global_load_lds((const unsigned*)((const char*)(gbase) + (voff)[_i]), (PG8_LAS unsigned*)(lds + (bufoff) + ldsw + _i * 8192), 16, 0, 0); } while (0)
; #define PG8_LDA(dst, b, h) do { _Pragma("unroll") for (int m = 0; m < 4; ++m) _Pragma("unroll") for (int k = 0; k < 2; ++k) dst[m][k] = *(const PG8_LAS bf16x8*)(lds + PG8_SA(b, h) + aoff + m * 2048 + k * 1024); } while (0)
; #define PG8_LDB(dst, b, h) do { _Pragma("unroll") for (int n = 0; n < 2; ++n) _Pragma("unroll") for (int k = 0; k < 2; ++k) dst[n][k] = *(const PG8_LAS bf16x8*)(lds + PG8_SB(b, h) + boff + n * 2048 + k * 1024); } while (0)
; #define PG8_MMA(ai, bj, At, Bt) do { __builtin_amdgcn_s_setprio(1); _Pragma("unroll") for (int m = 0; m < 4; ++m) _Pragma("unroll") for (int n = 0; n < 2; ++n) _Pragma("unroll") for (int k = 0; k < 2; ++k) \
;         acc[ai][bj][m][n] = __builtin_amdgcn_mfma_f32_16x16x32_bf16(Bt[n][k], At[m][k], acc[ai][bj][m][n], 0, 0, 0); __builtin_amdgcn_s_setprio(0); } while (0)
; #define PG8_WAIT_V(n) asm volatile("s_waitcnt vmcnt(" #n ")" ::: "memory")
; #define PG8_WAIT_L(n) asm volatile("s_waitcnt lgkmcnt(" #n ")" ::: "memory")
; #define PG8_BAR __builtin_amdgcn_s_barrier()
; #define PG8_SCHED __builtin_amdgcn_sched_barrier(0)
; template <class Epi, class Sched, bool ALIGN_EPI = false, bool SP2 = false>
; __device__ __forceinline__ void gemm_phase(PG8_LAS unsigned char* lds, const Gemm g, const Sched& S, const Epi& E, const int wid  ) {
;     ...
;             PG8_LDA(At, 0, 1); PG8_STAGE(PG8_SB(0, 0), b2, voffB); PG8_STAGE(PG8_SB(0, 1), b2 + hstep, voffB); PG8_STAGE(PG8_SA(0, 0), a2, voffA);
;             PG8_WAIT_V(8); PG8_WAIT_L(0); PG8_BAR; PG8_MMA(1, 0, At, B0); PG8_MMA(1, 1, At, B1); PG8_BAR; PG8_SCHED;
;             PG8_LDB(B0, 1, 0); PG8_LDB(B1, 1, 1); PG8_SCHED; PG8_LDA(At, 1, 0); PG8_STAGE(PG8_SA(0, 1), a2 + hstep, voffA);
	s_setprio 1
	s_waitcnt lgkmcnt(0)
	v_mfma_f32_16x16x32_bf16 v[60:63], v[72:75], v[160:163], v[60:63]
	v_mfma_f32_16x16x32_bf16 v[56:59], v[88:91], v[160:163], v[56:59]
	v_mfma_f32_16x16x32_bf16 v[44:47], v[72:75], v[184:187], v[44:47]
	v_mfma_f32_16x16x32_bf16 v[40:43], v[88:91], v[184:187], v[40:43]
	v_mfma_f32_16x16x32_bf16 v[28:31], v[72:75], v[192:195], v[28:31]
	v_mfma_f32_16x16x32_bf16 v[24:27], v[88:91], v[192:195], v[24:27]
	v_mfma_f32_16x16x32_bf16 v[12:15], v[72:75], v[208:211], v[12:15]
	v_mfma_f32_16x16x32_bf16 v[8:11], v[88:91], v[208:211], v[8:11]
	v_mfma_f32_16x16x32_bf16 v[60:63], v[76:79], v[164:167], v[60:63]
	v_mfma_f32_16x16x32_bf16 v[56:59], v[92:95], v[164:167], v[56:59]
	v_mfma_f32_16x16x32_bf16 v[44:47], v[76:79], v[188:191], v[44:47]
	v_mfma_f32_16x16x32_bf16 v[40:43], v[92:95], v[188:191], v[40:43]
	v_mfma_f32_16x16x32_bf16 v[28:31], v[76:79], v[204:207], v[28:31]
	v_mfma_f32_16x16x32_bf16 v[24:27], v[92:95], v[204:207], v[24:27]
	v_mfma_f32_16x16x32_bf16 v[12:15], v[76:79], v[212:215], v[12:15]
	v_mfma_f32_16x16x32_bf16 v[8:11], v[92:95], v[212:215], v[8:11]
	s_setprio 0
	s_setprio 1
	v_mfma_f32_16x16x32_bf16 v[52:55], v[144:147], v[160:163], v[52:55]
	v_mfma_f32_16x16x32_bf16 v[48:51], v[152:155], v[160:163], v[48:51]
	v_mfma_f32_16x16x32_bf16 v[36:39], v[144:147], v[184:187], v[36:39]
	v_mfma_f32_16x16x32_bf16 v[32:35], v[152:155], v[184:187], v[32:35]
	v_mfma_f32_16x16x32_bf16 v[20:23], v[144:147], v[192:195], v[20:23]
	v_mfma_f32_16x16x32_bf16 v[16:19], v[152:155], v[192:195], v[16:19]
	v_mfma_f32_16x16x32_bf16 v[4:7], v[144:147], v[208:211], v[4:7]
	v_mfma_f32_16x16x32_bf16 v[0:3], v[152:155], v[208:211], v[0:3]
	v_mfma_f32_16x16x32_bf16 v[52:55], v[148:151], v[164:167], v[52:55]
	v_mfma_f32_16x16x32_bf16 v[48:51], v[156:159], v[164:167], v[48:51]
	v_mfma_f32_16x16x32_bf16 v[36:39], v[148:151], v[188:191], v[36:39]
	v_mfma_f32_16x16x32_bf16 v[32:35], v[156:159], v[188:191], v[32:35]
	v_mfma_f32_16x16x32_bf16 v[20:23], v[148:151], v[204:207], v[20:23]
	v_mfma_f32_16x16x32_bf16 v[16:19], v[156:159], v[204:207], v[16:19]
	v_mfma_f32_16x16x32_bf16 v[4:7], v[148:151], v[212:215], v[4:7]
	v_mfma_f32_16x16x32_bf16 v[0:3], v[156:159], v[212:215], v[0:3]
	s_setprio 0
	s_barrier
	s_add_i32 s69, 0, 0x18000
	s_add_i32 s70, 0, 0x1c000
	v_add_u32_e32 v92, s69, v198
	v_add_u32_e32 v156, s70, v198
	ds_read_b128 v[72:75], v92
	ds_read_b128 v[76:79], v92 offset:1024
	ds_read_b128 v[88:91], v92 offset:2048
	ds_read_b128 v[92:95], v92 offset:3072
	ds_read_b128 v[144:147], v156
	ds_read_b128 v[148:151], v156 offset:1024
	ds_read_b128 v[152:155], v156 offset:2048
	ds_read_b128 v[156:159], v156 offset:3072
	v_lshl_add_u64 v[220:221], s[52:53], 0, v[168:169]
	s_mov_b32 m0, s34
	v_lshl_add_u64 v[222:223], s[52:53], 0, v[172:173]
	global_load_lds_dwordx4 v[220:221], off
	s_mov_b32 m0, s35
	s_nop 0
	global_load_lds_dwordx4 v[222:223], off
	s_add_u32 s46, s52, 0x160000
	s_addc_u32 s47, s53, 0
	s_mov_b32 m0, s37
	v_lshl_add_u64 v[224:225], s[46:47], 0, v[168:169]
	ds_read_b128 v[160:163], v202 offset:32768
	ds_read_b128 v[164:167], v202 offset:33792
	ds_read_b128 v[184:187], v202 offset:34816
	ds_read_b128 v[188:191], v202 offset:35840
	ds_read_b128 v[192:195], v202 offset:36864
	ds_read_b128 v[204:207], v202 offset:37888
	ds_read_b128 v[208:211], v202 offset:38912
	ds_read_b128 v[212:215], v202 offset:39936
	global_load_lds_dwordx4 v[224:225], off
	v_lshl_add_u64 v[224:225], s[46:47], 0, v[172:173]
	s_mov_b32 m0, s54
	s_nop 0
	global_load_lds_dwordx4 v[224:225], off
	s_waitcnt vmcnt(8)
	s_waitcnt lgkmcnt(0)
	s_barrier
; #define PG8_STAGE(bufoff, gbase, voff) do { _Pragma("unroll") for (int _i = 0; _i < 2; ++_i) \
;         __builtin_amdgcn_global_load_lds((const unsigned*)((const char*)(gbase) + (voff)[_i]), (PG8_LAS unsigned*)(lds + (bufoff) + ldsw + _i * 8192), 16, 0, 0); } while (0)
; #define PG8_LDA(dst, b, h) do { _Pragma("unroll") for (int m = 0; m < 4; ++m) _Pragma("unroll") for (int k = 0; k < 2; ++k) dst[m][k] = *(const PG8_LAS bf16x8*)(lds + PG8_SA(b, h) + aoff + m * 2048 + k * 1024); } while (0)
; #define PG8_LDB(dst, b, h) do { _Pragma("unroll") for (int n = 0; n < 2; ++n) _Pragma("unroll") for (int k = 0; k < 2; ++k) dst[n][k] = *(const PG8_LAS bf16x8*)(lds + PG8_SB(b, h) + boff + n * 2048 + k * 1024); } while (0)
; #define PG8_MMA(ai, bj, At, Bt) do { __builtin_amdgcn_s_setprio(1); _Pragma("unroll") for (int m = 0; m < 4; ++m) _Pragma("unroll") for (int n = 0; n < 2; ++n) _Pragma("unroll") for (int k = 0; k < 2; ++k) \
;         acc[ai][bj][m][n] = __builtin_amdgcn_mfma_f32_16x16x32_bf16(Bt[n][k], At[m][k], acc[ai][bj][m][n], 0, 0, 0); __builtin_amdgcn_s_setprio(0); } while (0)
; #define PG8_WAIT_V(n) asm volatile("s_waitcnt vmcnt(" #n ")" ::: "memory")
; #define PG8_WAIT_L(n) asm volatile("s_waitcnt lgkmcnt(" #n ")" ::: "memory")
; #define PG8_BAR __builtin_amdgcn_s_barrier()
; #define PG8_SCHED __builtin_amdgcn_sched_barrier(0)
; template <class Epi, class Sched, bool ALIGN_EPI = false, bool SP2 = false>
; __device__ __forceinline__ void gemm_phase(PG8_LAS unsigned char* lds, const Gemm g, const Sched& S, const Epi& E, const int wid  ) {
;     ...
;             PG8_LDB(B0, 1, 0); PG8_LDB(B1, 1, 1); PG8_SCHED; PG8_LDA(At, 1, 0); PG8_STAGE(PG8_SA(0, 1), a2 + hstep, voffA);
;             PG8_WAIT_V(8); PG8_WAIT_L(0); PG8_BAR; PG8_MMA(0, 0, At, B0); PG8_MMA(0, 1, At, B1); PG8_BAR; PG8_SCHED;
;             PG8_LDA(At, 1, 1); PG8_STAGE(PG8_SB(1, 0), b3, voffB); PG8_STAGE(PG8_SB(1, 1), b3 + hstep, voffB); PG8_STAGE(PG8_SA(1, 0), a3, voffA);
;             PG8_WAIT_V(8); PG8_WAIT_L(0); PG8_BAR; PG8_MMA(1, 0, At, B0); PG8_MMA(1, 1, At, B1); PG8_BAR; PG8_SCHED;
	s_setprio 1
	s_waitcnt lgkmcnt(0)
	v_mfma_f32_16x16x32_bf16 v[140:143], v[72:75], v[160:163], v[140:143]
	v_mfma_f32_16x16x32_bf16 v[136:139], v[88:91], v[160:163], v[136:139]
	v_mfma_f32_16x16x32_bf16 v[124:127], v[72:75], v[184:187], v[124:127]
	v_mfma_f32_16x16x32_bf16 v[120:123], v[88:91], v[184:187], v[120:123]
	v_mfma_f32_16x16x32_bf16 v[108:111], v[72:75], v[192:195], v[108:111]
	v_mfma_f32_16x16x32_bf16 v[104:107], v[88:91], v[192:195], v[104:107]
	v_mfma_f32_16x16x32_bf16 v[84:87], v[72:75], v[208:211], v[84:87]
	v_mfma_f32_16x16x32_bf16 v[80:83], v[88:91], v[208:211], v[80:83]
	v_mfma_f32_16x16x32_bf16 v[140:143], v[76:79], v[164:167], v[140:143]
	v_mfma_f32_16x16x32_bf16 v[136:139], v[92:95], v[164:167], v[136:139]
	v_mfma_f32_16x16x32_bf16 v[124:127], v[76:79], v[188:191], v[124:127]
	v_mfma_f32_16x16x32_bf16 v[120:123], v[92:95], v[188:191], v[120:123]
	v_mfma_f32_16x16x32_bf16 v[108:111], v[76:79], v[204:207], v[108:111]
	v_mfma_f32_16x16x32_bf16 v[104:107], v[92:95], v[204:207], v[104:107]
	v_mfma_f32_16x16x32_bf16 v[84:87], v[76:79], v[212:215], v[84:87]
	v_mfma_f32_16x16x32_bf16 v[80:83], v[92:95], v[212:215], v[80:83]
	s_setprio 0
	s_setprio 1
	v_mfma_f32_16x16x32_bf16 v[132:135], v[144:147], v[160:163], v[132:135]
	v_mfma_f32_16x16x32_bf16 v[128:131], v[152:155], v[160:163], v[128:131]
	v_mfma_f32_16x16x32_bf16 v[116:119], v[144:147], v[184:187], v[116:119]
	v_mfma_f32_16x16x32_bf16 v[112:115], v[152:155], v[184:187], v[112:115]
	v_mfma_f32_16x16x32_bf16 v[100:103], v[144:147], v[192:195], v[100:103]
	v_mfma_f32_16x16x32_bf16 v[96:99], v[152:155], v[192:195], v[96:99]
	v_mfma_f32_16x16x32_bf16 v[68:71], v[144:147], v[208:211], v[68:71]
	v_mfma_f32_16x16x32_bf16 v[64:67], v[152:155], v[208:211], v[64:67]
	v_mfma_f32_16x16x32_bf16 v[132:135], v[148:151], v[164:167], v[132:135]
	v_mfma_f32_16x16x32_bf16 v[128:131], v[156:159], v[164:167], v[128:131]
	v_mfma_f32_16x16x32_bf16 v[116:119], v[148:151], v[188:191], v[116:119]
	v_mfma_f32_16x16x32_bf16 v[112:115], v[156:159], v[188:191], v[112:115]
	v_mfma_f32_16x16x32_bf16 v[100:103], v[148:151], v[204:207], v[100:103]
	v_mfma_f32_16x16x32_bf16 v[96:99], v[156:159], v[204:207], v[96:99]
	v_mfma_f32_16x16x32_bf16 v[68:71], v[148:151], v[212:215], v[68:71]
	v_mfma_f32_16x16x32_bf16 v[64:67], v[156:159], v[212:215], v[64:67]
	s_setprio 0
	s_barrier
	s_add_i32 s46, s69, s31
	v_lshl_add_u64 v[216:217], v[216:217], 0, s[40:41]
	s_mov_b32 m0, s46
	ds_read_b128 v[160:163], v202 offset:49152
	ds_read_b128 v[164:167], v202 offset:50176
	ds_read_b128 v[184:187], v202 offset:51200
	ds_read_b128 v[188:191], v202 offset:52224
	ds_read_b128 v[192:195], v202 offset:53248
	ds_read_b128 v[204:207], v202 offset:54272
	ds_read_b128 v[208:211], v202 offset:55296
	ds_read_b128 v[212:215], v202 offset:56320
	global_load_lds_dwordx4 v[216:217], off
	s_add_i32 m0, s46, 0x2000
	s_add_u32 s46, s50, 0x160080
	v_lshl_add_u64 v[216:217], v[218:219], 0, s[40:41]
	s_addc_u32 s47, s51, 0
	s_add_i32 s50, s70, s31
	global_load_lds_dwordx4 v[216:217], off
	v_lshl_add_u64 v[216:217], s[46:47], 0, v[170:171]
	s_mov_b32 m0, s50
	s_nop 0
	global_load_lds_dwordx4 v[216:217], off
	v_lshl_add_u64 v[216:217], s[46:47], 0, v[174:175]
	s_add_i32 m0, s50, 0x2000
	s_nop 0
	global_load_lds_dwordx4 v[216:217], off
	s_waitcnt vmcnt(6)
	s_waitcnt lgkmcnt(0)
	s_barrier
	s_setprio 1
	s_waitcnt lgkmcnt(0)
	v_mfma_f32_16x16x32_bf16 v[60:63], v[72:75], v[160:163], v[60:63]
	v_mfma_f32_16x16x32_bf16 v[56:59], v[88:91], v[160:163], v[56:59]
	v_mfma_f32_16x16x32_bf16 v[44:47], v[72:75], v[184:187], v[44:47]
	v_mfma_f32_16x16x32_bf16 v[40:43], v[88:91], v[184:187], v[40:43]
	v_mfma_f32_16x16x32_bf16 v[28:31], v[72:75], v[192:195], v[28:31]
	v_mfma_f32_16x16x32_bf16 v[24:27], v[88:91], v[192:195], v[24:27]
	v_mfma_f32_16x16x32_bf16 v[12:15], v[72:75], v[208:211], v[12:15]
	v_mfma_f32_16x16x32_bf16 v[8:11], v[88:91], v[208:211], v[8:11]
	v_mfma_f32_16x16x32_bf16 v[60:63], v[76:79], v[164:167], v[60:63]
	v_mfma_f32_16x16x32_bf16 v[56:59], v[92:95], v[164:167], v[56:59]
	v_mfma_f32_16x16x32_bf16 v[44:47], v[76:79], v[188:191], v[44:47]
	v_mfma_f32_16x16x32_bf16 v[40:43], v[92:95], v[188:191], v[40:43]
	v_mfma_f32_16x16x32_bf16 v[28:31], v[76:79], v[204:207], v[28:31]
	v_mfma_f32_16x16x32_bf16 v[24:27], v[92:95], v[204:207], v[24:27]
	v_mfma_f32_16x16x32_bf16 v[12:15], v[76:79], v[212:215], v[12:15]
	v_mfma_f32_16x16x32_bf16 v[8:11], v[92:95], v[212:215], v[8:11]
	s_setprio 0
	s_setprio 1
	v_mfma_f32_16x16x32_bf16 v[52:55], v[144:147], v[160:163], v[52:55]
	v_mfma_f32_16x16x32_bf16 v[48:51], v[152:155], v[160:163], v[48:51]
	v_mfma_f32_16x16x32_bf16 v[36:39], v[144:147], v[184:187], v[36:39]
	v_mfma_f32_16x16x32_bf16 v[32:35], v[152:155], v[184:187], v[32:35]
	v_mfma_f32_16x16x32_bf16 v[20:23], v[144:147], v[192:195], v[20:23]
	v_mfma_f32_16x16x32_bf16 v[16:19], v[152:155], v[192:195], v[16:19]
	v_mfma_f32_16x16x32_bf16 v[4:7], v[144:147], v[208:211], v[4:7]
	v_mfma_f32_16x16x32_bf16 v[0:3], v[152:155], v[208:211], v[0:3]
	v_mfma_f32_16x16x32_bf16 v[52:55], v[148:151], v[164:167], v[52:55]
	v_mfma_f32_16x16x32_bf16 v[48:51], v[156:159], v[164:167], v[48:51]
	v_mfma_f32_16x16x32_bf16 v[36:39], v[148:151], v[188:191], v[36:39]
	v_mfma_f32_16x16x32_bf16 v[32:35], v[156:159], v[188:191], v[32:35]
	v_mfma_f32_16x16x32_bf16 v[20:23], v[148:151], v[204:207], v[20:23]
	v_mfma_f32_16x16x32_bf16 v[16:19], v[156:159], v[204:207], v[16:19]
	v_mfma_f32_16x16x32_bf16 v[4:7], v[148:151], v[212:215], v[4:7]
	v_mfma_f32_16x16x32_bf16 v[0:3], v[156:159], v[212:215], v[0:3]
	s_setprio 0
	s_barrier
	s_add_i32 s68, s68, 2
	s_add_u32 s66, s66, 0x100
	s_addc_u32 s67, s67, 0
	s_cmpk_gt_u32 s68, 0x55
	s_mov_b64 s[46:47], s[48:49]
	s_cbranch_scc0 .LBB0_780
	s_and_b64 vcc, exec, s[42:43]
	s_cbranch_vccz .LBB0_783
	s_barrier

; #define PG8_STAGE(bufoff, gbase, voff) do { _Pragma("unroll") for (int _i = 0; _i < 2; ++_i) \
;         __builtin_amdgcn_global_load_lds((const unsigned*)((const char*)(gbase) + (voff)[_i]), (PG8_LAS unsigned*)(lds + (bufoff) + ldsw + _i * 8192), 16, 0, 0); } while (0)
; #define PG8_LDA(dst, b, h) do { _Pragma("unroll") for (int m = 0; m < 4; ++m) _Pragma("unroll") for (int k = 0; k < 2; ++k) dst[m][k] = *(const PG8_LAS bf16x8*)(lds + PG8_SA(b, h) + aoff + m * 2048 + k * 1024); } while (0)
; #define PG8_LDB(dst, b, h) do { _Pragma("unroll") for (int n = 0; n < 2; ++n) _Pragma("unroll") for (int k = 0; k < 2; ++k) dst[n][k] = *(const PG8_LAS bf16x8*)(lds + PG8_SB(b, h) + boff + n * 2048 + k * 1024); } while (0)
; #define PG8_MMA(ai, bj, At, Bt) do { __builtin_amdgcn_s_setprio(1); _Pragma("unroll") for (int m = 0; m < 4; ++m) _Pragma("unroll") for (int n = 0; n < 2; ++n) _Pragma("unroll") for (int k = 0; k < 2; ++k) \
;         acc[ai][bj][m][n] = __builtin_amdgcn_mfma_f32_16x16x32_bf16(Bt[n][k], At[m][k], acc[ai][bj][m][n], 0, 0, 0); __builtin_amdgcn_s_setprio(0); } while (0)
; #define PG8_WAIT_V(n) asm volatile("s_waitcnt vmcnt(" #n ")" ::: "memory")
; #define PG8_WAIT_L(n) asm volatile("s_waitcnt lgkmcnt(" #n ")" ::: "memory")
; #define PG8_BAR __builtin_amdgcn_s_barrier()
; #define PG8_SCHED __builtin_amdgcn_sched_barrier(0)
; template <class Epi, class Sched, bool ALIGN_EPI = false, bool SP2 = false>
; __device__ __forceinline__ void gemm_phase(PG8_LAS unsigned char* lds, const Gemm g, const Sched& S, const Epi& E, const int wid  ) {
;     ...
;             const bool last = (t == nt - 2);
;             const char* a1 = cA + (size_t)(t + 1) * kstep;
;             const char* a2 = last ? nA : cA + (size_t)(t + 2) * kstep; const char* b2 = last ? nB : cB + (size_t)(t + 2) * kstep;
;             const char* a3 = a2 + kstep; const char* b3 = b2 + kstep;
;             if (last && has_next) S.a_ready(nxt);
;             if constexpr (SP2) {
;             PG8_LDB(B0, 0, 0); PG8_LDB(B1, 0, 1); PG8_SCHED; PG8_LDA(At, 0, 0); PG8_STAGE(PG8_SA(1, 1), a1 + hstep, voffA);
;             PG8_WAIT_V(8); PG8_WAIT_L(0); PG8_BAR; PG8_MMA(0, 0, At, B0); PG8_MMA(0, 1, At, B1); PG8_BAR; PG8_SCHED;
;             PG8_LDA(At, 0, 1); PG8_STAGE(PG8_SB(0, 0), b2, voffB); PG8_STAGE(PG8_SB(0, 1), b2 + hstep, voffB); PG8_STAGE(PG8_SA(0, 0), a2, voffA);
.LBB0_879:
	s_add_u32 s100, s10, 0xfff80000
	s_addc_u32 s101, s11, -1
	ds_read_b128 v[128:131], v187
	ds_read_b128 v[132:135], v187 offset:1024
	ds_read_b128 v[136:139], v187 offset:2048
	ds_read_b128 v[140:143], v187 offset:3072
	ds_read_b128 v[166:169], v188
	ds_read_b128 v[170:173], v188 offset:1024
	ds_read_b128 v[174:177], v188 offset:2048
	ds_read_b128 v[178:181], v188 offset:3072
	s_add_u32 s12, s10, 0xfff80080
	s_addc_u32 s13, s11, -1
	s_cmp_eq_u32 s80, 28
	s_cselect_b32 s15, s9, s13
	s_cselect_b32 s14, s63, s12
	s_cselect_b32 s13, s61, s79
	s_cselect_b32 s12, s77, s78
	v_lshl_add_u64 v[228:229], s[100:101], 0, v[158:159]
	s_mov_b32 m0, s68
	v_lshl_add_u64 v[230:231], s[100:101], 0, v[160:161]
	global_load_lds_dwordx4 v[228:229], off
	s_mov_b32 m0, s69
	s_nop 0
	global_load_lds_dwordx4 v[230:231], off
	v_lshl_add_u64 v[224:225], s[10:11], 0, v[158:159]
	s_add_i32 m0, s34, 0xc000
	ds_read_b128 v[192:195], v189
	ds_read_b128 v[196:199], v189 offset:1024
	ds_read_b128 v[200:203], v189 offset:2048
	ds_read_b128 v[204:207], v189 offset:3072
	ds_read_b128 v[208:211], v189 offset:4096
	ds_read_b128 v[212:215], v189 offset:5120
	ds_read_b128 v[216:219], v189 offset:6144
	ds_read_b128 v[220:223], v189 offset:7168
	global_load_lds_dwordx4 v[224:225], off
	v_lshl_add_u64 v[224:225], s[10:11], 0, v[160:161]
	s_add_i32 m0, s34, 0xe000
	s_nop 0
	global_load_lds_dwordx4 v[224:225], off
	s_waitcnt vmcnt(8)
	s_waitcnt lgkmcnt(0)
	s_barrier
	s_setprio 1
	s_waitcnt lgkmcnt(0)
	v_mfma_f32_16x16x32_bf16 v[124:127], v[128:131], v[192:195], v[124:127]
	v_mfma_f32_16x16x32_bf16 v[120:123], v[136:139], v[192:195], v[120:123]
	v_mfma_f32_16x16x32_bf16 v[116:119], v[128:131], v[200:203], v[116:119]
	v_mfma_f32_16x16x32_bf16 v[112:115], v[136:139], v[200:203], v[112:115]
	v_mfma_f32_16x16x32_bf16 v[108:111], v[128:131], v[208:211], v[108:111]
	v_mfma_f32_16x16x32_bf16 v[100:103], v[136:139], v[208:211], v[100:103]
	v_mfma_f32_16x16x32_bf16 v[92:95], v[128:131], v[216:219], v[92:95]
	v_mfma_f32_16x16x32_bf16 v[84:87], v[136:139], v[216:219], v[84:87]
	v_mfma_f32_16x16x32_bf16 v[124:127], v[132:135], v[196:199], v[124:127]
	v_mfma_f32_16x16x32_bf16 v[120:123], v[140:143], v[196:199], v[120:123]
	v_mfma_f32_16x16x32_bf16 v[116:119], v[132:135], v[204:207], v[116:119]
	v_mfma_f32_16x16x32_bf16 v[112:115], v[140:143], v[204:207], v[112:115]
	v_mfma_f32_16x16x32_bf16 v[108:111], v[132:135], v[212:215], v[108:111]
	v_mfma_f32_16x16x32_bf16 v[100:103], v[140:143], v[212:215], v[100:103]
	v_mfma_f32_16x16x32_bf16 v[92:95], v[132:135], v[220:223], v[92:95]
	v_mfma_f32_16x16x32_bf16 v[84:87], v[140:143], v[220:223], v[84:87]
	s_setprio 0
	s_setprio 1
	v_mfma_f32_16x16x32_bf16 v[104:107], v[166:169], v[192:195], v[104:107]
	v_mfma_f32_16x16x32_bf16 v[96:99], v[174:177], v[192:195], v[96:99]
	v_mfma_f32_16x16x32_bf16 v[88:91], v[166:169], v[200:203], v[88:91]
	v_mfma_f32_16x16x32_bf16 v[80:83], v[174:177], v[200:203], v[80:83]
	v_mfma_f32_16x16x32_bf16 v[76:79], v[166:169], v[208:211], v[76:79]
	v_mfma_f32_16x16x32_bf16 v[72:75], v[174:177], v[208:211], v[72:75]
	v_mfma_f32_16x16x32_bf16 v[68:71], v[166:169], v[216:219], v[68:71]
	v_mfma_f32_16x16x32_bf16 v[64:67], v[174:177], v[216:219], v[64:67]
	v_mfma_f32_16x16x32_bf16 v[104:107], v[170:173], v[196:199], v[104:107]
	v_mfma_f32_16x16x32_bf16 v[96:99], v[178:181], v[196:199], v[96:99]
	v_mfma_f32_16x16x32_bf16 v[88:91], v[170:173], v[204:207], v[88:91]
	v_mfma_f32_16x16x32_bf16 v[80:83], v[178:181], v[204:207], v[80:83]
	v_mfma_f32_16x16x32_bf16 v[76:79], v[170:173], v[212:215], v[76:79]
	v_mfma_f32_16x16x32_bf16 v[72:75], v[178:181], v[212:215], v[72:75]
	v_mfma_f32_16x16x32_bf16 v[68:71], v[170:173], v[220:223], v[68:71]
	v_mfma_f32_16x16x32_bf16 v[64:67], v[178:181], v[220:223], v[64:67]
	s_setprio 0
	s_barrier
	s_add_i32 s81, s73, s31
	v_lshl_add_u64 v[224:225], s[12:13], 0, v[146:147]
	s_mov_b32 m0, s81
	ds_read_b128 v[192:195], v189 offset:16384
	ds_read_b128 v[196:199], v189 offset:17408
	ds_read_b128 v[200:203], v189 offset:18432
	ds_read_b128 v[204:207], v189 offset:19456
	ds_read_b128 v[208:211], v189 offset:20480
	ds_read_b128 v[212:215], v189 offset:21504
	ds_read_b128 v[216:219], v189 offset:22528
	ds_read_b128 v[220:223], v189 offset:23552
	global_load_lds_dwordx4 v[224:225], off
	s_add_i32 m0, s81, 0x2000
	s_add_u32 s82, s12, 0x80000
	v_lshl_add_u64 v[226:227], s[12:13], 0, v[150:151]
	s_addc_u32 s83, s13, 0
	s_add_i32 s81, s74, s31
	global_load_lds_dwordx4 v[226:227], off
	v_lshl_add_u64 v[228:229], s[82:83], 0, v[146:147]
	s_mov_b32 m0, s81
	s_nop 0
	global_load_lds_dwordx4 v[228:229], off
	v_lshl_add_u64 v[228:229], s[82:83], 0, v[150:151]
	s_add_i32 m0, s81, 0x2000
	s_nop 0
	global_load_lds_dwordx4 v[228:229], off
	s_waitcnt vmcnt(6)
	s_waitcnt lgkmcnt(0)
	s_barrier
; #define PG8_STAGE(bufoff, gbase, voff) do { _Pragma("unroll") for (int _i = 0; _i < 2; ++_i) \
;         __builtin_amdgcn_global_load_lds((const unsigned*)((const char*)(gbase) + (voff)[_i]), (PG8_LAS unsigned*)(lds + (bufoff) + ldsw + _i * 8192), 16, 0, 0); } while (0)
; #define PG8_LDA(dst, b, h) do { _Pragma("unroll") for (int m = 0; m < 4; ++m) _Pragma("unroll") for (int k = 0; k < 2; ++k) dst[m][k] = *(const PG8_LAS bf16x8*)(lds + PG8_SA(b, h) + aoff + m * 2048 + k * 1024); } while (0)
; #define PG8_LDB(dst, b, h) do { _Pragma("unroll") for (int n = 0; n < 2; ++n) _Pragma("unroll") for (int k = 0; k < 2; ++k) dst[n][k] = *(const PG8_LAS bf16x8*)(lds + PG8_SB(b, h) + boff + n * 2048 + k * 1024); } while (0)
; #define PG8_MMA(ai, bj, At, Bt) do { __builtin_amdgcn_s_setprio(1); _Pragma("unroll") for (int m = 0; m < 4; ++m) _Pragma("unroll") for (int n = 0; n < 2; ++n) _Pragma("unroll") for (int k = 0; k < 2; ++k) \
;         acc[ai][bj][m][n] = __builtin_amdgcn_mfma_f32_16x16x32_bf16(Bt[n][k], At[m][k], acc[ai][bj][m][n], 0, 0, 0); __builtin_amdgcn_s_setprio(0); } while (0)
; #define PG8_WAIT_V(n) asm volatile("s_waitcnt vmcnt(" #n ")" ::: "memory")
; #define PG8_WAIT_L(n) asm volatile("s_waitcnt lgkmcnt(" #n ")" ::: "memory")
; #define PG8_BAR __builtin_amdgcn_s_barrier()
; #define PG8_SCHED __builtin_amdgcn_sched_barrier(0)
; template <class Epi, class Sched, bool ALIGN_EPI = false, bool SP2 = false>
; __device__ __forceinline__ void gemm_phase(PG8_LAS unsigned char* lds, const Gemm g, const Sched& S, const Epi& E, const int wid  ) {
;     ...
;             PG8_LDA(At, 0, 1); PG8_STAGE(PG8_SB(0, 0), b2, voffB); PG8_STAGE(PG8_SB(0, 1), b2 + hstep, voffB); PG8_STAGE(PG8_SA(0, 0), a2, voffA);
;             PG8_WAIT_V(8); PG8_WAIT_L(0); PG8_BAR; PG8_MMA(1, 0, At, B0); PG8_MMA(1, 1, At, B1); PG8_BAR; PG8_SCHED;
;             PG8_LDB(B0, 1, 0); PG8_LDB(B1, 1, 1); PG8_SCHED; PG8_LDA(At, 1, 0); PG8_STAGE(PG8_SA(0, 1), a2 + hstep, voffA);
	s_setprio 1
	s_waitcnt lgkmcnt(0)
	v_mfma_f32_16x16x32_bf16 v[60:63], v[128:131], v[192:195], v[60:63]
	v_mfma_f32_16x16x32_bf16 v[56:59], v[136:139], v[192:195], v[56:59]
	v_mfma_f32_16x16x32_bf16 v[52:55], v[128:131], v[200:203], v[52:55]
	v_mfma_f32_16x16x32_bf16 v[48:51], v[136:139], v[200:203], v[48:51]
	v_mfma_f32_16x16x32_bf16 v[40:43], v[128:131], v[208:211], v[40:43]
	v_mfma_f32_16x16x32_bf16 v[32:35], v[136:139], v[208:211], v[32:35]
	v_mfma_f32_16x16x32_bf16 v[20:23], v[128:131], v[216:219], v[20:23]
	v_mfma_f32_16x16x32_bf16 v[16:19], v[136:139], v[216:219], v[16:19]
	v_mfma_f32_16x16x32_bf16 v[60:63], v[132:135], v[196:199], v[60:63]
	v_mfma_f32_16x16x32_bf16 v[56:59], v[140:143], v[196:199], v[56:59]
	v_mfma_f32_16x16x32_bf16 v[52:55], v[132:135], v[204:207], v[52:55]
	v_mfma_f32_16x16x32_bf16 v[48:51], v[140:143], v[204:207], v[48:51]
	v_mfma_f32_16x16x32_bf16 v[40:43], v[132:135], v[212:215], v[40:43]
	v_mfma_f32_16x16x32_bf16 v[32:35], v[140:143], v[212:215], v[32:35]
	v_mfma_f32_16x16x32_bf16 v[20:23], v[132:135], v[220:223], v[20:23]
	v_mfma_f32_16x16x32_bf16 v[16:19], v[140:143], v[220:223], v[16:19]
	s_setprio 0
	s_setprio 1
	v_mfma_f32_16x16x32_bf16 v[44:47], v[166:169], v[192:195], v[44:47]
	v_mfma_f32_16x16x32_bf16 v[36:39], v[174:177], v[192:195], v[36:39]
	v_mfma_f32_16x16x32_bf16 v[28:31], v[166:169], v[200:203], v[28:31]
	v_mfma_f32_16x16x32_bf16 v[24:27], v[174:177], v[200:203], v[24:27]
	v_mfma_f32_16x16x32_bf16 v[12:15], v[166:169], v[208:211], v[12:15]
	v_mfma_f32_16x16x32_bf16 v[8:11], v[174:177], v[208:211], v[8:11]
	v_mfma_f32_16x16x32_bf16 v[4:7], v[166:169], v[216:219], v[4:7]
	v_mfma_f32_16x16x32_bf16 v[0:3], v[174:177], v[216:219], v[0:3]
	v_mfma_f32_16x16x32_bf16 v[44:47], v[170:173], v[196:199], v[44:47]
	v_mfma_f32_16x16x32_bf16 v[36:39], v[178:181], v[196:199], v[36:39]
	v_mfma_f32_16x16x32_bf16 v[28:31], v[170:173], v[204:207], v[28:31]
	v_mfma_f32_16x16x32_bf16 v[24:27], v[178:181], v[204:207], v[24:27]
	v_mfma_f32_16x16x32_bf16 v[12:15], v[170:173], v[212:215], v[12:15]
	v_mfma_f32_16x16x32_bf16 v[8:11], v[178:181], v[212:215], v[8:11]
	v_mfma_f32_16x16x32_bf16 v[4:7], v[170:173], v[220:223], v[4:7]
	v_mfma_f32_16x16x32_bf16 v[0:3], v[178:181], v[220:223], v[0:3]
	s_setprio 0
	s_barrier
	s_add_i32 s81, 0, 0x18000
	s_add_i32 s82, 0, 0x1c000
	v_add_u32_e32 v140, s81, v184
	v_add_u32_e32 v178, s82, v184
	ds_read_b128 v[128:131], v140
	ds_read_b128 v[132:135], v140 offset:1024
	ds_read_b128 v[136:139], v140 offset:2048
	ds_read_b128 v[140:143], v140 offset:3072
	ds_read_b128 v[166:169], v178
	ds_read_b128 v[170:173], v178 offset:1024
	ds_read_b128 v[174:177], v178 offset:2048
	ds_read_b128 v[178:181], v178 offset:3072
	v_lshl_add_u64 v[228:229], s[14:15], 0, v[144:145]
	s_mov_b32 m0, s34
	v_lshl_add_u64 v[230:231], s[14:15], 0, v[148:149]
	global_load_lds_dwordx4 v[228:229], off
	s_mov_b32 m0, s35
	s_nop 0
	global_load_lds_dwordx4 v[230:231], off
	s_add_u32 s14, s14, 0x80000
	s_addc_u32 s15, s15, 0
	s_mov_b32 m0, s37
	v_lshl_add_u64 v[232:233], s[14:15], 0, v[144:145]
	ds_read_b128 v[192:195], v189 offset:32768
	ds_read_b128 v[196:199], v189 offset:33792
	ds_read_b128 v[200:203], v189 offset:34816
	ds_read_b128 v[204:207], v189 offset:35840
	ds_read_b128 v[208:211], v189 offset:36864
	ds_read_b128 v[212:215], v189 offset:37888
	ds_read_b128 v[216:219], v189 offset:38912
	ds_read_b128 v[220:223], v189 offset:39936
	global_load_lds_dwordx4 v[232:233], off
	v_lshl_add_u64 v[232:233], s[14:15], 0, v[148:149]
	s_mov_b32 m0, s53
	s_nop 0
	global_load_lds_dwordx4 v[232:233], off
	s_waitcnt vmcnt(8)
	s_waitcnt lgkmcnt(0)
	s_barrier
; #define PG8_STAGE(bufoff, gbase, voff) do { _Pragma("unroll") for (int _i = 0; _i < 2; ++_i) \
;         __builtin_amdgcn_global_load_lds((const unsigned*)((const char*)(gbase) + (voff)[_i]), (PG8_LAS unsigned*)(lds + (bufoff) + ldsw + _i * 8192), 16, 0, 0); } while (0)
; #define PG8_LDA(dst, b, h) do { _Pragma("unroll") for (int m = 0; m < 4; ++m) _Pragma("unroll") for (int k = 0; k < 2; ++k) dst[m][k] = *(const PG8_LAS bf16x8*)(lds + PG8_SA(b, h) + aoff + m * 2048 + k * 1024); } while (0)
; #define PG8_LDB(dst, b, h) do { _Pragma("unroll") for (int n = 0; n < 2; ++n) _Pragma("unroll") for (int k = 0; k < 2; ++k) dst[n][k] = *(const PG8_LAS bf16x8*)(lds + PG8_SB(b, h) + boff + n * 2048 + k * 1024); } while (0)
; #define PG8_MMA(ai, bj, At, Bt) do { __builtin_amdgcn_s_setprio(1); _Pragma("unroll") for (int m = 0; m < 4; ++m) _Pragma("unroll") for (int n = 0; n < 2; ++n) _Pragma("unroll") for (int k = 0; k < 2; ++k) \
;         acc[ai][bj][m][n] = __builtin_amdgcn_mfma_f32_16x16x32_bf16(Bt[n][k], At[m][k], acc[ai][bj][m][n], 0, 0, 0); __builtin_amdgcn_s_setprio(0); } while (0)
; #define PG8_WAIT_V(n) asm volatile("s_waitcnt vmcnt(" #n ")" ::: "memory")
; #define PG8_WAIT_L(n) asm volatile("s_waitcnt lgkmcnt(" #n ")" ::: "memory")
; #define PG8_BAR __builtin_amdgcn_s_barrier()
; #define PG8_SCHED __builtin_amdgcn_sched_barrier(0)
; template <class Epi, class Sched, bool ALIGN_EPI = false, bool SP2 = false>
; __device__ __forceinline__ void gemm_phase(PG8_LAS unsigned char* lds, const Gemm g, const Sched& S, const Epi& E, const int wid  ) {
;     ...
;             PG8_LDB(B0, 1, 0); PG8_LDB(B1, 1, 1); PG8_SCHED; PG8_LDA(At, 1, 0); PG8_STAGE(PG8_SA(0, 1), a2 + hstep, voffA);
;             PG8_WAIT_V(8); PG8_WAIT_L(0); PG8_BAR; PG8_MMA(0, 0, At, B0); PG8_MMA(0, 1, At, B1); PG8_BAR; PG8_SCHED;
;             PG8_LDA(At, 1, 1); PG8_STAGE(PG8_SB(1, 0), b3, voffB); PG8_STAGE(PG8_SB(1, 1), b3 + hstep, voffB); PG8_STAGE(PG8_SA(1, 0), a3, voffA);
;             PG8_WAIT_V(8); PG8_WAIT_L(0); PG8_BAR; PG8_MMA(1, 0, At, B0); PG8_MMA(1, 1, At, B1); PG8_BAR; PG8_SCHED;
	s_setprio 1
	s_waitcnt lgkmcnt(0)
	v_mfma_f32_16x16x32_bf16 v[124:127], v[128:131], v[192:195], v[124:127]
	v_mfma_f32_16x16x32_bf16 v[120:123], v[136:139], v[192:195], v[120:123]
	v_mfma_f32_16x16x32_bf16 v[116:119], v[128:131], v[200:203], v[116:119]
	v_mfma_f32_16x16x32_bf16 v[112:115], v[136:139], v[200:203], v[112:115]
	v_mfma_f32_16x16x32_bf16 v[108:111], v[128:131], v[208:211], v[108:111]
	v_mfma_f32_16x16x32_bf16 v[100:103], v[136:139], v[208:211], v[100:103]
	v_mfma_f32_16x16x32_bf16 v[92:95], v[128:131], v[216:219], v[92:95]
	v_mfma_f32_16x16x32_bf16 v[84:87], v[136:139], v[216:219], v[84:87]
	v_mfma_f32_16x16x32_bf16 v[124:127], v[132:135], v[196:199], v[124:127]
	v_mfma_f32_16x16x32_bf16 v[120:123], v[140:143], v[196:199], v[120:123]
	v_mfma_f32_16x16x32_bf16 v[116:119], v[132:135], v[204:207], v[116:119]
	v_mfma_f32_16x16x32_bf16 v[112:115], v[140:143], v[204:207], v[112:115]
	v_mfma_f32_16x16x32_bf16 v[108:111], v[132:135], v[212:215], v[108:111]
	v_mfma_f32_16x16x32_bf16 v[100:103], v[140:143], v[212:215], v[100:103]
	v_mfma_f32_16x16x32_bf16 v[92:95], v[132:135], v[220:223], v[92:95]
	v_mfma_f32_16x16x32_bf16 v[84:87], v[140:143], v[220:223], v[84:87]
	s_setprio 0
	s_setprio 1
	v_mfma_f32_16x16x32_bf16 v[104:107], v[166:169], v[192:195], v[104:107]
	v_mfma_f32_16x16x32_bf16 v[96:99], v[174:177], v[192:195], v[96:99]
	v_mfma_f32_16x16x32_bf16 v[88:91], v[166:169], v[200:203], v[88:91]
	v_mfma_f32_16x16x32_bf16 v[80:83], v[174:177], v[200:203], v[80:83]
	v_mfma_f32_16x16x32_bf16 v[76:79], v[166:169], v[208:211], v[76:79]
	v_mfma_f32_16x16x32_bf16 v[72:75], v[174:177], v[208:211], v[72:75]
	v_mfma_f32_16x16x32_bf16 v[68:71], v[166:169], v[216:219], v[68:71]
	v_mfma_f32_16x16x32_bf16 v[64:67], v[174:177], v[216:219], v[64:67]
	v_mfma_f32_16x16x32_bf16 v[104:107], v[170:173], v[196:199], v[104:107]
	v_mfma_f32_16x16x32_bf16 v[96:99], v[178:181], v[196:199], v[96:99]
	v_mfma_f32_16x16x32_bf16 v[88:91], v[170:173], v[204:207], v[88:91]
	v_mfma_f32_16x16x32_bf16 v[80:83], v[178:181], v[204:207], v[80:83]
	v_mfma_f32_16x16x32_bf16 v[76:79], v[170:173], v[212:215], v[76:79]
	v_mfma_f32_16x16x32_bf16 v[72:75], v[178:181], v[212:215], v[72:75]
	v_mfma_f32_16x16x32_bf16 v[68:71], v[170:173], v[220:223], v[68:71]
	v_mfma_f32_16x16x32_bf16 v[64:67], v[178:181], v[220:223], v[64:67]
	s_setprio 0
	s_barrier
	s_add_i32 s14, s81, s31
	v_lshl_add_u64 v[224:225], v[224:225], 0, s[54:55]
	s_mov_b32 m0, s14
	ds_read_b128 v[192:195], v189 offset:49152
	ds_read_b128 v[196:199], v189 offset:50176
	ds_read_b128 v[200:203], v189 offset:51200
	ds_read_b128 v[204:207], v189 offset:52224
	ds_read_b128 v[208:211], v189 offset:53248
	ds_read_b128 v[212:215], v189 offset:54272
	ds_read_b128 v[216:219], v189 offset:55296
	ds_read_b128 v[220:223], v189 offset:56320
	global_load_lds_dwordx4 v[224:225], off
	s_add_i32 m0, s14, 0x2000
	s_add_u32 s12, s12, 0x80080
	v_lshl_add_u64 v[224:225], v[226:227], 0, s[54:55]
	s_addc_u32 s13, s13, 0
	s_add_i32 s14, s82, s31
	global_load_lds_dwordx4 v[224:225], off
	v_lshl_add_u64 v[224:225], s[12:13], 0, v[146:147]
	s_mov_b32 m0, s14
	s_nop 0
	global_load_lds_dwordx4 v[224:225], off
	v_lshl_add_u64 v[224:225], s[12:13], 0, v[150:151]
	s_add_i32 m0, s14, 0x2000
	s_nop 0
	global_load_lds_dwordx4 v[224:225], off
	s_waitcnt vmcnt(6)
	s_waitcnt lgkmcnt(0)
	s_barrier
	s_setprio 1
	s_waitcnt lgkmcnt(0)
	v_mfma_f32_16x16x32_bf16 v[60:63], v[128:131], v[192:195], v[60:63]
	v_mfma_f32_16x16x32_bf16 v[56:59], v[136:139], v[192:195], v[56:59]
	v_mfma_f32_16x16x32_bf16 v[52:55], v[128:131], v[200:203], v[52:55]
	v_mfma_f32_16x16x32_bf16 v[48:51], v[136:139], v[200:203], v[48:51]
	v_mfma_f32_16x16x32_bf16 v[40:43], v[128:131], v[208:211], v[40:43]
	v_mfma_f32_16x16x32_bf16 v[32:35], v[136:139], v[208:211], v[32:35]
	v_mfma_f32_16x16x32_bf16 v[20:23], v[128:131], v[216:219], v[20:23]
	v_mfma_f32_16x16x32_bf16 v[16:19], v[136:139], v[216:219], v[16:19]
	v_mfma_f32_16x16x32_bf16 v[60:63], v[132:135], v[196:199], v[60:63]
	v_mfma_f32_16x16x32_bf16 v[56:59], v[140:143], v[196:199], v[56:59]
	v_mfma_f32_16x16x32_bf16 v[52:55], v[132:135], v[204:207], v[52:55]
	v_mfma_f32_16x16x32_bf16 v[48:51], v[140:143], v[204:207], v[48:51]
	v_mfma_f32_16x16x32_bf16 v[40:43], v[132:135], v[212:215], v[40:43]
	v_mfma_f32_16x16x32_bf16 v[32:35], v[140:143], v[212:215], v[32:35]
	v_mfma_f32_16x16x32_bf16 v[20:23], v[132:135], v[220:223], v[20:23]
	v_mfma_f32_16x16x32_bf16 v[16:19], v[140:143], v[220:223], v[16:19]
	s_setprio 0
	s_setprio 1
	v_mfma_f32_16x16x32_bf16 v[44:47], v[166:169], v[192:195], v[44:47]
	v_mfma_f32_16x16x32_bf16 v[36:39], v[174:177], v[192:195], v[36:39]
	v_mfma_f32_16x16x32_bf16 v[28:31], v[166:169], v[200:203], v[28:31]
	v_mfma_f32_16x16x32_bf16 v[24:27], v[174:177], v[200:203], v[24:27]
	v_mfma_f32_16x16x32_bf16 v[12:15], v[166:169], v[208:211], v[12:15]
	v_mfma_f32_16x16x32_bf16 v[8:11], v[174:177], v[208:211], v[8:11]
	v_mfma_f32_16x16x32_bf16 v[4:7], v[166:169], v[216:219], v[4:7]
	v_mfma_f32_16x16x32_bf16 v[0:3], v[174:177], v[216:219], v[0:3]
	v_mfma_f32_16x16x32_bf16 v[44:47], v[170:173], v[196:199], v[44:47]
	v_mfma_f32_16x16x32_bf16 v[36:39], v[178:181], v[196:199], v[36:39]
	v_mfma_f32_16x16x32_bf16 v[28:31], v[170:173], v[204:207], v[28:31]
	v_mfma_f32_16x16x32_bf16 v[24:27], v[178:181], v[204:207], v[24:27]
	v_mfma_f32_16x16x32_bf16 v[12:15], v[170:173], v[212:215], v[12:15]
	v_mfma_f32_16x16x32_bf16 v[8:11], v[178:181], v[212:215], v[8:11]
	v_mfma_f32_16x16x32_bf16 v[4:7], v[170:173], v[220:223], v[4:7]
	v_mfma_f32_16x16x32_bf16 v[0:3], v[178:181], v[220:223], v[0:3]
	s_setprio 0
	s_barrier
	s_add_i32 s80, s80, 2
	s_add_u32 s10, s10, 0x100
	s_addc_u32 s11, s11, 0
	s_add_u32 s78, s78, 0x100
	s_addc_u32 s79, s79, 0
	s_cmp_gt_u32 s80, 29
	s_cbranch_scc0 .LBB0_879
	s_and_b64 vcc, exec, s[56:57]
	s_cbranch_vccz .LBB0_882
	s_barrier

; DI float bf2f(unsigned b) { return __uint_as_float(b << 16); }
; DI unsigned pk2(float lo, float hi) { const f32x2 v = {lo, hi}; return __builtin_bit_cast(unsigned, __builtin_convertvector(v, bf16x2_t)); }
; DI void dsa_post_row(const float* KRAW, const float* KIRAW, const float* knorm, const float* kinorm, float* kout, float* kiout, bf16* KB, bf16* KIB, const bf16* VB, unsigned char* K8, unsigned char* V8, int t, int lane) {
;     { const float* p = KRAW + (size_t)t * 512 + 8 * lane; f32x4 a = *(const f32x4*)p, b = *(const f32x4*)(p + 4);
;       const float rs = rsqrtf(grp16_sum((a.x * a.x + a.y * a.y) + (a.z * a.z + a.w * a.w) + (b.x * b.x + b.y * b.y) + (b.z * b.z + b.w * b.w)) * (1.f / 128.f) + EPS);
;       const float* gp = knorm + ((8 * lane) & 127); const f32x4 g0 = *(const f32x4*)gp, g1 = *(const f32x4*)(gp + 4);
;       a = a * rs * g0; b = b * rs * g1; float* o = kout + (size_t)t * 512 + 8 * lane; __builtin_nontemporal_store(a, (f32x4*)o); __builtin_nontemporal_store(b, (f32x4*)(o + 4)); *(bf16x8*)(KB + (size_t)t * 512 + 8 * lane) = pack8(a, b);
;       *(v2u*)(K8 + (size_t)t * 512 + 8 * lane) = (v2u){pk4_fp8(a[0], a[1], a[2], a[3]), pk4_fp8(b[0], b[1], b[2], b[3])};
;       const v4u vw = *(const v4u*)(VB + (size_t)t * 512 + 8 * lane);
;       *(v2u*)(V8 + (size_t)t * 512 + 8 * lane) = (v2u){pk4_fp8(bf2f(vw.x & 0xffffu), bf2f(vw.x >> 16), bf2f(vw.y & 0xffffu), bf2f(vw.y >> 16)), pk4_fp8(bf2f(vw.z & 0xffffu), bf2f(vw.z >> 16), bf2f(vw.w & 0xffffu), bf2f(vw.w >> 16))}; }
;     { const f32x2 a = *(const f32x2*)(KIRAW + (size_t)t * 128 + 2 * lane); const float rs = rsqrtf(wave_sum(a.x * a.x + a.y * a.y) * (1.f / 128.f) + EPS);
;       const f32x2 gk = *(const f32x2*)(kinorm + 2 * lane); const float x = a.x * rs * gk.x, y = a.y * rs * gk.y;
;       *(f32x2*)(kiout + (size_t)t * 128 + 2 * lane) = (f32x2){x, y}; *(unsigned*)(KIB + (size_t)t * 128 + 2 * lane) = pk2(x, y); }
; }
; __global__ void __launch_bounds__(NTHR, 2) mk_fwd(Args args) {
;     ...
;         if (gw < NGW - BS) for (int t = gw; t < T; t += NGW - BS) dsa_post_row(KRAW, KIRAW, b_k_norm, b_ki_norm, out + O_KP, out + O_KIP, KB, KIB, VB, (unsigned char*)(AP->ws + WS_K8), (unsigned char*)(AP->ws + WS_V8), t, lane);
.LBB0_995:
	s_cmp_lt_i32 s26, 9
	s_cselect_b64 s[4:5], -1, 0
	s_cmp_gt_i32 s27, 8
	s_cselect_b64 s[6:7], -1, 0
	s_and_b64 s[4:5], s[4:5], s[6:7]
	s_andn2_b64 vcc, exec, s[4:5]
	s_cbranch_vccnz .LBB0_1495
	s_add_i32 s14, s36, 0xffffff80
	s_cmp_ge_i32 s20, s14
	s_cselect_b64 s[4:5], -1, 0
	s_cmpk_gt_i32 s20, 0x1fff
	s_cselect_b64 s[6:7], -1, 0
	s_or_b64 s[4:5], s[4:5], s[6:7]
	s_mov_b64 s[12:13], s[0:1]
	s_and_b64 vcc, exec, s[4:5]
	v_mbcnt_lo_u32_b32 v0, -1, 0
	v_mbcnt_hi_u32_b32 v0, -1, v0
	s_cbranch_vccnz .LBB0_999
	s_waitcnt lgkmcnt(0)
	v_mbcnt_lo_u32_b32 v1, -1, 0
	v_mbcnt_hi_u32_b32 v4, -1, v1
	v_and_b32_e32 v1, 64, v4
	v_add_u32_e32 v5, 64, v1
	v_xor_b32_e32 v1, 1, v4
	v_cmp_lt_i32_e32 vcc, v1, v5
	v_xor_b32_e32 v2, 2, v4
	s_load_dwordx4 s[4:7], s[12:13], 0xa8
	s_load_dwordx4 s[8:11], s[12:13], 0x80
	v_cndmask_b32_e32 v1, v4, v1, vcc
	v_cmp_lt_i32_e32 vcc, v2, v5
	s_waitcnt vmcnt(0)
	v_xor_b32_e32 v8, 16, v4
	s_waitcnt lgkmcnt(0)
	s_add_u32 s16, s4, 0xe200000
	v_cndmask_b32_e32 v2, v4, v2, vcc
	v_lshlrev_b32_e32 v16, 2, v2
	v_xor_b32_e32 v2, 4, v4
	v_cmp_lt_i32_e32 vcc, v2, v5
	v_lshlrev_b32_e32 v6, 1, v0
	v_lshlrev_b32_e32 v14, 3, v0
	v_cndmask_b32_e32 v2, v4, v2, vcc
	v_lshlrev_b32_e32 v17, 2, v2
	v_xor_b32_e32 v2, 8, v4
	v_cmp_lt_i32_e32 vcc, v2, v5
	s_addc_u32 s17, s5, 0
	v_mov_b32_e32 v3, 0
	v_cndmask_b32_e32 v2, v4, v2, vcc
	v_cmp_lt_i32_e32 vcc, v8, v5
	v_lshlrev_b32_e32 v18, 2, v2
	v_lshlrev_b32_e32 v2, 5, v0
	v_cndmask_b32_e32 v8, v4, v8, vcc
	v_lshlrev_b32_e32 v19, 2, v8
	v_xor_b32_e32 v8, 32, v4
	v_and_b32_e32 v2, 0x1e0, v2
	v_ashrrev_i32_e32 v7, 31, v6
	v_cmp_lt_i32_e32 vcc, v8, v5
	s_ashr_i32 s21, s20, 31
	v_ashrrev_i32_e32 v15, 31, v14
	v_lshl_add_u64 v[2:3], s[8:9], 0, v[2:3]
	v_cndmask_b32_e32 v4, v4, v8, vcc
	v_lshlrev_b64 v[8:9], 2, v[6:7]
	s_lshl_b64 s[8:9], s[20:21], 8
	s_lshl_b64 s[18:19], s[20:21], 9
	v_lshlrev_b32_e32 v20, 2, v4
	v_lshl_add_u64 v[4:5], s[10:11], 0, v[8:9]
	v_lshl_add_u64 v[6:7], v[6:7], 1, s[8:9]
	s_mov_b64 s[8:9], 0x3bc00000
	s_ashr_i32 s15, s14, 31
	v_lshl_add_u64 v[8:9], s[18:19], 0, v[8:9]
	v_lshl_add_u64 v[10:11], s[18:19], 0, v[14:15]
	v_lshrrev_b32_e32 v64, 7, v14
	v_and_b32_e32 v65, 0x78, v14
	v_lshl_or_b32 v64, v64, 20, v65
	s_lshl_b32 s100, s20, 7
	v_add_u32_e32 v64, s100, v64
	v_mov_b32_e32 v65, 0
	s_lshl_b32 s101, s14, 7
	s_lshl_b64 s[18:19], s[20:21], 10
	s_lshl_b64 s[22:23], s[20:21], 11
	v_lshlrev_b32_e32 v1, 2, v1
	v_lshl_add_u64 v[6:7], v[6:7], 0, s[8:9]
	s_lshl_b64 s[8:9], s[14:15], 8
	s_lshl_b64 s[10:11], s[14:15], 9
	v_lshl_add_u64 v[12:13], v[14:15], 1, s[18:19]
	s_lshl_b64 s[18:19], s[14:15], 10
	v_lshl_add_u64 v[14:15], v[14:15], 2, s[22:23]
	s_lshl_b64 s[22:23], s[14:15], 11
	s_mov_b64 s[38:39], 0x39600000
	v_mov_b32_e32 v21, 0x358637bd
	s_mov_b32 s3, 0x800000
	s_mov_b32 s15, 0xc200000
	s_mov_b32 s21, 0x3ac00000
	s_mov_b32 s29, 0x4fc00000
	s_mov_b32 s30, 0x3b400000
	s_brev_b32 s31, 10
	s_mov_b32 s34, 0x3a600000
	s_mov_b32 s35, s20
; DI float bf2f(unsigned b) { return __uint_as_float(b << 16); }
; DI unsigned pk2(float lo, float hi) { const f32x2 v = {lo, hi}; return __builtin_bit_cast(unsigned, __builtin_convertvector(v, bf16x2_t)); }
; DI bf16x8 pack8(const f32x4& a, const f32x4& b) { v4u w; w.x = pk2(a[0], a[1]); w.y = pk2(a[2], a[3]); w.z = pk2(b[0], b[1]); w.w = pk2(b[2], b[3]); return __builtin_bit_cast(bf16x8, w); }
; DI unsigned pk4_fp8(float a, float b, float c, float d) { int p = __builtin_amdgcn_cvt_pk_fp8_f32(a, b, 0, false); p = __builtin_amdgcn_cvt_pk_fp8_f32(c, d, p, true); return (unsigned)p; }
; DI void dsa_post_row(const float* KRAW, const float* KIRAW, const float* knorm, const float* kinorm, float* kout, float* kiout, bf16* KB, bf16* KIB, const bf16* VB, unsigned char* K8, unsigned char* V8, int t, int lane) {
;     { const float* p = KRAW + (size_t)t * 512 + 8 * lane; f32x4 a = *(const f32x4*)p, b = *(const f32x4*)(p + 4);
;       const float rs = rsqrtf(grp16_sum((a.x * a.x + a.y * a.y) + (a.z * a.z + a.w * a.w) + (b.x * b.x + b.y * b.y) + (b.z * b.z + b.w * b.w)) * (1.f / 128.f) + EPS);
;       const float* gp = knorm + ((8 * lane) & 127); const f32x4 g0 = *(const f32x4*)gp, g1 = *(const f32x4*)(gp + 4);
;       a = a * rs * g0; b = b * rs * g1; float* o = kout + (size_t)t * 512 + 8 * lane; __builtin_nontemporal_store(a, (f32x4*)o); __builtin_nontemporal_store(b, (f32x4*)(o + 4)); *(bf16x8*)(KB + (size_t)t * 512 + 8 * lane) = pack8(a, b);
;       *(v2u*)(K8 + (size_t)t * 512 + 8 * lane) = (v2u){pk4_fp8(a[0], a[1], a[2], a[3]), pk4_fp8(b[0], b[1], b[2], b[3])};
;       const v4u vw = *(const v4u*)(VB + (size_t)t * 512 + 8 * lane);
;       *(v2u*)(V8 + (size_t)t * 512 + 8 * lane) = (v2u){pk4_fp8(bf2f(vw.x & 0xffffu), bf2f(vw.x >> 16), bf2f(vw.y & 0xffffu), bf2f(vw.y >> 16)), pk4_fp8(bf2f(vw.z & 0xffffu), bf2f(vw.z >> 16), bf2f(vw.w & 0xffffu), bf2f(vw.w >> 16))}; }
;     { const f32x2 a = *(const f32x2*)(KIRAW + (size_t)t * 128 + 2 * lane); const float rs = rsqrtf(wave_sum(a.x * a.x + a.y * a.y) * (1.f / 128.f) + EPS);
;       const f32x2 gk = *(const f32x2*)(kinorm + 2 * lane); const float x = a.x * rs * gk.x, y = a.y * rs * gk.y;
;       *(f32x2*)(kiout + (size_t)t * 128 + 2 * lane) = (f32x2){x, y}; *(unsigned*)(KIB + (size_t)t * 128 + 2 * lane) = pk2(x, y); }
.LBB0_998:
	v_lshl_add_u64 v[22:23], s[6:7], 0, v[14:15]
	v_add_co_u32_e32 v40, vcc, 0x39600000, v22
	v_lshl_add_u64 v[38:39], v[22:23], 0, s[38:39]
	s_nop 0
	v_addc_co_u32_e32 v41, vcc, 0, v23, vcc
	global_load_dwordx4 v[22:25], v[40:41], off
	global_load_dwordx4 v[26:29], v[38:39], off offset:16
	global_load_dwordx4 v[30:33], v[2:3], off
	global_load_dwordx4 v[34:37], v[2:3], off offset:16
	v_lshl_add_u64 v[38:39], s[4:5], 0, v[14:15]
	v_add_co_u32_e32 v38, vcc, s15, v38
	v_lshl_add_u64 v[40:41], s[6:7], 0, v[12:13]
	s_nop 0
	v_addc_co_u32_e32 v39, vcc, 0, v39, vcc
	v_add_co_u32_e32 v46, vcc, s21, v40
	v_lshl_add_u64 v[44:45], s[6:7], 0, v[10:11]
	s_nop 0
	v_addc_co_u32_e32 v47, vcc, 0, v41, vcc
	v_lshl_add_u64 v[48:49], s[6:7], 0, v[64:65]
	v_add_co_u32_e32 v48, vcc, s29, v48
	v_mov_b32_e32 v42, 0
	s_nop 0
	v_addc_co_u32_e32 v49, vcc, 0, v49, vcc
	v_add_co_u32_e32 v40, vcc, s30, v40
	v_mov_b32_e32 v43, 0
	s_nop 0
	v_addc_co_u32_e32 v41, vcc, 0, v41, vcc
	s_add_i32 s35, s35, s14
	v_add_u32_e32 v64, s101, v64
	v_lshl_add_u64 v[10:11], v[10:11], 0, s[10:11]
	v_lshl_add_u64 v[12:13], v[12:13], 0, s[18:19]
	v_lshl_add_u64 v[14:15], v[14:15], 0, s[22:23]
	s_cmpk_lt_i32 s35, 0x2000
	s_waitcnt vmcnt(3)
	v_pk_mul_f32 v[50:51], v[24:25], v[24:25]
	v_pk_mul_f32 v[52:53], v[22:23], v[22:23]
	s_waitcnt vmcnt(2)
	v_pk_mul_f32 v[54:55], v[28:29], v[28:29]
	v_pk_mul_f32 v[56:57], v[26:27], v[26:27]
	v_pk_mov_b32 v[58:59], v[52:53], v[50:51] op_sel:[1,0]
	v_mov_b32_e32 v53, v51
	v_mov_b32_e32 v50, v54
	v_mov_b32_e32 v51, v56
	v_mov_b32_e32 v56, v55
	v_pk_add_f32 v[52:53], v[58:59], v[52:53]
	v_pk_add_f32 v[50:51], v[50:51], v[56:57]
	v_add_f32_e32 v52, v52, v53
	v_add_f32_e32 v51, v52, v51
	v_add_f32_e32 v50, v50, v51
	ds_bpermute_b32 v51, v1, v50
	s_waitcnt lgkmcnt(0)
	v_add_f32_e32 v50, v50, v51
	ds_bpermute_b32 v51, v16, v50
	s_waitcnt lgkmcnt(0)
	v_add_f32_e32 v50, v50, v51
	ds_bpermute_b32 v51, v17, v50
	s_waitcnt lgkmcnt(0)
	v_add_f32_e32 v50, v50, v51
	ds_bpermute_b32 v51, v18, v50
	s_waitcnt lgkmcnt(0)
	v_add_f32_e32 v50, v50, v51
	v_fmamk_f32 v50, v50, 0x3c000000, v21
	v_mul_f32_e32 v51, 0x4b800000, v50
	v_cmp_gt_f32_e32 vcc, s3, v50
	s_nop 1
	v_cndmask_b32_e32 v50, v50, v51, vcc
	v_rsq_f32_e32 v50, v50
	s_nop 0
	v_mul_f32_e32 v51, 0x45800000, v50
	v_cndmask_b32_e32 v50, v50, v51, vcc
	v_pk_mul_f32 v[22:23], v[22:23], v[50:51] op_sel_hi:[1,0]
	v_pk_mul_f32 v[26:27], v[26:27], v[50:51] op_sel_hi:[1,0]
	s_waitcnt vmcnt(1)
	v_pk_mul_f32 v[22:23], v[30:31], v[22:23]
	s_waitcnt vmcnt(0)
	v_pk_mul_f32 v[26:27], v[34:35], v[26:27]
	v_cvt_pk_fp8_f32 v42, v22, v23
	v_cvt_pk_fp8_f32 v43, v26, v27
	v_pk_mul_f32 v[24:25], v[24:25], v[50:51] op_sel_hi:[1,0]
	v_pk_mul_f32 v[28:29], v[28:29], v[50:51] op_sel_hi:[1,0]
	v_pk_mul_f32 v[24:25], v[32:33], v[24:25]
	v_pk_mul_f32 v[28:29], v[36:37], v[28:29]
	v_cvt_pk_fp8_f32 v42, v24, v25 op_sel:[0,0,1]
	v_cvt_pk_fp8_f32 v43, v28, v29 op_sel:[0,0,1]
	v_cvt_pk_bf16_f32 v30, v22, v23
	v_cvt_pk_bf16_f32 v31, v24, v25
	v_cvt_pk_bf16_f32 v32, v26, v27
	v_cvt_pk_bf16_f32 v33, v28, v29
	global_store_dwordx4 v[38:39], v[22:25], off nt
	global_store_dwordx4 v[38:39], v[26:29], off offset:16 nt
	global_store_dwordx4 v[46:47], v[30:33], off
	global_store_dwordx2 v[48:49], v[42:43], off
	global_load_dwordx4 v[22:25], v[40:41], off
	v_mov_b32_e32 v26, 0
	v_mov_b32_e32 v27, 0
	v_add_co_u32_e32 v30, vcc, s31, v44
	v_lshl_add_u64 v[28:29], s[6:7], 0, v[8:9]
	s_nop 0
	v_addc_co_u32_e32 v31, vcc, 0, v45, vcc
	v_add_co_u32_e32 v28, vcc, s34, v28
	s_waitcnt vmcnt(0)
	v_lshlrev_b32_e32 v32, 16, v22
	v_and_b32_e32 v22, 0xffff0000, v22
	v_lshlrev_b32_e32 v34, 16, v24
	v_and_b32_e32 v24, 0xffff0000, v24
	v_cvt_pk_fp8_f32 v26, v32, v22
	v_cvt_pk_fp8_f32 v27, v34, v24
	v_lshlrev_b32_e32 v33, 16, v23
	v_and_b32_e32 v23, 0xffff0000, v23
	v_lshlrev_b32_e32 v35, 16, v25
	v_and_b32_e32 v25, 0xffff0000, v25
	v_cvt_pk_fp8_f32 v26, v33, v23 op_sel:[0,0,1]
	v_cvt_pk_fp8_f32 v27, v35, v25 op_sel:[0,0,1]
	v_addc_co_u32_e32 v29, vcc, 0, v29, vcc
	global_store_dwordx2 v[30:31], v[26:27], off
	global_load_dwordx2 v[22:23], v[28:29], off
	global_load_dwordx2 v[24:25], v[4:5], off
	s_waitcnt vmcnt(1)
	v_pk_mul_f32 v[26:27], v[22:23], v[22:23]
	s_nop 0
	v_add_f32_e32 v26, v26, v27
	ds_bpermute_b32 v27, v1, v26
	s_waitcnt lgkmcnt(0)
	v_add_f32_e32 v26, v26, v27
	ds_bpermute_b32 v27, v16, v26
	s_waitcnt lgkmcnt(0)
	v_add_f32_e32 v28, v26, v27
	ds_bpermute_b32 v29, v17, v28
	v_lshl_add_u64 v[26:27], s[16:17], 0, v[8:9]
	v_lshl_add_u64 v[8:9], v[8:9], 0, s[10:11]
	s_waitcnt lgkmcnt(0)
	v_add_f32_e32 v30, v28, v29
	ds_bpermute_b32 v31, v18, v30
	v_lshl_add_u64 v[28:29], s[6:7], 0, v[6:7]
	v_lshl_add_u64 v[6:7], v[6:7], 0, s[8:9]
	s_waitcnt lgkmcnt(0)
	v_add_f32_e32 v30, v30, v31
	ds_bpermute_b32 v31, v19, v30
	s_waitcnt lgkmcnt(0)
	v_add_f32_e32 v30, v30, v31
	ds_bpermute_b32 v31, v20, v30
	s_waitcnt lgkmcnt(0)
	v_add_f32_e32 v30, v30, v31
	v_fmamk_f32 v30, v30, 0x3c000000, v21
	v_mul_f32_e32 v31, 0x4b800000, v30
	v_cmp_gt_f32_e32 vcc, s3, v30
	s_nop 1
	v_cndmask_b32_e32 v30, v30, v31, vcc
	v_rsq_f32_e32 v30, v30
	s_nop 0
	v_mul_f32_e32 v31, 0x45800000, v30
	v_cndmask_b32_e32 v30, v30, v31, vcc
	v_pk_mul_f32 v[22:23], v[22:23], v[30:31] op_sel_hi:[1,0]
	s_waitcnt vmcnt(0)
	v_pk_mul_f32 v[22:23], v[24:25], v[22:23]
	global_store_dwordx2 v[26:27], v[22:23], off
	v_cvt_pk_bf16_f32 v22, v22, v23
	global_store_dword v[28:29], v22, off
	s_cbranch_scc1 .LBB0_998

; #define LAS __attribute__((address_space(3)))
; #define IX_PF_LOAD(h_) do { if (more) { _Pragma("unroll") for (int it = 0; it < 2; ++it) { const int ci = tid + 512 * (2 * (h_) + it), row = ci >> 4, ch = ci & 15; st[it] = *(const v4u*)(KIB + (size_t)(128 * ns + row) * 128 + 8 * ch); } } } while (0)
; #define IX_PF_STORE(h_) do { if (more) { _Pragma("unroll") for (int it = 0; it < 2; ++it) { const int ci = tid + 512 * (2 * (h_) + it), row = ci >> 4, ch = ci & 15; *(LAS v4u*)(NBUF + row * 272 + 16 * ch) = st[it]; } } } while (0)
; #define IX_CHAIN(acc_, a_) do { _Pragma("unroll") for (int i_ = 0; i_ < 16; ++i_) acc_[i_] = 0.f; __builtin_amdgcn_s_setprio(1); _Pragma("unroll") for (int s_ = 0; s_ < 8; ++s_) acc_ = MFMA32(af[a_][s_], bfr[s_], acc_); __builtin_amdgcn_s_setprio(0); } while (0)
; DI void indexer_prompt(LAS unsigned char* lds, const bf16* QIB, const bf16* KIB, const float* WI, float* SC, int bid, int G, int tid_) {
;     ...
; #pragma unroll
;         for (int bt = 0; bt < 4; ++bt) {
;             const int key0 = k0s + 32 * bt;
;             if (bt == 2) { IX_PF_STORE(0); IX_PF_LOAD(1); }
;             if (key0 <= qlast_w) {
;             bf16x8 bfr[8];
; #pragma unroll
;             for (int s_ = 0; s_ < 8; ++s_) bfr[s_] = *(const LAS bf16x8*)(SB + (32 * bt + m) * 272 + 32 * s_ + 16 * hh);
;             f32x16 accA;
;     ...
;             IX_CHAIN(accA, 0); IX_EPI(accA, 0);
;             IX_CHAIN(accA, 1); IX_EPI(accA, 1);
;             IX_CHAIN(accA, 2); IX_EPI(accA, 2);
;             IX_CHAIN(accA, 3); IX_EPI(accA, 3);
.LBB0_1510:
	s_mov_b32 s100, 0
	s_mov_b32 s101, 0
	s_and_b32 s41, s35, 1
	s_lshl_b32 s20, s18, 7
	s_add_i32 s21, s19, s31
	s_mul_i32 s18, s41, 0x8800
	s_or_b32 s12, s21, 7
	s_add_i32 s42, s18, 0
	s_cmp_eq_u32 s37, 0
	s_cselect_b64 s[18:19], -1, 0
	s_and_b64 s[22:23], s[18:19], exec
	s_cselect_b32 s22, 0, 0x12000
	s_add_i32 s22, s22, 0
	v_lshl_add_u32 v5, v0, 4, s42
	v_or_b32_e32 v1, s31, v0
	v_or_b32_e32 v0, s21, v0
	v_lshl_add_u32 v169, v1, 6, s22
	v_ashrrev_i32_e32 v1, 31, v0
	v_and_b32_e32 v4, 31, v171
	v_lshlrev_b64 v[2:3], 15, v[0:1]
	v_lshl_add_u64 v[2:3], s[10:11], 0, v[2:3]
	v_lshlrev_b32_e32 v152, 2, v4
	v_lshl_add_u64 v[162:163], v[2:3], 0, v[152:153]
	v_or_b32_e32 v2, 2, v0
	v_ashrrev_i32_e32 v3, 31, v2
	v_lshlrev_b64 v[2:3], 15, v[2:3]
	v_lshl_add_u64 v[2:3], s[10:11], 0, v[2:3]
	v_lshl_add_u64 v[160:161], v[2:3], 0, v[152:153]
	v_or_b32_e32 v2, 4, v0
	v_or_b32_e32 v0, 6, v0
	v_ashrrev_i32_e32 v3, 31, v2
	v_ashrrev_i32_e32 v1, 31, v0
	v_lshlrev_b64 v[2:3], 15, v[2:3]
	v_lshlrev_b64 v[0:1], 15, v[0:1]
	v_lshl_add_u64 v[2:3], s[10:11], 0, v[2:3]
	v_lshl_add_u64 v[0:1], s[10:11], 0, v[0:1]
	v_lshl_add_u64 v[158:159], v[2:3], 0, v[152:153]
	v_lshl_add_u64 v[156:157], v[0:1], 0, v[152:153]
	s_cmp_le_i32 s20, s12
	v_mad_u32_u24 v170, v4, s34, v5
	s_cbranch_scc0 .LBB0_1512
	ds_read_b128 v[174:177], v170 offset:4096
	ds_read_b128 v[178:181], v170 offset:4128
	ds_read_b128 v[182:185], v170 offset:4160
	ds_read_b128 v[186:189], v170 offset:4192
	ds_read_b128 v[190:193], v170 offset:4224
	ds_read_b128 v[194:197], v170 offset:4256
	ds_read_b128 v[198:201], v170 offset:4288
	ds_read_b128 v[202:205], v170 offset:4320
	s_setprio 1
	s_waitcnt lgkmcnt(7)
	v_mfma_f32_32x32x16_bf16 v[0:15], v[44:47], v[174:177], 0
	s_waitcnt lgkmcnt(6)
	v_mfma_f32_32x32x16_bf16 v[0:15], v[40:43], v[178:181], v[0:15]
	s_waitcnt lgkmcnt(5)
	v_mfma_f32_32x32x16_bf16 v[0:15], v[36:39], v[182:185], v[0:15]
	s_waitcnt lgkmcnt(4)
	v_mfma_f32_32x32x16_bf16 v[0:15], v[32:35], v[186:189], v[0:15]
	s_waitcnt lgkmcnt(3)
	v_mfma_f32_32x32x16_bf16 v[0:15], v[28:31], v[190:193], v[0:15]
	s_waitcnt lgkmcnt(2)
	v_mfma_f32_32x32x16_bf16 v[0:15], v[24:27], v[194:197], v[0:15]
	s_waitcnt lgkmcnt(1)
	v_mfma_f32_32x32x16_bf16 v[0:15], v[20:23], v[198:201], v[0:15]
	s_waitcnt lgkmcnt(0)
	v_mfma_f32_32x32x16_bf16 v[0:15], v[16:19], v[202:205], v[0:15]
	ds_read_b128 v[206:209], v169
	ds_read_b128 v[210:213], v169 offset:16
	ds_read_b128 v[214:217], v169 offset:32
	ds_read_b128 v[218:221], v169 offset:48
	v_mfma_f32_32x32x16_bf16 v[224:239], v[76:79], v[174:177], 0
	v_mfma_f32_32x32x16_bf16 v[224:239], v[72:75], v[178:181], v[224:239]
	v_mfma_f32_32x32x16_bf16 v[224:239], v[68:71], v[182:185], v[224:239]
	v_mfma_f32_32x32x16_bf16 v[224:239], v[64:67], v[186:189], v[224:239]
	s_nop 3
	v_med3_f32 v0, v0, 0, v167
	s_waitcnt lgkmcnt(3)
	v_fma_f32 v0, v0, v206, 0
	v_med3_f32 v1, v1, 0, v167
	v_med3_f32 v2, v2, 0, v167
	v_fma_f32 v1, v1, v207, 0
	v_fmac_f32_e32 v0, v2, v208
	v_med3_f32 v2, v3, 0, v167
	v_mfma_f32_32x32x16_bf16 v[224:239], v[60:63], v[190:193], v[224:239]
	v_fmac_f32_e32 v1, v2, v209
	v_med3_f32 v2, v4, 0, v167
	s_waitcnt lgkmcnt(2)
	v_fmac_f32_e32 v0, v2, v210
	v_med3_f32 v2, v5, 0, v167
	v_fmac_f32_e32 v1, v2, v211
	v_med3_f32 v2, v6, 0, v167
	v_fmac_f32_e32 v0, v2, v212
	v_mfma_f32_32x32x16_bf16 v[224:239], v[56:59], v[194:197], v[224:239]
	v_med3_f32 v2, v7, 0, v167
	v_fmac_f32_e32 v1, v2, v213
	v_med3_f32 v2, v8, 0, v167
	s_waitcnt lgkmcnt(1)
	v_fmac_f32_e32 v0, v2, v214
	v_med3_f32 v2, v9, 0, v167
	v_fmac_f32_e32 v1, v2, v215
	v_med3_f32 v2, v10, 0, v167
	v_mfma_f32_32x32x16_bf16 v[224:239], v[52:55], v[198:201], v[224:239]
	v_fmac_f32_e32 v0, v2, v216
	v_med3_f32 v2, v11, 0, v167
	v_fmac_f32_e32 v1, v2, v217
	v_med3_f32 v2, v12, 0, v167
	s_waitcnt lgkmcnt(0)
	v_fmac_f32_e32 v0, v2, v218
	v_med3_f32 v2, v13, 0, v167
	v_fmac_f32_e32 v1, v2, v219
	v_mfma_f32_32x32x16_bf16 v[224:239], v[48:51], v[202:205], v[224:239]
	v_med3_f32 v2, v14, 0, v167
	v_fmac_f32_e32 v0, v2, v220
	v_med3_f32 v2, v15, 0, v167
	s_ashr_i32 s21, s20, 31
	v_fmac_f32_e32 v1, v2, v221
	s_lshl_b64 s[22:23], s[20:21], 2
	v_add_f32_e32 v2, v0, v1
	v_lshl_add_u64 v[0:1], v[162:163], 0, s[22:23]
	global_store_dword v[0:1], v2, off
	ds_read_b128 v[206:209], v169 offset:128
	ds_read_b128 v[210:213], v169 offset:144
	ds_read_b128 v[214:217], v169 offset:160
	ds_read_b128 v[218:221], v169 offset:176
	v_mfma_f32_32x32x16_bf16 v[0:15], v[108:111], v[174:177], 0
	v_mfma_f32_32x32x16_bf16 v[0:15], v[104:107], v[178:181], v[0:15]
	v_mfma_f32_32x32x16_bf16 v[0:15], v[100:103], v[182:185], v[0:15]
	v_mfma_f32_32x32x16_bf16 v[0:15], v[96:99], v[186:189], v[0:15]
	s_nop 3
	v_med3_f32 v224, v224, 0, v167
	s_waitcnt lgkmcnt(3)
	v_fma_f32 v224, v224, v206, 0
	v_med3_f32 v225, v225, 0, v167
	v_med3_f32 v226, v226, 0, v167
	v_fma_f32 v225, v225, v207, 0
	v_fmac_f32_e32 v224, v226, v208
	v_med3_f32 v226, v227, 0, v167
	v_mfma_f32_32x32x16_bf16 v[0:15], v[92:95], v[190:193], v[0:15]
	v_fmac_f32_e32 v225, v226, v209
	v_med3_f32 v226, v228, 0, v167
	s_waitcnt lgkmcnt(2)
	v_fmac_f32_e32 v224, v226, v210
	v_med3_f32 v226, v229, 0, v167
	v_fmac_f32_e32 v225, v226, v211
	v_med3_f32 v226, v230, 0, v167
	v_fmac_f32_e32 v224, v226, v212
	v_mfma_f32_32x32x16_bf16 v[0:15], v[88:91], v[194:197], v[0:15]
	v_med3_f32 v226, v231, 0, v167
	v_fmac_f32_e32 v225, v226, v213
	v_med3_f32 v226, v232, 0, v167
	s_waitcnt lgkmcnt(1)
	v_fmac_f32_e32 v224, v226, v214
	v_med3_f32 v226, v233, 0, v167
	v_fmac_f32_e32 v225, v226, v215
	v_med3_f32 v226, v234, 0, v167
	v_mfma_f32_32x32x16_bf16 v[0:15], v[84:87], v[198:201], v[0:15]
	v_fmac_f32_e32 v224, v226, v216
	v_med3_f32 v226, v235, 0, v167
	v_fmac_f32_e32 v225, v226, v217
	v_med3_f32 v226, v236, 0, v167
	s_waitcnt lgkmcnt(0)
; #define LAS __attribute__((address_space(3)))
; #define IX_CHAIN(acc_, a_) do { _Pragma("unroll") for (int i_ = 0; i_ < 16; ++i_) acc_[i_] = 0.f; __builtin_amdgcn_s_setprio(1); _Pragma("unroll") for (int s_ = 0; s_ < 8; ++s_) acc_ = MFMA32(af[a_][s_], bfr[s_], acc_); __builtin_amdgcn_s_setprio(0); } while (0)
; DI void indexer_prompt(LAS unsigned char* lds, const bf16* QIB, const bf16* KIB, const float* WI, float* SC, int bid, int G, int tid_) {
;     ...
;             if (key0 <= qlast_w) {
;             bf16x8 bfr[8];
; #pragma unroll
;             for (int s_ = 0; s_ < 8; ++s_) bfr[s_] = *(const LAS bf16x8*)(SB + (32 * bt + m) * 272 + 32 * s_ + 16 * hh);
;             f32x16 accA;
;     ...
;             IX_CHAIN(accA, 0); IX_EPI(accA, 0);
;             IX_CHAIN(accA, 1); IX_EPI(accA, 1);
;             IX_CHAIN(accA, 2); IX_EPI(accA, 2);
;             IX_CHAIN(accA, 3); IX_EPI(accA, 3);
	v_fmac_f32_e32 v224, v226, v218
	v_med3_f32 v226, v237, 0, v167
	v_fmac_f32_e32 v225, v226, v219
	v_mfma_f32_32x32x16_bf16 v[0:15], v[80:83], v[202:205], v[0:15]
	v_med3_f32 v226, v238, 0, v167
	v_fmac_f32_e32 v224, v226, v220
	v_med3_f32 v226, v239, 0, v167
	v_fmac_f32_e32 v225, v226, v221
	v_add_f32_e32 v226, v224, v225
	v_lshl_add_u64 v[224:225], v[160:161], 0, s[22:23]
	global_store_dword v[224:225], v226, off
	ds_read_b128 v[206:209], v169 offset:256
	ds_read_b128 v[210:213], v169 offset:272
	ds_read_b128 v[214:217], v169 offset:288
	ds_read_b128 v[218:221], v169 offset:304
	v_mfma_f32_32x32x16_bf16 v[224:239], v[148:151], v[174:177], 0
	v_mfma_f32_32x32x16_bf16 v[224:239], v[144:147], v[178:181], v[224:239]
	v_mfma_f32_32x32x16_bf16 v[224:239], v[140:143], v[182:185], v[224:239]
	v_mfma_f32_32x32x16_bf16 v[224:239], v[136:139], v[186:189], v[224:239]
	s_nop 3
	v_med3_f32 v0, v0, 0, v167
	s_waitcnt lgkmcnt(3)
	v_fma_f32 v0, v0, v206, 0
	v_med3_f32 v1, v1, 0, v167
	v_med3_f32 v2, v2, 0, v167
	v_fma_f32 v1, v1, v207, 0
	v_fmac_f32_e32 v0, v2, v208
	v_med3_f32 v2, v3, 0, v167
	v_mfma_f32_32x32x16_bf16 v[224:239], v[132:135], v[190:193], v[224:239]
	v_fmac_f32_e32 v1, v2, v209
	v_med3_f32 v2, v4, 0, v167
	s_waitcnt lgkmcnt(2)
	v_fmac_f32_e32 v0, v2, v210
	v_med3_f32 v2, v5, 0, v167
	v_fmac_f32_e32 v1, v2, v211
	v_med3_f32 v2, v6, 0, v167
	v_fmac_f32_e32 v0, v2, v212
	v_mfma_f32_32x32x16_bf16 v[224:239], v[128:131], v[194:197], v[224:239]
	v_med3_f32 v2, v7, 0, v167
	v_fmac_f32_e32 v1, v2, v213
	v_med3_f32 v2, v8, 0, v167
	s_waitcnt lgkmcnt(1)
	v_fmac_f32_e32 v0, v2, v214
	v_med3_f32 v2, v9, 0, v167
	v_fmac_f32_e32 v1, v2, v215
	v_med3_f32 v2, v10, 0, v167
	v_mfma_f32_32x32x16_bf16 v[224:239], v[124:127], v[198:201], v[224:239]
	v_fmac_f32_e32 v0, v2, v216
	v_med3_f32 v2, v11, 0, v167
	v_fmac_f32_e32 v1, v2, v217
	v_med3_f32 v2, v12, 0, v167
	s_waitcnt lgkmcnt(0)
	v_fmac_f32_e32 v0, v2, v218
	v_med3_f32 v2, v13, 0, v167
	v_fmac_f32_e32 v1, v2, v219
	v_mfma_f32_32x32x16_bf16 v[224:239], v[120:123], v[202:205], v[224:239]
	v_med3_f32 v2, v14, 0, v167
	v_fmac_f32_e32 v0, v2, v220
	v_med3_f32 v2, v15, 0, v167
	v_fmac_f32_e32 v1, v2, v221
	v_add_f32_e32 v2, v0, v1
	v_lshl_add_u64 v[0:1], v[158:159], 0, s[22:23]
	global_store_dword v[0:1], v2, off
	s_setprio 0
	ds_read_b128 v[174:177], v169 offset:384
	ds_read_b128 v[178:181], v169 offset:400
	ds_read_b128 v[182:185], v169 offset:416
	ds_read_b128 v[186:189], v169 offset:432
	s_nop 7
	v_med3_f32 v224, v224, 0, v167
	s_waitcnt lgkmcnt(3)
	v_fma_f32 v224, v224, v174, 0
	v_med3_f32 v225, v225, 0, v167
	v_med3_f32 v226, v226, 0, v167
	v_fma_f32 v225, v225, v175, 0
	v_fmac_f32_e32 v224, v226, v176
	v_med3_f32 v226, v227, 0, v167
	v_fmac_f32_e32 v225, v226, v177
	v_med3_f32 v226, v228, 0, v167
	s_waitcnt lgkmcnt(2)
	v_fmac_f32_e32 v224, v226, v178
	v_med3_f32 v226, v229, 0, v167
	v_fmac_f32_e32 v225, v226, v179
	v_med3_f32 v226, v230, 0, v167
	v_fmac_f32_e32 v224, v226, v180
	v_med3_f32 v226, v231, 0, v167
	v_fmac_f32_e32 v225, v226, v181
	v_med3_f32 v226, v232, 0, v167
	s_waitcnt lgkmcnt(1)
	v_fmac_f32_e32 v224, v226, v182
	v_med3_f32 v226, v233, 0, v167
	v_fmac_f32_e32 v225, v226, v183
	v_med3_f32 v226, v234, 0, v167
	v_fmac_f32_e32 v224, v226, v184
	v_med3_f32 v226, v235, 0, v167
	v_fmac_f32_e32 v225, v226, v185
	v_med3_f32 v226, v236, 0, v167
	s_waitcnt lgkmcnt(0)
	v_fmac_f32_e32 v224, v226, v186
	v_med3_f32 v226, v237, 0, v167
	v_fmac_f32_e32 v225, v226, v187
	v_med3_f32 v226, v238, 0, v167
	v_fmac_f32_e32 v224, v226, v188
	v_med3_f32 v226, v239, 0, v167
	v_fmac_f32_e32 v225, v226, v189
	v_add_f32_e32 v226, v224, v225
	v_lshl_add_u64 v[224:225], v[156:157], 0, s[22:23]
	global_store_dword v[224:225], v226, off
.LBB0_1512:
	s_or_b32 s21, s20, 32
	s_cmp_gt_i32 s21, s12
	s_cbranch_scc1 .LBB0_1514
	s_mov_b32 s100, 1
	ds_read_b128 v[174:177], v170 offset:12800
	ds_read_b128 v[178:181], v170 offset:12832
	ds_read_b128 v[182:185], v170 offset:12864
	ds_read_b128 v[186:189], v170 offset:12896
	ds_read_b128 v[190:193], v170 offset:12928
	ds_read_b128 v[194:197], v170 offset:12960
	ds_read_b128 v[198:201], v170 offset:12992
	ds_read_b128 v[202:205], v170 offset:13024
	s_setprio 1
	s_waitcnt lgkmcnt(7)
	v_mfma_f32_32x32x16_bf16 v[0:15], v[44:47], v[174:177], 0
	s_waitcnt lgkmcnt(6)
	v_mfma_f32_32x32x16_bf16 v[0:15], v[40:43], v[178:181], v[0:15]
	s_waitcnt lgkmcnt(5)
	v_mfma_f32_32x32x16_bf16 v[0:15], v[36:39], v[182:185], v[0:15]
	s_waitcnt lgkmcnt(4)
	v_mfma_f32_32x32x16_bf16 v[0:15], v[32:35], v[186:189], v[0:15]
	s_waitcnt lgkmcnt(3)
	v_mfma_f32_32x32x16_bf16 v[0:15], v[28:31], v[190:193], v[0:15]
	s_waitcnt lgkmcnt(2)
	v_mfma_f32_32x32x16_bf16 v[0:15], v[24:27], v[194:197], v[0:15]
	s_waitcnt lgkmcnt(1)
	v_mfma_f32_32x32x16_bf16 v[0:15], v[20:23], v[198:201], v[0:15]
	s_waitcnt lgkmcnt(0)
	v_mfma_f32_32x32x16_bf16 v[0:15], v[16:19], v[202:205], v[0:15]
	ds_read_b128 v[206:209], v169
	ds_read_b128 v[210:213], v169 offset:16
	ds_read_b128 v[214:217], v169 offset:32
	ds_read_b128 v[218:221], v169 offset:48
	v_mfma_f32_32x32x16_bf16 v[224:239], v[76:79], v[174:177], 0
	v_mfma_f32_32x32x16_bf16 v[224:239], v[72:75], v[178:181], v[224:239]
	v_mfma_f32_32x32x16_bf16 v[224:239], v[68:71], v[182:185], v[224:239]
	v_mfma_f32_32x32x16_bf16 v[224:239], v[64:67], v[186:189], v[224:239]
	s_nop 3
	v_med3_f32 v0, v0, 0, v167
	s_waitcnt lgkmcnt(3)
	v_fma_f32 v0, v0, v206, 0
	v_med3_f32 v1, v1, 0, v167
	v_med3_f32 v2, v2, 0, v167
	v_fma_f32 v1, v1, v207, 0
	v_fmac_f32_e32 v0, v2, v208
	v_med3_f32 v2, v3, 0, v167
	v_mfma_f32_32x32x16_bf16 v[224:239], v[60:63], v[190:193], v[224:239]
	v_fmac_f32_e32 v1, v2, v209
	v_med3_f32 v2, v4, 0, v167
	s_waitcnt lgkmcnt(2)
; #define LAS __attribute__((address_space(3)))
; #define IX_CHAIN(acc_, a_) do { _Pragma("unroll") for (int i_ = 0; i_ < 16; ++i_) acc_[i_] = 0.f; __builtin_amdgcn_s_setprio(1); _Pragma("unroll") for (int s_ = 0; s_ < 8; ++s_) acc_ = MFMA32(af[a_][s_], bfr[s_], acc_); __builtin_amdgcn_s_setprio(0); } while (0)
; DI void indexer_prompt(LAS unsigned char* lds, const bf16* QIB, const bf16* KIB, const float* WI, float* SC, int bid, int G, int tid_) {
;     ...
;             if (key0 <= qlast_w) {
;             bf16x8 bfr[8];
; #pragma unroll
;             for (int s_ = 0; s_ < 8; ++s_) bfr[s_] = *(const LAS bf16x8*)(SB + (32 * bt + m) * 272 + 32 * s_ + 16 * hh);
;             f32x16 accA;
;     ...
;             IX_CHAIN(accA, 0); IX_EPI(accA, 0);
;             IX_CHAIN(accA, 1); IX_EPI(accA, 1);
;             IX_CHAIN(accA, 2); IX_EPI(accA, 2);
;             IX_CHAIN(accA, 3); IX_EPI(accA, 3);
	v_fmac_f32_e32 v0, v2, v210
	v_med3_f32 v2, v5, 0, v167
	v_fmac_f32_e32 v1, v2, v211
	v_med3_f32 v2, v6, 0, v167
	v_fmac_f32_e32 v0, v2, v212
	v_mfma_f32_32x32x16_bf16 v[224:239], v[56:59], v[194:197], v[224:239]
	v_med3_f32 v2, v7, 0, v167
	v_fmac_f32_e32 v1, v2, v213
	v_med3_f32 v2, v8, 0, v167
	s_waitcnt lgkmcnt(1)
	v_fmac_f32_e32 v0, v2, v214
	v_med3_f32 v2, v9, 0, v167
	v_fmac_f32_e32 v1, v2, v215
	v_med3_f32 v2, v10, 0, v167
	v_mfma_f32_32x32x16_bf16 v[224:239], v[52:55], v[198:201], v[224:239]
	v_fmac_f32_e32 v0, v2, v216
	v_med3_f32 v2, v11, 0, v167
	v_fmac_f32_e32 v1, v2, v217
	v_med3_f32 v2, v12, 0, v167
	s_waitcnt lgkmcnt(0)
	v_fmac_f32_e32 v0, v2, v218
	v_med3_f32 v2, v13, 0, v167
	v_fmac_f32_e32 v1, v2, v219
	v_mfma_f32_32x32x16_bf16 v[224:239], v[48:51], v[202:205], v[224:239]
	v_med3_f32 v2, v14, 0, v167
	v_fmac_f32_e32 v0, v2, v220
	v_med3_f32 v2, v15, 0, v167
	s_ashr_i32 s21, s20, 31
	v_fmac_f32_e32 v1, v2, v221
	s_lshl_b64 s[22:23], s[20:21], 2
	v_add_f32_e32 v2, v0, v1
	v_lshl_add_u64 v[0:1], v[162:163], 0, s[22:23]
	global_store_dword v[0:1], v2, off offset:128
	ds_read_b128 v[206:209], v169 offset:128
	ds_read_b128 v[210:213], v169 offset:144
	ds_read_b128 v[214:217], v169 offset:160
	ds_read_b128 v[218:221], v169 offset:176
	v_mfma_f32_32x32x16_bf16 v[0:15], v[108:111], v[174:177], 0
	v_mfma_f32_32x32x16_bf16 v[0:15], v[104:107], v[178:181], v[0:15]
	v_mfma_f32_32x32x16_bf16 v[0:15], v[100:103], v[182:185], v[0:15]
	v_mfma_f32_32x32x16_bf16 v[0:15], v[96:99], v[186:189], v[0:15]
	s_nop 3
	v_med3_f32 v224, v224, 0, v167
	s_waitcnt lgkmcnt(3)
	v_fma_f32 v224, v224, v206, 0
	v_med3_f32 v225, v225, 0, v167
	v_med3_f32 v226, v226, 0, v167
	v_fma_f32 v225, v225, v207, 0
	v_fmac_f32_e32 v224, v226, v208
	v_med3_f32 v226, v227, 0, v167
	v_mfma_f32_32x32x16_bf16 v[0:15], v[92:95], v[190:193], v[0:15]
	v_fmac_f32_e32 v225, v226, v209
	v_med3_f32 v226, v228, 0, v167
	s_waitcnt lgkmcnt(2)
	v_fmac_f32_e32 v224, v226, v210
	v_med3_f32 v226, v229, 0, v167
	v_fmac_f32_e32 v225, v226, v211
	v_med3_f32 v226, v230, 0, v167
	v_fmac_f32_e32 v224, v226, v212
	v_mfma_f32_32x32x16_bf16 v[0:15], v[88:91], v[194:197], v[0:15]
	v_med3_f32 v226, v231, 0, v167
	v_fmac_f32_e32 v225, v226, v213
	v_med3_f32 v226, v232, 0, v167
	s_waitcnt lgkmcnt(1)
	v_fmac_f32_e32 v224, v226, v214
	v_med3_f32 v226, v233, 0, v167
	v_fmac_f32_e32 v225, v226, v215
	v_med3_f32 v226, v234, 0, v167
	v_mfma_f32_32x32x16_bf16 v[0:15], v[84:87], v[198:201], v[0:15]
	v_fmac_f32_e32 v224, v226, v216
	v_med3_f32 v226, v235, 0, v167
	v_fmac_f32_e32 v225, v226, v217
	v_med3_f32 v226, v236, 0, v167
	s_waitcnt lgkmcnt(0)
	v_fmac_f32_e32 v224, v226, v218
	v_med3_f32 v226, v237, 0, v167
	v_fmac_f32_e32 v225, v226, v219
	v_mfma_f32_32x32x16_bf16 v[0:15], v[80:83], v[202:205], v[0:15]
	v_med3_f32 v226, v238, 0, v167
	v_fmac_f32_e32 v224, v226, v220
	v_med3_f32 v226, v239, 0, v167
	v_fmac_f32_e32 v225, v226, v221
	v_add_f32_e32 v226, v224, v225
	v_lshl_add_u64 v[224:225], v[160:161], 0, s[22:23]
	global_store_dword v[224:225], v226, off offset:128
	ds_read_b128 v[206:209], v169 offset:256
	ds_read_b128 v[210:213], v169 offset:272
	ds_read_b128 v[214:217], v169 offset:288
	ds_read_b128 v[218:221], v169 offset:304
	v_mfma_f32_32x32x16_bf16 v[224:239], v[148:151], v[174:177], 0
	v_mfma_f32_32x32x16_bf16 v[224:239], v[144:147], v[178:181], v[224:239]
	v_mfma_f32_32x32x16_bf16 v[224:239], v[140:143], v[182:185], v[224:239]
	v_mfma_f32_32x32x16_bf16 v[224:239], v[136:139], v[186:189], v[224:239]
	s_nop 3
	v_med3_f32 v0, v0, 0, v167
	s_waitcnt lgkmcnt(3)
	v_fma_f32 v0, v0, v206, 0
	v_med3_f32 v1, v1, 0, v167
	v_med3_f32 v2, v2, 0, v167
	v_fma_f32 v1, v1, v207, 0
	v_fmac_f32_e32 v0, v2, v208
	v_med3_f32 v2, v3, 0, v167
	v_mfma_f32_32x32x16_bf16 v[224:239], v[132:135], v[190:193], v[224:239]
	v_fmac_f32_e32 v1, v2, v209
	v_med3_f32 v2, v4, 0, v167
	s_waitcnt lgkmcnt(2)
	v_fmac_f32_e32 v0, v2, v210
	v_med3_f32 v2, v5, 0, v167
	v_fmac_f32_e32 v1, v2, v211
	v_med3_f32 v2, v6, 0, v167
	v_fmac_f32_e32 v0, v2, v212
	v_mfma_f32_32x32x16_bf16 v[224:239], v[128:131], v[194:197], v[224:239]
	v_med3_f32 v2, v7, 0, v167
	v_fmac_f32_e32 v1, v2, v213
	v_med3_f32 v2, v8, 0, v167
	s_waitcnt lgkmcnt(1)
	v_fmac_f32_e32 v0, v2, v214
	v_med3_f32 v2, v9, 0, v167
	v_fmac_f32_e32 v1, v2, v215
	v_med3_f32 v2, v10, 0, v167
	v_mfma_f32_32x32x16_bf16 v[224:239], v[124:127], v[198:201], v[224:239]
	v_fmac_f32_e32 v0, v2, v216
	v_med3_f32 v2, v11, 0, v167
	v_fmac_f32_e32 v1, v2, v217
	v_med3_f32 v2, v12, 0, v167
	s_waitcnt lgkmcnt(0)
	v_fmac_f32_e32 v0, v2, v218
	v_med3_f32 v2, v13, 0, v167
	v_fmac_f32_e32 v1, v2, v219
	v_mfma_f32_32x32x16_bf16 v[224:239], v[120:123], v[202:205], v[224:239]
	v_med3_f32 v2, v14, 0, v167
	v_fmac_f32_e32 v0, v2, v220
	v_med3_f32 v2, v15, 0, v167
	v_fmac_f32_e32 v1, v2, v221
	v_add_f32_e32 v2, v0, v1
	v_lshl_add_u64 v[0:1], v[158:159], 0, s[22:23]
	global_store_dword v[0:1], v2, off offset:128
	s_setprio 0
	ds_read_b128 v[174:177], v169 offset:384
	ds_read_b128 v[178:181], v169 offset:400
	ds_read_b128 v[182:185], v169 offset:416
	ds_read_b128 v[186:189], v169 offset:432
	s_nop 7
	v_med3_f32 v224, v224, 0, v167
	s_waitcnt lgkmcnt(3)
	v_fma_f32 v224, v224, v174, 0
	v_med3_f32 v225, v225, 0, v167
	v_med3_f32 v226, v226, 0, v167
	v_fma_f32 v225, v225, v175, 0
	v_fmac_f32_e32 v224, v226, v176
	v_med3_f32 v226, v227, 0, v167
	v_fmac_f32_e32 v225, v226, v177
	v_med3_f32 v226, v228, 0, v167
	s_waitcnt lgkmcnt(2)
	v_fmac_f32_e32 v224, v226, v178
	v_med3_f32 v226, v229, 0, v167
	v_fmac_f32_e32 v225, v226, v179
	v_med3_f32 v226, v230, 0, v167
	v_fmac_f32_e32 v224, v226, v180
	v_med3_f32 v226, v231, 0, v167
	v_fmac_f32_e32 v225, v226, v181
	v_med3_f32 v226, v232, 0, v167
	s_waitcnt lgkmcnt(1)
	v_fmac_f32_e32 v224, v226, v182
	v_med3_f32 v226, v233, 0, v167
	v_fmac_f32_e32 v225, v226, v183
	v_med3_f32 v226, v234, 0, v167
	v_fmac_f32_e32 v224, v226, v184
	v_med3_f32 v226, v235, 0, v167
	v_fmac_f32_e32 v225, v226, v185
	v_med3_f32 v226, v236, 0, v167
	s_waitcnt lgkmcnt(0)
	v_fmac_f32_e32 v224, v226, v186
	v_med3_f32 v226, v237, 0, v167
	v_fmac_f32_e32 v225, v226, v187
	v_med3_f32 v226, v238, 0, v167
	v_fmac_f32_e32 v224, v226, v188
	v_med3_f32 v226, v239, 0, v167
	v_fmac_f32_e32 v225, v226, v189
	v_add_f32_e32 v226, v224, v225
	v_lshl_add_u64 v[224:225], v[156:157], 0, s[22:23]
	global_store_dword v[224:225], v226, off offset:128
; #define LAS __attribute__((address_space(3)))
; #define IX_PF_LOAD(h_) do { if (more) { _Pragma("unroll") for (int it = 0; it < 2; ++it) { const int ci = tid + 512 * (2 * (h_) + it), row = ci >> 4, ch = ci & 15; st[it] = *(const v4u*)(KIB + (size_t)(128 * ns + row) * 128 + 8 * ch); } } } while (0)
; #define IX_PF_STORE(h_) do { if (more) { _Pragma("unroll") for (int it = 0; it < 2; ++it) { const int ci = tid + 512 * (2 * (h_) + it), row = ci >> 4, ch = ci & 15; *(LAS v4u*)(NBUF + row * 272 + 16 * ch) = st[it]; } } } while (0)
; DI void indexer_prompt(LAS unsigned char* lds, const bf16* QIB, const bf16* KIB, const float* WI, float* SC, int bid, int G, int tid_) {
;     ...
;         LAS unsigned char* NBUF = lds + IX_ST0 + (((item - lo) & 1) ^ 1) * IX_STB;
;     ...
;         IX_PF_LOAD(0);
;         f32x2 wn = (f32x2){0.f, 0.f};
;         if (more && nqb != qb) wn = *(const f32x2*)(WI + (size_t)(64 * nqb) * 16 + 2 * tid);
;         const int qlast_w = q0 + 8 * wave + 7;
;         const int par = (item - lo) & 1;
;         LAS unsigned char* SB = lds + IX_ST0 + par * IX_STB;
;         LAS unsigned char* WBUF = lds + (wsel ? IX_W2 : IX_W);
; #pragma unroll
;         for (int bt = 0; bt < 4; ++bt) {
;             const int key0 = k0s + 32 * bt;
;             if (bt == 2) { IX_PF_STORE(0); IX_PF_LOAD(1); }
.LBB0_1514:
	s_xor_b32 s21, s41, 1
	s_mul_i32 s21, s21, 0x8800
	v_lshlrev_b32_e32 v0, 4, v171
	s_add_i32 s21, s21, 0
	v_and_b32_e32 v0, 0xf0, v0
	v_add_u32_e32 v152, s21, v0
	v_add_u32_e32 v173, 0x400, v171
	s_andn2_b64 vcc, exec, s[16:17]
	v_add_u32_e32 v174, 0x600, v171
	s_cbranch_vccnz .LBB0_1518
	v_lshrrev_b32_e32 v2, 4, v171
	v_mad_u64_u32 v[2:3], s[22:23], v2, s34, v[152:153]
	s_cmp_eq_u32 s100, 1
	s_cbranch_scc1 .Lmy_p9w1
	s_waitcnt vmcnt(1)
.Lmy_p9w1:
	s_waitcnt vmcnt(9)
	ds_write_b128 v2, v[116:119] offset:4096
	v_lshrrev_b32_e32 v2, 4, v172
	v_mad_u64_u32 v[2:3], s[22:23], v2, s34, v[152:153]
	s_cmp_eq_u32 s100, 1
	s_cbranch_scc1 .Lmy_p9w2
	s_waitcnt vmcnt(0)
.Lmy_p9w2:
	s_waitcnt vmcnt(8)
	ds_write_b128 v2, v[112:115] offset:4096
	v_ashrrev_i32_e32 v2, 4, v173
	v_add_u32_e32 v2, s40, v2
	v_ashrrev_i32_e32 v4, 4, v174
	v_mov_b32_e32 v165, v153
	v_ashrrev_i32_e32 v3, 31, v2
	v_add_u32_e32 v4, s40, v4
	v_lshl_add_u64 v[0:1], s[6:7], 0, v[164:165]
	v_lshlrev_b64 v[2:3], 8, v[2:3]
	v_ashrrev_i32_e32 v5, 31, v4
	v_lshl_add_u64 v[2:3], v[0:1], 0, v[2:3]
	v_lshlrev_b64 v[4:5], 8, v[4:5]
	v_lshl_add_u64 v[0:1], v[0:1], 0, v[4:5]
	global_load_dwordx4 v[116:119], v[2:3], off
	global_load_dwordx4 v[112:115], v[0:1], off
	s_or_b32 s21, s20, 64
	s_cmp_gt_i32 s21, s12
	s_cbranch_scc0 .LBB0_1519

; #define LAS __attribute__((address_space(3)))
; #define IX_CHAIN(acc_, a_) do { _Pragma("unroll") for (int i_ = 0; i_ < 16; ++i_) acc_[i_] = 0.f; __builtin_amdgcn_s_setprio(1); _Pragma("unroll") for (int s_ = 0; s_ < 8; ++s_) acc_ = MFMA32(af[a_][s_], bfr[s_], acc_); __builtin_amdgcn_s_setprio(0); } while (0)
; DI void indexer_prompt(LAS unsigned char* lds, const bf16* QIB, const bf16* KIB, const float* WI, float* SC, int bid, int G, int tid_) {
;     ...
;             if (key0 <= qlast_w) {
;             bf16x8 bfr[8];
; #pragma unroll
;             for (int s_ = 0; s_ < 8; ++s_) bfr[s_] = *(const LAS bf16x8*)(SB + (32 * bt + m) * 272 + 32 * s_ + 16 * hh);
;             f32x16 accA;
;     ...
;             IX_CHAIN(accA, 0); IX_EPI(accA, 0);
;             IX_CHAIN(accA, 1); IX_EPI(accA, 1);
;             IX_CHAIN(accA, 2); IX_EPI(accA, 2);
;             IX_CHAIN(accA, 3); IX_EPI(accA, 3);
.LBB0_1517:
	s_mov_b32 s101, 1
	ds_read_b128 v[176:179], v170 offset:30208
	ds_read_b128 v[180:183], v170 offset:30240
	ds_read_b128 v[184:187], v170 offset:30272
	ds_read_b128 v[188:191], v170 offset:30304
	ds_read_b128 v[192:195], v170 offset:30336
	ds_read_b128 v[196:199], v170 offset:30368
	ds_read_b128 v[200:203], v170 offset:30400
	ds_read_b128 v[204:207], v170 offset:30432
	s_setprio 1
	s_waitcnt lgkmcnt(7)
	v_mfma_f32_32x32x16_bf16 v[0:15], v[44:47], v[176:179], 0
	s_waitcnt lgkmcnt(6)
	v_mfma_f32_32x32x16_bf16 v[0:15], v[40:43], v[180:183], v[0:15]
	s_waitcnt lgkmcnt(5)
	v_mfma_f32_32x32x16_bf16 v[0:15], v[36:39], v[184:187], v[0:15]
	s_waitcnt lgkmcnt(4)
	v_mfma_f32_32x32x16_bf16 v[0:15], v[32:35], v[188:191], v[0:15]
	s_waitcnt lgkmcnt(3)
	v_mfma_f32_32x32x16_bf16 v[0:15], v[28:31], v[192:195], v[0:15]
	s_waitcnt lgkmcnt(2)
	v_mfma_f32_32x32x16_bf16 v[0:15], v[24:27], v[196:199], v[0:15]
	s_waitcnt lgkmcnt(1)
	v_mfma_f32_32x32x16_bf16 v[0:15], v[20:23], v[200:203], v[0:15]
	s_waitcnt lgkmcnt(0)
	v_mfma_f32_32x32x16_bf16 v[0:15], v[16:19], v[204:207], v[0:15]
	ds_read_b128 v[208:211], v169
	ds_read_b128 v[212:215], v169 offset:16
	ds_read_b128 v[216:219], v169 offset:32
	ds_read_b128 v[220:223], v169 offset:48
	v_mfma_f32_32x32x16_bf16 v[224:239], v[76:79], v[176:179], 0
	v_mfma_f32_32x32x16_bf16 v[224:239], v[72:75], v[180:183], v[224:239]
	v_mfma_f32_32x32x16_bf16 v[224:239], v[68:71], v[184:187], v[224:239]
	v_mfma_f32_32x32x16_bf16 v[224:239], v[64:67], v[188:191], v[224:239]
	s_nop 3
	v_med3_f32 v0, v0, 0, v167
	s_waitcnt lgkmcnt(3)
	v_fma_f32 v0, v0, v208, 0
	v_med3_f32 v1, v1, 0, v167
	v_med3_f32 v2, v2, 0, v167
	v_fma_f32 v1, v1, v209, 0
	v_fmac_f32_e32 v0, v2, v210
	v_med3_f32 v2, v3, 0, v167
	v_mfma_f32_32x32x16_bf16 v[224:239], v[60:63], v[192:195], v[224:239]
	v_fmac_f32_e32 v1, v2, v211
	v_med3_f32 v2, v4, 0, v167
	s_waitcnt lgkmcnt(2)
	v_fmac_f32_e32 v0, v2, v212
	v_med3_f32 v2, v5, 0, v167
	v_fmac_f32_e32 v1, v2, v213
	v_med3_f32 v2, v6, 0, v167
	v_fmac_f32_e32 v0, v2, v214
	v_mfma_f32_32x32x16_bf16 v[224:239], v[56:59], v[196:199], v[224:239]
	v_med3_f32 v2, v7, 0, v167
	v_fmac_f32_e32 v1, v2, v215
	v_med3_f32 v2, v8, 0, v167
	s_waitcnt lgkmcnt(1)
	v_fmac_f32_e32 v0, v2, v216
	v_med3_f32 v2, v9, 0, v167
	v_fmac_f32_e32 v1, v2, v217
	v_med3_f32 v2, v10, 0, v167
	v_mfma_f32_32x32x16_bf16 v[224:239], v[52:55], v[200:203], v[224:239]
	v_fmac_f32_e32 v0, v2, v218
	v_med3_f32 v2, v11, 0, v167
	v_fmac_f32_e32 v1, v2, v219
	v_med3_f32 v2, v12, 0, v167
	s_waitcnt lgkmcnt(0)
	v_fmac_f32_e32 v0, v2, v220
	v_med3_f32 v2, v13, 0, v167
	v_fmac_f32_e32 v1, v2, v221
	v_mfma_f32_32x32x16_bf16 v[224:239], v[48:51], v[204:207], v[224:239]
	v_med3_f32 v2, v14, 0, v167
	v_fmac_f32_e32 v0, v2, v222
	v_med3_f32 v2, v15, 0, v167
	s_ashr_i32 s21, s20, 31
	v_fmac_f32_e32 v1, v2, v223
	s_lshl_b64 s[20:21], s[20:21], 2
	v_add_f32_e32 v2, v0, v1
	v_lshl_add_u64 v[0:1], v[162:163], 0, s[20:21]
	global_store_dword v[0:1], v2, off offset:384
	ds_read_b128 v[162:165], v169 offset:128
	ds_read_b128 v[208:211], v169 offset:144
	ds_read_b128 v[212:215], v169 offset:160
	ds_read_b128 v[216:219], v169 offset:176
	v_mfma_f32_32x32x16_bf16 v[0:15], v[108:111], v[176:179], 0
	v_mfma_f32_32x32x16_bf16 v[0:15], v[104:107], v[180:183], v[0:15]
	v_mfma_f32_32x32x16_bf16 v[0:15], v[100:103], v[184:187], v[0:15]
	v_mfma_f32_32x32x16_bf16 v[0:15], v[96:99], v[188:191], v[0:15]
	s_nop 3
	v_med3_f32 v224, v224, 0, v167
	s_waitcnt lgkmcnt(3)
	v_fma_f32 v224, v224, v162, 0
	v_med3_f32 v225, v225, 0, v167
	v_med3_f32 v226, v226, 0, v167
	v_fma_f32 v225, v225, v163, 0
	v_fmac_f32_e32 v224, v226, v164
	v_med3_f32 v226, v227, 0, v167
	v_mfma_f32_32x32x16_bf16 v[0:15], v[92:95], v[192:195], v[0:15]
	v_fmac_f32_e32 v225, v226, v165
	v_med3_f32 v226, v228, 0, v167
	s_waitcnt lgkmcnt(2)
	v_fmac_f32_e32 v224, v226, v208
	v_med3_f32 v226, v229, 0, v167
	v_fmac_f32_e32 v225, v226, v209
	v_med3_f32 v226, v230, 0, v167
	v_fmac_f32_e32 v224, v226, v210
	v_mfma_f32_32x32x16_bf16 v[0:15], v[88:91], v[196:199], v[0:15]
	v_med3_f32 v226, v231, 0, v167
	v_fmac_f32_e32 v225, v226, v211
	v_med3_f32 v226, v232, 0, v167
	s_waitcnt lgkmcnt(1)
; #define LAS __attribute__((address_space(3)))
; #define IX_CHAIN(acc_, a_) do { _Pragma("unroll") for (int i_ = 0; i_ < 16; ++i_) acc_[i_] = 0.f; __builtin_amdgcn_s_setprio(1); _Pragma("unroll") for (int s_ = 0; s_ < 8; ++s_) acc_ = MFMA32(af[a_][s_], bfr[s_], acc_); __builtin_amdgcn_s_setprio(0); } while (0)
; DI void indexer_prompt(LAS unsigned char* lds, const bf16* QIB, const bf16* KIB, const float* WI, float* SC, int bid, int G, int tid_) {
;     ...
;             if (key0 <= qlast_w) {
;             bf16x8 bfr[8];
; #pragma unroll
;             for (int s_ = 0; s_ < 8; ++s_) bfr[s_] = *(const LAS bf16x8*)(SB + (32 * bt + m) * 272 + 32 * s_ + 16 * hh);
;             f32x16 accA;
;     ...
;             IX_CHAIN(accA, 0); IX_EPI(accA, 0);
;             IX_CHAIN(accA, 1); IX_EPI(accA, 1);
;             IX_CHAIN(accA, 2); IX_EPI(accA, 2);
;             IX_CHAIN(accA, 3); IX_EPI(accA, 3);
	v_fmac_f32_e32 v224, v226, v212
	v_med3_f32 v226, v233, 0, v167
	v_fmac_f32_e32 v225, v226, v213
	v_med3_f32 v226, v234, 0, v167
	v_mfma_f32_32x32x16_bf16 v[0:15], v[84:87], v[200:203], v[0:15]
	v_fmac_f32_e32 v224, v226, v214
	v_med3_f32 v226, v235, 0, v167
	v_fmac_f32_e32 v225, v226, v215
	v_med3_f32 v226, v236, 0, v167
	s_waitcnt lgkmcnt(0)
	v_fmac_f32_e32 v224, v226, v216
	v_med3_f32 v226, v237, 0, v167
	v_fmac_f32_e32 v225, v226, v217
	v_mfma_f32_32x32x16_bf16 v[0:15], v[80:83], v[204:207], v[0:15]
	v_med3_f32 v226, v238, 0, v167
	v_fmac_f32_e32 v224, v226, v218
	v_med3_f32 v226, v239, 0, v167
	v_fmac_f32_e32 v225, v226, v219
	v_add_f32_e32 v226, v224, v225
	v_lshl_add_u64 v[224:225], v[160:161], 0, s[20:21]
	global_store_dword v[224:225], v226, off offset:384
	ds_read_b128 v[160:163], v169 offset:256
	ds_read_b128 v[208:211], v169 offset:272
	ds_read_b128 v[212:215], v169 offset:288
	ds_read_b128 v[216:219], v169 offset:304
	v_mfma_f32_32x32x16_bf16 v[224:239], v[148:151], v[176:179], 0
	v_mfma_f32_32x32x16_bf16 v[224:239], v[144:147], v[180:183], v[224:239]
	v_mfma_f32_32x32x16_bf16 v[224:239], v[140:143], v[184:187], v[224:239]
	v_mfma_f32_32x32x16_bf16 v[224:239], v[136:139], v[188:191], v[224:239]
	s_nop 3
	v_med3_f32 v0, v0, 0, v167
	s_waitcnt lgkmcnt(3)
	v_fma_f32 v0, v0, v160, 0
	v_med3_f32 v1, v1, 0, v167
	v_med3_f32 v2, v2, 0, v167
	v_fma_f32 v1, v1, v161, 0
	v_fmac_f32_e32 v0, v2, v162
	v_med3_f32 v2, v3, 0, v167
	v_mfma_f32_32x32x16_bf16 v[224:239], v[132:135], v[192:195], v[224:239]
	v_fmac_f32_e32 v1, v2, v163
	v_med3_f32 v2, v4, 0, v167
	s_waitcnt lgkmcnt(2)
	v_fmac_f32_e32 v0, v2, v208
	v_med3_f32 v2, v5, 0, v167
	v_fmac_f32_e32 v1, v2, v209
	v_med3_f32 v2, v6, 0, v167
	v_fmac_f32_e32 v0, v2, v210
	v_mfma_f32_32x32x16_bf16 v[224:239], v[128:131], v[196:199], v[224:239]
	v_med3_f32 v2, v7, 0, v167
	v_fmac_f32_e32 v1, v2, v211
	v_med3_f32 v2, v8, 0, v167
	s_waitcnt lgkmcnt(1)
	v_fmac_f32_e32 v0, v2, v212
	v_med3_f32 v2, v9, 0, v167
	v_fmac_f32_e32 v1, v2, v213
	v_med3_f32 v2, v10, 0, v167
	v_mfma_f32_32x32x16_bf16 v[224:239], v[124:127], v[200:203], v[224:239]
	v_fmac_f32_e32 v0, v2, v214
	v_med3_f32 v2, v11, 0, v167
	v_fmac_f32_e32 v1, v2, v215
	v_med3_f32 v2, v12, 0, v167
	s_waitcnt lgkmcnt(0)
	v_fmac_f32_e32 v0, v2, v216
	v_med3_f32 v2, v13, 0, v167
	v_fmac_f32_e32 v1, v2, v217
	v_mfma_f32_32x32x16_bf16 v[224:239], v[120:123], v[204:207], v[224:239]
	v_med3_f32 v2, v14, 0, v167
	v_fmac_f32_e32 v0, v2, v218
	v_med3_f32 v2, v15, 0, v167
	v_fmac_f32_e32 v1, v2, v219
	v_add_f32_e32 v2, v0, v1
	v_lshl_add_u64 v[0:1], v[158:159], 0, s[20:21]
	global_store_dword v[0:1], v2, off offset:384
	s_setprio 0
	ds_read_b128 v[158:161], v169 offset:384
	ds_read_b128 v[162:165], v169 offset:400
	ds_read_b128 v[176:179], v169 offset:416
	ds_read_b128 v[180:183], v169 offset:432
	s_nop 7
	v_med3_f32 v224, v224, 0, v167
	s_waitcnt lgkmcnt(3)
	v_fma_f32 v224, v224, v158, 0
	v_med3_f32 v225, v225, 0, v167
	v_med3_f32 v226, v226, 0, v167
	v_fma_f32 v225, v225, v159, 0
	v_fmac_f32_e32 v224, v226, v160
	v_med3_f32 v226, v227, 0, v167
	v_fmac_f32_e32 v225, v226, v161
	v_med3_f32 v226, v228, 0, v167
	s_waitcnt lgkmcnt(2)
	v_fmac_f32_e32 v224, v226, v162
	v_med3_f32 v226, v229, 0, v167
	v_fmac_f32_e32 v225, v226, v163
	v_med3_f32 v226, v230, 0, v167
	v_fmac_f32_e32 v224, v226, v164
	v_med3_f32 v226, v231, 0, v167
	v_fmac_f32_e32 v225, v226, v165
	v_med3_f32 v226, v232, 0, v167
	s_waitcnt lgkmcnt(1)
	v_fmac_f32_e32 v224, v226, v176
	v_med3_f32 v226, v233, 0, v167
	v_fmac_f32_e32 v225, v226, v177
	v_med3_f32 v226, v234, 0, v167
	v_fmac_f32_e32 v224, v226, v178
	v_med3_f32 v226, v235, 0, v167
	v_fmac_f32_e32 v225, v226, v179
	v_med3_f32 v226, v236, 0, v167
	s_waitcnt lgkmcnt(0)
	v_fmac_f32_e32 v224, v226, v180
	v_med3_f32 v226, v237, 0, v167
	v_fmac_f32_e32 v225, v226, v181
	v_med3_f32 v226, v238, 0, v167
	v_fmac_f32_e32 v224, v226, v182
	v_med3_f32 v226, v239, 0, v167
	v_fmac_f32_e32 v225, v226, v183
	v_add_f32_e32 v226, v224, v225
	v_lshl_add_u64 v[224:225], v[156:157], 0, s[20:21]
	global_store_dword v[224:225], v226, off offset:384
	s_and_b64 vcc, exec, s[16:17]
	s_cbranch_vccz .LBB0_1504
	s_branch .LBB0_1521

; #define LAS __attribute__((address_space(3)))
; #define IX_PF_LOAD(h_) do { if (more) { _Pragma("unroll") for (int it = 0; it < 2; ++it) { const int ci = tid + 512 * (2 * (h_) + it), row = ci >> 4, ch = ci & 15; st[it] = *(const v4u*)(KIB + (size_t)(128 * ns + row) * 128 + 8 * ch); } } } while (0)
; #define IX_PF_STORE(h_) do { if (more) { _Pragma("unroll") for (int it = 0; it < 2; ++it) { const int ci = tid + 512 * (2 * (h_) + it), row = ci >> 4, ch = ci & 15; *(LAS v4u*)(NBUF + row * 272 + 16 * ch) = st[it]; } } } while (0)
; #define IX_CHAIN(acc_, a_) do { _Pragma("unroll") for (int i_ = 0; i_ < 16; ++i_) acc_[i_] = 0.f; __builtin_amdgcn_s_setprio(1); _Pragma("unroll") for (int s_ = 0; s_ < 8; ++s_) acc_ = MFMA32(af[a_][s_], bfr[s_], acc_); __builtin_amdgcn_s_setprio(0); } while (0)
; DI void indexer_prompt(LAS unsigned char* lds, const bf16* QIB, const bf16* KIB, const float* WI, float* SC, int bid, int G, int tid_) {
;     ...
;         for (int bt = 0; bt < 4; ++bt) {
;             const int key0 = k0s + 32 * bt;
;             if (bt == 2) { IX_PF_STORE(0); IX_PF_LOAD(1); }
;             if (key0 <= qlast_w) {
;             bf16x8 bfr[8];
; #pragma unroll
;             for (int s_ = 0; s_ < 8; ++s_) bfr[s_] = *(const LAS bf16x8*)(SB + (32 * bt + m) * 272 + 32 * s_ + 16 * hh);
;             f32x16 accA;
;     ...
;             IX_CHAIN(accA, 0); IX_EPI(accA, 0);
;             IX_CHAIN(accA, 1); IX_EPI(accA, 1);
;             IX_CHAIN(accA, 2); IX_EPI(accA, 2);
;             IX_CHAIN(accA, 3); IX_EPI(accA, 3);
.LBB0_1519:
	ds_read_b128 v[176:179], v170 offset:21504
	ds_read_b128 v[180:183], v170 offset:21536
	ds_read_b128 v[184:187], v170 offset:21568
	ds_read_b128 v[188:191], v170 offset:21600
	ds_read_b128 v[192:195], v170 offset:21632
	ds_read_b128 v[196:199], v170 offset:21664
	ds_read_b128 v[200:203], v170 offset:21696
	ds_read_b128 v[204:207], v170 offset:21728
	s_setprio 1
	s_waitcnt lgkmcnt(7)
	v_mfma_f32_32x32x16_bf16 v[0:15], v[44:47], v[176:179], 0
	s_waitcnt lgkmcnt(6)
	v_mfma_f32_32x32x16_bf16 v[0:15], v[40:43], v[180:183], v[0:15]
	s_waitcnt lgkmcnt(5)
	v_mfma_f32_32x32x16_bf16 v[0:15], v[36:39], v[184:187], v[0:15]
	s_waitcnt lgkmcnt(4)
	v_mfma_f32_32x32x16_bf16 v[0:15], v[32:35], v[188:191], v[0:15]
	s_waitcnt lgkmcnt(3)
	v_mfma_f32_32x32x16_bf16 v[0:15], v[28:31], v[192:195], v[0:15]
	s_waitcnt lgkmcnt(2)
	v_mfma_f32_32x32x16_bf16 v[0:15], v[24:27], v[196:199], v[0:15]
	s_waitcnt lgkmcnt(1)
	v_mfma_f32_32x32x16_bf16 v[0:15], v[20:23], v[200:203], v[0:15]
	s_waitcnt lgkmcnt(0)
	v_mfma_f32_32x32x16_bf16 v[0:15], v[16:19], v[204:207], v[0:15]
	ds_read_b128 v[208:211], v169
	ds_read_b128 v[212:215], v169 offset:16
	ds_read_b128 v[216:219], v169 offset:32
	ds_read_b128 v[220:223], v169 offset:48
	v_mfma_f32_32x32x16_bf16 v[224:239], v[76:79], v[176:179], 0
	v_mfma_f32_32x32x16_bf16 v[224:239], v[72:75], v[180:183], v[224:239]
	v_mfma_f32_32x32x16_bf16 v[224:239], v[68:71], v[184:187], v[224:239]
	v_mfma_f32_32x32x16_bf16 v[224:239], v[64:67], v[188:191], v[224:239]
	s_nop 3
	v_med3_f32 v0, v0, 0, v167
	s_waitcnt lgkmcnt(3)
	v_fma_f32 v0, v0, v208, 0
	v_med3_f32 v1, v1, 0, v167
	v_med3_f32 v2, v2, 0, v167
	v_fma_f32 v1, v1, v209, 0
	v_fmac_f32_e32 v0, v2, v210
	v_med3_f32 v2, v3, 0, v167
	v_mfma_f32_32x32x16_bf16 v[224:239], v[60:63], v[192:195], v[224:239]
	v_fmac_f32_e32 v1, v2, v211
	v_med3_f32 v2, v4, 0, v167
	s_waitcnt lgkmcnt(2)
	v_fmac_f32_e32 v0, v2, v212
	v_med3_f32 v2, v5, 0, v167
	v_fmac_f32_e32 v1, v2, v213
	v_med3_f32 v2, v6, 0, v167
	v_fmac_f32_e32 v0, v2, v214
	v_mfma_f32_32x32x16_bf16 v[224:239], v[56:59], v[196:199], v[224:239]
	v_med3_f32 v2, v7, 0, v167
	v_fmac_f32_e32 v1, v2, v215
	v_med3_f32 v2, v8, 0, v167
	s_waitcnt lgkmcnt(1)
	v_fmac_f32_e32 v0, v2, v216
	v_med3_f32 v2, v9, 0, v167
	v_fmac_f32_e32 v1, v2, v217
	v_med3_f32 v2, v10, 0, v167
	v_mfma_f32_32x32x16_bf16 v[224:239], v[52:55], v[200:203], v[224:239]
	v_fmac_f32_e32 v0, v2, v218
	v_med3_f32 v2, v11, 0, v167
	v_fmac_f32_e32 v1, v2, v219
	v_med3_f32 v2, v12, 0, v167
	s_waitcnt lgkmcnt(0)
	v_fmac_f32_e32 v0, v2, v220
	v_med3_f32 v2, v13, 0, v167
	v_fmac_f32_e32 v1, v2, v221
	v_mfma_f32_32x32x16_bf16 v[224:239], v[48:51], v[204:207], v[224:239]
	v_med3_f32 v2, v14, 0, v167
	v_fmac_f32_e32 v0, v2, v222
	v_med3_f32 v2, v15, 0, v167
	s_ashr_i32 s21, s20, 31
	v_fmac_f32_e32 v1, v2, v223
	s_lshl_b64 s[22:23], s[20:21], 2
	v_add_f32_e32 v2, v0, v1
	v_lshl_add_u64 v[0:1], v[162:163], 0, s[22:23]
	global_store_dword v[0:1], v2, off offset:256
	ds_read_b128 v[208:211], v169 offset:128
	ds_read_b128 v[212:215], v169 offset:144
	ds_read_b128 v[216:219], v169 offset:160
	ds_read_b128 v[220:223], v169 offset:176
	v_mfma_f32_32x32x16_bf16 v[0:15], v[108:111], v[176:179], 0
	v_mfma_f32_32x32x16_bf16 v[0:15], v[104:107], v[180:183], v[0:15]
	v_mfma_f32_32x32x16_bf16 v[0:15], v[100:103], v[184:187], v[0:15]
	v_mfma_f32_32x32x16_bf16 v[0:15], v[96:99], v[188:191], v[0:15]
	s_nop 3
	v_med3_f32 v224, v224, 0, v167
	s_waitcnt lgkmcnt(3)
	v_fma_f32 v224, v224, v208, 0
	v_med3_f32 v225, v225, 0, v167
	v_med3_f32 v226, v226, 0, v167
	v_fma_f32 v225, v225, v209, 0
	v_fmac_f32_e32 v224, v226, v210
	v_med3_f32 v226, v227, 0, v167
	v_mfma_f32_32x32x16_bf16 v[0:15], v[92:95], v[192:195], v[0:15]
	v_fmac_f32_e32 v225, v226, v211
	v_med3_f32 v226, v228, 0, v167
	s_waitcnt lgkmcnt(2)
	v_fmac_f32_e32 v224, v226, v212
	v_med3_f32 v226, v229, 0, v167
	v_fmac_f32_e32 v225, v226, v213
	v_med3_f32 v226, v230, 0, v167
	v_fmac_f32_e32 v224, v226, v214
	v_mfma_f32_32x32x16_bf16 v[0:15], v[88:91], v[196:199], v[0:15]
	v_med3_f32 v226, v231, 0, v167
	v_fmac_f32_e32 v225, v226, v215
	v_med3_f32 v226, v232, 0, v167
	s_waitcnt lgkmcnt(1)
; #define LAS __attribute__((address_space(3)))
; #define IX_PF_LOAD(h_) do { if (more) { _Pragma("unroll") for (int it = 0; it < 2; ++it) { const int ci = tid + 512 * (2 * (h_) + it), row = ci >> 4, ch = ci & 15; st[it] = *(const v4u*)(KIB + (size_t)(128 * ns + row) * 128 + 8 * ch); } } } while (0)
; #define IX_PF_STORE(h_) do { if (more) { _Pragma("unroll") for (int it = 0; it < 2; ++it) { const int ci = tid + 512 * (2 * (h_) + it), row = ci >> 4, ch = ci & 15; *(LAS v4u*)(NBUF + row * 272 + 16 * ch) = st[it]; } } } while (0)
; #define IX_CHAIN(acc_, a_) do { _Pragma("unroll") for (int i_ = 0; i_ < 16; ++i_) acc_[i_] = 0.f; __builtin_amdgcn_s_setprio(1); _Pragma("unroll") for (int s_ = 0; s_ < 8; ++s_) acc_ = MFMA32(af[a_][s_], bfr[s_], acc_); __builtin_amdgcn_s_setprio(0); } while (0)
; DI void indexer_prompt(LAS unsigned char* lds, const bf16* QIB, const bf16* KIB, const float* WI, float* SC, int bid, int G, int tid_) {
;     ...
;         for (int bt = 0; bt < 4; ++bt) {
;             const int key0 = k0s + 32 * bt;
;             if (bt == 2) { IX_PF_STORE(0); IX_PF_LOAD(1); }
;             if (key0 <= qlast_w) {
;             bf16x8 bfr[8];
; #pragma unroll
;             for (int s_ = 0; s_ < 8; ++s_) bfr[s_] = *(const LAS bf16x8*)(SB + (32 * bt + m) * 272 + 32 * s_ + 16 * hh);
;             f32x16 accA;
;     ...
;             IX_CHAIN(accA, 0); IX_EPI(accA, 0);
;             IX_CHAIN(accA, 1); IX_EPI(accA, 1);
;             IX_CHAIN(accA, 2); IX_EPI(accA, 2);
;             IX_CHAIN(accA, 3); IX_EPI(accA, 3);
	v_fmac_f32_e32 v224, v226, v216
	v_med3_f32 v226, v233, 0, v167
	v_fmac_f32_e32 v225, v226, v217
	v_med3_f32 v226, v234, 0, v167
	v_mfma_f32_32x32x16_bf16 v[0:15], v[84:87], v[200:203], v[0:15]
	v_fmac_f32_e32 v224, v226, v218
	v_med3_f32 v226, v235, 0, v167
	v_fmac_f32_e32 v225, v226, v219
	v_med3_f32 v226, v236, 0, v167
	s_waitcnt lgkmcnt(0)
	v_fmac_f32_e32 v224, v226, v220
	v_med3_f32 v226, v237, 0, v167
	v_fmac_f32_e32 v225, v226, v221
	v_mfma_f32_32x32x16_bf16 v[0:15], v[80:83], v[204:207], v[0:15]
	v_med3_f32 v226, v238, 0, v167
	v_fmac_f32_e32 v224, v226, v222
	v_med3_f32 v226, v239, 0, v167
	v_fmac_f32_e32 v225, v226, v223
	v_add_f32_e32 v226, v224, v225
	v_lshl_add_u64 v[224:225], v[160:161], 0, s[22:23]
	global_store_dword v[224:225], v226, off offset:256
	ds_read_b128 v[208:211], v169 offset:256
	ds_read_b128 v[212:215], v169 offset:272
	ds_read_b128 v[216:219], v169 offset:288
	ds_read_b128 v[220:223], v169 offset:304
	v_mfma_f32_32x32x16_bf16 v[224:239], v[148:151], v[176:179], 0
	v_mfma_f32_32x32x16_bf16 v[224:239], v[144:147], v[180:183], v[224:239]
	v_mfma_f32_32x32x16_bf16 v[224:239], v[140:143], v[184:187], v[224:239]
	v_mfma_f32_32x32x16_bf16 v[224:239], v[136:139], v[188:191], v[224:239]
	s_nop 3
	v_med3_f32 v0, v0, 0, v167
	s_waitcnt lgkmcnt(3)
	v_fma_f32 v0, v0, v208, 0
	v_med3_f32 v1, v1, 0, v167
	v_med3_f32 v2, v2, 0, v167
	v_fma_f32 v1, v1, v209, 0
	v_fmac_f32_e32 v0, v2, v210
	v_med3_f32 v2, v3, 0, v167
	v_mfma_f32_32x32x16_bf16 v[224:239], v[132:135], v[192:195], v[224:239]
	v_fmac_f32_e32 v1, v2, v211
	v_med3_f32 v2, v4, 0, v167
	s_waitcnt lgkmcnt(2)
	v_fmac_f32_e32 v0, v2, v212
	v_med3_f32 v2, v5, 0, v167
	v_fmac_f32_e32 v1, v2, v213
	v_med3_f32 v2, v6, 0, v167
	v_fmac_f32_e32 v0, v2, v214
	v_mfma_f32_32x32x16_bf16 v[224:239], v[128:131], v[196:199], v[224:239]
	v_med3_f32 v2, v7, 0, v167
	v_fmac_f32_e32 v1, v2, v215
	v_med3_f32 v2, v8, 0, v167
	s_waitcnt lgkmcnt(1)
	v_fmac_f32_e32 v0, v2, v216
	v_med3_f32 v2, v9, 0, v167
	v_fmac_f32_e32 v1, v2, v217
	v_med3_f32 v2, v10, 0, v167
	v_mfma_f32_32x32x16_bf16 v[224:239], v[124:127], v[200:203], v[224:239]
	v_fmac_f32_e32 v0, v2, v218
	v_med3_f32 v2, v11, 0, v167
	v_fmac_f32_e32 v1, v2, v219
	v_med3_f32 v2, v12, 0, v167
	s_waitcnt lgkmcnt(0)
	v_fmac_f32_e32 v0, v2, v220
	v_med3_f32 v2, v13, 0, v167
	v_fmac_f32_e32 v1, v2, v221
	v_mfma_f32_32x32x16_bf16 v[224:239], v[120:123], v[204:207], v[224:239]
	v_med3_f32 v2, v14, 0, v167
	v_fmac_f32_e32 v0, v2, v222
	v_med3_f32 v2, v15, 0, v167
	v_fmac_f32_e32 v1, v2, v223
	v_add_f32_e32 v2, v0, v1
	v_lshl_add_u64 v[0:1], v[158:159], 0, s[22:23]
	global_store_dword v[0:1], v2, off offset:256
	s_setprio 0
	ds_read_b128 v[176:179], v169 offset:384
	ds_read_b128 v[180:183], v169 offset:400
	ds_read_b128 v[184:187], v169 offset:416
	ds_read_b128 v[188:191], v169 offset:432
	s_nop 7
	v_med3_f32 v224, v224, 0, v167
	s_waitcnt lgkmcnt(3)
	v_fma_f32 v224, v224, v176, 0
	v_med3_f32 v225, v225, 0, v167
	v_med3_f32 v226, v226, 0, v167
	v_fma_f32 v225, v225, v177, 0
	v_fmac_f32_e32 v224, v226, v178
	v_med3_f32 v226, v227, 0, v167
	v_fmac_f32_e32 v225, v226, v179
	v_med3_f32 v226, v228, 0, v167
	s_waitcnt lgkmcnt(2)
	v_fmac_f32_e32 v224, v226, v180
	v_med3_f32 v226, v229, 0, v167
	v_fmac_f32_e32 v225, v226, v181
	v_med3_f32 v226, v230, 0, v167
	v_fmac_f32_e32 v224, v226, v182
	v_med3_f32 v226, v231, 0, v167
	v_fmac_f32_e32 v225, v226, v183
	v_med3_f32 v226, v232, 0, v167
	s_waitcnt lgkmcnt(1)
	v_fmac_f32_e32 v224, v226, v184
	v_med3_f32 v226, v233, 0, v167
	v_fmac_f32_e32 v225, v226, v185
	v_med3_f32 v226, v234, 0, v167
	v_fmac_f32_e32 v224, v226, v186
	v_med3_f32 v226, v235, 0, v167
	v_fmac_f32_e32 v225, v226, v187
	v_med3_f32 v226, v236, 0, v167
	s_waitcnt lgkmcnt(0)
	v_fmac_f32_e32 v224, v226, v188
	v_med3_f32 v226, v237, 0, v167
	v_fmac_f32_e32 v225, v226, v189
	v_med3_f32 v226, v238, 0, v167
	v_fmac_f32_e32 v224, v226, v190
	v_med3_f32 v226, v239, 0, v167
	v_fmac_f32_e32 v225, v226, v191
	v_add_f32_e32 v226, v224, v225
	v_lshl_add_u64 v[224:225], v[156:157], 0, s[22:23]
	global_store_dword v[224:225], v226, off offset:256
	s_or_b32 s21, s20, 0x60
	s_cmp_gt_i32 s21, s12
	s_cbranch_scc0 .LBB0_1517

; #define LAS __attribute__((address_space(3)))
; #define IX_PF_STORE(h_) do { if (more) { _Pragma("unroll") for (int it = 0; it < 2; ++it) { const int ci = tid + 512 * (2 * (h_) + it), row = ci >> 4, ch = ci & 15; *(LAS v4u*)(NBUF + row * 272 + 16 * ch) = st[it]; } } } while (0)
; DI void indexer_prompt(LAS unsigned char* lds, const bf16* QIB, const bf16* KIB, const float* WI, float* SC, int bid, int G, int tid_) {
;     ...
;         IX_PF_STORE(1);
;     ...
;         if (more) {
;             if (nqb != qb) *(LAS f32x2*)(lds + (wsel ? IX_W : IX_W2) + 8 * tid) = wn;
;         }
.LBB0_1521:
	v_lshrrev_b32_e32 v0, 4, v173
	v_mad_u64_u32 v[0:1], s[16:17], v0, s34, v[152:153]
	s_cmp_eq_u32 s101, 1
	s_cbranch_scc1 .Lmy_p9w3
	s_waitcnt vmcnt(1)
.Lmy_p9w3:
	s_waitcnt vmcnt(9)
	ds_write_b128 v0, v[116:119] offset:4096
	v_lshrrev_b32_e32 v0, 4, v174
	v_mad_u64_u32 v[0:1], s[16:17], v0, s34, v[152:153]
	s_and_b64 vcc, exec, s[14:15]
	s_cmp_eq_u32 s101, 1
	s_cbranch_scc1 .Lmy_p9w4
	s_waitcnt vmcnt(0)
.Lmy_p9w4:
	s_waitcnt vmcnt(8)
	ds_write_b128 v0, v[112:115] offset:4096
	s_cbranch_vccz .LBB0_1504
	s_and_b64 s[16:17], s[18:19], exec
	s_cselect_b32 s12, 0x12000, 0
	s_add_i32 s12, s12, 0
	v_add_u32_e32 v0, s12, v168
	ds_write_b64 v0, v[154:155]
	s_branch .LBB0_1504

; #define LAS __attribute__((address_space(3)))
; DI void attn_unit_f8(LAS unsigned char* vbuf  , const LAS float* lut2  , const long (&qf)[4], const int* idx, int cnt_, int qpos_, int kvh, const unsigned char* K8, const bf16* VB, bf16* orow, int lane_) {
;     ...
;     const int cnt = __builtin_amdgcn_readfirstlane(cnt_), qpos = __builtin_amdgcn_readfirstlane(qpos_);
;     const int g = lane >> 4, lr = lane & 15;
;     const unsigned vb_addr = (unsigned)(size_t)vbuf;
;     const unsigned q_ = (unsigned)lr >> 2, p_ = (unsigned)lr & 3u;
;     const unsigned rb0 = vb_addr + 2048u * (unsigned)g + 64u * q_ + 8u * (p_ & 1u);
;     const unsigned x0 = (unsigned)(2 * g) & 3u, x1 = (unsigned)(2 * g + 1) & 3u;
;     const unsigned te = rb0 + 16u * ((p_ >> 1) ^ x0), teb = rb0 + 256u + 16u * ((p_ >> 1) ^ x1), to = rb0 + 16u * ((2u + (p_ >> 1)) ^ x0), tob = rb0 + 256u + 16u * ((2u + (p_ >> 1)) ^ x1);
;     const unsigned wb = 512u * ((unsigned)lr >> 2) + 64u * (unsigned)g;
;     const unsigned wx0 = wb + 16u * (((unsigned)lr & 3u) ^ 0u), wx1 = wb + 16u * (((unsigned)lr & 3u) ^ 1u), wx2 = wb + 16u * (((unsigned)lr & 3u) ^ 2u), wx3 = wb + 16u * (((unsigned)lr & 3u) ^ 3u);
; __global__ void __launch_bounds__(NTHR, 2) mk_fwd(Args args) {
;     ...
;             const int kvh = bid & 3, g = lane >> 4, lr = lane & 15, nslots = (G >> 2) * NWAVES;
;             const unsigned char* K8 = (const unsigned char*)(AP->ws + WS_K8);
;             if (tid == 0) ((volatile LAS int*)(lds + MISC_OFF))[12] = 0;
;             __syncthreads();
;             constexpr int NATT = 128, NLATE = 26;
.LBB0_5530:
	s_or_b64 exec, exec, s[4:5]
	s_mov_b32 s41, 0
	v_cmp_eq_u32_e32 vcc, 0, v79
	s_waitcnt lgkmcnt(0)
	s_barrier
	s_and_saveexec_b64 s[4:5], vcc
	s_add_i32 s3, 0, 0x228b0
	v_mov_b32_e32 v0, 0
	v_mov_b32_e32 v1, s3
	ds_write_b32 v1, v0
	s_or_b64 exec, exec, s[4:5]
	s_lshl_b32 s3, s28, 1
	s_and_b32 s8, s2, 3
	s_and_b32 s3, s3, -8
	s_add_u32 s44, s38, 0x4fc00000
	s_addc_u32 s45, s39, 0
	s_lshl_b32 s6, s2, 1
	s_and_b32 s29, s6, -8
	s_add_i32 s30, s97, 0
	s_add_u32 s31, s38, 0x4c000000
	s_addc_u32 s34, s39, 0
	v_lshlrev_b32_e32 v0, 8, v92
	s_add_u32 s46, s38, 0x3b400000
	v_ashrrev_i32_e32 v95, 4, v92
	v_and_b32_e32 v0, 0x300, v0
	s_addc_u32 s47, s39, 0
	s_lshl_b32 s9, s8, 4
	v_lshl_or_b32 v72, s8, 10, v0
	v_mov_b32_e32 v73, 0
	v_lshlrev_b32_e32 v74, 5, v95
	s_add_i32 s55, s9, 0
	v_lshl_add_u64 v[0:1], s[38:39], 0, v[72:73]
	v_ashrrev_i32_e32 v75, 31, v74
	s_lshl_b32 s35, s8, 20
	s_lshl_b32 s54, s8, 2
	s_add_i32 s55, s55, 0x20800
	s_lshl_b32 s56, s8, 8
	v_lshl_add_u64 v[0:1], v[74:75], 1, v[0:1]
	s_mov_b64 s[6:7], 0x35600000
	s_add_u32 s57, s38, 0x4c800000
	v_lshl_add_u64 v[76:77], v[0:1], 0, s[6:7]
	s_addc_u32 s58, s39, 0
	v_lshlrev_b32_e32 v0, 2, v92
	s_add_u32 s48, s38, 0xb600000
	v_and_b32_e32 v78, 60, v0
	v_lshlrev_b32_e32 v0, 3, v92
	s_addc_u32 s49, s39, 0
	v_and_b32_e32 v0, 56, v0
	s_add_u32 s50, s38, 0x8a00000
	v_mul_u32_u24_e32 v3, 0x104, v0
	v_lshlrev_b32_e32 v80, 1, v0
	v_mbcnt_lo_u32_b32 v0, -1, 0
	v_and_b32_e32 v2, 12, v92
	s_addc_u32 s51, s39, 0
	s_movk_i32 s8, 0x104
	v_ashrrev_i32_e32 v96, 3, v92
	v_mbcnt_hi_u32_b32 v93, -1, v0
	v_cmp_eq_u32_e64 s[6:7], 0, v2
	s_add_u32 s42, s38, 0x8200000
	v_lshl_add_u32 v1, v78, 2, s30
	v_mul_lo_u32 v2, v95, s8
	v_lshlrev_b32_e32 v4, 2, v96
	v_and_b32_e32 v101, 64, v93
	v_cmp_eq_u32_e64 s[4:5], 0, v92
	s_addc_u32 s43, s39, 0
	v_add3_u32 v97, s30, v3, v4
	s_add_i32 s59, 0, 0x228b0
	v_mov_b32_e32 v98, 0x358637bd
	s_mov_b32 s60, 0x800000
	s_movk_i32 s61, 0x80
	s_mov_b32 s62, 0xff61b1e6
	v_add_u32_e32 v99, v1, v2
	v_xor_b32_e32 v100, 16, v93
	v_add_u32_e32 v94, 64, v101
	v_xor_b32_e32 v102, 32, v93
	v_mov_b32_e32 v103, 0xff61b1e6
	s_waitcnt lgkmcnt(0)
	s_barrier
	s_branch .LBB0_5537

; DI float bf2f(unsigned b) { return __uint_as_float(b << 16); }
; DI unsigned pk4_fp8(float a, float b, float c, float d) { int p = __builtin_amdgcn_cvt_pk_fp8_f32(a, b, 0, false); p = __builtin_amdgcn_cvt_pk_fp8_f32(c, d, p, true); return (unsigned)p; }
; #define A8_ISSUE_K(kt) do { const char* kr_ = (const char*)K8 + (unsigned)(R[kt] * 512 + kvh * 128 + 32 * g); ring[(2 * (kt)) & 15] = *(const v4u*)kr_; ring[(2 * (kt) + 1) & 15] = *(const v4u*)(kr_ + 16); } while (0)
; DI void attn_unit_f8(LAS unsigned char* vbuf  , const LAS float* lut2  , const long (&qf)[4], const int* idx, int cnt_, int qpos_, int kvh, const unsigned char* K8, const bf16* VB, bf16* orow, int lane_) {
;     ...
;     for (int kt = 0; kt < 16; ++kt) R[kt] = idx[16 * kt + lr];
;     ...
; #pragma unroll
;     for (int i = 0; i < 8; ++i) A8_ISSUE_K(i);
; __global__ void __launch_bounds__(NTHR, 2) mk_fwd(Args args) {
;     ...
;                 for (int s = 0; s < 4; ++s) { const v4u w = *(const v4u*)(qr + 32 * g + 8 * s);
;                     qv[s][0] = bf2f(w.x & 0xffffu); qv[s][1] = bf2f(w.x >> 16); qv[s][2] = bf2f(w.y & 0xffffu); qv[s][3] = bf2f(w.y >> 16);
;                     qv[s][4] = bf2f(w.z & 0xffffu); qv[s][5] = bf2f(w.z >> 16); qv[s][6] = bf2f(w.w & 0xffffu); qv[s][7] = bf2f(w.w >> 16);
; #pragma unroll
;                     for (int e = 0; e < 8; ++e) ss += qv[s][e] * qv[s][e]; }
;                 ss += __shfl_xor(ss, 16); ss += __shfl_xor(ss, 32);
;                 const float rs = (lr < 4) ? rsqrtf(ss * (1.f / 128.f) + EPS) : 0.f;
;                 long qf[4];
; #pragma unroll
;                 for (int s = 0; s < 4; ++s) { const f32x4 g0 = *(const f32x4*)(b_q_norm + 32 * g + 8 * s), g1 = *(const f32x4*)(b_q_norm + 32 * g + 8 * s + 4);
;                     const unsigned lo = pk4_fp8(qv[s][0] * rs * g0[0], qv[s][1] * rs * g0[1], qv[s][2] * rs * g0[2], qv[s][3] * rs * g0[3]);
;                     const unsigned hi = pk4_fp8(qv[s][4] * rs * g1[0], qv[s][5] * rs * g1[1], qv[s][6] * rs * g1[2], qv[s][7] * rs * g1[3]);
;                     qf[s] = (long)(((unsigned long long)hi << 32) | lo); }
;                 const int cnt = t + 1 < TOPK ? t + 1 : TOPK;
.LBB0_5547:
	s_or_b64 exec, exec, s[8:9]
	s_load_dwordx2 s[8:9], s[22:23], 0x78
	v_mul_f32_e32 v62, v8, v30
	v_mul_f32_e32 v63, v8, v31
	v_mul_f32_e32 v64, v8, v32
	s_min_i32 s63, s52, 0xff
	s_waitcnt lgkmcnt(0)
	v_lshl_add_u64 v[58:59], v[74:75], 2, s[8:9]
	global_load_dwordx4 v[34:37], v[58:59], off
	global_load_dwordx4 v[38:41], v[58:59], off offset:16
	global_load_dwordx4 v[42:45], v[58:59], off offset:32
	global_load_dwordx4 v[46:49], v[58:59], off offset:48
	global_load_dwordx4 v[50:53], v[58:59], off offset:64
	global_load_dwordx4 v[54:57], v[58:59], off offset:80
	global_load_dwordx4 v[30:33], v[58:59], off offset:112
	s_nop 0
	global_load_dwordx4 v[58:61], v[58:59], off offset:96
	s_lshl_b64 s[8:9], s[52:53], 10
	v_mov_b32_e32 v65, v92
	s_add_u32 s8, s31, s8
	s_addc_u32 s9, s34, s9
	v_and_b32_e32 v83, 15, v65
	v_lshlrev_b32_e32 v66, 2, v83
	global_load_dword v147, v66, s[8:9]
	global_load_dword v142, v66, s[8:9] offset:64
	global_load_dword v132, v66, s[8:9] offset:128
	global_load_dword v125, v66, s[8:9] offset:192
	global_load_dword v122, v66, s[8:9] offset:256
	global_load_dword v121, v66, s[8:9] offset:320
	global_load_dword v120, v66, s[8:9] offset:384
	global_load_dword v118, v66, s[8:9] offset:448
	v_mul_f32_e32 v17, v8, v17
	v_mul_f32_e32 v18, v8, v18
	v_mul_f32_e32 v13, v8, v13
	v_mul_f32_e32 v14, v8, v14
	v_mul_f32_e32 v7, v8, v7
	v_mul_f32_e32 v6, v8, v6
	v_mov_b32_e32 v87, v73
	v_mov_b32_e32 v88, v73
	v_mov_b32_e32 v90, v73
	v_mul_f32_e32 v5, v8, v5
	v_mul_f32_e32 v3, v8, v3
	v_mul_f32_e32 v2, v8, v2
	v_ashrrev_i32_e32 v148, 4, v65
	v_mul_f32_e32 v19, v8, v19
	v_mul_f32_e32 v20, v8, v20
	v_mul_f32_e32 v15, v8, v15
	v_mul_f32_e32 v16, v8, v16
	v_mul_f32_e32 v4, v8, v4
	v_mov_b32_e32 v91, v73
	v_mul_f32_e32 v1, v8, v1
	v_mul_f32_e32 v0, v8, v0
	v_mul_f32_e32 v25, v8, v25
	v_mul_f32_e32 v26, v8, v26
	v_mul_f32_e32 v21, v8, v21
	v_mul_f32_e32 v22, v8, v22
	v_mul_f32_e32 v9, v8, v9
	v_mul_f32_e32 v10, v8, v10
	v_mul_f32_e32 v29, v8, v29
	v_mul_f32_e32 v27, v8, v27
	v_mul_f32_e32 v28, v8, v28
	v_mov_b32_e32 v85, v73
	v_mul_f32_e32 v23, v8, v23
	v_mul_f32_e32 v24, v8, v24
	v_mov_b32_e32 v86, v73
	v_mul_f32_e32 v11, v8, v11
	v_mul_f32_e32 v12, v8, v12
	v_mov_b32_e32 v89, v73
	v_bfe_u32 v8, v65, 1, 1
	v_lshlrev_b32_e32 v82, 2, v148
	v_mov_b32_e32 v84, v73
	v_cmp_ge_i32_e32 vcc, s63, v82
	v_cmp_gt_i32_e64 s[10:11], s63, v82
	v_or_b32_e32 v141, 2, v82
	v_cmp_ge_i32_e64 s[14:15], s63, v141
	v_or_b32_e32 v139, 3, v82
	v_cmp_ge_i32_e64 s[18:19], s63, v139
	v_or_b32_e32 v140, 1, v82
	v_lshl_or_b32 v111, v83, 4, s56
	s_waitcnt vmcnt(15)
	v_mul_f32_e32 v29, v34, v29
	s_waitcnt vmcnt(14)
	v_mul_f32_e32 v25, v38, v25
	v_mul_f32_e32 v26, v39, v26
	s_waitcnt vmcnt(12)
	v_mul_f32_e32 v17, v46, v17
	v_mul_f32_e32 v18, v47, v18
	s_waitcnt vmcnt(11)
	v_mul_f32_e32 v13, v50, v13
	v_mul_f32_e32 v14, v51, v14
	s_waitcnt vmcnt(8)
	v_mul_f32_e32 v7, v58, v7
	v_mul_f32_e32 v6, v59, v6
	v_cvt_pk_fp8_f32 v87, v17, v18
	v_cvt_pk_fp8_f32 v88, v13, v14
	v_cvt_pk_fp8_f32 v90, v7, v6
	v_mul_f32_e32 v5, v60, v5
	v_mul_f32_e32 v3, v30, v3
	v_mul_f32_e32 v2, v31, v2
	v_lshl_add_u32 v60, v148, 5, s35
	v_mul_f32_e32 v19, v48, v19
	v_mul_f32_e32 v20, v49, v20
	v_mul_f32_e32 v15, v52, v15
	v_mul_f32_e32 v16, v53, v16
	v_mul_f32_e32 v4, v61, v4
	v_cvt_pk_fp8_f32 v91, v3, v2
	s_waitcnt vmcnt(7)
	v_lshl_add_u32 v2, v147, 7, v60
	v_cvt_pk_fp8_f32 v87, v19, v20 op_sel:[0,0,1]
	v_cvt_pk_fp8_f32 v88, v15, v16 op_sel:[0,0,1]
	v_cvt_pk_fp8_f32 v90, v5, v4 op_sel:[0,0,1]
	global_load_dwordx4 v[4:7], v2, s[44:45] offset:16
	global_load_dwordx4 v[16:19], v2, s[44:45]
	v_mul_f32_e32 v1, v32, v1
	v_mul_f32_e32 v0, v33, v0
	v_cvt_pk_fp8_f32 v91, v1, v0 op_sel:[0,0,1]
	v_lshl_add_u32 v1, v148, 11, s30
	v_lshlrev_b32_e32 v2, 3, v65
	v_and_or_b32 v1, v2, 8, v1
	v_lshlrev_b32_e32 v2, 1, v148
	v_mul_f32_e32 v21, v42, v21
	v_mul_f32_e32 v22, v43, v22
	v_mul_f32_e32 v9, v54, v9
	v_mul_f32_e32 v10, v55, v10
	v_bfe_u32 v0, v65, 2, 2
	v_and_b32_e32 v3, 2, v2
	v_cvt_pk_fp8_f32 v85, v25, v26
	v_cvt_pk_fp8_f32 v86, v21, v22
	v_cvt_pk_fp8_f32 v89, v9, v10
	v_lshl_add_u32 v1, v0, 6, v1
	v_or_b32_e32 v9, v3, v8
	v_lshl_add_u32 v104, v9, 4, v1
	v_or_b32_e32 v9, 2, v8
	global_load_dword v119, v66, s[8:9] offset:512
	global_load_dword v117, v66, s[8:9] offset:576
	global_load_dword v116, v66, s[8:9] offset:640
	global_load_dword v115, v66, s[8:9] offset:704
	global_load_dword v114, v66, s[8:9] offset:768
	global_load_dword v113, v66, s[8:9] offset:832
	global_load_dword v112, v66, s[8:9] offset:896
	global_load_dword v110, v66, s[8:9] offset:960
	v_mul_f32_e32 v34, v35, v62
	v_bitop3_b32 v126, v3, v8, 1 bitop3:0x36
	v_bitop3_b32 v62, v3, v9, 1 bitop3:0x36
	v_lshlrev_b32_e32 v3, 6, v148
	v_mul_f32_e32 v27, v40, v27
	v_mul_f32_e32 v28, v41, v28
	v_mul_f32_e32 v23, v44, v23
	v_mul_f32_e32 v24, v45, v24
	v_mul_f32_e32 v11, v56, v11
	v_mul_f32_e32 v12, v57, v12
	v_lshl_add_u32 v123, v0, 9, v3
	s_waitcnt vmcnt(16)
	v_lshl_add_u32 v0, v142, 7, v60
	v_cvt_pk_fp8_f32 v85, v27, v28 op_sel:[0,0,1]
	v_cvt_pk_fp8_f32 v86, v23, v24 op_sel:[0,0,1]
	v_cvt_pk_fp8_f32 v89, v11, v12 op_sel:[0,0,1]
	v_bitop3_b32 v2, v8, v2, 2 bitop3:0x72
	global_load_dwordx4 v[8:11], v0, s[44:45] offset:16
	global_load_dwordx4 v[24:27], v0, s[44:45]
	s_waitcnt vmcnt(17)
	v_lshl_add_u32 v0, v132, 7, v60
	global_load_dwordx4 v[56:59], v0, s[44:45] offset:16
	global_load_dwordx4 v[150:153], v0, s[44:45]
	v_and_b32_e32 v61, 3, v65
	v_lshlrev_b32_e32 v124, 4, v61
	v_lshl_add_u32 v133, v61, 2, s55
	v_and_or_b32 v61, v82, 60, v101
	v_add_u32_e32 v127, 0x100, v1
	v_lshlrev_b32_e32 v138, 2, v61
	v_cvt_pk_fp8_f32 v84, v29, v34
	v_lshl_add_u32 v106, v62, 4, v127
	ds_bpermute_b32 v62, v138, v147 offset:4
	v_mul_f32_e32 v35, v36, v63
	ds_bpermute_b32 v63, v138, v147 offset:8
	v_mul_f32_e32 v36, v37, v64
	v_cvt_pk_fp8_f32 v84, v35, v36 op_sel:[0,0,1]
	s_waitcnt lgkmcnt(1)
; #define A8_ISSUE_K(kt) do { const char* kr_ = (const char*)K8 + (unsigned)(R[kt] * 512 + kvh * 128 + 32 * g); ring[(2 * (kt)) & 15] = *(const v4u*)kr_; ring[(2 * (kt) + 1) & 15] = *(const v4u*)(kr_ + 16); } while (0)
; #define A8_ISSUE_V(hc) do { _Pragma("unroll") for (int q2_ = 0; q2_ < 4; ++q2_) { const int rid_ = __shfl(R[hc], 4 * q2_ + g); \
;         ring[(4 * (hc) + q2_) & 15] = *(const v4u*)((const char*)VB + (unsigned)(rid_ * 1024 + kvh * 256 + 16 * lr)); } } while (0)
; DI void attn_unit_f8(LAS unsigned char* vbuf  , const LAS float* lut2  , const long (&qf)[4], const int* idx, int cnt_, int qpos_, int kvh, const unsigned char* K8, const bf16* VB, bf16* orow, int lane_) {
;     ...
;     for (int i = 0; i < 16; ++i) {
;         asm volatile("" ::: "memory");
;         {
;             int kp4[4];
; #pragma unroll
;             for (int e = 0; e < 4; ++e) kp4[e] = __shfl(R[i], 4 * g + e);
;             f32x4 acc = (f32x4){0.f, 0.f, 0.f, 0.f};
; #pragma unroll
;             for (int s = 0; s < 4; ++s) { const v4u w = ring[(2 * i + (s >> 1)) & 15]; const unsigned long long ka = (s & 1) ? ((unsigned long long)w.w << 32 | w.z) : ((unsigned long long)w.y << 32 | w.x);
;                 acc = __builtin_amdgcn_mfma_f32_16x16x32_fp8_fp8((long)ka, qf[s], acc, 0, 0, 0); }
;             float bs[4]; bool okv[4];
; #pragma unroll
;             for (int e = 0; e < 4; ++e) { const int rel = qpos - kp4[e]; okv[e] = (4 * g + e < cnt - 16 * i) && rel >= 0; const int rc = rel > 128 ? 128 : (rel < 0 ? 0 : rel); bs[e] = lut2[rc * 16 + hcol]; }
;             asm volatile("" : "+v"(bs[0]), "+v"(bs[1]), "+v"(bs[2]), "+v"(bs[3]));
; #pragma unroll
;             for (int e = 0; e < 4; ++e) acc[e] = okv[e] ? acc[e] * (0.08838834764831845f * 1.4426950408889634f) + bs[e] : -3.0e38f;
;             lg[i] = acc;
;         }
;         if (i + 8 < 16) A8_ISSUE_K(i + 8);
;         else if ((i & 1) == 1) A8_ISSUE_V((i - 9) / 2);
	v_sub_u32_e32 v62, s52, v62
	v_cmp_lt_i32_e64 s[12:13], -1, v62
	v_med3_i32 v62, v62, 0, s61
	v_lshl_add_u32 v67, v62, 6, v133
	s_waitcnt lgkmcnt(0)
	v_sub_u32_e32 v62, s52, v63
	s_waitcnt vmcnt(18)
	v_lshl_add_u32 v0, v125, 7, v60
	v_cmp_lt_i32_e64 s[16:17], -1, v62
	v_med3_i32 v68, v62, 0, s61
	global_load_dwordx4 v[20:23], v0, s[44:45] offset:16
	global_load_dwordx4 v[28:31], v0, s[44:45]
	ds_bpermute_b32 v61, v138, v147
	s_waitcnt vmcnt(14)
	v_mfma_f32_16x16x32_fp8_fp8 v[62:65], v[16:17], v[84:85], 0
	ds_bpermute_b32 v66, v138, v147 offset:12
	v_lshl_add_u32 v0, v122, 7, v60
	global_load_dwordx4 v[32:35], v0, s[44:45] offset:16
	global_load_dwordx4 v[40:43], v0, s[44:45]
	v_mfma_f32_16x16x32_fp8_fp8 v[16:19], v[18:19], v[86:87], v[62:65]
	v_lshl_add_u32 v0, v121, 7, v60
	s_waitcnt lgkmcnt(1)
	v_sub_u32_e32 v61, s52, v61
	s_waitcnt lgkmcnt(0)
	v_sub_u32_e32 v66, s52, v66
	global_load_dwordx4 v[36:39], v0, s[44:45] offset:16
	global_load_dwordx4 v[44:47], v0, s[44:45]
	v_lshl_add_u32 v0, v120, 7, v60
	v_lshl_add_u32 v12, v118, 7, v60
	v_cmp_lt_i32_e64 s[8:9], -1, v61
	v_med3_i32 v61, v61, 0, s61
	v_med3_i32 v62, v66, 0, s61
	v_mfma_f32_16x16x32_fp8_fp8 v[16:19], v[4:5], v[88:89], v[16:19]
	v_lshl_add_u32 v105, v2, 4, v1
	global_load_dwordx4 v[48:51], v0, s[44:45] offset:16
	global_load_dwordx4 v[52:55], v0, s[44:45]
	s_nop 0
	global_load_dwordx4 v[0:3], v12, s[44:45] offset:16
	s_nop 0
	global_load_dwordx4 v[12:15], v12, s[44:45]
	v_lshl_add_u32 v61, v61, 6, v133
	v_lshl_add_u32 v62, v62, 6, v133
	v_lshl_add_u32 v68, v68, 6, v133
	ds_read_b32 v62, v62
	ds_read_b32 v63, v68
	ds_read_b32 v64, v67
	ds_read_b32 v61, v61
	v_mfma_f32_16x16x32_fp8_fp8 v[4:7], v[6:7], v[90:91], v[16:19]
	s_waitcnt lgkmcnt(0)
	s_and_b64 vcc, vcc, s[8:9]
	s_nop 5
	v_fmac_f32_e32 v61, 0x3e0293ee, v4
	v_cndmask_b32_e32 v128, v103, v61, vcc
	v_fmac_f32_e32 v64, 0x3e0293ee, v5
	s_and_b64 vcc, s[10:11], s[12:13]
	s_waitcnt vmcnt(21)
	v_lshl_add_u32 v16, v119, 7, v60
	v_cmp_lt_i32_e64 s[20:21], -1, v66
	v_cndmask_b32_e32 v129, v103, v64, vcc
	v_fmac_f32_e32 v63, 0x3e0293ee, v6
	v_fmac_f32_e32 v62, 0x3e0293ee, v7
	global_load_dwordx4 v[4:7], v16, s[44:45] offset:16
	global_load_dwordx4 v[64:67], v16, s[44:45]
	ds_bpermute_b32 v16, v138, v142
	ds_bpermute_b32 v17, v138, v142 offset:4
	ds_bpermute_b32 v18, v138, v142 offset:8
	s_and_b64 vcc, s[14:15], s[16:17]
	v_cndmask_b32_e32 v130, v103, v63, vcc
	s_waitcnt lgkmcnt(2)
	v_sub_u32_e32 v16, s52, v16
	s_and_b64 vcc, s[18:19], s[20:21]
	v_cmp_lt_i32_e64 s[8:9], -1, v16
	v_med3_i32 v16, v16, 0, s61
	v_cndmask_b32_e32 v131, v103, v62, vcc
	v_lshl_add_u32 v62, v16, 6, v133
	s_waitcnt lgkmcnt(1)
	v_sub_u32_e32 v16, s52, v17
	v_cmp_lt_i32_e64 s[12:13], -1, v16
	v_med3_i32 v16, v16, 0, s61
	v_lshl_add_u32 v63, v16, 6, v133
	s_waitcnt lgkmcnt(0)
	v_sub_u32_e32 v68, s52, v18
	s_waitcnt vmcnt(14)
	v_mfma_f32_16x16x32_fp8_fp8 v[16:19], v[24:25], v[84:85], 0
	ds_bpermute_b32 v61, v138, v142 offset:12
	v_med3_i32 v24, v68, 0, s61
	v_mfma_f32_16x16x32_fp8_fp8 v[16:19], v[26:27], v[86:87], v[16:19]
	v_lshl_add_u32 v24, v24, 6, v133
	s_waitcnt lgkmcnt(0)
	v_sub_u32_e32 v25, s52, v61
	v_med3_i32 v26, v25, 0, s61
	v_mfma_f32_16x16x32_fp8_fp8 v[16:19], v[8:9], v[88:89], v[16:19]
	v_lshl_add_u32 v26, v26, 6, v133
	ds_read_b32 v26, v26
	ds_read_b32 v24, v24
	ds_read_b32 v27, v63
	ds_read_b32 v61, v62
	s_waitcnt lgkmcnt(0)
	v_mfma_f32_16x16x32_fp8_fp8 v[8:11], v[10:11], v[90:91], v[16:19]
	v_cmp_lt_i32_e64 s[16:17], -1, v68
	s_add_i32 s18, s63, -15
	v_cmp_gt_i32_e32 vcc, s18, v82
	v_lshl_add_u32 v16, v117, 7, v60
	ds_bpermute_b32 v17, v138, v132 offset:4
	s_nop 2
	v_fmac_f32_e32 v61, 0x3e0293ee, v8
	v_fmac_f32_e32 v27, 0x3e0293ee, v9
	v_fmac_f32_e32 v24, 0x3e0293ee, v10
	v_fmac_f32_e32 v26, 0x3e0293ee, v11
	global_load_dwordx4 v[8:11], v16, s[44:45] offset:16
	global_load_dwordx4 v[68:71], v16, s[44:45]
	ds_bpermute_b32 v16, v138, v132
	ds_bpermute_b32 v18, v138, v132 offset:8
	v_cmp_gt_i32_e64 s[10:11], s18, v140
	s_and_b64 vcc, vcc, s[8:9]
	v_cmp_gt_i32_e64 s[14:15], s18, v141
	s_waitcnt lgkmcnt(1)
	v_sub_u32_e32 v16, s52, v16
	v_cndmask_b32_e32 v134, v103, v61, vcc
	s_and_b64 vcc, s[10:11], s[12:13]
	v_cmp_lt_i32_e64 s[8:9], -1, v16
	v_med3_i32 v16, v16, 0, s61
	v_cmp_gt_i32_e64 s[18:19], s18, v139
	v_cmp_lt_i32_e64 s[20:21], -1, v25
	v_cndmask_b32_e32 v135, v103, v27, vcc
	s_and_b64 vcc, s[14:15], s[16:17]
	v_lshl_add_u32 v25, v16, 6, v133
	v_sub_u32_e32 v16, s52, v17
	v_cndmask_b32_e32 v136, v103, v24, vcc
	s_and_b64 vcc, s[18:19], s[20:21]
	v_cmp_lt_i32_e64 s[12:13], -1, v16
	v_med3_i32 v16, v16, 0, s61
	v_cndmask_b32_e32 v137, v103, v26, vcc
	v_lshl_add_u32 v26, v16, 6, v133
	s_waitcnt lgkmcnt(0)
	v_sub_u32_e32 v27, s52, v18
	s_waitcnt vmcnt(14)
	v_mfma_f32_16x16x32_fp8_fp8 v[16:19], v[150:151], v[84:85], 0
	ds_bpermute_b32 v24, v138, v132 offset:12
	v_cmp_lt_i32_e64 s[16:17], -1, v27
	v_med3_i32 v27, v27, 0, s61
	v_mfma_f32_16x16x32_fp8_fp8 v[16:19], v[152:153], v[86:87], v[16:19]
	s_waitcnt lgkmcnt(0)
	v_sub_u32_e32 v24, s52, v24
	v_med3_i32 v61, v24, 0, s61
	v_mfma_f32_16x16x32_fp8_fp8 v[16:19], v[56:57], v[88:89], v[16:19]
	v_lshl_add_u32 v27, v27, 6, v133
	v_lshl_add_u32 v61, v61, 6, v133
	ds_read_b32 v56, v61
	ds_read_b32 v27, v27
	ds_read_b32 v26, v26
	ds_read_b32 v25, v25
	v_mfma_f32_16x16x32_fp8_fp8 v[16:19], v[58:59], v[90:91], v[16:19]
	s_sub_i32 s18, s63, 31
	v_cmp_gt_i32_e32 vcc, s18, v82
	s_waitcnt lgkmcnt(0)
; #define A8_ISSUE_K(kt) do { const char* kr_ = (const char*)K8 + (unsigned)(R[kt] * 512 + kvh * 128 + 32 * g); ring[(2 * (kt)) & 15] = *(const v4u*)kr_; ring[(2 * (kt) + 1) & 15] = *(const v4u*)(kr_ + 16); } while (0)
; #define A8_ISSUE_V(hc) do { _Pragma("unroll") for (int q2_ = 0; q2_ < 4; ++q2_) { const int rid_ = __shfl(R[hc], 4 * q2_ + g); \
;         ring[(4 * (hc) + q2_) & 15] = *(const v4u*)((const char*)VB + (unsigned)(rid_ * 1024 + kvh * 256 + 16 * lr)); } } while (0)
; DI void attn_unit_f8(LAS unsigned char* vbuf  , const LAS float* lut2  , const long (&qf)[4], const int* idx, int cnt_, int qpos_, int kvh, const unsigned char* K8, const bf16* VB, bf16* orow, int lane_) {
;     ...
;     for (int i = 0; i < 16; ++i) {
;         asm volatile("" ::: "memory");
;         {
;             int kp4[4];
; #pragma unroll
;             for (int e = 0; e < 4; ++e) kp4[e] = __shfl(R[i], 4 * g + e);
;             f32x4 acc = (f32x4){0.f, 0.f, 0.f, 0.f};
; #pragma unroll
;             for (int s = 0; s < 4; ++s) { const v4u w = ring[(2 * i + (s >> 1)) & 15]; const unsigned long long ka = (s & 1) ? ((unsigned long long)w.w << 32 | w.z) : ((unsigned long long)w.y << 32 | w.x);
;                 acc = __builtin_amdgcn_mfma_f32_16x16x32_fp8_fp8((long)ka, qf[s], acc, 0, 0, 0); }
;             float bs[4]; bool okv[4];
; #pragma unroll
;             for (int e = 0; e < 4; ++e) { const int rel = qpos - kp4[e]; okv[e] = (4 * g + e < cnt - 16 * i) && rel >= 0; const int rc = rel > 128 ? 128 : (rel < 0 ? 0 : rel); bs[e] = lut2[rc * 16 + hcol]; }
;             asm volatile("" : "+v"(bs[0]), "+v"(bs[1]), "+v"(bs[2]), "+v"(bs[3]));
; #pragma unroll
;             for (int e = 0; e < 4; ++e) acc[e] = okv[e] ? acc[e] * (0.08838834764831845f * 1.4426950408889634f) + bs[e] : -3.0e38f;
;             lg[i] = acc;
;         }
;         if (i + 8 < 16) A8_ISSUE_K(i + 8);
;         else if ((i & 1) == 1) A8_ISSUE_V((i - 9) / 2);
	v_cmp_gt_i32_e64 s[10:11], s18, v140
	s_nop 3
	v_fmac_f32_e32 v25, 0x3e0293ee, v16
	s_and_b64 vcc, vcc, s[8:9]
	v_cmp_gt_i32_e64 s[14:15], s18, v141
	v_cndmask_b32_e32 v143, v103, v25, vcc
	v_fmac_f32_e32 v26, 0x3e0293ee, v17
	s_and_b64 vcc, s[10:11], s[12:13]
	v_cmp_gt_i32_e64 s[18:19], s18, v139
	v_cmp_lt_i32_e64 s[20:21], -1, v24
	v_cndmask_b32_e32 v144, v103, v26, vcc
	v_fmac_f32_e32 v27, 0x3e0293ee, v18
	s_and_b64 vcc, s[14:15], s[16:17]
	v_cndmask_b32_e32 v145, v103, v27, vcc
	v_fmac_f32_e32 v56, 0x3e0293ee, v19
	s_and_b64 vcc, s[18:19], s[20:21]
	v_cndmask_b32_e32 v146, v103, v56, vcc
	ds_bpermute_b32 v56, v138, v125
	ds_bpermute_b32 v57, v138, v125 offset:4
	ds_bpermute_b32 v58, v138, v125 offset:8
	ds_bpermute_b32 v61, v138, v125 offset:12
	v_lshl_add_u32 v24, v116, 7, v60
	s_waitcnt lgkmcnt(3)
	v_sub_u32_e32 v56, s52, v56
	v_cmp_lt_i32_e64 s[8:9], -1, v56
	v_med3_i32 v56, v56, 0, s61
	v_lshl_add_u32 v62, v56, 6, v133
	s_waitcnt lgkmcnt(2)
	v_sub_u32_e32 v56, s52, v57
	v_cmp_lt_i32_e64 s[12:13], -1, v56
	v_med3_i32 v56, v56, 0, s61
	v_lshl_add_u32 v63, v56, 6, v133
	s_waitcnt lgkmcnt(1)
	v_sub_u32_e32 v149, s52, v58
	s_waitcnt vmcnt(12)
	v_mfma_f32_16x16x32_fp8_fp8 v[56:59], v[28:29], v[84:85], 0
	v_med3_i32 v28, v149, 0, s61
	v_cmp_lt_i32_e64 s[16:17], -1, v149
	v_lshl_add_u32 v149, v28, 6, v133
	v_mfma_f32_16x16x32_fp8_fp8 v[28:31], v[30:31], v[86:87], v[56:59]
	s_waitcnt lgkmcnt(0)
	v_sub_u32_e32 v61, s52, v61
	global_load_dwordx4 v[16:19], v24, s[44:45] offset:16
	s_nop 0
	global_load_dwordx4 v[24:27], v24, s[44:45]
	v_med3_i32 v56, v61, 0, s61
	v_mfma_f32_16x16x32_fp8_fp8 v[28:31], v[20:21], v[88:89], v[28:31]
	v_lshl_add_u32 v56, v56, 6, v133
	ds_read_b32 v56, v56
	ds_read_b32 v57, v149
	ds_read_b32 v58, v63
	ds_read_b32 v59, v62
	v_mfma_f32_16x16x32_fp8_fp8 v[20:23], v[22:23], v[90:91], v[28:31]
	s_sub_i32 s18, s63, 47
	v_cmp_gt_i32_e32 vcc, s18, v82
	s_waitcnt lgkmcnt(0)
	v_cmp_gt_i32_e64 s[10:11], s18, v140
	s_nop 3
	v_fmac_f32_e32 v59, 0x3e0293ee, v20
	s_and_b64 vcc, vcc, s[8:9]
	v_cmp_gt_i32_e64 s[14:15], s18, v141
	v_cndmask_b32_e32 v150, v103, v59, vcc
	v_fmac_f32_e32 v58, 0x3e0293ee, v21
	s_and_b64 vcc, s[10:11], s[12:13]
	v_cmp_gt_i32_e64 s[18:19], s18, v139
	v_cmp_lt_i32_e64 s[20:21], -1, v61
	v_cndmask_b32_e32 v151, v103, v58, vcc
	v_fmac_f32_e32 v57, 0x3e0293ee, v22
	s_and_b64 vcc, s[14:15], s[16:17]
	v_cndmask_b32_e32 v152, v103, v57, vcc
	v_fmac_f32_e32 v56, 0x3e0293ee, v23
	s_and_b64 vcc, s[18:19], s[20:21]
	v_cndmask_b32_e32 v153, v103, v56, vcc
	ds_bpermute_b32 v56, v138, v122
	ds_bpermute_b32 v57, v138, v122 offset:4
	ds_bpermute_b32 v58, v138, v122 offset:8
	ds_bpermute_b32 v61, v138, v122 offset:12
	v_lshl_add_u32 v28, v115, 7, v60
	s_waitcnt lgkmcnt(3)
	v_sub_u32_e32 v56, s52, v56
	v_cmp_lt_i32_e64 s[8:9], -1, v56
	v_med3_i32 v56, v56, 0, s61
	v_lshl_add_u32 v62, v56, 6, v133
	s_waitcnt lgkmcnt(2)
	v_sub_u32_e32 v56, s52, v57
	v_cmp_lt_i32_e64 s[12:13], -1, v56
	v_med3_i32 v56, v56, 0, s61
	v_lshl_add_u32 v63, v56, 6, v133
	s_waitcnt lgkmcnt(1)
	v_sub_u32_e32 v149, s52, v58
	s_waitcnt vmcnt(12)
	v_mfma_f32_16x16x32_fp8_fp8 v[56:59], v[40:41], v[84:85], 0
	v_med3_i32 v40, v149, 0, s61
	v_cmp_lt_i32_e64 s[16:17], -1, v149
	v_lshl_add_u32 v149, v40, 6, v133
	v_mfma_f32_16x16x32_fp8_fp8 v[40:43], v[42:43], v[86:87], v[56:59]
	s_waitcnt lgkmcnt(0)
	v_sub_u32_e32 v61, s52, v61
	global_load_dwordx4 v[20:23], v28, s[44:45] offset:16
	s_nop 0
	global_load_dwordx4 v[28:31], v28, s[44:45]
	v_med3_i32 v56, v61, 0, s61
	v_mfma_f32_16x16x32_fp8_fp8 v[40:43], v[32:33], v[88:89], v[40:43]
	v_lshl_add_u32 v56, v56, 6, v133
	ds_read_b32 v56, v56
	ds_read_b32 v57, v149
	ds_read_b32 v58, v63
	ds_read_b32 v59, v62
	v_mfma_f32_16x16x32_fp8_fp8 v[32:35], v[34:35], v[90:91], v[40:43]
	s_sub_i32 s18, s63, 63
	v_cmp_gt_i32_e32 vcc, s18, v82
	s_waitcnt lgkmcnt(0)
	v_cmp_gt_i32_e64 s[10:11], s18, v140
	s_nop 3
	v_fmac_f32_e32 v59, 0x3e0293ee, v32
	s_and_b64 vcc, vcc, s[8:9]
	v_cmp_gt_i32_e64 s[14:15], s18, v141
	v_cndmask_b32_e32 v155, v103, v59, vcc
	v_fmac_f32_e32 v58, 0x3e0293ee, v33
	s_and_b64 vcc, s[10:11], s[12:13]
	v_cmp_gt_i32_e64 s[18:19], s18, v139
	v_cmp_lt_i32_e64 s[20:21], -1, v61
	v_cndmask_b32_e32 v156, v103, v58, vcc
	v_fmac_f32_e32 v57, 0x3e0293ee, v34
	s_and_b64 vcc, s[14:15], s[16:17]
	v_cndmask_b32_e32 v157, v103, v57, vcc
	v_fmac_f32_e32 v56, 0x3e0293ee, v35
	s_and_b64 vcc, s[18:19], s[20:21]
	v_cndmask_b32_e32 v158, v103, v56, vcc
	ds_bpermute_b32 v56, v138, v121
	ds_bpermute_b32 v57, v138, v121 offset:4
	ds_bpermute_b32 v58, v138, v121 offset:8
	ds_bpermute_b32 v61, v138, v121 offset:12
	v_lshl_add_u32 v40, v114, 7, v60
	s_waitcnt lgkmcnt(3)
	v_sub_u32_e32 v56, s52, v56
	v_cmp_lt_i32_e64 s[8:9], -1, v56
	v_med3_i32 v56, v56, 0, s61
	v_lshl_add_u32 v62, v56, 6, v133
	s_waitcnt lgkmcnt(2)
	v_sub_u32_e32 v56, s52, v57
	v_cmp_lt_i32_e64 s[12:13], -1, v56
	v_med3_i32 v56, v56, 0, s61
	v_lshl_add_u32 v63, v56, 6, v133
	s_waitcnt lgkmcnt(1)
	v_sub_u32_e32 v149, s52, v58
	s_waitcnt vmcnt(12)
	v_mfma_f32_16x16x32_fp8_fp8 v[56:59], v[44:45], v[84:85], 0
	v_med3_i32 v44, v149, 0, s61
	v_cmp_lt_i32_e64 s[16:17], -1, v149
	v_lshl_add_u32 v149, v44, 6, v133
	v_mfma_f32_16x16x32_fp8_fp8 v[44:47], v[46:47], v[86:87], v[56:59]
	s_waitcnt lgkmcnt(0)
	v_sub_u32_e32 v61, s52, v61
	global_load_dwordx4 v[32:35], v40, s[44:45] offset:16
	s_nop 0
	global_load_dwordx4 v[40:43], v40, s[44:45]
	v_med3_i32 v56, v61, 0, s61
	v_mfma_f32_16x16x32_fp8_fp8 v[44:47], v[36:37], v[88:89], v[44:47]
	v_lshl_add_u32 v56, v56, 6, v133
	ds_read_b32 v56, v56
	ds_read_b32 v57, v149
	ds_read_b32 v58, v63
	ds_read_b32 v59, v62
	v_mfma_f32_16x16x32_fp8_fp8 v[36:39], v[38:39], v[90:91], v[44:47]
	s_add_i32 s18, s63, 0xffffffb1
	v_cmp_gt_i32_e32 vcc, s18, v82
	s_waitcnt lgkmcnt(0)
; #define A8_ISSUE_K(kt) do { const char* kr_ = (const char*)K8 + (unsigned)(R[kt] * 512 + kvh * 128 + 32 * g); ring[(2 * (kt)) & 15] = *(const v4u*)kr_; ring[(2 * (kt) + 1) & 15] = *(const v4u*)(kr_ + 16); } while (0)
; #define A8_ISSUE_V(hc) do { _Pragma("unroll") for (int q2_ = 0; q2_ < 4; ++q2_) { const int rid_ = __shfl(R[hc], 4 * q2_ + g); \
;         ring[(4 * (hc) + q2_) & 15] = *(const v4u*)((const char*)VB + (unsigned)(rid_ * 1024 + kvh * 256 + 16 * lr)); } } while (0)
; DI void attn_unit_f8(LAS unsigned char* vbuf  , const LAS float* lut2  , const long (&qf)[4], const int* idx, int cnt_, int qpos_, int kvh, const unsigned char* K8, const bf16* VB, bf16* orow, int lane_) {
;     ...
;     for (int i = 0; i < 16; ++i) {
;         asm volatile("" ::: "memory");
;         {
;             int kp4[4];
; #pragma unroll
;             for (int e = 0; e < 4; ++e) kp4[e] = __shfl(R[i], 4 * g + e);
;             f32x4 acc = (f32x4){0.f, 0.f, 0.f, 0.f};
; #pragma unroll
;             for (int s = 0; s < 4; ++s) { const v4u w = ring[(2 * i + (s >> 1)) & 15]; const unsigned long long ka = (s & 1) ? ((unsigned long long)w.w << 32 | w.z) : ((unsigned long long)w.y << 32 | w.x);
;                 acc = __builtin_amdgcn_mfma_f32_16x16x32_fp8_fp8((long)ka, qf[s], acc, 0, 0, 0); }
;             float bs[4]; bool okv[4];
; #pragma unroll
;             for (int e = 0; e < 4; ++e) { const int rel = qpos - kp4[e]; okv[e] = (4 * g + e < cnt - 16 * i) && rel >= 0; const int rc = rel > 128 ? 128 : (rel < 0 ? 0 : rel); bs[e] = lut2[rc * 16 + hcol]; }
;             asm volatile("" : "+v"(bs[0]), "+v"(bs[1]), "+v"(bs[2]), "+v"(bs[3]));
; #pragma unroll
;             for (int e = 0; e < 4; ++e) acc[e] = okv[e] ? acc[e] * (0.08838834764831845f * 1.4426950408889634f) + bs[e] : -3.0e38f;
;             lg[i] = acc;
;         }
;         if (i + 8 < 16) A8_ISSUE_K(i + 8);
;         else if ((i & 1) == 1) A8_ISSUE_V((i - 9) / 2);
	v_cmp_gt_i32_e64 s[10:11], s18, v140
	s_nop 3
	v_fmac_f32_e32 v59, 0x3e0293ee, v36
	s_and_b64 vcc, vcc, s[8:9]
	v_cmp_gt_i32_e64 s[14:15], s18, v141
	v_cndmask_b32_e32 v161, v103, v59, vcc
	v_fmac_f32_e32 v58, 0x3e0293ee, v37
	s_and_b64 vcc, s[10:11], s[12:13]
	v_cmp_gt_i32_e64 s[18:19], s18, v139
	v_cmp_lt_i32_e64 s[20:21], -1, v61
	v_cndmask_b32_e32 v162, v103, v58, vcc
	v_fmac_f32_e32 v57, 0x3e0293ee, v38
	s_and_b64 vcc, s[14:15], s[16:17]
	v_cndmask_b32_e32 v163, v103, v57, vcc
	v_fmac_f32_e32 v56, 0x3e0293ee, v39
	s_and_b64 vcc, s[18:19], s[20:21]
	v_cndmask_b32_e32 v164, v103, v56, vcc
	ds_bpermute_b32 v56, v138, v120
	ds_bpermute_b32 v57, v138, v120 offset:4
	ds_bpermute_b32 v58, v138, v120 offset:8
	ds_bpermute_b32 v61, v138, v120 offset:12
	v_lshl_add_u32 v44, v113, 7, v60
	s_waitcnt lgkmcnt(3)
	v_sub_u32_e32 v56, s52, v56
	v_cmp_lt_i32_e64 s[8:9], -1, v56
	v_med3_i32 v56, v56, 0, s61
	v_lshl_add_u32 v62, v56, 6, v133
	s_waitcnt lgkmcnt(2)
	v_sub_u32_e32 v56, s52, v57
	v_cmp_lt_i32_e64 s[12:13], -1, v56
	v_med3_i32 v56, v56, 0, s61
	v_lshl_add_u32 v63, v56, 6, v133
	s_waitcnt lgkmcnt(1)
	v_sub_u32_e32 v149, s52, v58
	s_waitcnt vmcnt(12)
	v_mfma_f32_16x16x32_fp8_fp8 v[56:59], v[52:53], v[84:85], 0
	v_med3_i32 v52, v149, 0, s61
	v_cmp_lt_i32_e64 s[16:17], -1, v149
	v_lshl_add_u32 v149, v52, 6, v133
	v_mfma_f32_16x16x32_fp8_fp8 v[52:55], v[54:55], v[86:87], v[56:59]
	s_waitcnt lgkmcnt(0)
	v_sub_u32_e32 v61, s52, v61
	global_load_dwordx4 v[36:39], v44, s[44:45] offset:16
	s_nop 0
	global_load_dwordx4 v[44:47], v44, s[44:45]
	v_med3_i32 v56, v61, 0, s61
	v_mfma_f32_16x16x32_fp8_fp8 v[52:55], v[48:49], v[88:89], v[52:55]
	v_lshl_add_u32 v56, v56, 6, v133
	ds_read_b32 v56, v56
	ds_read_b32 v57, v149
	ds_read_b32 v58, v63
	ds_read_b32 v59, v62
	v_mfma_f32_16x16x32_fp8_fp8 v[48:51], v[50:51], v[90:91], v[52:55]
	s_add_i32 s18, s63, 0xffffffa1
	v_cmp_gt_i32_e32 vcc, s18, v82
	s_waitcnt lgkmcnt(0)
	v_cmp_gt_i32_e64 s[10:11], s18, v140
	s_nop 3
	v_fmac_f32_e32 v59, 0x3e0293ee, v48
	s_and_b64 vcc, vcc, s[8:9]
	v_cmp_gt_i32_e64 s[14:15], s18, v141
	v_cndmask_b32_e32 v167, v103, v59, vcc
	v_fmac_f32_e32 v58, 0x3e0293ee, v49
	s_and_b64 vcc, s[10:11], s[12:13]
	v_cmp_gt_i32_e64 s[18:19], s18, v139
	v_cmp_lt_i32_e64 s[20:21], -1, v61
	v_cndmask_b32_e32 v168, v103, v58, vcc
	v_fmac_f32_e32 v57, 0x3e0293ee, v50
	s_and_b64 vcc, s[14:15], s[16:17]
	v_cndmask_b32_e32 v169, v103, v57, vcc
	v_fmac_f32_e32 v56, 0x3e0293ee, v51
	s_and_b64 vcc, s[18:19], s[20:21]
	v_lshl_add_u32 v52, v112, 7, v60
	v_cndmask_b32_e32 v170, v103, v56, vcc
	global_load_dwordx4 v[48:51], v52, s[44:45] offset:16
	global_load_dwordx4 v[56:59], v52, s[44:45]
	ds_bpermute_b32 v52, v138, v118
	ds_bpermute_b32 v53, v138, v118 offset:4
	ds_bpermute_b32 v54, v138, v118 offset:8
	ds_bpermute_b32 v61, v138, v118 offset:12
	s_waitcnt lgkmcnt(3)
	v_sub_u32_e32 v52, s52, v52
	v_cmp_lt_i32_e64 s[8:9], -1, v52
	v_med3_i32 v52, v52, 0, s61
	v_lshl_add_u32 v62, v52, 6, v133
	s_waitcnt lgkmcnt(2)
	v_sub_u32_e32 v52, s52, v53
	v_cmp_lt_i32_e64 s[12:13], -1, v52
	v_med3_i32 v52, v52, 0, s61
	v_lshl_add_u32 v63, v52, 6, v133
	s_waitcnt lgkmcnt(1)
	v_sub_u32_e32 v149, s52, v54
	s_waitcnt vmcnt(14)
	v_mfma_f32_16x16x32_fp8_fp8 v[52:55], v[12:13], v[84:85], 0
	v_med3_i32 v12, v149, 0, s61
	v_cmp_lt_i32_e64 s[16:17], -1, v149
	v_lshl_add_u32 v149, v12, 6, v133
	v_mfma_f32_16x16x32_fp8_fp8 v[12:15], v[14:15], v[86:87], v[52:55]
	s_waitcnt lgkmcnt(0)
	v_sub_u32_e32 v61, s52, v61
	s_add_i32 s18, s63, 0xffffff91
	v_cmp_gt_i32_e32 vcc, s18, v82
	v_med3_i32 v52, v61, 0, s61
	v_mfma_f32_16x16x32_fp8_fp8 v[12:15], v[0:1], v[88:89], v[12:15]
	v_lshl_add_u32 v52, v52, 6, v133
	ds_read_b32 v52, v52
	ds_read_b32 v53, v149
	ds_read_b32 v54, v63
	ds_read_b32 v55, v62
	s_waitcnt lgkmcnt(0)
	v_mfma_f32_16x16x32_fp8_fp8 v[0:3], v[2:3], v[90:91], v[12:15]
	v_cmp_gt_i32_e64 s[10:11], s18, v140
	s_and_b64 vcc, vcc, s[8:9]
	v_cmp_gt_i32_e64 s[14:15], s18, v141
	v_cmp_gt_i32_e64 s[18:19], s18, v139
	v_cmp_lt_i32_e64 s[20:21], -1, v61
	s_nop 2
	v_fmac_f32_e32 v55, 0x3e0293ee, v0
	v_cndmask_b32_e32 v172, v103, v55, vcc
	v_fmac_f32_e32 v54, 0x3e0293ee, v1
	s_and_b64 vcc, s[10:11], s[12:13]
	v_cndmask_b32_e32 v173, v103, v54, vcc
	v_fmac_f32_e32 v53, 0x3e0293ee, v2
	s_and_b64 vcc, s[14:15], s[16:17]
	v_cndmask_b32_e32 v174, v103, v53, vcc
	v_fmac_f32_e32 v52, 0x3e0293ee, v3
	s_and_b64 vcc, s[18:19], s[20:21]
	v_lshl_add_u32 v0, v110, 7, v60
	v_cndmask_b32_e32 v175, v103, v52, vcc
	global_load_dwordx4 v[52:55], v0, s[44:45] offset:16
	global_load_dwordx4 v[60:63], v0, s[44:45]
	ds_bpermute_b32 v0, v138, v119
	ds_bpermute_b32 v1, v138, v119 offset:4
	ds_bpermute_b32 v2, v138, v119 offset:8
	ds_bpermute_b32 v12, v138, v119 offset:12
	s_waitcnt lgkmcnt(3)
	v_sub_u32_e32 v0, s52, v0
	v_cmp_lt_i32_e64 s[8:9], -1, v0
	v_med3_i32 v0, v0, 0, s61
	v_lshl_add_u32 v13, v0, 6, v133
	s_waitcnt lgkmcnt(2)
	v_sub_u32_e32 v0, s52, v1
	v_cmp_lt_i32_e64 s[12:13], -1, v0
	v_med3_i32 v0, v0, 0, s61
	v_lshl_add_u32 v14, v0, 6, v133
	s_waitcnt lgkmcnt(1)
	v_sub_u32_e32 v15, s52, v2
	s_waitcnt vmcnt(14)
	v_mfma_f32_16x16x32_fp8_fp8 v[0:3], v[64:65], v[84:85], 0
	s_waitcnt lgkmcnt(0)
	v_sub_u32_e32 v12, s52, v12
	v_med3_i32 v64, v12, 0, s61
	v_cmp_lt_i32_e64 s[16:17], -1, v15
	v_mfma_f32_16x16x32_fp8_fp8 v[0:3], v[66:67], v[86:87], v[0:3]
	v_med3_i32 v15, v15, 0, s61
	v_lshl_add_u32 v64, v64, 6, v133
	v_lshl_add_u32 v15, v15, 6, v133
	v_mfma_f32_16x16x32_fp8_fp8 v[0:3], v[4:5], v[88:89], v[0:3]
	ds_read_b32 v4, v64
	ds_read_b32 v5, v15
	ds_read_b32 v14, v14
	ds_read_b32 v13, v13
	s_waitcnt lgkmcnt(0)
; #define A8_ISSUE_K(kt) do { const char* kr_ = (const char*)K8 + (unsigned)(R[kt] * 512 + kvh * 128 + 32 * g); ring[(2 * (kt)) & 15] = *(const v4u*)kr_; ring[(2 * (kt) + 1) & 15] = *(const v4u*)(kr_ + 16); } while (0)
; #define A8_ISSUE_V(hc) do { _Pragma("unroll") for (int q2_ = 0; q2_ < 4; ++q2_) { const int rid_ = __shfl(R[hc], 4 * q2_ + g); \
;         ring[(4 * (hc) + q2_) & 15] = *(const v4u*)((const char*)VB + (unsigned)(rid_ * 1024 + kvh * 256 + 16 * lr)); } } while (0)
; DI void attn_unit_f8(LAS unsigned char* vbuf  , const LAS float* lut2  , const long (&qf)[4], const int* idx, int cnt_, int qpos_, int kvh, const unsigned char* K8, const bf16* VB, bf16* orow, int lane_) {
;     ...
;     for (int i = 0; i < 16; ++i) {
;         asm volatile("" ::: "memory");
;         {
;             int kp4[4];
; #pragma unroll
;             for (int e = 0; e < 4; ++e) kp4[e] = __shfl(R[i], 4 * g + e);
;             f32x4 acc = (f32x4){0.f, 0.f, 0.f, 0.f};
; #pragma unroll
;             for (int s = 0; s < 4; ++s) { const v4u w = ring[(2 * i + (s >> 1)) & 15]; const unsigned long long ka = (s & 1) ? ((unsigned long long)w.w << 32 | w.z) : ((unsigned long long)w.y << 32 | w.x);
;                 acc = __builtin_amdgcn_mfma_f32_16x16x32_fp8_fp8((long)ka, qf[s], acc, 0, 0, 0); }
;             float bs[4]; bool okv[4];
; #pragma unroll
;             for (int e = 0; e < 4; ++e) { const int rel = qpos - kp4[e]; okv[e] = (4 * g + e < cnt - 16 * i) && rel >= 0; const int rc = rel > 128 ? 128 : (rel < 0 ? 0 : rel); bs[e] = lut2[rc * 16 + hcol]; }
;             asm volatile("" : "+v"(bs[0]), "+v"(bs[1]), "+v"(bs[2]), "+v"(bs[3]));
; #pragma unroll
;             for (int e = 0; e < 4; ++e) acc[e] = okv[e] ? acc[e] * (0.08838834764831845f * 1.4426950408889634f) + bs[e] : -3.0e38f;
;             lg[i] = acc;
;         }
;         if (i + 8 < 16) A8_ISSUE_K(i + 8);
;         else if ((i & 1) == 1) A8_ISSUE_V((i - 9) / 2);
	v_mfma_f32_16x16x32_fp8_fp8 v[0:3], v[6:7], v[90:91], v[0:3]
	s_add_i32 s18, s63, 0xffffff81
	v_cmp_gt_i32_e32 vcc, s18, v82
	v_cmp_gt_i32_e64 s[10:11], s18, v140
	s_and_b64 vcc, vcc, s[8:9]
	v_cmp_gt_i32_e64 s[14:15], s18, v141
	s_nop 2
	v_fmac_f32_e32 v13, 0x3e0293ee, v0
	ds_bpermute_b32 v0, v138, v117
	v_fmac_f32_e32 v14, 0x3e0293ee, v1
	ds_bpermute_b32 v1, v138, v117 offset:4
	v_fmac_f32_e32 v5, 0x3e0293ee, v2
	ds_bpermute_b32 v2, v138, v117 offset:8
	v_cndmask_b32_e32 v178, v103, v13, vcc
	s_and_b64 vcc, s[10:11], s[12:13]
	s_waitcnt lgkmcnt(2)
	v_sub_u32_e32 v0, s52, v0
	v_cndmask_b32_e32 v179, v103, v14, vcc
	s_and_b64 vcc, s[14:15], s[16:17]
	v_cmp_lt_i32_e64 s[8:9], -1, v0
	v_med3_i32 v0, v0, 0, s61
	v_cndmask_b32_e32 v181, v103, v5, vcc
	v_lshl_add_u32 v5, v0, 6, v133
	s_waitcnt lgkmcnt(1)
	v_sub_u32_e32 v0, s52, v1
	v_cmp_lt_i32_e64 s[12:13], -1, v0
	v_med3_i32 v0, v0, 0, s61
	v_cmp_gt_i32_e64 s[18:19], s18, v139
	v_cmp_lt_i32_e64 s[20:21], -1, v12
	v_fmac_f32_e32 v4, 0x3e0293ee, v3
	v_lshl_add_u32 v6, v0, 6, v133
	s_waitcnt lgkmcnt(0)
	v_sub_u32_e32 v7, s52, v2
	s_waitcnt vmcnt(12)
	v_mfma_f32_16x16x32_fp8_fp8 v[0:3], v[68:69], v[84:85], 0
	s_and_b64 vcc, s[18:19], s[20:21]
	v_cndmask_b32_e32 v182, v103, v4, vcc
	ds_bpermute_b32 v4, v138, v117 offset:12
	v_mfma_f32_16x16x32_fp8_fp8 v[0:3], v[70:71], v[86:87], v[0:3]
	v_cmp_lt_i32_e64 s[16:17], -1, v7
	v_med3_i32 v7, v7, 0, s61
	s_waitcnt lgkmcnt(0)
	v_sub_u32_e32 v4, s52, v4
	v_med3_i32 v12, v4, 0, s61
	v_mfma_f32_16x16x32_fp8_fp8 v[0:3], v[8:9], v[88:89], v[0:3]
	v_lshl_add_u32 v7, v7, 6, v133
	v_lshl_add_u32 v12, v12, 6, v133
	ds_bpermute_b32 v68, v138, v116
	ds_read_b32 v8, v12
	ds_read_b32 v7, v7
	ds_read_b32 v6, v6
	ds_read_b32 v5, v5
	ds_bpermute_b32 v69, v138, v116 offset:4
	v_mfma_f32_16x16x32_fp8_fp8 v[0:3], v[10:11], v[90:91], v[0:3]
	s_add_i32 s18, s63, 0xffffff71
	ds_bpermute_b32 v70, v138, v116 offset:8
	v_cmp_gt_i32_e32 vcc, s18, v82
	s_waitcnt lgkmcnt(6)
	v_sub_u32_e32 v68, s52, v68
	s_waitcnt lgkmcnt(2)
	s_and_b64 vcc, vcc, s[8:9]
	v_cmp_lt_i32_e64 s[8:9], -1, v68
	v_med3_i32 v68, v68, 0, s61
	v_cmp_gt_i32_e64 s[10:11], s18, v140
	v_fmac_f32_e32 v5, 0x3e0293ee, v0
	v_fmac_f32_e32 v6, 0x3e0293ee, v1
	v_fmac_f32_e32 v7, 0x3e0293ee, v2
	v_and_or_b32 v0, v148, 63, v101
	v_fmac_f32_e32 v8, 0x3e0293ee, v3
	v_add_u32_e32 v1, 4, v148
	v_add_u32_e32 v2, 8, v148
	v_add_u32_e32 v3, 12, v148
	v_lshl_add_u32 v148, v68, 6, v133
	s_waitcnt lgkmcnt(1)
	v_sub_u32_e32 v68, s52, v69
	v_cndmask_b32_e32 v184, v103, v5, vcc
	s_and_b64 vcc, s[10:11], s[12:13]
	v_cmp_lt_i32_e64 s[12:13], -1, v68
	v_med3_i32 v68, v68, 0, s61
	v_and_or_b32 v1, v1, 63, v101
	v_and_or_b32 v2, v2, 63, v101
	v_and_or_b32 v3, v3, 63, v101
	v_lshl_add_u32 v149, v68, 6, v133
	s_waitcnt lgkmcnt(0)
	v_sub_u32_e32 v154, s52, v70
	s_waitcnt vmcnt(10)
	v_mfma_f32_16x16x32_fp8_fp8 v[68:71], v[24:25], v[84:85], 0
	v_lshlrev_b32_e32 v64, 2, v0
	v_lshlrev_b32_e32 v65, 2, v1
	v_lshlrev_b32_e32 v66, 2, v2
	v_lshlrev_b32_e32 v67, 2, v3
	ds_bpermute_b32 v0, v64, v147
	ds_bpermute_b32 v1, v65, v147
	ds_bpermute_b32 v2, v66, v147
	ds_bpermute_b32 v3, v67, v147
	ds_bpermute_b32 v147, v138, v116 offset:12
	v_cmp_gt_i32_e64 s[14:15], s18, v141
	v_med3_i32 v24, v154, 0, s61
	v_cndmask_b32_e32 v185, v103, v6, vcc
	s_and_b64 vcc, s[14:15], s[16:17]
	v_cmp_lt_i32_e64 s[16:17], -1, v154
	v_lshl_add_u32 v154, v24, 6, v133
	v_mfma_f32_16x16x32_fp8_fp8 v[24:27], v[26:27], v[86:87], v[68:71]
	v_cmp_gt_i32_e64 s[18:19], s18, v139
	v_cmp_lt_i32_e64 s[20:21], -1, v4
	s_waitcnt lgkmcnt(4)
	v_lshl_or_b32 v0, v0, 10, v111
	s_waitcnt lgkmcnt(3)
	v_lshl_or_b32 v1, v1, 10, v111
	s_waitcnt lgkmcnt(0)
	v_sub_u32_e32 v147, s52, v147
	v_cndmask_b32_e32 v186, v103, v7, vcc
	s_and_b64 vcc, s[18:19], s[20:21]
	global_load_dwordx4 v[12:15], v0, s[46:47]
	global_load_dwordx4 v[4:7], v1, s[46:47]
	v_lshl_or_b32 v0, v2, 10, v111
	v_lshl_or_b32 v1, v3, 10, v111
	v_med3_i32 v68, v147, 0, s61
	v_mfma_f32_16x16x32_fp8_fp8 v[24:27], v[16:17], v[88:89], v[24:27]
	v_cndmask_b32_e32 v187, v103, v8, vcc
	global_load_dwordx4 v[8:11], v0, s[46:47]
	s_nop 0
	global_load_dwordx4 v[0:3], v1, s[46:47]
	v_lshl_add_u32 v68, v68, 6, v133
	ds_read_b32 v68, v68
	ds_read_b32 v69, v154
	ds_read_b32 v70, v149
	ds_read_b32 v71, v148
	v_mfma_f32_16x16x32_fp8_fp8 v[16:19], v[18:19], v[90:91], v[24:27]
	s_waitcnt lgkmcnt(0)
	s_add_i32 s18, s63, 0xffffff61
	s_nop 5
	v_fmac_f32_e32 v71, 0x3e0293ee, v16
	ds_bpermute_b32 v16, v138, v115
	v_fmac_f32_e32 v70, 0x3e0293ee, v17
	ds_bpermute_b32 v17, v138, v115 offset:4
	v_fmac_f32_e32 v69, 0x3e0293ee, v18
	ds_bpermute_b32 v18, v138, v115 offset:8
	v_cmp_gt_i32_e32 vcc, s18, v82
	s_waitcnt lgkmcnt(2)
	v_sub_u32_e32 v16, s52, v16
	s_and_b64 vcc, vcc, s[8:9]
	v_cmp_lt_i32_e64 s[8:9], -1, v16
	v_med3_i32 v16, v16, 0, s61
	v_cmp_gt_i32_e64 s[10:11], s18, v140
	v_lshl_add_u32 v25, v16, 6, v133
	s_waitcnt lgkmcnt(1)
	v_sub_u32_e32 v16, s52, v17
	v_cndmask_b32_e32 v188, v103, v71, vcc
	s_and_b64 vcc, s[10:11], s[12:13]
	v_cmp_lt_i32_e64 s[12:13], -1, v16
	v_med3_i32 v16, v16, 0, s61
	v_fmac_f32_e32 v68, 0x3e0293ee, v19
	v_lshl_add_u32 v26, v16, 6, v133
	s_waitcnt lgkmcnt(0)
	v_sub_u32_e32 v27, s52, v18
	s_waitcnt vmcnt(12)
	v_mfma_f32_16x16x32_fp8_fp8 v[16:19], v[28:29], v[84:85], 0
	ds_bpermute_b32 v24, v138, v115 offset:12
	v_cmp_gt_i32_e64 s[14:15], s18, v141
	v_cmp_gt_i32_e64 s[18:19], s18, v139
	v_mfma_f32_16x16x32_fp8_fp8 v[16:19], v[30:31], v[86:87], v[16:19]
	v_cmp_lt_i32_e64 s[20:21], -1, v147
	v_cndmask_b32_e32 v189, v103, v70, vcc
	s_and_b64 vcc, s[14:15], s[16:17]
	s_waitcnt lgkmcnt(0)
; #define A8_ISSUE_K(kt) do { const char* kr_ = (const char*)K8 + (unsigned)(R[kt] * 512 + kvh * 128 + 32 * g); ring[(2 * (kt)) & 15] = *(const v4u*)kr_; ring[(2 * (kt) + 1) & 15] = *(const v4u*)(kr_ + 16); } while (0)
; #define A8_ISSUE_V(hc) do { _Pragma("unroll") for (int q2_ = 0; q2_ < 4; ++q2_) { const int rid_ = __shfl(R[hc], 4 * q2_ + g); \
;         ring[(4 * (hc) + q2_) & 15] = *(const v4u*)((const char*)VB + (unsigned)(rid_ * 1024 + kvh * 256 + 16 * lr)); } } while (0)
; DI void attn_unit_f8(LAS unsigned char* vbuf  , const LAS float* lut2  , const long (&qf)[4], const int* idx, int cnt_, int qpos_, int kvh, const unsigned char* K8, const bf16* VB, bf16* orow, int lane_) {
;     ...
;     for (int i = 0; i < 16; ++i) {
;         asm volatile("" ::: "memory");
;         {
;             int kp4[4];
; #pragma unroll
;             for (int e = 0; e < 4; ++e) kp4[e] = __shfl(R[i], 4 * g + e);
;             f32x4 acc = (f32x4){0.f, 0.f, 0.f, 0.f};
; #pragma unroll
;             for (int s = 0; s < 4; ++s) { const v4u w = ring[(2 * i + (s >> 1)) & 15]; const unsigned long long ka = (s & 1) ? ((unsigned long long)w.w << 32 | w.z) : ((unsigned long long)w.y << 32 | w.x);
;                 acc = __builtin_amdgcn_mfma_f32_16x16x32_fp8_fp8((long)ka, qf[s], acc, 0, 0, 0); }
;             float bs[4]; bool okv[4];
; #pragma unroll
;             for (int e = 0; e < 4; ++e) { const int rel = qpos - kp4[e]; okv[e] = (4 * g + e < cnt - 16 * i) && rel >= 0; const int rc = rel > 128 ? 128 : (rel < 0 ? 0 : rel); bs[e] = lut2[rc * 16 + hcol]; }
;             asm volatile("" : "+v"(bs[0]), "+v"(bs[1]), "+v"(bs[2]), "+v"(bs[3]));
; #pragma unroll
;             for (int e = 0; e < 4; ++e) acc[e] = okv[e] ? acc[e] * (0.08838834764831845f * 1.4426950408889634f) + bs[e] : -3.0e38f;
;             lg[i] = acc;
;         }
;         if (i + 8 < 16) A8_ISSUE_K(i + 8);
;         else if ((i & 1) == 1) A8_ISSUE_V((i - 9) / 2);
	v_sub_u32_e32 v24, s52, v24
	v_cndmask_b32_e32 v190, v103, v69, vcc
	s_and_b64 vcc, s[18:19], s[20:21]
	v_med3_i32 v28, v24, 0, s61
	v_mfma_f32_16x16x32_fp8_fp8 v[16:19], v[20:21], v[88:89], v[16:19]
	v_cndmask_b32_e32 v191, v103, v68, vcc
	v_cmp_lt_i32_e64 s[16:17], -1, v27
	v_med3_i32 v27, v27, 0, s61
	v_lshl_add_u32 v28, v28, 6, v133
	ds_bpermute_b32 v68, v138, v114
	v_lshl_add_u32 v27, v27, 6, v133
	ds_read_b32 v20, v28
	ds_read_b32 v21, v27
	ds_read_b32 v26, v26
	ds_read_b32 v25, v25
	ds_bpermute_b32 v69, v138, v114 offset:4
	v_mfma_f32_16x16x32_fp8_fp8 v[16:19], v[22:23], v[90:91], v[16:19]
	s_add_i32 s18, s63, 0xffffff51
	ds_bpermute_b32 v70, v138, v114 offset:8
	v_cmp_gt_i32_e32 vcc, s18, v82
	s_waitcnt lgkmcnt(6)
	v_sub_u32_e32 v68, s52, v68
	s_waitcnt lgkmcnt(2)
	s_and_b64 vcc, vcc, s[8:9]
	v_cmp_lt_i32_e64 s[8:9], -1, v68
	v_med3_i32 v68, v68, 0, s61
	v_cmp_gt_i32_e64 s[10:11], s18, v140
	v_fmac_f32_e32 v25, 0x3e0293ee, v16
	v_lshl_add_u32 v147, v68, 6, v133
	s_waitcnt lgkmcnt(1)
	v_sub_u32_e32 v68, s52, v69
	v_cndmask_b32_e32 v192, v103, v25, vcc
	s_and_b64 vcc, s[10:11], s[12:13]
	v_cmp_lt_i32_e64 s[12:13], -1, v68
	v_med3_i32 v68, v68, 0, s61
	v_lshl_add_u32 v148, v68, 6, v133
	s_waitcnt lgkmcnt(0)
	v_sub_u32_e32 v149, s52, v70
	s_waitcnt vmcnt(10)
	v_mfma_f32_16x16x32_fp8_fp8 v[68:71], v[40:41], v[84:85], 0
	v_cmp_lt_i32_e64 s[20:21], -1, v24
	v_fmac_f32_e32 v26, 0x3e0293ee, v17
	ds_bpermute_b32 v16, v64, v142
	ds_bpermute_b32 v17, v65, v142
	ds_bpermute_b32 v24, v66, v142
	ds_bpermute_b32 v25, v67, v142
	ds_bpermute_b32 v142, v138, v114 offset:12
	v_cmp_gt_i32_e64 s[14:15], s18, v141
	v_med3_i32 v40, v149, 0, s61
	v_cndmask_b32_e32 v183, v103, v26, vcc
	s_and_b64 vcc, s[14:15], s[16:17]
	v_cmp_lt_i32_e64 s[16:17], -1, v149
	v_lshl_add_u32 v149, v40, 6, v133
	v_mfma_f32_16x16x32_fp8_fp8 v[40:43], v[42:43], v[86:87], v[68:71]
	v_cmp_gt_i32_e64 s[18:19], s18, v139
	v_fmac_f32_e32 v21, 0x3e0293ee, v18
	s_waitcnt lgkmcnt(0)
	v_sub_u32_e32 v142, s52, v142
	v_cndmask_b32_e32 v180, v103, v21, vcc
	v_fmac_f32_e32 v20, 0x3e0293ee, v19
	s_and_b64 vcc, s[18:19], s[20:21]
	v_lshl_or_b32 v16, v16, 10, v111
	v_lshl_or_b32 v17, v17, 10, v111
	v_lshl_or_b32 v24, v24, 10, v111
	v_lshl_or_b32 v28, v25, 10, v111
	v_med3_i32 v68, v142, 0, s61
	v_mfma_f32_16x16x32_fp8_fp8 v[40:43], v[32:33], v[88:89], v[40:43]
	v_cndmask_b32_e32 v171, v103, v20, vcc
	global_load_dwordx4 v[20:23], v16, s[46:47]
	s_nop 0
	global_load_dwordx4 v[16:19], v17, s[46:47]
	s_nop 0
	global_load_dwordx4 v[24:27], v24, s[46:47]
	s_nop 0
	global_load_dwordx4 v[28:31], v28, s[46:47]
	v_lshl_add_u32 v68, v68, 6, v133
	ds_read_b32 v68, v68
	ds_read_b32 v69, v149
	ds_read_b32 v70, v148
	ds_read_b32 v71, v147
	v_mfma_f32_16x16x32_fp8_fp8 v[32:35], v[34:35], v[90:91], v[40:43]
	s_waitcnt lgkmcnt(0)
	s_add_i32 s18, s63, 0xffffff41
	s_nop 5
	v_fmac_f32_e32 v71, 0x3e0293ee, v32
	ds_bpermute_b32 v32, v138, v113
	v_fmac_f32_e32 v70, 0x3e0293ee, v33
	ds_bpermute_b32 v33, v138, v113 offset:4
	v_fmac_f32_e32 v69, 0x3e0293ee, v34
	ds_bpermute_b32 v34, v138, v113 offset:8
	v_cmp_gt_i32_e32 vcc, s18, v82
	s_waitcnt lgkmcnt(2)
	v_sub_u32_e32 v32, s52, v32
	s_and_b64 vcc, vcc, s[8:9]
	v_cmp_lt_i32_e64 s[8:9], -1, v32
	v_med3_i32 v32, v32, 0, s61
	v_cmp_gt_i32_e64 s[10:11], s18, v140
	v_lshl_add_u32 v41, v32, 6, v133
	s_waitcnt lgkmcnt(1)
	v_sub_u32_e32 v32, s52, v33
	v_cndmask_b32_e32 v177, v103, v71, vcc
	s_and_b64 vcc, s[10:11], s[12:13]
	v_cmp_lt_i32_e64 s[12:13], -1, v32
	v_med3_i32 v32, v32, 0, s61
	v_fmac_f32_e32 v68, 0x3e0293ee, v35
	v_lshl_add_u32 v42, v32, 6, v133
	s_waitcnt lgkmcnt(0)
	v_sub_u32_e32 v43, s52, v34
	s_waitcnt vmcnt(12)
	v_mfma_f32_16x16x32_fp8_fp8 v[32:35], v[44:45], v[84:85], 0
	ds_bpermute_b32 v40, v138, v113 offset:12
	v_cmp_gt_i32_e64 s[14:15], s18, v141
	v_cmp_gt_i32_e64 s[18:19], s18, v139
	v_mfma_f32_16x16x32_fp8_fp8 v[32:35], v[46:47], v[86:87], v[32:35]
	v_cmp_lt_i32_e64 s[20:21], -1, v142
	v_cndmask_b32_e32 v176, v103, v70, vcc
	s_and_b64 vcc, s[14:15], s[16:17]
	s_waitcnt lgkmcnt(0)
	v_sub_u32_e32 v40, s52, v40
	v_cndmask_b32_e32 v166, v103, v69, vcc
	s_and_b64 vcc, s[18:19], s[20:21]
	v_med3_i32 v44, v40, 0, s61
	v_mfma_f32_16x16x32_fp8_fp8 v[32:35], v[36:37], v[88:89], v[32:35]
	v_cndmask_b32_e32 v165, v103, v68, vcc
	v_cmp_lt_i32_e64 s[16:17], -1, v43
	v_med3_i32 v43, v43, 0, s61
	v_lshl_add_u32 v44, v44, 6, v133
	ds_bpermute_b32 v68, v138, v112
	v_lshl_add_u32 v43, v43, 6, v133
	ds_read_b32 v36, v44
	ds_read_b32 v37, v43
	ds_read_b32 v42, v42
	ds_read_b32 v41, v41
	ds_bpermute_b32 v69, v138, v112 offset:4
	v_mfma_f32_16x16x32_fp8_fp8 v[32:35], v[38:39], v[90:91], v[32:35]
	s_add_i32 s18, s63, 0xffffff31
	ds_bpermute_b32 v70, v138, v112 offset:8
	v_cmp_gt_i32_e32 vcc, s18, v82
	s_waitcnt lgkmcnt(6)
	v_sub_u32_e32 v68, s52, v68
	s_waitcnt lgkmcnt(2)
	s_and_b64 vcc, vcc, s[8:9]
	v_cmp_lt_i32_e64 s[8:9], -1, v68
	v_med3_i32 v68, v68, 0, s61
	v_cmp_gt_i32_e64 s[10:11], s18, v140
	v_fmac_f32_e32 v41, 0x3e0293ee, v32
	v_lshl_add_u32 v142, v68, 6, v133
	s_waitcnt lgkmcnt(1)
	v_sub_u32_e32 v68, s52, v69
	v_cndmask_b32_e32 v160, v103, v41, vcc
	s_and_b64 vcc, s[10:11], s[12:13]
	v_cmp_lt_i32_e64 s[12:13], -1, v68
	v_med3_i32 v68, v68, 0, s61
	v_lshl_add_u32 v147, v68, 6, v133
	s_waitcnt lgkmcnt(0)
	v_sub_u32_e32 v154, s52, v70
	s_waitcnt vmcnt(10)
; #define A8_ISSUE_K(kt) do { const char* kr_ = (const char*)K8 + (unsigned)(R[kt] * 512 + kvh * 128 + 32 * g); ring[(2 * (kt)) & 15] = *(const v4u*)kr_; ring[(2 * (kt) + 1) & 15] = *(const v4u*)(kr_ + 16); } while (0)
; #define A8_ISSUE_V(hc) do { _Pragma("unroll") for (int q2_ = 0; q2_ < 4; ++q2_) { const int rid_ = __shfl(R[hc], 4 * q2_ + g); \
;         ring[(4 * (hc) + q2_) & 15] = *(const v4u*)((const char*)VB + (unsigned)(rid_ * 1024 + kvh * 256 + 16 * lr)); } } while (0)
; DI void attn_unit_f8(LAS unsigned char* vbuf  , const LAS float* lut2  , const long (&qf)[4], const int* idx, int cnt_, int qpos_, int kvh, const unsigned char* K8, const bf16* VB, bf16* orow, int lane_) {
;     ...
;             for (int s = 0; s < 4; ++s) { const v4u w = ring[(2 * i + (s >> 1)) & 15]; const unsigned long long ka = (s & 1) ? ((unsigned long long)w.w << 32 | w.z) : ((unsigned long long)w.y << 32 | w.x);
;                 acc = __builtin_amdgcn_mfma_f32_16x16x32_fp8_fp8((long)ka, qf[s], acc, 0, 0, 0); }
;             float bs[4]; bool okv[4];
; #pragma unroll
;             for (int e = 0; e < 4; ++e) { const int rel = qpos - kp4[e]; okv[e] = (4 * g + e < cnt - 16 * i) && rel >= 0; const int rc = rel > 128 ? 128 : (rel < 0 ? 0 : rel); bs[e] = lut2[rc * 16 + hcol]; }
;             asm volatile("" : "+v"(bs[0]), "+v"(bs[1]), "+v"(bs[2]), "+v"(bs[3]));
; #pragma unroll
;             for (int e = 0; e < 4; ++e) acc[e] = okv[e] ? acc[e] * (0.08838834764831845f * 1.4426950408889634f) + bs[e] : -3.0e38f;
;             lg[i] = acc;
;         }
;         if (i + 8 < 16) A8_ISSUE_K(i + 8);
;         else if ((i & 1) == 1) A8_ISSUE_V((i - 9) / 2);
;     }
;     {
;         float mx = -3.0e38f;
; #pragma unroll
;         for (int kt = 0; kt < 16; ++kt) mx = fmaxf(fmaxf(fmaxf(lg[kt][0], lg[kt][1]), fmaxf(lg[kt][2], lg[kt][3])), mx);
;         mx = fmaxf(mx, __shfl_xor(mx, 16)); mx = fmaxf(mx, __shfl_xor(mx, 32));
	v_mfma_f32_16x16x32_fp8_fp8 v[68:71], v[56:57], v[84:85], 0
	v_fmac_f32_e32 v42, 0x3e0293ee, v33
	v_fmac_f32_e32 v37, 0x3e0293ee, v34
	ds_bpermute_b32 v32, v64, v132
	v_fmac_f32_e32 v36, 0x3e0293ee, v35
	ds_bpermute_b32 v33, v65, v132
	ds_bpermute_b32 v34, v66, v132
	ds_bpermute_b32 v35, v67, v132
	ds_bpermute_b32 v132, v138, v112 offset:12
	v_cmp_gt_i32_e64 s[14:15], s18, v141
	v_med3_i32 v56, v154, 0, s61
	v_cndmask_b32_e32 v159, v103, v42, vcc
	s_and_b64 vcc, s[14:15], s[16:17]
	v_cmp_lt_i32_e64 s[16:17], -1, v154
	v_lshl_add_u32 v154, v56, 6, v133
	v_mfma_f32_16x16x32_fp8_fp8 v[56:59], v[58:59], v[86:87], v[68:71]
	v_cmp_gt_i32_e64 s[18:19], s18, v139
	v_cmp_lt_i32_e64 s[20:21], -1, v40
	v_cndmask_b32_e32 v149, v103, v37, vcc
	s_and_b64 vcc, s[18:19], s[20:21]
	s_waitcnt lgkmcnt(4)
	v_lshl_or_b32 v32, v32, 10, v111
	s_waitcnt lgkmcnt(3)
	v_lshl_or_b32 v33, v33, 10, v111
	s_waitcnt lgkmcnt(0)
	v_sub_u32_e32 v132, s52, v132
	v_cndmask_b32_e32 v148, v103, v36, vcc
	global_load_dwordx4 v[44:47], v32, s[46:47]
	global_load_dwordx4 v[36:39], v33, s[46:47]
	v_lshl_or_b32 v32, v34, 10, v111
	v_lshl_or_b32 v33, v35, 10, v111
	v_med3_i32 v68, v132, 0, s61
	v_mfma_f32_16x16x32_fp8_fp8 v[56:59], v[48:49], v[88:89], v[56:59]
	global_load_dwordx4 v[40:43], v32, s[46:47]
	s_nop 0
	global_load_dwordx4 v[32:35], v33, s[46:47]
	v_lshl_add_u32 v68, v68, 6, v133
	ds_read_b32 v68, v68
	ds_read_b32 v69, v154
	ds_read_b32 v70, v147
	ds_read_b32 v71, v142
	v_mfma_f32_16x16x32_fp8_fp8 v[48:51], v[50:51], v[90:91], v[56:59]
	s_waitcnt lgkmcnt(0)
	s_add_i32 s18, s63, 0xffffff21
	s_nop 5
	v_fmac_f32_e32 v71, 0x3e0293ee, v48
	ds_bpermute_b32 v48, v138, v110
	v_fmac_f32_e32 v70, 0x3e0293ee, v49
	ds_bpermute_b32 v49, v138, v110 offset:4
	v_fmac_f32_e32 v69, 0x3e0293ee, v50
	ds_bpermute_b32 v50, v138, v110 offset:8
	v_cmp_gt_i32_e32 vcc, s18, v82
	s_waitcnt lgkmcnt(2)
	v_sub_u32_e32 v48, s52, v48
	s_and_b64 vcc, vcc, s[8:9]
	v_cmp_lt_i32_e64 s[8:9], -1, v48
	v_med3_i32 v48, v48, 0, s61
	v_cmp_gt_i32_e64 s[10:11], s18, v140
	v_lshl_add_u32 v57, v48, 6, v133
	s_waitcnt lgkmcnt(1)
	v_sub_u32_e32 v48, s52, v49
	v_cndmask_b32_e32 v154, v103, v71, vcc
	s_and_b64 vcc, s[10:11], s[12:13]
	v_cmp_lt_i32_e64 s[12:13], -1, v48
	v_med3_i32 v48, v48, 0, s61
	v_fmac_f32_e32 v68, 0x3e0293ee, v51
	v_lshl_add_u32 v58, v48, 6, v133
	s_waitcnt lgkmcnt(0)
	v_sub_u32_e32 v59, s52, v50
	s_waitcnt vmcnt(12)
	v_mfma_f32_16x16x32_fp8_fp8 v[48:51], v[60:61], v[84:85], 0
	ds_bpermute_b32 v56, v138, v110 offset:12
	v_cmp_gt_i32_e64 s[14:15], s18, v141
	v_cndmask_b32_e32 v147, v103, v70, vcc
	v_mfma_f32_16x16x32_fp8_fp8 v[48:51], v[62:63], v[86:87], v[48:51]
	s_and_b64 vcc, s[14:15], s[16:17]
	s_waitcnt lgkmcnt(0)
	v_sub_u32_e32 v56, s52, v56
	v_med3_i32 v60, v56, 0, s61
	v_mfma_f32_16x16x32_fp8_fp8 v[48:51], v[52:53], v[88:89], v[48:51]
	v_cmp_lt_i32_e64 s[16:17], -1, v59
	v_med3_i32 v59, v59, 0, s61
	v_lshl_add_u32 v60, v60, 6, v133
	v_lshl_add_u32 v59, v59, 6, v133
	ds_read_b32 v52, v60
	ds_read_b32 v53, v59
	ds_read_b32 v58, v58
	ds_read_b32 v57, v57
	v_mfma_f32_16x16x32_fp8_fp8 v[48:51], v[54:55], v[90:91], v[48:51]
	v_cmp_gt_i32_e64 s[18:19], s18, v139
	v_cmp_lt_i32_e64 s[20:21], -1, v132
	v_cndmask_b32_e32 v132, v103, v69, vcc
	s_and_b64 vcc, s[18:19], s[20:21]
	s_addk_i32 s63, 0xff11
	v_cndmask_b32_e32 v142, v103, v68, vcc
	v_cmp_gt_i32_e32 vcc, s63, v82
	s_waitcnt lgkmcnt(0)
	v_cmp_gt_i32_e64 s[10:11], s63, v140
	v_fmac_f32_e32 v57, 0x3e0293ee, v48
	s_and_b64 vcc, vcc, s[8:9]
	v_cmp_gt_i32_e64 s[14:15], s63, v141
	v_cndmask_b32_e32 v71, v103, v57, vcc
	v_fmac_f32_e32 v58, 0x3e0293ee, v49
	s_and_b64 vcc, s[10:11], s[12:13]
	v_cmp_gt_i32_e64 s[18:19], s63, v139
	v_cmp_lt_i32_e64 s[20:21], -1, v56
	v_cndmask_b32_e32 v84, v103, v58, vcc
	v_fmac_f32_e32 v53, 0x3e0293ee, v50
	s_and_b64 vcc, s[14:15], s[16:17]
	v_cndmask_b32_e32 v70, v103, v53, vcc
	v_fmac_f32_e32 v52, 0x3e0293ee, v51
	s_and_b64 vcc, s[18:19], s[20:21]
	v_max_f32_e32 v50, v128, v129
	v_max_f32_e32 v51, v130, v131
	v_cndmask_b32_e32 v69, v103, v52, vcc
	v_max3_f32 v50, v50, v51, s62
	v_max_f32_e32 v51, v134, v135
	v_max_f32_e32 v52, v136, v137
	v_max3_f32 v50, v51, v52, v50
	v_max_f32_e32 v51, v143, v144
	v_max_f32_e32 v52, v145, v146
	v_max3_f32 v50, v51, v52, v50
	v_max_f32_e32 v51, v150, v151
	v_max_f32_e32 v52, v152, v153
	v_max3_f32 v50, v51, v52, v50
	v_max_f32_e32 v51, v155, v156
	v_max_f32_e32 v52, v157, v158
	v_max3_f32 v50, v51, v52, v50
	v_max_f32_e32 v51, v161, v162
	v_max_f32_e32 v52, v163, v164
	v_max3_f32 v50, v51, v52, v50
	v_max_f32_e32 v51, v167, v168
	v_max_f32_e32 v52, v169, v170
	v_max3_f32 v50, v51, v52, v50
	v_max_f32_e32 v51, v172, v173
	v_max_f32_e32 v52, v174, v175
	v_max3_f32 v50, v51, v52, v50
	v_max_f32_e32 v51, v178, v179
	v_max_f32_e32 v52, v181, v182
	v_max3_f32 v50, v51, v52, v50
	v_max_f32_e32 v51, v184, v185
	v_max_f32_e32 v52, v186, v187
	v_max3_f32 v50, v51, v52, v50
	v_max_f32_e32 v51, v188, v189
	v_max_f32_e32 v52, v190, v191
	v_max3_f32 v50, v51, v52, v50
	v_max_f32_e32 v51, v192, v183
	v_max_f32_e32 v52, v180, v171
	v_max3_f32 v50, v51, v52, v50
	v_max_f32_e32 v51, v177, v176
	v_max_f32_e32 v52, v166, v165
	v_max3_f32 v50, v51, v52, v50
	v_max_f32_e32 v51, v160, v159
	v_max_f32_e32 v52, v149, v148
	v_max3_f32 v50, v51, v52, v50
	v_max_f32_e32 v51, v154, v147
	v_max_f32_e32 v52, v132, v142
	v_max3_f32 v50, v51, v52, v50
	v_max_f32_e32 v51, v71, v84
	v_max_f32_e32 v52, v70, v69
	v_max3_f32 v57, v51, v52, v50
	ds_bpermute_b32 v58, v72, v57
	ds_bpermute_b32 v48, v64, v125
	ds_bpermute_b32 v49, v65, v125
	ds_bpermute_b32 v56, v66, v125
	ds_bpermute_b32 v59, v67, v125
	s_waitcnt lgkmcnt(4)
; #define LAS __attribute__((address_space(3)))
; DI bf16x8 pack8(const f32x4& a, const f32x4& b) { v4u w; w.x = pk2(a[0], a[1]); w.y = pk2(a[2], a[3]); w.z = pk2(b[0], b[1]); w.w = pk2(b[2], b[3]); return __builtin_bit_cast(bf16x8, w); }
; DI void attn_unit_f8(LAS unsigned char* vbuf  , const LAS float* lut2  , const long (&qf)[4], const int* idx, int cnt_, int qpos_, int kvh, const unsigned char* K8, const bf16* VB, bf16* orow, int lane_) {
;     ...
;     {
;         float mx = -3.0e38f;
; #pragma unroll
;         for (int kt = 0; kt < 16; ++kt) mx = fmaxf(fmaxf(fmaxf(lg[kt][0], lg[kt][1]), fmaxf(lg[kt][2], lg[kt][3])), mx);
;         mx = fmaxf(mx, __shfl_xor(mx, 16)); mx = fmaxf(mx, __shfl_xor(mx, 32));
;         float sum = 0.f;
; #pragma unroll
;         for (int kt = 0; kt < 16; ++kt)
; #pragma unroll
;             for (int e = 0; e < 4; ++e) { const float p = __builtin_amdgcn_exp2f(lg[kt][e] - mx); lg[kt][e] = p; sum += p; }
;         sum += __shfl_xor(sum, 16); sum += __shfl_xor(sum, 32);
;         inv = 1.f / sum;
; #pragma unroll
;         for (int ks = 0; ks < 8; ++ks) pf[ks] = pack8(lg[2 * ks], lg[2 * ks + 1]);
;     }
; #pragma unroll
;     for (int dt = 0; dt < 8; ++dt) o[dt] = (f32x4){0.f, 0.f, 0.f, 0.f};
; #pragma unroll
;     for (int hc = 0; hc < 16; ++hc) {
;         asm volatile("" ::: "memory");
;         const int ks = hc >> 1, par = hc & 1;
;         {
;             unsigned w0 = wx0, w1 = wx1, w2 = wx2, w3 = wx3; asm volatile("" : "+v"(w0), "+v"(w1), "+v"(w2), "+v"(w3));
; #pragma unroll
;             for (int q2 = 0; q2 < 4; ++q2) { const int xr = (par + 2 * q2) & 3; const unsigned bs = xr == 0 ? w0 : (xr == 1 ? w1 : (xr == 2 ? w2 : w3));
;                 *(LAS v4u*)(vbuf + bs + (unsigned)((ks & 1) * 8192 + 2048 * q2 + 256 * par)) = ring[(4 * hc + q2) & 15]; }
	v_max_f32_e32 v58, v58, v58
	v_max_f32_e32 v85, v57, v58
	ds_bpermute_b32 v86, v81, v85
	s_waitcnt lgkmcnt(4)
	v_lshl_or_b32 v48, v48, 10, v111
	s_waitcnt lgkmcnt(3)
	v_lshl_or_b32 v49, v49, 10, v111
	s_waitcnt lgkmcnt(2)
	v_lshl_or_b32 v56, v56, 10, v111
	s_waitcnt lgkmcnt(1)
	v_lshl_or_b32 v60, v59, 10, v111
	s_waitcnt lgkmcnt(0)
	v_max_f32_e32 v86, v86, v86
	v_max_f32_e32 v85, v85, v86
	v_sub_f32_e32 v86, v128, v85
	v_exp_f32_e32 v86, v86
	v_sub_f32_e32 v87, v129, v85
	v_exp_f32_e32 v141, v87
	v_sub_f32_e32 v87, v130, v85
	v_exp_f32_e32 v193, v87
	v_sub_f32_e32 v87, v131, v85
	v_exp_f32_e32 v194, v87
	v_sub_f32_e32 v88, v134, v85
	v_add_f32_e32 v87, 0, v86
	v_exp_f32_e32 v195, v88
	v_sub_f32_e32 v88, v135, v85
	v_add_f32_e32 v87, v141, v87
	v_exp_f32_e32 v196, v88
	v_sub_f32_e32 v88, v136, v85
	v_add_f32_e32 v87, v193, v87
	v_exp_f32_e32 v197, v88
	v_sub_f32_e32 v88, v137, v85
	v_add_f32_e32 v87, v194, v87
	v_exp_f32_e32 v198, v88
	v_sub_f32_e32 v88, v143, v85
	v_add_f32_e32 v87, v195, v87
	v_exp_f32_e32 v143, v88
	v_sub_f32_e32 v88, v144, v85
	v_add_f32_e32 v87, v196, v87
	v_exp_f32_e32 v144, v88
	v_sub_f32_e32 v88, v145, v85
	v_add_f32_e32 v87, v197, v87
	v_exp_f32_e32 v145, v88
	v_sub_f32_e32 v88, v146, v85
	v_add_f32_e32 v87, v198, v87
	v_exp_f32_e32 v146, v88
	v_sub_f32_e32 v88, v150, v85
	v_add_f32_e32 v87, v143, v87
	v_exp_f32_e32 v199, v88
	v_sub_f32_e32 v88, v151, v85
	v_add_f32_e32 v87, v144, v87
	v_exp_f32_e32 v200, v88
	v_sub_f32_e32 v88, v152, v85
	v_add_f32_e32 v87, v145, v87
	v_exp_f32_e32 v201, v88
	v_sub_f32_e32 v88, v153, v85
	v_add_f32_e32 v87, v146, v87
	v_exp_f32_e32 v202, v88
	v_sub_f32_e32 v88, v155, v85
	v_add_f32_e32 v87, v199, v87
	v_exp_f32_e32 v155, v88
	v_sub_f32_e32 v88, v156, v85
	v_add_f32_e32 v87, v200, v87
	v_exp_f32_e32 v156, v88
	v_sub_f32_e32 v88, v157, v85
	v_add_f32_e32 v87, v201, v87
	v_exp_f32_e32 v157, v88
	v_sub_f32_e32 v88, v158, v85
	v_add_f32_e32 v87, v202, v87
	v_exp_f32_e32 v158, v88
	v_sub_f32_e32 v88, v161, v85
	global_load_dwordx4 v[52:55], v48, s[46:47]
	s_nop 0
	global_load_dwordx4 v[48:51], v49, s[46:47]
	s_nop 0
	global_load_dwordx4 v[56:59], v56, s[46:47]
	s_nop 0
	global_load_dwordx4 v[60:63], v60, s[46:47]
	v_add_f32_e32 v87, v155, v87
	v_exp_f32_e32 v161, v88
	v_sub_f32_e32 v88, v162, v85
	v_add_f32_e32 v87, v156, v87
	v_exp_f32_e32 v162, v88
	v_sub_f32_e32 v88, v163, v85
	v_add_f32_e32 v87, v157, v87
	v_exp_f32_e32 v163, v88
	v_sub_f32_e32 v88, v164, v85
	v_add_f32_e32 v87, v158, v87
	v_exp_f32_e32 v164, v88
	v_sub_f32_e32 v88, v167, v85
	v_add_f32_e32 v87, v161, v87
	v_exp_f32_e32 v133, v88
	v_sub_f32_e32 v88, v168, v85
	v_add_f32_e32 v87, v162, v87
	v_exp_f32_e32 v135, v88
	v_sub_f32_e32 v88, v169, v85
	v_add_f32_e32 v87, v163, v87
	v_exp_f32_e32 v137, v88
	v_sub_f32_e32 v88, v170, v85
	v_add_f32_e32 v87, v164, v87
	v_exp_f32_e32 v139, v88
	v_sub_f32_e32 v88, v172, v85
	v_add_f32_e32 v87, v133, v87
	v_exp_f32_e32 v134, v88
	v_sub_f32_e32 v88, v173, v85
	v_add_f32_e32 v87, v135, v87
	v_exp_f32_e32 v136, v88
	v_sub_f32_e32 v88, v174, v85
	v_add_f32_e32 v87, v137, v87
	v_exp_f32_e32 v138, v88
	v_sub_f32_e32 v88, v175, v85
	v_add_f32_e32 v87, v139, v87
	v_exp_f32_e32 v140, v88
	v_sub_f32_e32 v88, v178, v85
	v_add_f32_e32 v87, v134, v87
	v_exp_f32_e32 v91, v88
	v_sub_f32_e32 v88, v179, v85
	v_lshl_add_u32 v68, v126, 4, v127
	v_add_f32_e32 v87, v136, v87
	v_exp_f32_e32 v126, v88
	v_sub_f32_e32 v88, v181, v85
	v_add_f32_e32 v87, v138, v87
	v_exp_f32_e32 v128, v88
	v_sub_f32_e32 v88, v182, v85
	v_add_f32_e32 v87, v140, v87
	v_exp_f32_e32 v130, v88
	v_sub_f32_e32 v88, v184, v85
	v_add_f32_e32 v87, v91, v87
	v_exp_f32_e32 v125, v88
	v_sub_f32_e32 v88, v185, v85
	v_add_f32_e32 v87, v126, v87
	v_exp_f32_e32 v127, v88
	v_sub_f32_e32 v88, v186, v85
	v_add_f32_e32 v87, v128, v87
	v_exp_f32_e32 v129, v88
	v_sub_f32_e32 v88, v187, v85
	v_add_f32_e32 v87, v130, v87
	v_exp_f32_e32 v131, v88
	v_add_f32_e32 v87, v125, v87
	v_add_f32_e32 v87, v127, v87
	v_add_f32_e32 v87, v129, v87
	v_add_f32_e32 v150, v131, v87
	v_sub_f32_e32 v87, v188, v85
	v_exp_f32_e32 v87, v87
	v_sub_f32_e32 v88, v189, v85
	v_exp_f32_e32 v88, v88
	v_sub_f32_e32 v89, v190, v85
	v_exp_f32_e32 v89, v89
	v_sub_f32_e32 v90, v191, v85
	v_exp_f32_e32 v90, v90
	v_add_f32_e32 v150, v87, v150
	v_add_f32_e32 v150, v88, v150
	v_add_f32_e32 v150, v89, v150
	v_or_b32_e32 v107, v123, v124
	v_bitop3_b32 v108, v123, 32, v124 bitop3:0x36
	v_bitop3_b32 v109, v123, 16, v124 bitop3:0x36
	v_add_f32_e32 v167, v90, v150
	v_cvt_pk_bf16_f32 v150, v86, v141
	v_bitop3_b32 v86, v123, 48, v124 bitop3:0x36
	v_mov_b32_e32 v123, v107
	v_mov_b32_e32 v124, v108
	v_mov_b32_e32 v141, v109
	v_mov_b32_e32 v169, v86
	v_sub_f32_e32 v168, v192, v85
	v_add_u32_e32 v123, s30, v123
	s_waitcnt vmcnt(15)
	ds_write_b128 v123, v[12:15]
	v_add_u32_e32 v12, s30, v124
	ds_bpermute_b32 v13, v64, v122
	s_waitcnt vmcnt(14)
	ds_write_b128 v12, v[4:7] offset:2048
	s_waitcnt vmcnt(13)
	ds_write_b128 v123, v[8:11] offset:4096
	ds_bpermute_b32 v4, v65, v122
	s_waitcnt vmcnt(12)
	ds_write_b128 v12, v[0:3] offset:6144
	ds_bpermute_b32 v1, v66, v122
	ds_bpermute_b32 v2, v67, v122
	s_waitcnt lgkmcnt(6)
	v_lshl_or_b32 v0, v13, 10, v111
	s_waitcnt lgkmcnt(3)
	v_lshl_or_b32 v3, v4, 10, v111
	global_load_dwordx4 v[4:7], v0, s[46:47]
	global_load_dwordx4 v[8:11], v3, s[46:47]
	s_waitcnt lgkmcnt(1)
	v_lshl_or_b32 v0, v1, 10, v111
	s_waitcnt lgkmcnt(0)
	v_lshl_or_b32 v1, v2, 10, v111
	global_load_dwordx4 v[12:15], v0, s[46:47]
	global_load_dwordx4 v[172:175], v1, s[46:47]
	v_mov_b32_e32 v0, v107
	v_mov_b32_e32 v1, v108
	v_mov_b32_e32 v2, v109
	v_mov_b32_e32 v3, v86
	v_mov_b32_e32 v122, v106
	v_add_u32_e32 v0, s30, v2
	v_add_u32_e32 v1, s30, v3
	s_waitcnt vmcnt(15)
; #define LAS __attribute__((address_space(3)))
; #define LDS_WAIT() asm volatile("s_waitcnt lgkmcnt(0)" ::: "memory")
; #define A8_ISSUE_V(hc) do { _Pragma("unroll") for (int q2_ = 0; q2_ < 4; ++q2_) { const int rid_ = __shfl(R[hc], 4 * q2_ + g); \
;         ring[(4 * (hc) + q2_) & 15] = *(const v4u*)((const char*)VB + (unsigned)(rid_ * 1024 + kvh * 256 + 16 * lr)); } } while (0)
; #define A8_TRP(OFF) asm volatile("ds_read_b64_tr_b16 %0, %4 offset:" #OFF "\n\tds_read_b64_tr_b16 %1, %5 offset:" #OFF "\n\tds_read_b64_tr_b16 %2, %6 offset:" #OFF "\n\tds_read_b64_tr_b16 %3, %7 offset:" #OFF "\n\ts_waitcnt lgkmcnt(0)" \
;                 : "=&v"(r0), "=&v"(r1), "=&v"(r2), "=&v"(r3) : "v"(tE), "v"(tEb), "v"(tO), "v"(tOb) : "memory")
; DI void attn_unit_f8(LAS unsigned char* vbuf  , const LAS float* lut2  , const long (&qf)[4], const int* idx, int cnt_, int qpos_, int kvh, const unsigned char* K8, const bf16* VB, bf16* orow, int lane_) {
;     ...
;     for (int hc = 0; hc < 16; ++hc) {
;         asm volatile("" ::: "memory");
;         const int ks = hc >> 1, par = hc & 1;
;         {
;             unsigned w0 = wx0, w1 = wx1, w2 = wx2, w3 = wx3; asm volatile("" : "+v"(w0), "+v"(w1), "+v"(w2), "+v"(w3));
; #pragma unroll
;             for (int q2 = 0; q2 < 4; ++q2) { const int xr = (par + 2 * q2) & 3; const unsigned bs = xr == 0 ? w0 : (xr == 1 ? w1 : (xr == 2 ? w2 : w3));
;                 *(LAS v4u*)(vbuf + bs + (unsigned)((ks & 1) * 8192 + 2048 * q2 + 256 * par)) = ring[(4 * hc + q2) & 15]; }
;         }
;         if (par == 1) {
;             LDS_WAIT(); asm volatile("" ::: "memory");
;             s16x4 r0, r1, r2, r3; bf16x8 va, vb2;
;     ...
;             unsigned tE = te, tEb = teb, tO = to, tOb = tob; asm volatile("" : "+v"(tE), "+v"(tEb), "+v"(tO), "+v"(tOb));
;     ...
;             if ((ks & 1) == 0) { A8_TRP(0); A8_PV(0); A8_TRP(512); A8_PV(2); A8_TRP(1024); A8_PV(4); A8_TRP(1536); A8_PV(6); }
;             else { A8_TRP(8192); A8_PV(0); A8_TRP(8704); A8_PV(2); A8_TRP(9216); A8_PV(4); A8_TRP(9728); A8_PV(6); }
;     ...
;         }
;         if (hc + 4 < 16) A8_ISSUE_V(hc + 4);
	ds_write_b128 v0, v[20:23] offset:256
	s_waitcnt vmcnt(14)
	ds_write_b128 v1, v[16:19] offset:2304
	s_waitcnt vmcnt(13)
	ds_write_b128 v0, v[24:27] offset:4352
	s_waitcnt vmcnt(12)
	ds_write_b128 v1, v[28:31] offset:6400
	s_waitcnt lgkmcnt(0)
	v_mov_b32_e32 v123, v104
	v_mov_b32_e32 v124, v105
	v_mov_b32_e32 v141, v68
	v_cvt_pk_bf16_f32 v151, v193, v194
	v_cvt_pk_bf16_f32 v152, v195, v196
	v_cvt_pk_bf16_f32 v153, v197, v198
	v_cvt_pk_bf16_f32 v188, v199, v200
	ds_read_b64_tr_b16 v[0:1], v123 offset:0
	ds_read_b64_tr_b16 v[2:3], v141 offset:0
	ds_read_b64_tr_b16 v[16:17], v124 offset:0
	ds_read_b64_tr_b16 v[18:19], v122 offset:0
	s_waitcnt lgkmcnt(0)
	ds_read_b64_tr_b16 v[28:29], v123 offset:512
	ds_read_b64_tr_b16 v[30:31], v141 offset:512
	ds_read_b64_tr_b16 v[24:25], v124 offset:512
	ds_read_b64_tr_b16 v[26:27], v122 offset:512
	s_waitcnt lgkmcnt(0)
	v_cvt_pk_bf16_f32 v189, v201, v202
	v_mfma_f32_16x16x32_bf16 v[20:23], v[0:3], v[150:153], 0
	v_exp_f32_e32 v0, v168
	v_sub_f32_e32 v1, v183, v85
	v_exp_f32_e32 v1, v1
	v_mfma_f32_16x16x32_bf16 v[16:19], v[16:19], v[150:153], 0
	v_add_f32_e32 v2, v0, v167
	v_cvt_pk_bf16_f32 v186, v143, v144
	v_add_f32_e32 v3, v1, v2
	v_sub_f32_e32 v2, v180, v85
	ds_read_b64_tr_b16 v[182:183], v123 offset:1024
	ds_read_b64_tr_b16 v[184:185], v141 offset:1024
	ds_read_b64_tr_b16 v[178:179], v124 offset:1024
	ds_read_b64_tr_b16 v[180:181], v122 offset:1024
	s_waitcnt lgkmcnt(0)
	ds_read_b64_tr_b16 v[194:195], v123 offset:1536
	ds_read_b64_tr_b16 v[196:197], v141 offset:1536
	ds_read_b64_tr_b16 v[190:191], v124 offset:1536
	ds_read_b64_tr_b16 v[192:193], v122 offset:1536
	s_waitcnt lgkmcnt(0)
	ds_bpermute_b32 v122, v64, v121
	ds_bpermute_b32 v123, v65, v121
	ds_bpermute_b32 v124, v66, v121
	ds_bpermute_b32 v121, v67, v121
	v_mfma_f32_16x16x32_bf16 v[28:31], v[28:31], v[150:153], 0
	s_waitcnt lgkmcnt(3)
	v_lshl_or_b32 v122, v122, 10, v111
	s_waitcnt lgkmcnt(2)
	v_lshl_or_b32 v123, v123, 10, v111
	v_mov_b32_e32 v141, v68
	v_mfma_f32_16x16x32_bf16 v[24:27], v[24:27], v[150:153], 0
	s_waitcnt lgkmcnt(0)
	v_lshl_or_b32 v121, v121, 10, v111
	v_cvt_pk_bf16_f32 v187, v145, v146
	ds_bpermute_b32 v146, v66, v118
	v_mfma_f32_16x16x32_bf16 v[182:185], v[182:185], v[150:153], 0
	v_exp_f32_e32 v2, v2
	v_sub_f32_e32 v145, v176, v85
	v_exp_f32_e32 v145, v145
	v_mfma_f32_16x16x32_bf16 v[178:181], v[178:181], v[150:153], 0
	v_add_f32_e32 v3, v2, v3
	v_cvt_pk_bf16_f32 v88, v87, v88
	ds_bpermute_b32 v87, v64, v113
	v_mfma_f32_16x16x32_bf16 v[194:197], v[194:197], v[150:153], 0
	v_cvt_pk_bf16_f32 v89, v89, v90
	v_cvt_pk_bf16_f32 v90, v0, v1
	ds_bpermute_b32 v0, v65, v113
	v_mfma_f32_16x16x32_bf16 v[150:153], v[190:193], v[150:153], 0
	global_load_dwordx4 v[190:193], v122, s[46:47]
	global_load_dwordx4 v[198:201], v123, s[46:47]
	v_lshl_or_b32 v122, v124, 10, v111
	global_load_dwordx4 v[202:205], v122, s[46:47]
	global_load_dwordx4 v[206:209], v121, s[46:47]
	v_mov_b32_e32 v121, v107
	v_mov_b32_e32 v122, v108
	v_mov_b32_e32 v123, v109
	v_mov_b32_e32 v124, v86
	s_waitcnt lgkmcnt(1)
	v_lshl_or_b32 v1, v87, 10, v111
	v_add_u32_e32 v121, s30, v121
	s_waitcnt vmcnt(15)
	ds_write_b128 v121, v[44:47] offset:8192
	v_add_u32_e32 v44, s30, v122
	ds_bpermute_b32 v45, v64, v120
	s_waitcnt vmcnt(14)
	ds_write_b128 v44, v[36:39] offset:10240
	s_waitcnt vmcnt(13)
	ds_write_b128 v121, v[40:43] offset:12288
	ds_bpermute_b32 v36, v65, v120
	ds_bpermute_b32 v40, v66, v120
	ds_bpermute_b32 v41, v67, v120
	s_waitcnt vmcnt(12)
	ds_write_b128 v44, v[32:35] offset:14336
	s_waitcnt lgkmcnt(6)
	v_lshl_or_b32 v32, v45, 10, v111
	s_waitcnt lgkmcnt(3)
	v_lshl_or_b32 v36, v36, 10, v111
	s_waitcnt lgkmcnt(2)
	v_lshl_or_b32 v40, v40, 10, v111
	s_waitcnt lgkmcnt(1)
	v_lshl_or_b32 v44, v41, 10, v111
	v_mov_b32_e32 v120, v107
	v_mov_b32_e32 v121, v108
	v_mov_b32_e32 v122, v109
	v_mov_b32_e32 v123, v86
	global_load_dwordx4 v[32:35], v32, s[46:47]
	s_nop 0
	global_load_dwordx4 v[36:39], v36, s[46:47]
	s_nop 0
	global_load_dwordx4 v[40:43], v40, s[46:47]
	s_nop 0
	global_load_dwordx4 v[44:47], v44, s[46:47]
	v_mov_b32_e32 v124, v105
	v_add_u32_e32 v120, s30, v122
	s_waitcnt vmcnt(15)
	ds_write_b128 v120, v[52:55] offset:8448
	v_add_u32_e32 v52, s30, v123
	s_waitcnt vmcnt(14)
	ds_write_b128 v52, v[48:51] offset:10496
	s_waitcnt vmcnt(13)
	ds_write_b128 v120, v[56:59] offset:12544
	s_waitcnt vmcnt(12)
	ds_write_b128 v52, v[60:63] offset:14592
	s_waitcnt lgkmcnt(0)
	v_mov_b32_e32 v58, v106
	v_mov_b32_e32 v59, v104
	v_cvt_pk_bf16_f32 v56, v155, v156
	ds_read_b64_tr_b16 v[52:53], v59 offset:8192
	ds_read_b64_tr_b16 v[54:55], v141 offset:8192
	ds_read_b64_tr_b16 v[48:49], v124 offset:8192
	ds_read_b64_tr_b16 v[50:51], v58 offset:8192
	s_waitcnt lgkmcnt(0)
	v_mov_b32_e32 v155, v68
	v_mfma_f32_16x16x32_bf16 v[20:23], v[52:55], v[186:189], v[20:23]
	v_sub_f32_e32 v52, v171, v85
	v_exp_f32_e32 v143, v52
	v_cvt_pk_bf16_f32 v57, v157, v158
	v_mfma_f32_16x16x32_bf16 v[16:19], v[48:51], v[186:189], v[16:19]
	ds_read_b64_tr_b16 v[52:53], v59 offset:8704
	ds_read_b64_tr_b16 v[54:55], v141 offset:8704
	ds_read_b64_tr_b16 v[48:49], v124 offset:8704
	ds_read_b64_tr_b16 v[50:51], v58 offset:8704
	s_waitcnt lgkmcnt(0)
	v_add_f32_e32 v144, v143, v3
	v_sub_f32_e32 v3, v177, v85
	v_mfma_f32_16x16x32_bf16 v[28:31], v[52:55], v[186:189], v[28:31]
	v_sub_f32_e32 v156, v165, v85
	v_exp_f32_e32 v3, v3
	ds_bpermute_b32 v87, v67, v113
	v_mfma_f32_16x16x32_bf16 v[24:27], v[48:51], v[186:189], v[24:27]
	ds_read_b64_tr_b16 v[52:53], v59 offset:9216
	ds_read_b64_tr_b16 v[54:55], v141 offset:9216
	ds_read_b64_tr_b16 v[48:49], v124 offset:9216
	ds_read_b64_tr_b16 v[50:51], v58 offset:9216
	s_waitcnt lgkmcnt(0)
; #define LAS __attribute__((address_space(3)))
; #define LDS_WAIT() asm volatile("s_waitcnt lgkmcnt(0)" ::: "memory")
; #define A8_ISSUE_V(hc) do { _Pragma("unroll") for (int q2_ = 0; q2_ < 4; ++q2_) { const int rid_ = __shfl(R[hc], 4 * q2_ + g); \
;         ring[(4 * (hc) + q2_) & 15] = *(const v4u*)((const char*)VB + (unsigned)(rid_ * 1024 + kvh * 256 + 16 * lr)); } } while (0)
; #define A8_TRP(OFF) asm volatile("ds_read_b64_tr_b16 %0, %4 offset:" #OFF "\n\tds_read_b64_tr_b16 %1, %5 offset:" #OFF "\n\tds_read_b64_tr_b16 %2, %6 offset:" #OFF "\n\tds_read_b64_tr_b16 %3, %7 offset:" #OFF "\n\ts_waitcnt lgkmcnt(0)" \
;                 : "=&v"(r0), "=&v"(r1), "=&v"(r2), "=&v"(r3) : "v"(tE), "v"(tEb), "v"(tO), "v"(tOb) : "memory")
; DI void attn_unit_f8(LAS unsigned char* vbuf  , const LAS float* lut2  , const long (&qf)[4], const int* idx, int cnt_, int qpos_, int kvh, const unsigned char* K8, const bf16* VB, bf16* orow, int lane_) {
;     ...
;     for (int hc = 0; hc < 16; ++hc) {
;         asm volatile("" ::: "memory");
;         const int ks = hc >> 1, par = hc & 1;
;         {
;             unsigned w0 = wx0, w1 = wx1, w2 = wx2, w3 = wx3; asm volatile("" : "+v"(w0), "+v"(w1), "+v"(w2), "+v"(w3));
; #pragma unroll
;             for (int q2 = 0; q2 < 4; ++q2) { const int xr = (par + 2 * q2) & 3; const unsigned bs = xr == 0 ? w0 : (xr == 1 ? w1 : (xr == 2 ? w2 : w3));
;                 *(LAS v4u*)(vbuf + bs + (unsigned)((ks & 1) * 8192 + 2048 * q2 + 256 * par)) = ring[(4 * hc + q2) & 15]; }
;         }
;         if (par == 1) {
;             LDS_WAIT(); asm volatile("" ::: "memory");
;             s16x4 r0, r1, r2, r3; bf16x8 va, vb2;
;     ...
;             unsigned tE = te, tEb = teb, tO = to, tOb = tob; asm volatile("" : "+v"(tE), "+v"(tEb), "+v"(tO), "+v"(tOb));
;     ...
;             if ((ks & 1) == 0) { A8_TRP(0); A8_PV(0); A8_TRP(512); A8_PV(2); A8_TRP(1024); A8_PV(4); A8_TRP(1536); A8_PV(6); }
;             else { A8_TRP(8192); A8_PV(0); A8_TRP(8704); A8_PV(2); A8_TRP(9216); A8_PV(4); A8_TRP(9728); A8_PV(6); }
;     ...
;         }
;         if (hc + 4 < 16) A8_ISSUE_V(hc + 4);
	ds_read_b64_tr_b16 v[120:121], v59 offset:9728
	ds_read_b64_tr_b16 v[122:123], v141 offset:9728
	ds_read_b64_tr_b16 v[60:61], v124 offset:9728
	ds_read_b64_tr_b16 v[62:63], v58 offset:9728
	s_waitcnt lgkmcnt(0)
	ds_bpermute_b32 v124, v64, v118
	ds_bpermute_b32 v141, v65, v118
	ds_bpermute_b32 v118, v67, v118
	v_mfma_f32_16x16x32_bf16 v[60:63], v[60:63], v[186:189], v[150:153]
	v_cvt_pk_bf16_f32 v58, v161, v162
	s_waitcnt lgkmcnt(2)
	v_lshl_or_b32 v124, v124, 10, v111
	s_waitcnt lgkmcnt(1)
	v_lshl_or_b32 v141, v141, 10, v111
	global_load_dwordx4 v[150:153], v124, s[46:47]
	global_load_dwordx4 v[168:171], v141, s[46:47]
	v_lshl_or_b32 v124, v146, 10, v111
	v_mfma_f32_16x16x32_bf16 v[52:55], v[52:55], v[186:189], v[182:185]
	s_waitcnt lgkmcnt(0)
	v_lshl_or_b32 v118, v118, 10, v111
	v_mov_b32_e32 v141, v109
	v_mov_b32_e32 v146, v86
	v_mfma_f32_16x16x32_bf16 v[48:51], v[48:51], v[186:189], v[178:181]
	s_nop 2
	global_load_dwordx4 v[176:179], v124, s[46:47]
	global_load_dwordx4 v[180:183], v118, s[46:47]
	v_mov_b32_e32 v118, v107
	v_mov_b32_e32 v124, v108
	v_mfma_f32_16x16x32_bf16 v[120:123], v[120:123], v[186:189], v[194:197]
	v_add_u32_e32 v118, s30, v118
	s_waitcnt vmcnt(15)
	ds_write_b128 v118, v[4:7]
	v_add_u32_e32 v4, s30, v124
	ds_bpermute_b32 v5, v64, v119
	s_waitcnt vmcnt(14)
	ds_write_b128 v4, v[8:11] offset:2048
	s_waitcnt vmcnt(13)
	ds_write_b128 v118, v[12:15] offset:4096
	ds_bpermute_b32 v6, v65, v119
	ds_bpermute_b32 v12, v66, v119
	ds_bpermute_b32 v13, v67, v119
	s_waitcnt vmcnt(12)
	ds_write_b128 v4, v[172:175] offset:6144
	s_waitcnt lgkmcnt(6)
	v_lshl_or_b32 v4, v5, 10, v111
	s_waitcnt lgkmcnt(3)
	v_lshl_or_b32 v8, v6, 10, v111
	s_waitcnt lgkmcnt(2)
	v_lshl_or_b32 v12, v12, 10, v111
	s_waitcnt lgkmcnt(1)
	v_lshl_or_b32 v118, v13, 10, v111
	global_load_dwordx4 v[4:7], v4, s[46:47]
	s_nop 0
	global_load_dwordx4 v[8:11], v8, s[46:47]
	s_nop 0
	global_load_dwordx4 v[12:15], v12, s[46:47]
	s_nop 0
	global_load_dwordx4 v[172:175], v118, s[46:47]
	v_mov_b32_e32 v118, v107
	v_mov_b32_e32 v119, v108
	v_mov_b32_e32 v124, v109
	v_mov_b32_e32 v141, v86
	v_mov_b32_e32 v146, v105
	v_add_u32_e32 v118, s30, v124
	v_add_u32_e32 v119, s30, v141
	s_waitcnt vmcnt(15)
	ds_write_b128 v118, v[190:193] offset:256
	s_waitcnt vmcnt(14)
	ds_write_b128 v119, v[198:201] offset:2304
	s_waitcnt vmcnt(13)
	ds_write_b128 v118, v[202:205] offset:4352
	s_waitcnt vmcnt(12)
	ds_write_b128 v119, v[206:209] offset:6400
	s_waitcnt lgkmcnt(0)
	v_mov_b32_e32 v124, v106
	v_mov_b32_e32 v141, v104
	v_cvt_pk_bf16_f32 v59, v163, v164
	v_sub_f32_e32 v118, v166, v85
	ds_read_b64_tr_b16 v[188:189], v141 offset:0
	ds_read_b64_tr_b16 v[190:191], v155 offset:0
	ds_read_b64_tr_b16 v[184:185], v146 offset:0
	ds_read_b64_tr_b16 v[186:187], v124 offset:0
	s_waitcnt lgkmcnt(0)
	v_exp_f32_e32 v161, v118
	v_mfma_f32_16x16x32_bf16 v[20:23], v[188:191], v[56:59], v[20:23]
	v_add_f32_e32 v118, v3, v144
	v_add_f32_e32 v118, v145, v118
	v_add_f32_e32 v144, v161, v118
	v_mfma_f32_16x16x32_bf16 v[16:19], v[184:187], v[56:59], v[16:19]
	ds_read_b64_tr_b16 v[188:189], v141 offset:512
	ds_read_b64_tr_b16 v[190:191], v155 offset:512
	ds_read_b64_tr_b16 v[184:185], v146 offset:512
	ds_read_b64_tr_b16 v[186:187], v124 offset:512
	s_waitcnt lgkmcnt(0)
	v_cvt_pk_bf16_f32 v118, v133, v135
	v_cvt_pk_bf16_f32 v119, v137, v139
	v_mfma_f32_16x16x32_bf16 v[28:31], v[188:191], v[56:59], v[28:31]
	v_mov_b32_e32 v133, v68
	v_lshl_or_b32 v0, v0, 10, v111
	v_cmp_gt_u32_e32 vcc, 4, v83
	v_mfma_f32_16x16x32_bf16 v[24:27], v[184:187], v[56:59], v[24:27]
	ds_read_b64_tr_b16 v[188:189], v141 offset:1024
	ds_read_b64_tr_b16 v[190:191], v155 offset:1024
	ds_read_b64_tr_b16 v[184:185], v146 offset:1024
	ds_read_b64_tr_b16 v[186:187], v124 offset:1024
	s_waitcnt lgkmcnt(0)
	s_nop 0
	v_mfma_f32_16x16x32_bf16 v[48:51], v[184:187], v[56:59], v[48:51]
	ds_read_b64_tr_b16 v[184:185], v141 offset:1536
	ds_read_b64_tr_b16 v[186:187], v155 offset:1536
	ds_read_b64_tr_b16 v[162:163], v146 offset:1536
	ds_read_b64_tr_b16 v[164:165], v124 offset:1536
	s_waitcnt lgkmcnt(0)
	v_mov_b32_e32 v124, v86
	v_exp_f32_e32 v146, v156
	v_mfma_f32_16x16x32_bf16 v[184:187], v[184:187], v[56:59], v[120:123]
	s_nop 2
	ds_bpermute_b32 v122, v64, v117
	v_mfma_f32_16x16x32_bf16 v[52:55], v[188:191], v[56:59], v[52:55]
	ds_bpermute_b32 v123, v65, v117
	v_cvt_pk_bf16_f32 v120, v134, v136
	v_cvt_pk_bf16_f32 v121, v138, v140
	v_mfma_f32_16x16x32_bf16 v[56:59], v[162:165], v[56:59], v[60:63]
	s_waitcnt lgkmcnt(0)
	v_lshl_or_b32 v123, v123, 10, v111
	s_nop 0
	v_lshl_or_b32 v60, v122, 10, v111
	ds_bpermute_b32 v122, v66, v117
	ds_bpermute_b32 v117, v67, v117
	global_load_dwordx4 v[60:63], v60, s[46:47]
	s_nop 0
	global_load_dwordx4 v[134:137], v123, s[46:47]
	v_mov_b32_e32 v123, v109
	s_waitcnt lgkmcnt(1)
	v_lshl_or_b32 v122, v122, 10, v111
	s_waitcnt lgkmcnt(0)
	v_lshl_or_b32 v117, v117, 10, v111
	global_load_dwordx4 v[138:141], v122, s[46:47]
	global_load_dwordx4 v[162:165], v117, s[46:47]
	v_mov_b32_e32 v117, v107
	v_mov_b32_e32 v122, v108
	s_nop 0
	v_add_u32_e32 v117, s30, v117
	s_waitcnt vmcnt(15)
	ds_write_b128 v117, v[32:35] offset:8192
	v_add_u32_e32 v32, s30, v122
	ds_bpermute_b32 v33, v64, v116
	s_waitcnt vmcnt(14)
	ds_write_b128 v32, v[36:39] offset:10240
	s_waitcnt vmcnt(13)
	ds_write_b128 v117, v[40:43] offset:12288
	ds_bpermute_b32 v34, v65, v116
	ds_bpermute_b32 v40, v66, v116
	ds_bpermute_b32 v41, v67, v116
	s_waitcnt vmcnt(12)
	ds_write_b128 v32, v[44:47] offset:14336
	s_waitcnt lgkmcnt(6)
	v_lshl_or_b32 v32, v33, 10, v111
	s_waitcnt lgkmcnt(3)
	v_lshl_or_b32 v36, v34, 10, v111
	s_waitcnt lgkmcnt(2)
	v_lshl_or_b32 v40, v40, 10, v111
	s_waitcnt lgkmcnt(1)
; #define LAS __attribute__((address_space(3)))
; #define LDS_WAIT() asm volatile("s_waitcnt lgkmcnt(0)" ::: "memory")
; #define A8_ISSUE_V(hc) do { _Pragma("unroll") for (int q2_ = 0; q2_ < 4; ++q2_) { const int rid_ = __shfl(R[hc], 4 * q2_ + g); \
;         ring[(4 * (hc) + q2_) & 15] = *(const v4u*)((const char*)VB + (unsigned)(rid_ * 1024 + kvh * 256 + 16 * lr)); } } while (0)
; #define A8_TRP(OFF) asm volatile("ds_read_b64_tr_b16 %0, %4 offset:" #OFF "\n\tds_read_b64_tr_b16 %1, %5 offset:" #OFF "\n\tds_read_b64_tr_b16 %2, %6 offset:" #OFF "\n\tds_read_b64_tr_b16 %3, %7 offset:" #OFF "\n\ts_waitcnt lgkmcnt(0)" \
;                 : "=&v"(r0), "=&v"(r1), "=&v"(r2), "=&v"(r3) : "v"(tE), "v"(tEb), "v"(tO), "v"(tOb) : "memory")
; DI void attn_unit_f8(LAS unsigned char* vbuf  , const LAS float* lut2  , const long (&qf)[4], const int* idx, int cnt_, int qpos_, int kvh, const unsigned char* K8, const bf16* VB, bf16* orow, int lane_) {
;     ...
;     for (int hc = 0; hc < 16; ++hc) {
;         asm volatile("" ::: "memory");
;         const int ks = hc >> 1, par = hc & 1;
;         {
;             unsigned w0 = wx0, w1 = wx1, w2 = wx2, w3 = wx3; asm volatile("" : "+v"(w0), "+v"(w1), "+v"(w2), "+v"(w3));
; #pragma unroll
;             for (int q2 = 0; q2 < 4; ++q2) { const int xr = (par + 2 * q2) & 3; const unsigned bs = xr == 0 ? w0 : (xr == 1 ? w1 : (xr == 2 ? w2 : w3));
;                 *(LAS v4u*)(vbuf + bs + (unsigned)((ks & 1) * 8192 + 2048 * q2 + 256 * par)) = ring[(4 * hc + q2) & 15]; }
;         }
;         if (par == 1) {
;             LDS_WAIT(); asm volatile("" ::: "memory");
;             s16x4 r0, r1, r2, r3; bf16x8 va, vb2;
;     ...
;             unsigned tE = te, tEb = teb, tO = to, tOb = tob; asm volatile("" : "+v"(tE), "+v"(tEb), "+v"(tO), "+v"(tOb));
;     ...
;             if ((ks & 1) == 0) { A8_TRP(0); A8_PV(0); A8_TRP(512); A8_PV(2); A8_TRP(1024); A8_PV(4); A8_TRP(1536); A8_PV(6); }
;             else { A8_TRP(8192); A8_PV(0); A8_TRP(8704); A8_PV(2); A8_TRP(9216); A8_PV(4); A8_TRP(9728); A8_PV(6); }
;     ...
;         }
;         if (hc + 4 < 16) A8_ISSUE_V(hc + 4);
	v_lshl_or_b32 v44, v41, 10, v111
	v_mov_b32_e32 v116, v107
	v_mov_b32_e32 v117, v108
	v_mov_b32_e32 v122, v109
	v_mov_b32_e32 v123, v86
	global_load_dwordx4 v[32:35], v32, s[46:47]
	s_nop 0
	global_load_dwordx4 v[36:39], v36, s[46:47]
	s_nop 0
	global_load_dwordx4 v[40:43], v40, s[46:47]
	s_nop 0
	global_load_dwordx4 v[44:47], v44, s[46:47]
	v_mov_b32_e32 v124, v105
	v_add_u32_e32 v116, s30, v122
	v_add_u32_e32 v117, s30, v123
	v_sub_f32_e32 v122, v160, v85
	s_waitcnt vmcnt(15)
	ds_write_b128 v116, v[150:153] offset:8448
	s_waitcnt vmcnt(14)
	ds_write_b128 v117, v[168:171] offset:10496
	s_waitcnt vmcnt(13)
	ds_write_b128 v116, v[176:179] offset:12544
	s_waitcnt vmcnt(12)
	ds_write_b128 v117, v[180:183] offset:14592
	v_exp_f32_e32 v160, v122
	s_waitcnt lgkmcnt(0)
	v_mov_b32_e32 v116, v106
	v_mov_b32_e32 v117, v104
	v_add_f32_e32 v122, v146, v144
	ds_read_b64_tr_b16 v[166:167], v117 offset:8192
	ds_read_b64_tr_b16 v[168:169], v133 offset:8192
	ds_read_b64_tr_b16 v[150:151], v124 offset:8192
	ds_read_b64_tr_b16 v[152:153], v116 offset:8192
	s_waitcnt lgkmcnt(0)
	v_add_f32_e32 v144, v160, v122
	v_mfma_f32_16x16x32_bf16 v[20:23], v[166:169], v[118:121], v[20:23]
	v_sub_f32_e32 v122, v159, v85
	v_exp_f32_e32 v176, v122
	v_cvt_pk_bf16_f32 v122, v91, v126
	v_mfma_f32_16x16x32_bf16 v[16:19], v[150:153], v[118:121], v[16:19]
	ds_read_b64_tr_b16 v[166:167], v117 offset:8704
	ds_read_b64_tr_b16 v[168:169], v133 offset:8704
	ds_read_b64_tr_b16 v[150:151], v124 offset:8704
	ds_read_b64_tr_b16 v[152:153], v116 offset:8704
	s_waitcnt lgkmcnt(0)
	ds_bpermute_b32 v91, v64, v115
	v_cvt_pk_bf16_f32 v123, v128, v130
	v_mfma_f32_16x16x32_bf16 v[24:27], v[150:153], v[118:121], v[24:27]
	ds_read_b64_tr_b16 v[156:157], v117 offset:9216
	ds_read_b64_tr_b16 v[158:159], v133 offset:9216
	ds_read_b64_tr_b16 v[150:151], v124 offset:9216
	ds_read_b64_tr_b16 v[152:153], v116 offset:9216
	s_waitcnt lgkmcnt(0)
	v_sub_f32_e32 v130, v149, v85
	s_waitcnt lgkmcnt(0)
	v_lshl_or_b32 v91, v91, 10, v111
	v_mfma_f32_16x16x32_bf16 v[52:55], v[156:159], v[118:121], v[52:55]
	v_exp_f32_e32 v130, v130
	v_mfma_f32_16x16x32_bf16 v[48:51], v[150:153], v[118:121], v[48:51]
	ds_read_b64_tr_b16 v[156:157], v117 offset:9728
	ds_read_b64_tr_b16 v[158:159], v133 offset:9728
	ds_read_b64_tr_b16 v[150:151], v124 offset:9728
	ds_read_b64_tr_b16 v[152:153], v116 offset:9728
	s_waitcnt lgkmcnt(0)
	ds_bpermute_b32 v116, v65, v115
	v_cvt_pk_bf16_f32 v124, v125, v127
	v_mfma_f32_16x16x32_bf16 v[28:31], v[166:169], v[118:121], v[28:31]
	v_cvt_pk_bf16_f32 v125, v129, v131
	v_mfma_f32_16x16x32_bf16 v[156:159], v[156:159], v[118:121], v[184:187]
	v_mfma_f32_16x16x32_bf16 v[56:59], v[150:153], v[118:121], v[56:59]
	ds_bpermute_b32 v120, v66, v115
	ds_bpermute_b32 v115, v67, v115
	s_waitcnt lgkmcnt(2)
	v_lshl_or_b32 v121, v116, 10, v111
	global_load_dwordx4 v[116:119], v91, s[46:47]
	global_load_dwordx4 v[126:129], v121, s[46:47]
	v_mov_b32_e32 v121, v86
	s_waitcnt lgkmcnt(1)
	v_lshl_or_b32 v91, v120, 10, v111
	s_waitcnt lgkmcnt(0)
	v_lshl_or_b32 v115, v115, 10, v111
	global_load_dwordx4 v[150:153], v91, s[46:47]
	global_load_dwordx4 v[166:169], v115, s[46:47]
	v_mov_b32_e32 v91, v107
	v_mov_b32_e32 v115, v108
	v_mov_b32_e32 v120, v109
	s_nop 0
	v_add_u32_e32 v91, s30, v91
	s_waitcnt vmcnt(15)
	ds_write_b128 v91, v[4:7]
	v_add_u32_e32 v4, s30, v115
	ds_bpermute_b32 v5, v64, v114
	s_waitcnt vmcnt(14)
	ds_write_b128 v4, v[8:11] offset:2048
	s_waitcnt vmcnt(13)
	ds_write_b128 v91, v[12:15] offset:4096
	ds_bpermute_b32 v6, v65, v114
	ds_bpermute_b32 v12, v66, v114
	ds_bpermute_b32 v13, v67, v114
	s_waitcnt vmcnt(12)
	ds_write_b128 v4, v[172:175] offset:6144
	s_waitcnt lgkmcnt(6)
	v_lshl_or_b32 v4, v5, 10, v111
	s_waitcnt lgkmcnt(3)
	v_lshl_or_b32 v8, v6, 10, v111
	s_waitcnt lgkmcnt(2)
	v_lshl_or_b32 v12, v12, 10, v111
	s_waitcnt lgkmcnt(1)
	v_lshl_or_b32 v91, v13, 10, v111
	global_load_dwordx4 v[4:7], v4, s[46:47]
	s_nop 0
	global_load_dwordx4 v[8:11], v8, s[46:47]
	s_nop 0
	global_load_dwordx4 v[12:15], v12, s[46:47]
	s_nop 0
	global_load_dwordx4 v[170:173], v91, s[46:47]
	v_mov_b32_e32 v91, v107
	v_mov_b32_e32 v114, v108
	v_mov_b32_e32 v115, v109
	v_mov_b32_e32 v120, v86
	v_add_f32_e32 v121, v176, v144
	v_add_u32_e32 v91, s30, v115
	s_waitcnt vmcnt(15)
	ds_write_b128 v91, v[60:63] offset:256
	v_add_u32_e32 v60, s30, v120
	s_waitcnt vmcnt(14)
	ds_write_b128 v60, v[134:137] offset:2304
	s_waitcnt vmcnt(13)
	ds_write_b128 v91, v[138:141] offset:4352
	s_waitcnt vmcnt(12)
	ds_write_b128 v60, v[162:165] offset:6400
	s_waitcnt lgkmcnt(0)
	v_mov_b32_e32 v91, v106
	v_mov_b32_e32 v114, v104
	v_mov_b32_e32 v115, v105
	v_mov_b32_e32 v120, v68
	v_add_f32_e32 v131, v130, v121
	ds_read_b64_tr_b16 v[134:135], v114 offset:0
	ds_read_b64_tr_b16 v[136:137], v120 offset:0
	ds_read_b64_tr_b16 v[60:61], v115 offset:0
	ds_read_b64_tr_b16 v[62:63], v91 offset:0
	s_waitcnt lgkmcnt(0)
	v_sub_f32_e32 v121, v148, v85
	v_mfma_f32_16x16x32_bf16 v[20:23], v[134:137], v[122:125], v[20:23]
	v_exp_f32_e32 v133, v121
	v_sub_f32_e32 v144, v154, v85
	v_mfma_f32_16x16x32_bf16 v[16:19], v[60:63], v[122:125], v[16:19]
	ds_read_b64_tr_b16 v[134:135], v114 offset:512
	ds_read_b64_tr_b16 v[136:137], v120 offset:512
	ds_read_b64_tr_b16 v[60:61], v115 offset:512
	ds_read_b64_tr_b16 v[62:63], v91 offset:512
	s_waitcnt lgkmcnt(0)
	s_nop 0
	v_mfma_f32_16x16x32_bf16 v[28:31], v[134:137], v[122:125], v[28:31]
	v_mfma_f32_16x16x32_bf16 v[24:27], v[60:63], v[122:125], v[24:27]
	ds_read_b64_tr_b16 v[134:135], v114 offset:1024
	ds_read_b64_tr_b16 v[136:137], v120 offset:1024
	ds_read_b64_tr_b16 v[60:61], v115 offset:1024
	ds_read_b64_tr_b16 v[62:63], v91 offset:1024
	s_waitcnt lgkmcnt(0)
; #define LAS __attribute__((address_space(3)))
; #define LDS_WAIT() asm volatile("s_waitcnt lgkmcnt(0)" ::: "memory")
; #define A8_ISSUE_V(hc) do { _Pragma("unroll") for (int q2_ = 0; q2_ < 4; ++q2_) { const int rid_ = __shfl(R[hc], 4 * q2_ + g); \
;         ring[(4 * (hc) + q2_) & 15] = *(const v4u*)((const char*)VB + (unsigned)(rid_ * 1024 + kvh * 256 + 16 * lr)); } } while (0)
; #define A8_TRP(OFF) asm volatile("ds_read_b64_tr_b16 %0, %4 offset:" #OFF "\n\tds_read_b64_tr_b16 %1, %5 offset:" #OFF "\n\tds_read_b64_tr_b16 %2, %6 offset:" #OFF "\n\tds_read_b64_tr_b16 %3, %7 offset:" #OFF "\n\ts_waitcnt lgkmcnt(0)" \
;                 : "=&v"(r0), "=&v"(r1), "=&v"(r2), "=&v"(r3) : "v"(tE), "v"(tEb), "v"(tO), "v"(tOb) : "memory")
; DI void attn_unit_f8(LAS unsigned char* vbuf  , const LAS float* lut2  , const long (&qf)[4], const int* idx, int cnt_, int qpos_, int kvh, const unsigned char* K8, const bf16* VB, bf16* orow, int lane_) {
;     ...
;     for (int hc = 0; hc < 16; ++hc) {
;         asm volatile("" ::: "memory");
;         const int ks = hc >> 1, par = hc & 1;
;         {
;             unsigned w0 = wx0, w1 = wx1, w2 = wx2, w3 = wx3; asm volatile("" : "+v"(w0), "+v"(w1), "+v"(w2), "+v"(w3));
; #pragma unroll
;             for (int q2 = 0; q2 < 4; ++q2) { const int xr = (par + 2 * q2) & 3; const unsigned bs = xr == 0 ? w0 : (xr == 1 ? w1 : (xr == 2 ? w2 : w3));
;                 *(LAS v4u*)(vbuf + bs + (unsigned)((ks & 1) * 8192 + 2048 * q2 + 256 * par)) = ring[(4 * hc + q2) & 15]; }
;         }
;         if (par == 1) {
;             LDS_WAIT(); asm volatile("" ::: "memory");
;             s16x4 r0, r1, r2, r3; bf16x8 va, vb2;
;     ...
;             unsigned tE = te, tEb = teb, tO = to, tOb = tob; asm volatile("" : "+v"(tE), "+v"(tEb), "+v"(tO), "+v"(tOb));
;     ...
;             if ((ks & 1) == 0) { A8_TRP(0); A8_PV(0); A8_TRP(512); A8_PV(2); A8_TRP(1024); A8_PV(4); A8_TRP(1536); A8_PV(6); }
;             else { A8_TRP(8192); A8_PV(0); A8_TRP(8704); A8_PV(2); A8_TRP(9216); A8_PV(4); A8_TRP(9728); A8_PV(6); }
;     ...
;         }
;         if (hc + 4 < 16) A8_ISSUE_V(hc + 4);
	s_nop 0
	v_mfma_f32_16x16x32_bf16 v[52:55], v[134:137], v[122:125], v[52:55]
	v_mfma_f32_16x16x32_bf16 v[48:51], v[60:63], v[122:125], v[48:51]
	ds_read_b64_tr_b16 v[134:135], v114 offset:1536
	ds_read_b64_tr_b16 v[136:137], v120 offset:1536
	ds_read_b64_tr_b16 v[60:61], v115 offset:1536
	ds_read_b64_tr_b16 v[62:63], v91 offset:1536
	s_waitcnt lgkmcnt(0)
	v_cvt_pk_bf16_f32 v91, v2, v143
	ds_bpermute_b32 v2, v66, v113
	v_mfma_f32_16x16x32_bf16 v[134:137], v[134:137], v[122:125], v[156:159]
	v_mfma_f32_16x16x32_bf16 v[56:59], v[60:63], v[122:125], v[56:59]
	global_load_dwordx4 v[60:63], v1, s[46:47]
	global_load_dwordx4 v[120:123], v0, s[46:47]
	s_waitcnt lgkmcnt(0)
	v_lshl_or_b32 v0, v2, 10, v111
	v_lshl_or_b32 v1, v87, 10, v111
	global_load_dwordx4 v[138:141], v0, s[46:47]
	global_load_dwordx4 v[154:157], v1, s[46:47]
	v_mov_b32_e32 v0, v107
	v_mov_b32_e32 v1, v108
	v_mov_b32_e32 v2, v109
	v_mov_b32_e32 v87, v86
	ds_bpermute_b32 v2, v64, v112
	v_add_u32_e32 v0, s30, v0
	v_add_u32_e32 v1, s30, v1
	s_waitcnt vmcnt(15)
	ds_write_b128 v0, v[32:35] offset:8192
	s_waitcnt vmcnt(14)
	ds_write_b128 v1, v[36:39] offset:10240
	s_waitcnt vmcnt(13)
	ds_write_b128 v0, v[40:43] offset:12288
	ds_bpermute_b32 v0, v65, v112
	s_waitcnt vmcnt(12)
	ds_write_b128 v1, v[44:47] offset:14336
	s_waitcnt lgkmcnt(5)
	v_lshl_or_b32 v1, v2, 10, v111
	ds_bpermute_b32 v2, v66, v112
	ds_bpermute_b32 v40, v67, v112
	s_waitcnt lgkmcnt(3)
	v_lshl_or_b32 v0, v0, 10, v111
	global_load_dwordx4 v[32:35], v1, s[46:47]
	global_load_dwordx4 v[36:39], v0, s[46:47]
	v_mov_b32_e32 v87, v86
	s_waitcnt lgkmcnt(1)
	v_lshl_or_b32 v0, v2, 10, v111
	s_waitcnt lgkmcnt(0)
	v_lshl_or_b32 v1, v40, 10, v111
	global_load_dwordx4 v[40:43], v0, s[46:47]
	global_load_dwordx4 v[44:47], v1, s[46:47]
	v_mov_b32_e32 v0, v107
	v_mov_b32_e32 v1, v108
	v_mov_b32_e32 v2, v109
	v_mov_b32_e32 v124, v105
	v_add_u32_e32 v0, s30, v2
	v_add_u32_e32 v1, s30, v87
	s_waitcnt vmcnt(15)
	ds_write_b128 v0, v[116:119] offset:8448
	s_waitcnt vmcnt(14)
	ds_write_b128 v1, v[126:129] offset:10496
	s_waitcnt vmcnt(13)
	ds_write_b128 v0, v[150:153] offset:12544
	s_waitcnt vmcnt(12)
	ds_write_b128 v1, v[166:169] offset:14592
	s_waitcnt lgkmcnt(0)
	v_mov_b32_e32 v2, v106
	v_mov_b32_e32 v87, v104
	v_mov_b32_e32 v125, v68
	ds_bpermute_b32 v64, v64, v110
	ds_read_b64_tr_b16 v[116:117], v87 offset:8192
	ds_read_b64_tr_b16 v[118:119], v125 offset:8192
	ds_read_b64_tr_b16 v[112:113], v124 offset:8192
	ds_read_b64_tr_b16 v[114:115], v2 offset:8192
	s_waitcnt lgkmcnt(0)
	ds_bpermute_b32 v65, v65, v110
	v_mfma_f32_16x16x32_bf16 v[20:23], v[116:119], v[88:91], v[20:23]
	v_sub_f32_e32 v0, v147, v85
	s_waitcnt lgkmcnt(1)
	v_lshl_or_b32 v64, v64, 10, v111
	v_exp_f32_e32 v129, v0
	v_mfma_f32_16x16x32_bf16 v[16:19], v[112:115], v[88:91], v[16:19]
	ds_read_b64_tr_b16 v[116:117], v87 offset:8704
	ds_read_b64_tr_b16 v[118:119], v125 offset:8704
	ds_read_b64_tr_b16 v[112:113], v124 offset:8704
	ds_read_b64_tr_b16 v[114:115], v2 offset:8704
	s_waitcnt lgkmcnt(0)
	v_sub_f32_e32 v0, v132, v85
	v_exp_f32_e32 v132, v0
	v_mfma_f32_16x16x32_bf16 v[28:31], v[116:119], v[88:91], v[28:31]
	v_sub_f32_e32 v0, v142, v85
	v_exp_f32_e32 v142, v0
	v_cvt_pk_bf16_f32 v0, v3, v145
	v_mfma_f32_16x16x32_bf16 v[24:27], v[112:115], v[88:91], v[24:27]
	ds_read_b64_tr_b16 v[116:117], v87 offset:9216
	ds_read_b64_tr_b16 v[118:119], v125 offset:9216
	ds_read_b64_tr_b16 v[112:113], v124 offset:9216
	ds_read_b64_tr_b16 v[114:115], v2 offset:9216
	s_waitcnt lgkmcnt(0)
	v_cvt_pk_bf16_f32 v3, v130, v133
	v_mov_b32_e32 v130, v86
	v_mfma_f32_16x16x32_bf16 v[52:55], v[116:119], v[88:91], v[52:55]
	v_cvt_pk_bf16_f32 v1, v161, v146
	v_exp_f32_e32 v128, v144
	v_mfma_f32_16x16x32_bf16 v[48:51], v[112:115], v[88:91], v[48:51]
	ds_read_b64_tr_b16 v[116:117], v87 offset:9728
	ds_read_b64_tr_b16 v[118:119], v125 offset:9728
	ds_read_b64_tr_b16 v[112:113], v124 offset:9728
	ds_read_b64_tr_b16 v[114:115], v2 offset:9728
	s_waitcnt lgkmcnt(0)
	ds_bpermute_b32 v87, v66, v110
	ds_bpermute_b32 v110, v67, v110
	v_mfma_f32_16x16x32_bf16 v[116:119], v[116:119], v[88:91], v[134:137]
	v_cvt_pk_bf16_f32 v2, v160, v176
	s_waitcnt lgkmcnt(1)
	v_lshl_or_b32 v87, v87, 10, v111
	v_mfma_f32_16x16x32_bf16 v[56:59], v[112:115], v[88:91], v[56:59]
	v_lshl_or_b32 v88, v65, 10, v111
	global_load_dwordx4 v[64:67], v64, s[46:47]
	s_nop 0
	global_load_dwordx4 v[88:91], v88, s[46:47]
	s_waitcnt lgkmcnt(0)
	v_lshl_or_b32 v114, v110, 10, v111
	global_load_dwordx4 v[110:113], v87, s[46:47]
	global_load_dwordx4 v[124:127], v114, s[46:47]
	v_mov_b32_e32 v87, v107
	v_mov_b32_e32 v114, v108
	v_mov_b32_e32 v115, v109
	s_nop 0
	v_add_u32_e32 v87, s30, v87
	s_waitcnt vmcnt(15)
	ds_write_b128 v87, v[4:7]
	v_add_u32_e32 v4, s30, v114
	s_waitcnt vmcnt(14)
	ds_write_b128 v4, v[8:11] offset:2048
	s_waitcnt vmcnt(13)
	ds_write_b128 v87, v[12:15] offset:4096
	s_waitcnt vmcnt(12)
	ds_write_b128 v4, v[170:173] offset:6144
	v_mov_b32_e32 v4, v107
	v_mov_b32_e32 v5, v108
	v_mov_b32_e32 v6, v109
	v_mov_b32_e32 v7, v86
	v_mov_b32_e32 v87, v68
	v_add_u32_e32 v4, s30, v6
	v_add_u32_e32 v5, s30, v7
	s_waitcnt vmcnt(11)
	ds_write_b128 v4, v[60:63] offset:256
	s_waitcnt vmcnt(10)
	ds_write_b128 v5, v[120:123] offset:2304
	s_waitcnt vmcnt(9)
	ds_write_b128 v4, v[138:141] offset:4352
	s_waitcnt vmcnt(8)
	ds_write_b128 v5, v[154:157] offset:6400
	s_waitcnt lgkmcnt(0)
	v_mov_b32_e32 v61, v106
	v_mov_b32_e32 v62, v104
	v_mov_b32_e32 v63, v105
	v_sub_f32_e32 v12, v71, v85
	ds_read_b64_tr_b16 v[8:9], v62 offset:0
	ds_read_b64_tr_b16 v[10:11], v87 offset:0
	ds_read_b64_tr_b16 v[4:5], v63 offset:0
	ds_read_b64_tr_b16 v[6:7], v61 offset:0
	s_waitcnt lgkmcnt(0)
; #define LAS __attribute__((address_space(3)))
; DI unsigned pk2(float lo, float hi) { const f32x2 v = {lo, hi}; return __builtin_bit_cast(unsigned, __builtin_convertvector(v, bf16x2_t)); }
; #define LDS_WAIT() asm volatile("s_waitcnt lgkmcnt(0)" ::: "memory")
; #define A8_ISSUE_V(hc) do { _Pragma("unroll") for (int q2_ = 0; q2_ < 4; ++q2_) { const int rid_ = __shfl(R[hc], 4 * q2_ + g); \
;         ring[(4 * (hc) + q2_) & 15] = *(const v4u*)((const char*)VB + (unsigned)(rid_ * 1024 + kvh * 256 + 16 * lr)); } } while (0)
; DI void attn_unit_f8(LAS unsigned char* vbuf  , const LAS float* lut2  , const long (&qf)[4], const int* idx, int cnt_, int qpos_, int kvh, const unsigned char* K8, const bf16* VB, bf16* orow, int lane_) {
;     ...
;     for (int hc = 0; hc < 16; ++hc) {
;         asm volatile("" ::: "memory");
;         const int ks = hc >> 1, par = hc & 1;
;         {
;             unsigned w0 = wx0, w1 = wx1, w2 = wx2, w3 = wx3; asm volatile("" : "+v"(w0), "+v"(w1), "+v"(w2), "+v"(w3));
; #pragma unroll
;             for (int q2 = 0; q2 < 4; ++q2) { const int xr = (par + 2 * q2) & 3; const unsigned bs = xr == 0 ? w0 : (xr == 1 ? w1 : (xr == 2 ? w2 : w3));
;                 *(LAS v4u*)(vbuf + bs + (unsigned)((ks & 1) * 8192 + 2048 * q2 + 256 * par)) = ring[(4 * hc + q2) & 15]; }
;         }
;         if (par == 1) {
;             LDS_WAIT(); asm volatile("" ::: "memory");
;             s16x4 r0, r1, r2, r3; bf16x8 va, vb2;
;     ...
;             unsigned tE = te, tEb = teb, tO = to, tOb = tob; asm volatile("" : "+v"(tE), "+v"(tEb), "+v"(tO), "+v"(tOb));
;     ...
;             if ((ks & 1) == 0) { A8_TRP(0); A8_PV(0); A8_TRP(512); A8_PV(2); A8_TRP(1024); A8_PV(4); A8_TRP(1536); A8_PV(6); }
;             else { A8_TRP(8192); A8_PV(0); A8_TRP(8704); A8_PV(2); A8_TRP(9216); A8_PV(4); A8_TRP(9728); A8_PV(6); }
;     ...
;         }
;         if (hc + 4 < 16) A8_ISSUE_V(hc + 4);
;     }
;     if (lr < 4) {
; #pragma unroll
;         for (int dt = 0; dt < 8; ++dt) { v2u w; w.x = pk2(o[dt][0] * inv, o[dt][1] * inv); w.y = pk2(o[dt][2] * inv, o[dt][3] * inv); *(v2u*)(orow + (4 * kvh + lr) * 128 + 16 * dt + 4 * g) = w; } }
	v_exp_f32_e32 v71, v12
	v_mfma_f32_16x16x32_bf16 v[8:11], v[8:11], v[0:3], v[20:23]
	v_cvt_pk_bf16_f32 v60, v128, v129
	s_nop 1
	v_sub_f32_e32 v20, v84, v85
	v_mfma_f32_16x16x32_bf16 v[4:7], v[4:7], v[0:3], v[16:19]
	ds_read_b64_tr_b16 v[16:17], v62 offset:512
	ds_read_b64_tr_b16 v[18:19], v87 offset:512
	ds_read_b64_tr_b16 v[12:13], v63 offset:512
	ds_read_b64_tr_b16 v[14:15], v61 offset:512
	s_waitcnt lgkmcnt(0)
	v_exp_f32_e32 v84, v20
	v_sub_f32_e32 v20, v70, v85
	v_exp_f32_e32 v70, v20
	v_mfma_f32_16x16x32_bf16 v[12:15], v[12:15], v[0:3], v[24:27]
	ds_read_b64_tr_b16 v[24:25], v62 offset:1024
	ds_read_b64_tr_b16 v[26:27], v87 offset:1024
	ds_read_b64_tr_b16 v[20:21], v63 offset:1024
	ds_read_b64_tr_b16 v[22:23], v61 offset:1024
	s_waitcnt lgkmcnt(0)
	s_nop 0
	v_mfma_f32_16x16x32_bf16 v[52:55], v[24:27], v[0:3], v[52:55]
	s_nop 0
	v_sub_f32_e32 v24, v69, v85
	v_exp_f32_e32 v69, v24
	v_mfma_f32_16x16x32_bf16 v[48:51], v[20:23], v[0:3], v[48:51]
	ds_read_b64_tr_b16 v[24:25], v62 offset:1536
	ds_read_b64_tr_b16 v[26:27], v87 offset:1536
	ds_read_b64_tr_b16 v[20:21], v63 offset:1536
	ds_read_b64_tr_b16 v[22:23], v61 offset:1536
	s_waitcnt lgkmcnt(0)
	v_cvt_pk_bf16_f32 v61, v132, v142
	v_mfma_f32_16x16x32_bf16 v[16:19], v[16:19], v[0:3], v[28:31]
	v_cvt_pk_bf16_f32 v62, v71, v84
	v_cvt_pk_bf16_f32 v63, v70, v69
	v_mfma_f32_16x16x32_bf16 v[114:117], v[24:27], v[0:3], v[116:119]
	v_mfma_f32_16x16x32_bf16 v[0:3], v[20:23], v[0:3], v[56:59]
	v_mov_b32_e32 v20, v107
	v_mov_b32_e32 v21, v108
	v_mov_b32_e32 v22, v109
	v_mov_b32_e32 v23, v86
	s_nop 0
	v_add_u32_e32 v20, s30, v20
	v_add_u32_e32 v21, s30, v21
	s_waitcnt vmcnt(7)
	ds_write_b128 v20, v[32:35] offset:8192
	s_waitcnt vmcnt(6)
	ds_write_b128 v21, v[36:39] offset:10240
	s_waitcnt vmcnt(5)
	ds_write_b128 v20, v[40:43] offset:12288
	s_waitcnt vmcnt(4)
	ds_write_b128 v21, v[44:47] offset:14336
	s_nop 0
	v_add_u32_e32 v20, s30, v109
	v_add_u32_e32 v21, s30, v86
	s_waitcnt vmcnt(3)
	ds_write_b128 v20, v[64:67] offset:8448
	s_waitcnt vmcnt(2)
	ds_write_b128 v21, v[88:91] offset:10496
	s_waitcnt vmcnt(1)
	ds_write_b128 v20, v[110:113] offset:12544
	s_waitcnt vmcnt(0)
	ds_write_b128 v21, v[124:127] offset:14592
	s_waitcnt lgkmcnt(0)
	s_nop 0
	ds_read_b64_tr_b16 v[24:25], v104 offset:8192
	ds_read_b64_tr_b16 v[26:27], v68 offset:8192
	ds_read_b64_tr_b16 v[20:21], v105 offset:8192
	ds_read_b64_tr_b16 v[22:23], v106 offset:8192
	s_waitcnt lgkmcnt(0)
	s_nop 0
	v_mfma_f32_16x16x32_bf16 v[28:31], v[24:27], v[60:63], v[8:11]
	s_nop 2
	v_add_f32_e32 v8, v133, v131
	v_add_f32_e32 v8, v128, v8
	v_add_f32_e32 v32, v129, v8
	v_mfma_f32_16x16x32_bf16 v[20:23], v[20:23], v[60:63], v[4:7]
	ds_read_b64_tr_b16 v[8:9], v104 offset:8704
	ds_read_b64_tr_b16 v[10:11], v68 offset:8704
	ds_read_b64_tr_b16 v[4:5], v105 offset:8704
	ds_read_b64_tr_b16 v[6:7], v106 offset:8704
	s_waitcnt lgkmcnt(0)
	s_nop 0
	v_mfma_f32_16x16x32_bf16 v[24:27], v[8:11], v[60:63], v[16:19]
	v_add_f32_e32 v8, v132, v32
	v_add_f32_e32 v8, v142, v8
	v_add_f32_e32 v32, v71, v8
	v_mfma_f32_16x16x32_bf16 v[12:15], v[4:7], v[60:63], v[12:15]
	ds_read_b64_tr_b16 v[8:9], v104 offset:9216
	ds_read_b64_tr_b16 v[10:11], v68 offset:9216
	ds_read_b64_tr_b16 v[4:5], v105 offset:9216
	ds_read_b64_tr_b16 v[6:7], v106 offset:9216
	s_waitcnt lgkmcnt(0)
	s_nop 0
	v_mfma_f32_16x16x32_bf16 v[16:19], v[8:11], v[60:63], v[52:55]
	v_add_f32_e32 v8, v84, v32
	v_add_f32_e32 v8, v70, v8
	v_add_f32_e32 v32, v69, v8
	ds_bpermute_b32 v33, v72, v32
	ds_read_b64_tr_b16 v[8:9], v104 offset:9728
	ds_read_b64_tr_b16 v[10:11], v68 offset:9728
	ds_read_b64_tr_b16 v[34:35], v105 offset:9728
	ds_read_b64_tr_b16 v[36:37], v106 offset:9728
	s_waitcnt lgkmcnt(0)
	v_mfma_f32_16x16x32_bf16 v[4:7], v[4:7], v[60:63], v[48:51]
	s_waitcnt lgkmcnt(0)
	v_add_f32_e32 v32, v32, v33
	ds_bpermute_b32 v33, v81, v32
	v_mfma_f32_16x16x32_bf16 v[8:11], v[8:11], v[60:63], v[114:117]
	v_mfma_f32_16x16x32_bf16 v[0:3], v[34:37], v[60:63], v[0:3]
	s_and_saveexec_b64 s[8:9], vcc
	s_xor_b64 s[8:9], exec, s[8:9]
	s_cbranch_execz .LBB0_5549
	s_waitcnt lgkmcnt(0)
	v_add_f32_e32 v32, v32, v33
	s_lshl_b64 s[10:11], s[52:53], 11
	s_lshl_b64 s[10:11], s[10:11], 1
	s_add_u32 s10, s57, s10
	v_rcp_f32_e32 v32, v32
	v_or_b32_e32 v33, s54, v83
	s_addc_u32 s11, s58, s11
	v_lshlrev_b32_e32 v72, 8, v33
	v_lshl_add_u64 v[34:35], s[10:11], 0, v[72:73]
	v_ashrrev_i32_e32 v83, 31, v82
	v_pk_mul_f32 v[20:21], v[32:33], v[20:21] op_sel_hi:[0,1]
	v_pk_mul_f32 v[22:23], v[32:33], v[22:23] op_sel_hi:[0,1]
	v_pk_mul_f32 v[12:13], v[32:33], v[12:13] op_sel_hi:[0,1]
	v_pk_mul_f32 v[14:15], v[32:33], v[14:15] op_sel_hi:[0,1]
	v_pk_mul_f32 v[4:5], v[32:33], v[4:5] op_sel_hi:[0,1]
	v_pk_mul_f32 v[6:7], v[32:33], v[6:7] op_sel_hi:[0,1]
	v_lshl_add_u64 v[34:35], v[82:83], 1, v[34:35]
	v_cvt_pk_bf16_f32 v20, v20, v21
	v_cvt_pk_bf16_f32 v21, v22, v23
	v_cvt_pk_bf16_f32 v12, v12, v13
	v_cvt_pk_bf16_f32 v13, v14, v15
	v_cvt_pk_bf16_f32 v4, v4, v5
	v_cvt_pk_bf16_f32 v5, v6, v7
	v_pk_mul_f32 v[28:29], v[32:33], v[28:29] op_sel_hi:[0,1]
	v_pk_mul_f32 v[30:31], v[32:33], v[30:31] op_sel_hi:[0,1]
	global_store_dwordx2 v[34:35], v[20:21], off offset:32
	v_pk_mul_f32 v[20:21], v[32:33], v[24:25] op_sel_hi:[0,1]
	v_pk_mul_f32 v[22:23], v[32:33], v[26:27] op_sel_hi:[0,1]
	global_store_dwordx2 v[34:35], v[12:13], off offset:96
	v_pk_mul_f32 v[12:13], v[32:33], v[16:17] op_sel_hi:[0,1]
	v_pk_mul_f32 v[14:15], v[32:33], v[18:19] op_sel_hi:[0,1]
	global_store_dwordx2 v[34:35], v[4:5], off offset:160
	v_pk_mul_f32 v[4:5], v[32:33], v[8:9] op_sel_hi:[0,1]
	v_pk_mul_f32 v[6:7], v[32:33], v[10:11] op_sel_hi:[0,1]
	v_pk_mul_f32 v[0:1], v[32:33], v[0:1] op_sel_hi:[0,1]
	v_pk_mul_f32 v[2:3], v[32:33], v[2:3] op_sel_hi:[0,1]
	v_cvt_pk_bf16_f32 v28, v28, v29
	v_cvt_pk_bf16_f32 v29, v30, v31
	v_cvt_pk_bf16_f32 v20, v20, v21
	v_cvt_pk_bf16_f32 v21, v22, v23
	v_cvt_pk_bf16_f32 v12, v12, v13
	v_cvt_pk_bf16_f32 v13, v14, v15
	v_cvt_pk_bf16_f32 v4, v4, v5
	v_cvt_pk_bf16_f32 v5, v6, v7
	v_cvt_pk_bf16_f32 v0, v0, v1
	v_cvt_pk_bf16_f32 v1, v2, v3
	global_store_dwordx2 v[34:35], v[28:29], off
	global_store_dwordx2 v[34:35], v[20:21], off offset:64
	global_store_dwordx2 v[34:35], v[12:13], off offset:128
	global_store_dwordx2 v[34:35], v[4:5], off offset:192
	global_store_dwordx2 v[34:35], v[0:1], off offset:224

; #define PG8_STAGE(bufoff, gbase, voff) do { _Pragma("unroll") for (int _i = 0; _i < 2; ++_i) \
;         __builtin_amdgcn_global_load_lds((const unsigned*)((const char*)(gbase) + (voff)[_i]), (PG8_LAS unsigned*)(lds + (bufoff) + ldsw + _i * 8192), 16, 0, 0); } while (0)
; #define PG8_LDA(dst, b, h) do { _Pragma("unroll") for (int m = 0; m < 4; ++m) _Pragma("unroll") for (int k = 0; k < 2; ++k) dst[m][k] = *(const PG8_LAS bf16x8*)(lds + PG8_SA(b, h) + aoff + m * 2048 + k * 1024); } while (0)
; #define PG8_LDB(dst, b, h) do { _Pragma("unroll") for (int n = 0; n < 2; ++n) _Pragma("unroll") for (int k = 0; k < 2; ++k) dst[n][k] = *(const PG8_LAS bf16x8*)(lds + PG8_SB(b, h) + boff + n * 2048 + k * 1024); } while (0)
; #define PG8_MMA(ai, bj, At, Bt) do { __builtin_amdgcn_s_setprio(1); _Pragma("unroll") for (int m = 0; m < 4; ++m) _Pragma("unroll") for (int n = 0; n < 2; ++n) _Pragma("unroll") for (int k = 0; k < 2; ++k) \
;         acc[ai][bj][m][n] = __builtin_amdgcn_mfma_f32_16x16x32_bf16(Bt[n][k], At[m][k], acc[ai][bj][m][n], 0, 0, 0); __builtin_amdgcn_s_setprio(0); } while (0)
; #define PG8_WAIT_V(n) asm volatile("s_waitcnt vmcnt(" #n ")" ::: "memory")
; #define PG8_WAIT_L(n) asm volatile("s_waitcnt lgkmcnt(" #n ")" ::: "memory")
; #define PG8_BAR __builtin_amdgcn_s_barrier()
; #define PG8_SCHED __builtin_amdgcn_sched_barrier(0)
; template <class Epi, class Sched, bool ALIGN_EPI = false, bool SP2 = false>
; __device__ __forceinline__ void gemm_phase(PG8_LAS unsigned char* lds, const Gemm g, const Sched& S, const Epi& E, const int wid  ) {
;     ...
;             PG8_LDB(B0, 0, 0); PG8_LDB(B1, 0, 1); PG8_SCHED; PG8_LDA(At, 0, 0); PG8_STAGE(PG8_SA(1, 1), a1 + hstep, voffA);
;             PG8_WAIT_V(8); PG8_WAIT_L(0); PG8_BAR; PG8_MMA(0, 0, At, B0); PG8_MMA(0, 1, At, B1); PG8_BAR; PG8_SCHED;
;             PG8_LDA(At, 0, 1); PG8_STAGE(PG8_SB(0, 0), b2, voffB); PG8_STAGE(PG8_SB(0, 1), b2 + hstep, voffB); PG8_STAGE(PG8_SA(0, 0), a2, voffA);
.LBB0_5665:
	s_add_u32 s100, s50, 0xfff80000
	s_addc_u32 s101, s51, -1
	ds_read_b128 v[72:75], v200
	ds_read_b128 v[76:79], v200 offset:1024
	ds_read_b128 v[88:91], v200 offset:2048
	ds_read_b128 v[92:95], v200 offset:3072
	ds_read_b128 v[144:147], v201
	ds_read_b128 v[148:151], v201 offset:1024
	ds_read_b128 v[152:155], v201 offset:2048
	ds_read_b128 v[156:159], v201 offset:3072
	s_add_u32 s52, s50, 0xfff80080
	s_addc_u32 s53, s51, -1
	s_cmp_eq_u32 s68, 28
	s_cselect_b32 s55, s41, s53
	s_cselect_b32 s54, s47, s52
	s_cselect_b32 s53, s39, s67
	s_cselect_b32 s52, s65, s66
	v_lshl_add_u64 v[220:221], s[100:101], 0, v[176:177]
	s_mov_b32 m0, s59
	v_lshl_add_u64 v[222:223], s[100:101], 0, v[178:179]
	global_load_lds_dwordx4 v[220:221], off
	s_mov_b32 m0, s60
	s_nop 0
	global_load_lds_dwordx4 v[222:223], off
	v_lshl_add_u64 v[216:217], s[50:51], 0, v[176:177]
	s_add_i32 m0, s35, 0xc000
	ds_read_b128 v[160:163], v202
	ds_read_b128 v[164:167], v202 offset:1024
	ds_read_b128 v[184:187], v202 offset:2048
	ds_read_b128 v[188:191], v202 offset:3072
	ds_read_b128 v[192:195], v202 offset:4096
	ds_read_b128 v[204:207], v202 offset:5120
	ds_read_b128 v[208:211], v202 offset:6144
	ds_read_b128 v[212:215], v202 offset:7168
	global_load_lds_dwordx4 v[216:217], off
	v_lshl_add_u64 v[216:217], s[50:51], 0, v[178:179]
	s_add_i32 m0, s35, 0xe000
	s_nop 0
	global_load_lds_dwordx4 v[216:217], off
	s_waitcnt vmcnt(8)
	s_waitcnt lgkmcnt(0)
	s_barrier
	s_setprio 1
	s_waitcnt lgkmcnt(0)
	v_mfma_f32_16x16x32_bf16 v[140:143], v[72:75], v[160:163], v[140:143]
	v_mfma_f32_16x16x32_bf16 v[136:139], v[88:91], v[160:163], v[136:139]
	v_mfma_f32_16x16x32_bf16 v[124:127], v[72:75], v[184:187], v[124:127]
	v_mfma_f32_16x16x32_bf16 v[120:123], v[88:91], v[184:187], v[120:123]
	v_mfma_f32_16x16x32_bf16 v[108:111], v[72:75], v[192:195], v[108:111]
	v_mfma_f32_16x16x32_bf16 v[104:107], v[88:91], v[192:195], v[104:107]
	v_mfma_f32_16x16x32_bf16 v[84:87], v[72:75], v[208:211], v[84:87]
	v_mfma_f32_16x16x32_bf16 v[80:83], v[88:91], v[208:211], v[80:83]
	v_mfma_f32_16x16x32_bf16 v[140:143], v[76:79], v[164:167], v[140:143]
	v_mfma_f32_16x16x32_bf16 v[136:139], v[92:95], v[164:167], v[136:139]
	v_mfma_f32_16x16x32_bf16 v[124:127], v[76:79], v[188:191], v[124:127]
	v_mfma_f32_16x16x32_bf16 v[120:123], v[92:95], v[188:191], v[120:123]
	v_mfma_f32_16x16x32_bf16 v[108:111], v[76:79], v[204:207], v[108:111]
	v_mfma_f32_16x16x32_bf16 v[104:107], v[92:95], v[204:207], v[104:107]
	v_mfma_f32_16x16x32_bf16 v[84:87], v[76:79], v[212:215], v[84:87]
	v_mfma_f32_16x16x32_bf16 v[80:83], v[92:95], v[212:215], v[80:83]
	s_setprio 0
	s_setprio 1
	v_mfma_f32_16x16x32_bf16 v[132:135], v[144:147], v[160:163], v[132:135]
	v_mfma_f32_16x16x32_bf16 v[128:131], v[152:155], v[160:163], v[128:131]
	v_mfma_f32_16x16x32_bf16 v[116:119], v[144:147], v[184:187], v[116:119]
	v_mfma_f32_16x16x32_bf16 v[112:115], v[152:155], v[184:187], v[112:115]
	v_mfma_f32_16x16x32_bf16 v[100:103], v[144:147], v[192:195], v[100:103]
	v_mfma_f32_16x16x32_bf16 v[96:99], v[152:155], v[192:195], v[96:99]
	v_mfma_f32_16x16x32_bf16 v[68:71], v[144:147], v[208:211], v[68:71]
	v_mfma_f32_16x16x32_bf16 v[64:67], v[152:155], v[208:211], v[64:67]
	v_mfma_f32_16x16x32_bf16 v[132:135], v[148:151], v[164:167], v[132:135]
	v_mfma_f32_16x16x32_bf16 v[128:131], v[156:159], v[164:167], v[128:131]
	v_mfma_f32_16x16x32_bf16 v[116:119], v[148:151], v[188:191], v[116:119]
	v_mfma_f32_16x16x32_bf16 v[112:115], v[156:159], v[188:191], v[112:115]
	v_mfma_f32_16x16x32_bf16 v[100:103], v[148:151], v[204:207], v[100:103]
	v_mfma_f32_16x16x32_bf16 v[96:99], v[156:159], v[204:207], v[96:99]
	v_mfma_f32_16x16x32_bf16 v[68:71], v[148:151], v[212:215], v[68:71]
	v_mfma_f32_16x16x32_bf16 v[64:67], v[156:159], v[212:215], v[64:67]
	s_setprio 0
	s_barrier
	s_add_i32 s69, s63, s34
	v_lshl_add_u64 v[216:217], s[52:53], 0, v[170:171]
	s_mov_b32 m0, s69
	ds_read_b128 v[160:163], v202 offset:16384
	ds_read_b128 v[164:167], v202 offset:17408
	ds_read_b128 v[184:187], v202 offset:18432
	ds_read_b128 v[188:191], v202 offset:19456
	ds_read_b128 v[192:195], v202 offset:20480
	ds_read_b128 v[204:207], v202 offset:21504
	ds_read_b128 v[208:211], v202 offset:22528
	ds_read_b128 v[212:215], v202 offset:23552
	global_load_lds_dwordx4 v[216:217], off
	s_add_i32 m0, s69, 0x2000
	s_add_u32 s70, s52, 0x80000
	v_lshl_add_u64 v[218:219], s[52:53], 0, v[174:175]
	s_addc_u32 s71, s53, 0
	s_add_i32 s69, s64, s34
	global_load_lds_dwordx4 v[218:219], off
	v_lshl_add_u64 v[220:221], s[70:71], 0, v[170:171]
	s_mov_b32 m0, s69
	s_nop 0
	global_load_lds_dwordx4 v[220:221], off
	v_lshl_add_u64 v[220:221], s[70:71], 0, v[174:175]
	s_add_i32 m0, s69, 0x2000
	s_nop 0
	global_load_lds_dwordx4 v[220:221], off
	s_waitcnt vmcnt(6)
	s_waitcnt lgkmcnt(0)
	s_barrier
; #define PG8_STAGE(bufoff, gbase, voff) do { _Pragma("unroll") for (int _i = 0; _i < 2; ++_i) \
;         __builtin_amdgcn_global_load_lds((const unsigned*)((const char*)(gbase) + (voff)[_i]), (PG8_LAS unsigned*)(lds + (bufoff) + ldsw + _i * 8192), 16, 0, 0); } while (0)
; #define PG8_LDA(dst, b, h) do { _Pragma("unroll") for (int m = 0; m < 4; ++m) _Pragma("unroll") for (int k = 0; k < 2; ++k) dst[m][k] = *(const PG8_LAS bf16x8*)(lds + PG8_SA(b, h) + aoff + m * 2048 + k * 1024); } while (0)
; #define PG8_LDB(dst, b, h) do { _Pragma("unroll") for (int n = 0; n < 2; ++n) _Pragma("unroll") for (int k = 0; k < 2; ++k) dst[n][k] = *(const PG8_LAS bf16x8*)(lds + PG8_SB(b, h) + boff + n * 2048 + k * 1024); } while (0)
; #define PG8_MMA(ai, bj, At, Bt) do { __builtin_amdgcn_s_setprio(1); _Pragma("unroll") for (int m = 0; m < 4; ++m) _Pragma("unroll") for (int n = 0; n < 2; ++n) _Pragma("unroll") for (int k = 0; k < 2; ++k) \
;         acc[ai][bj][m][n] = __builtin_amdgcn_mfma_f32_16x16x32_bf16(Bt[n][k], At[m][k], acc[ai][bj][m][n], 0, 0, 0); __builtin_amdgcn_s_setprio(0); } while (0)
; #define PG8_WAIT_V(n) asm volatile("s_waitcnt vmcnt(" #n ")" ::: "memory")
; #define PG8_WAIT_L(n) asm volatile("s_waitcnt lgkmcnt(" #n ")" ::: "memory")
; #define PG8_BAR __builtin_amdgcn_s_barrier()
; #define PG8_SCHED __builtin_amdgcn_sched_barrier(0)
; template <class Epi, class Sched, bool ALIGN_EPI = false, bool SP2 = false>
; __device__ __forceinline__ void gemm_phase(PG8_LAS unsigned char* lds, const Gemm g, const Sched& S, const Epi& E, const int wid  ) {
;     ...
;             PG8_WAIT_V(8); PG8_WAIT_L(0); PG8_BAR; PG8_MMA(1, 0, At, B0); PG8_MMA(1, 1, At, B1); PG8_BAR; PG8_SCHED;
;             PG8_LDB(B0, 1, 0); PG8_LDB(B1, 1, 1); PG8_SCHED; PG8_LDA(At, 1, 0); PG8_STAGE(PG8_SA(0, 1), a2 + hstep, voffA);
	s_setprio 1
	s_waitcnt lgkmcnt(0)
	v_mfma_f32_16x16x32_bf16 v[60:63], v[72:75], v[160:163], v[60:63]
	v_mfma_f32_16x16x32_bf16 v[56:59], v[88:91], v[160:163], v[56:59]
	v_mfma_f32_16x16x32_bf16 v[44:47], v[72:75], v[184:187], v[44:47]
	v_mfma_f32_16x16x32_bf16 v[40:43], v[88:91], v[184:187], v[40:43]
	v_mfma_f32_16x16x32_bf16 v[28:31], v[72:75], v[192:195], v[28:31]
	v_mfma_f32_16x16x32_bf16 v[24:27], v[88:91], v[192:195], v[24:27]
	v_mfma_f32_16x16x32_bf16 v[12:15], v[72:75], v[208:211], v[12:15]
	v_mfma_f32_16x16x32_bf16 v[8:11], v[88:91], v[208:211], v[8:11]
	v_mfma_f32_16x16x32_bf16 v[60:63], v[76:79], v[164:167], v[60:63]
	v_mfma_f32_16x16x32_bf16 v[56:59], v[92:95], v[164:167], v[56:59]
	v_mfma_f32_16x16x32_bf16 v[44:47], v[76:79], v[188:191], v[44:47]
	v_mfma_f32_16x16x32_bf16 v[40:43], v[92:95], v[188:191], v[40:43]
	v_mfma_f32_16x16x32_bf16 v[28:31], v[76:79], v[204:207], v[28:31]
	v_mfma_f32_16x16x32_bf16 v[24:27], v[92:95], v[204:207], v[24:27]
	v_mfma_f32_16x16x32_bf16 v[12:15], v[76:79], v[212:215], v[12:15]
	v_mfma_f32_16x16x32_bf16 v[8:11], v[92:95], v[212:215], v[8:11]
	s_setprio 0
	s_setprio 1
	v_mfma_f32_16x16x32_bf16 v[52:55], v[144:147], v[160:163], v[52:55]
	v_mfma_f32_16x16x32_bf16 v[48:51], v[152:155], v[160:163], v[48:51]
	v_mfma_f32_16x16x32_bf16 v[36:39], v[144:147], v[184:187], v[36:39]
	v_mfma_f32_16x16x32_bf16 v[32:35], v[152:155], v[184:187], v[32:35]
	v_mfma_f32_16x16x32_bf16 v[20:23], v[144:147], v[192:195], v[20:23]
	v_mfma_f32_16x16x32_bf16 v[16:19], v[152:155], v[192:195], v[16:19]
	v_mfma_f32_16x16x32_bf16 v[4:7], v[144:147], v[208:211], v[4:7]
	v_mfma_f32_16x16x32_bf16 v[0:3], v[152:155], v[208:211], v[0:3]
	v_mfma_f32_16x16x32_bf16 v[52:55], v[148:151], v[164:167], v[52:55]
	v_mfma_f32_16x16x32_bf16 v[48:51], v[156:159], v[164:167], v[48:51]
	v_mfma_f32_16x16x32_bf16 v[36:39], v[148:151], v[188:191], v[36:39]
	v_mfma_f32_16x16x32_bf16 v[32:35], v[156:159], v[188:191], v[32:35]
	v_mfma_f32_16x16x32_bf16 v[20:23], v[148:151], v[204:207], v[20:23]
	v_mfma_f32_16x16x32_bf16 v[16:19], v[156:159], v[204:207], v[16:19]
	v_mfma_f32_16x16x32_bf16 v[4:7], v[148:151], v[212:215], v[4:7]
	v_mfma_f32_16x16x32_bf16 v[0:3], v[156:159], v[212:215], v[0:3]
	s_setprio 0
	s_barrier
	s_add_i32 s69, 0, 0x18000
	s_add_i32 s70, 0, 0x1c000
	v_add_u32_e32 v92, s69, v198
	v_add_u32_e32 v156, s70, v198
	ds_read_b128 v[72:75], v92
	ds_read_b128 v[76:79], v92 offset:1024
	ds_read_b128 v[88:91], v92 offset:2048
	ds_read_b128 v[92:95], v92 offset:3072
	ds_read_b128 v[144:147], v156
	ds_read_b128 v[148:151], v156 offset:1024
	ds_read_b128 v[152:155], v156 offset:2048
	ds_read_b128 v[156:159], v156 offset:3072
	v_lshl_add_u64 v[220:221], s[54:55], 0, v[168:169]
	s_mov_b32 m0, s35
	v_lshl_add_u64 v[222:223], s[54:55], 0, v[172:173]
	global_load_lds_dwordx4 v[220:221], off
	s_mov_b32 m0, s49
	s_nop 0
	global_load_lds_dwordx4 v[222:223], off
	s_add_u32 s54, s54, 0x80000
	s_addc_u32 s55, s55, 0
	s_mov_b32 m0, s56
	v_lshl_add_u64 v[224:225], s[54:55], 0, v[168:169]
	ds_read_b128 v[160:163], v202 offset:32768
	ds_read_b128 v[164:167], v202 offset:33792
	ds_read_b128 v[184:187], v202 offset:34816
	ds_read_b128 v[188:191], v202 offset:35840
	ds_read_b128 v[192:195], v202 offset:36864
	ds_read_b128 v[204:207], v202 offset:37888
	ds_read_b128 v[208:211], v202 offset:38912
	ds_read_b128 v[212:215], v202 offset:39936
	global_load_lds_dwordx4 v[224:225], off
	v_lshl_add_u64 v[224:225], s[54:55], 0, v[172:173]
	s_mov_b32 m0, s57
	s_nop 0
	global_load_lds_dwordx4 v[224:225], off
	s_waitcnt vmcnt(8)
	s_waitcnt lgkmcnt(0)
	s_barrier
; #define PG8_STAGE(bufoff, gbase, voff) do { _Pragma("unroll") for (int _i = 0; _i < 2; ++_i) \
;         __builtin_amdgcn_global_load_lds((const unsigned*)((const char*)(gbase) + (voff)[_i]), (PG8_LAS unsigned*)(lds + (bufoff) + ldsw + _i * 8192), 16, 0, 0); } while (0)
; #define PG8_LDA(dst, b, h) do { _Pragma("unroll") for (int m = 0; m < 4; ++m) _Pragma("unroll") for (int k = 0; k < 2; ++k) dst[m][k] = *(const PG8_LAS bf16x8*)(lds + PG8_SA(b, h) + aoff + m * 2048 + k * 1024); } while (0)
; #define PG8_MMA(ai, bj, At, Bt) do { __builtin_amdgcn_s_setprio(1); _Pragma("unroll") for (int m = 0; m < 4; ++m) _Pragma("unroll") for (int n = 0; n < 2; ++n) _Pragma("unroll") for (int k = 0; k < 2; ++k) \
;         acc[ai][bj][m][n] = __builtin_amdgcn_mfma_f32_16x16x32_bf16(Bt[n][k], At[m][k], acc[ai][bj][m][n], 0, 0, 0); __builtin_amdgcn_s_setprio(0); } while (0)
; #define PG8_WAIT_V(n) asm volatile("s_waitcnt vmcnt(" #n ")" ::: "memory")
; #define PG8_WAIT_L(n) asm volatile("s_waitcnt lgkmcnt(" #n ")" ::: "memory")
; #define PG8_BAR __builtin_amdgcn_s_barrier()
; #define PG8_SCHED __builtin_amdgcn_sched_barrier(0)
; template <class Epi, class Sched, bool ALIGN_EPI = false, bool SP2 = false>
; __device__ __forceinline__ void gemm_phase(PG8_LAS unsigned char* lds, const Gemm g, const Sched& S, const Epi& E, const int wid  ) {
;     ...
;         for (int t = 0; t < nt; t += 2) {
;     ...
;             PG8_WAIT_V(8); PG8_WAIT_L(0); PG8_BAR; PG8_MMA(0, 0, At, B0); PG8_MMA(0, 1, At, B1); PG8_BAR; PG8_SCHED;
;             PG8_LDA(At, 1, 1); PG8_STAGE(PG8_SB(1, 0), b3, voffB); PG8_STAGE(PG8_SB(1, 1), b3 + hstep, voffB); PG8_STAGE(PG8_SA(1, 0), a3, voffA);
;             PG8_WAIT_V(8); PG8_WAIT_L(0); PG8_BAR; PG8_MMA(1, 0, At, B0); PG8_MMA(1, 1, At, B1); PG8_BAR; PG8_SCHED;
	s_setprio 1
	s_waitcnt lgkmcnt(0)
	v_mfma_f32_16x16x32_bf16 v[140:143], v[72:75], v[160:163], v[140:143]
	v_mfma_f32_16x16x32_bf16 v[136:139], v[88:91], v[160:163], v[136:139]
	v_mfma_f32_16x16x32_bf16 v[124:127], v[72:75], v[184:187], v[124:127]
	v_mfma_f32_16x16x32_bf16 v[120:123], v[88:91], v[184:187], v[120:123]
	v_mfma_f32_16x16x32_bf16 v[108:111], v[72:75], v[192:195], v[108:111]
	v_mfma_f32_16x16x32_bf16 v[104:107], v[88:91], v[192:195], v[104:107]
	v_mfma_f32_16x16x32_bf16 v[84:87], v[72:75], v[208:211], v[84:87]
	v_mfma_f32_16x16x32_bf16 v[80:83], v[88:91], v[208:211], v[80:83]
	v_mfma_f32_16x16x32_bf16 v[140:143], v[76:79], v[164:167], v[140:143]
	v_mfma_f32_16x16x32_bf16 v[136:139], v[92:95], v[164:167], v[136:139]
	v_mfma_f32_16x16x32_bf16 v[124:127], v[76:79], v[188:191], v[124:127]
	v_mfma_f32_16x16x32_bf16 v[120:123], v[92:95], v[188:191], v[120:123]
	v_mfma_f32_16x16x32_bf16 v[108:111], v[76:79], v[204:207], v[108:111]
	v_mfma_f32_16x16x32_bf16 v[104:107], v[92:95], v[204:207], v[104:107]
	v_mfma_f32_16x16x32_bf16 v[84:87], v[76:79], v[212:215], v[84:87]
	v_mfma_f32_16x16x32_bf16 v[80:83], v[92:95], v[212:215], v[80:83]
	s_setprio 0
	s_setprio 1
	v_mfma_f32_16x16x32_bf16 v[132:135], v[144:147], v[160:163], v[132:135]
	v_mfma_f32_16x16x32_bf16 v[128:131], v[152:155], v[160:163], v[128:131]
	v_mfma_f32_16x16x32_bf16 v[116:119], v[144:147], v[184:187], v[116:119]
	v_mfma_f32_16x16x32_bf16 v[112:115], v[152:155], v[184:187], v[112:115]
	v_mfma_f32_16x16x32_bf16 v[100:103], v[144:147], v[192:195], v[100:103]
	v_mfma_f32_16x16x32_bf16 v[96:99], v[152:155], v[192:195], v[96:99]
	v_mfma_f32_16x16x32_bf16 v[68:71], v[144:147], v[208:211], v[68:71]
	v_mfma_f32_16x16x32_bf16 v[64:67], v[152:155], v[208:211], v[64:67]
	v_mfma_f32_16x16x32_bf16 v[132:135], v[148:151], v[164:167], v[132:135]
	v_mfma_f32_16x16x32_bf16 v[128:131], v[156:159], v[164:167], v[128:131]
	v_mfma_f32_16x16x32_bf16 v[116:119], v[148:151], v[188:191], v[116:119]
	v_mfma_f32_16x16x32_bf16 v[112:115], v[156:159], v[188:191], v[112:115]
	v_mfma_f32_16x16x32_bf16 v[100:103], v[148:151], v[204:207], v[100:103]
	v_mfma_f32_16x16x32_bf16 v[96:99], v[156:159], v[204:207], v[96:99]
	v_mfma_f32_16x16x32_bf16 v[68:71], v[148:151], v[212:215], v[68:71]
	v_mfma_f32_16x16x32_bf16 v[64:67], v[156:159], v[212:215], v[64:67]
	s_setprio 0
	s_barrier
	s_add_i32 s54, s69, s34
	v_lshl_add_u64 v[216:217], v[216:217], 0, s[22:23]
	s_mov_b32 m0, s54
	ds_read_b128 v[160:163], v202 offset:49152
	ds_read_b128 v[164:167], v202 offset:50176
	ds_read_b128 v[184:187], v202 offset:51200
	ds_read_b128 v[188:191], v202 offset:52224
	ds_read_b128 v[192:195], v202 offset:53248
	ds_read_b128 v[204:207], v202 offset:54272
	ds_read_b128 v[208:211], v202 offset:55296
	ds_read_b128 v[212:215], v202 offset:56320
	global_load_lds_dwordx4 v[216:217], off
	s_add_i32 m0, s54, 0x2000
	s_add_u32 s52, s52, 0x80080
	v_lshl_add_u64 v[216:217], v[218:219], 0, s[22:23]
	s_addc_u32 s53, s53, 0
	s_add_i32 s54, s70, s34
	global_load_lds_dwordx4 v[216:217], off
	v_lshl_add_u64 v[216:217], s[52:53], 0, v[170:171]
	s_mov_b32 m0, s54
	s_nop 0
	global_load_lds_dwordx4 v[216:217], off
	v_lshl_add_u64 v[216:217], s[52:53], 0, v[174:175]
	s_add_i32 m0, s54, 0x2000
	s_nop 0
	global_load_lds_dwordx4 v[216:217], off
	s_waitcnt vmcnt(6)
	s_waitcnt lgkmcnt(0)
	s_barrier
	s_setprio 1
	s_waitcnt lgkmcnt(0)
	v_mfma_f32_16x16x32_bf16 v[60:63], v[72:75], v[160:163], v[60:63]
	v_mfma_f32_16x16x32_bf16 v[56:59], v[88:91], v[160:163], v[56:59]
	v_mfma_f32_16x16x32_bf16 v[44:47], v[72:75], v[184:187], v[44:47]
	v_mfma_f32_16x16x32_bf16 v[40:43], v[88:91], v[184:187], v[40:43]
	v_mfma_f32_16x16x32_bf16 v[28:31], v[72:75], v[192:195], v[28:31]
	v_mfma_f32_16x16x32_bf16 v[24:27], v[88:91], v[192:195], v[24:27]
	v_mfma_f32_16x16x32_bf16 v[12:15], v[72:75], v[208:211], v[12:15]
	v_mfma_f32_16x16x32_bf16 v[8:11], v[88:91], v[208:211], v[8:11]
	v_mfma_f32_16x16x32_bf16 v[60:63], v[76:79], v[164:167], v[60:63]
	v_mfma_f32_16x16x32_bf16 v[56:59], v[92:95], v[164:167], v[56:59]
	v_mfma_f32_16x16x32_bf16 v[44:47], v[76:79], v[188:191], v[44:47]
	v_mfma_f32_16x16x32_bf16 v[40:43], v[92:95], v[188:191], v[40:43]
	v_mfma_f32_16x16x32_bf16 v[28:31], v[76:79], v[204:207], v[28:31]
	v_mfma_f32_16x16x32_bf16 v[24:27], v[92:95], v[204:207], v[24:27]
	v_mfma_f32_16x16x32_bf16 v[12:15], v[76:79], v[212:215], v[12:15]
	v_mfma_f32_16x16x32_bf16 v[8:11], v[92:95], v[212:215], v[8:11]
	s_setprio 0
	s_setprio 1
	v_mfma_f32_16x16x32_bf16 v[52:55], v[144:147], v[160:163], v[52:55]
	v_mfma_f32_16x16x32_bf16 v[48:51], v[152:155], v[160:163], v[48:51]
	v_mfma_f32_16x16x32_bf16 v[36:39], v[144:147], v[184:187], v[36:39]
	v_mfma_f32_16x16x32_bf16 v[32:35], v[152:155], v[184:187], v[32:35]
	v_mfma_f32_16x16x32_bf16 v[20:23], v[144:147], v[192:195], v[20:23]
	v_mfma_f32_16x16x32_bf16 v[16:19], v[152:155], v[192:195], v[16:19]
	v_mfma_f32_16x16x32_bf16 v[4:7], v[144:147], v[208:211], v[4:7]
	v_mfma_f32_16x16x32_bf16 v[0:3], v[152:155], v[208:211], v[0:3]
	v_mfma_f32_16x16x32_bf16 v[52:55], v[148:151], v[164:167], v[52:55]
	v_mfma_f32_16x16x32_bf16 v[48:51], v[156:159], v[164:167], v[48:51]
	v_mfma_f32_16x16x32_bf16 v[36:39], v[148:151], v[188:191], v[36:39]
	v_mfma_f32_16x16x32_bf16 v[32:35], v[156:159], v[188:191], v[32:35]
	v_mfma_f32_16x16x32_bf16 v[20:23], v[148:151], v[204:207], v[20:23]
	v_mfma_f32_16x16x32_bf16 v[16:19], v[156:159], v[204:207], v[16:19]
	v_mfma_f32_16x16x32_bf16 v[4:7], v[148:151], v[212:215], v[4:7]
	v_mfma_f32_16x16x32_bf16 v[0:3], v[156:159], v[212:215], v[0:3]
	s_setprio 0
	s_barrier
	s_add_i32 s68, s68, 2
	s_add_u32 s50, s50, 0x100
	s_addc_u32 s51, s51, 0
	s_add_u32 s66, s66, 0x100
	s_addc_u32 s67, s67, 0
	s_cmp_gt_u32 s68, 29
	s_cbranch_scc0 .LBB0_5665
	s_and_b64 vcc, exec, s[36:37]
	s_cbranch_vccz .LBB0_5668
	s_barrier

; #define PG8_STAGE(bufoff, gbase, voff) do { _Pragma("unroll") for (int _i = 0; _i < 2; ++_i) \
;         __builtin_amdgcn_global_load_lds((const unsigned*)((const char*)(gbase) + (voff)[_i]), (PG8_LAS unsigned*)(lds + (bufoff) + ldsw + _i * 8192), 16, 0, 0); } while (0)
; #define PG8_LDA(dst, b, h) do { _Pragma("unroll") for (int m = 0; m < 4; ++m) _Pragma("unroll") for (int k = 0; k < 2; ++k) dst[m][k] = *(const PG8_LAS bf16x8*)(lds + PG8_SA(b, h) + aoff + m * 2048 + k * 1024); } while (0)
; #define PG8_LDB(dst, b, h) do { _Pragma("unroll") for (int n = 0; n < 2; ++n) _Pragma("unroll") for (int k = 0; k < 2; ++k) dst[n][k] = *(const PG8_LAS bf16x8*)(lds + PG8_SB(b, h) + boff + n * 2048 + k * 1024); } while (0)
; #define PG8_MMA(ai, bj, At, Bt) do { __builtin_amdgcn_s_setprio(1); _Pragma("unroll") for (int m = 0; m < 4; ++m) _Pragma("unroll") for (int n = 0; n < 2; ++n) _Pragma("unroll") for (int k = 0; k < 2; ++k) \
;         acc[ai][bj][m][n] = __builtin_amdgcn_mfma_f32_16x16x32_bf16(Bt[n][k], At[m][k], acc[ai][bj][m][n], 0, 0, 0); __builtin_amdgcn_s_setprio(0); } while (0)
; #define PG8_WAIT_V(n) asm volatile("s_waitcnt vmcnt(" #n ")" ::: "memory")
; #define PG8_WAIT_L(n) asm volatile("s_waitcnt lgkmcnt(" #n ")" ::: "memory")
; #define PG8_BAR __builtin_amdgcn_s_barrier()
; #define PG8_SCHED __builtin_amdgcn_sched_barrier(0)
; template <class Epi, class Sched, bool ALIGN_EPI = false, bool SP2 = false>
; __device__ __forceinline__ void gemm_phase(PG8_LAS unsigned char* lds, const Gemm g, const Sched& S, const Epi& E, const int wid  ) {
;     ...
;             PG8_LDB(B0, 0, 0); PG8_LDB(B1, 0, 1); PG8_SCHED; PG8_LDA(At, 0, 0); PG8_STAGE(PG8_SA(1, 1), a1 + hstep, voffA);
;             PG8_WAIT_V(8); PG8_WAIT_L(0); PG8_BAR; PG8_MMA(0, 0, At, B0); PG8_MMA(0, 1, At, B1); PG8_BAR; PG8_SCHED;
;             PG8_LDA(At, 0, 1); PG8_STAGE(PG8_SB(0, 0), b2, voffB); PG8_STAGE(PG8_SB(0, 1), b2 + hstep, voffB); PG8_STAGE(PG8_SA(0, 0), a2, voffA);
.LBB0_5761:
	s_add_u32 s100, s8, 0xfff80000
	s_addc_u32 s101, s9, -1
	ds_read_b128 v[144:147], v153
	ds_read_b128 v[158:161], v153 offset:1024
	ds_read_b128 v[162:165], v153 offset:2048
	ds_read_b128 v[166:169], v153 offset:3072
	ds_read_b128 v[170:173], v154
	ds_read_b128 v[174:177], v154 offset:1024
	ds_read_b128 v[178:181], v154 offset:2048
	ds_read_b128 v[182:185], v154 offset:3072
	s_add_u32 s10, s8, 0xfff80080
	s_addc_u32 s11, s9, -1
	s_cmp_eq_u32 s65, 28
	s_cselect_b32 s13, s14, s11
	s_cselect_b32 s12, s15, s10
	s_cselect_b32 s11, s43, s64
	s_cselect_b32 s10, s45, s63
	v_lshl_add_u64 v[222:223], s[100:101], 0, v[136:137]
	s_mov_b32 m0, s56
	v_lshl_add_u64 v[224:225], s[100:101], 0, v[138:139]
	global_load_lds_dwordx4 v[222:223], off
	s_mov_b32 m0, s57
	s_nop 0
	global_load_lds_dwordx4 v[224:225], off
	v_lshl_add_u64 v[218:219], s[8:9], 0, v[136:137]
	s_add_i32 m0, s51, 0xc000
	ds_read_b128 v[186:189], v155
	ds_read_b128 v[190:193], v155 offset:1024
	ds_read_b128 v[194:197], v155 offset:2048
	ds_read_b128 v[198:201], v155 offset:3072
	ds_read_b128 v[202:205], v155 offset:4096
	ds_read_b128 v[206:209], v155 offset:5120
	ds_read_b128 v[210:213], v155 offset:6144
	ds_read_b128 v[214:217], v155 offset:7168
	global_load_lds_dwordx4 v[218:219], off
	v_lshl_add_u64 v[218:219], s[8:9], 0, v[138:139]
	s_add_i32 m0, s51, 0xe000
	s_nop 0
	global_load_lds_dwordx4 v[218:219], off
	s_waitcnt vmcnt(8)
	s_waitcnt lgkmcnt(0)
	s_barrier
	s_setprio 1
	s_waitcnt lgkmcnt(0)
	v_mfma_f32_16x16x32_bf16 v[124:127], v[144:147], v[186:189], v[124:127]
	v_mfma_f32_16x16x32_bf16 v[120:123], v[162:165], v[186:189], v[120:123]
	v_mfma_f32_16x16x32_bf16 v[108:111], v[144:147], v[194:197], v[108:111]
	v_mfma_f32_16x16x32_bf16 v[104:107], v[162:165], v[194:197], v[104:107]
	v_mfma_f32_16x16x32_bf16 v[92:95], v[144:147], v[202:205], v[92:95]
	v_mfma_f32_16x16x32_bf16 v[88:91], v[162:165], v[202:205], v[88:91]
	v_mfma_f32_16x16x32_bf16 v[76:79], v[144:147], v[210:213], v[76:79]
	v_mfma_f32_16x16x32_bf16 v[72:75], v[162:165], v[210:213], v[72:75]
	v_mfma_f32_16x16x32_bf16 v[124:127], v[158:161], v[190:193], v[124:127]
	v_mfma_f32_16x16x32_bf16 v[120:123], v[166:169], v[190:193], v[120:123]
	v_mfma_f32_16x16x32_bf16 v[108:111], v[158:161], v[198:201], v[108:111]
	v_mfma_f32_16x16x32_bf16 v[104:107], v[166:169], v[198:201], v[104:107]
	v_mfma_f32_16x16x32_bf16 v[92:95], v[158:161], v[206:209], v[92:95]
	v_mfma_f32_16x16x32_bf16 v[88:91], v[166:169], v[206:209], v[88:91]
	v_mfma_f32_16x16x32_bf16 v[76:79], v[158:161], v[214:217], v[76:79]
	v_mfma_f32_16x16x32_bf16 v[72:75], v[166:169], v[214:217], v[72:75]
	s_setprio 0
	s_setprio 1
	v_mfma_f32_16x16x32_bf16 v[116:119], v[170:173], v[186:189], v[116:119]
	v_mfma_f32_16x16x32_bf16 v[112:115], v[178:181], v[186:189], v[112:115]
	v_mfma_f32_16x16x32_bf16 v[100:103], v[170:173], v[194:197], v[100:103]
	v_mfma_f32_16x16x32_bf16 v[96:99], v[178:181], v[194:197], v[96:99]
	v_mfma_f32_16x16x32_bf16 v[84:87], v[170:173], v[202:205], v[84:87]
	v_mfma_f32_16x16x32_bf16 v[80:83], v[178:181], v[202:205], v[80:83]
	v_mfma_f32_16x16x32_bf16 v[68:71], v[170:173], v[210:213], v[68:71]
	v_mfma_f32_16x16x32_bf16 v[64:67], v[178:181], v[210:213], v[64:67]
	v_mfma_f32_16x16x32_bf16 v[116:119], v[174:177], v[190:193], v[116:119]
	v_mfma_f32_16x16x32_bf16 v[112:115], v[182:185], v[190:193], v[112:115]
	v_mfma_f32_16x16x32_bf16 v[100:103], v[174:177], v[198:201], v[100:103]
	v_mfma_f32_16x16x32_bf16 v[96:99], v[182:185], v[198:201], v[96:99]
	v_mfma_f32_16x16x32_bf16 v[84:87], v[174:177], v[206:209], v[84:87]
	v_mfma_f32_16x16x32_bf16 v[80:83], v[182:185], v[206:209], v[80:83]
	v_mfma_f32_16x16x32_bf16 v[68:71], v[174:177], v[214:217], v[68:71]
	v_mfma_f32_16x16x32_bf16 v[64:67], v[182:185], v[214:217], v[64:67]
	s_setprio 0
	s_barrier
	s_add_i32 s66, s59, s34
	v_lshl_add_u64 v[218:219], s[10:11], 0, v[132:133]
	s_mov_b32 m0, s66
	ds_read_b128 v[186:189], v155 offset:16384
	ds_read_b128 v[190:193], v155 offset:17408
	ds_read_b128 v[194:197], v155 offset:18432
	ds_read_b128 v[198:201], v155 offset:19456
	ds_read_b128 v[202:205], v155 offset:20480
	ds_read_b128 v[206:209], v155 offset:21504
	ds_read_b128 v[210:213], v155 offset:22528
	ds_read_b128 v[214:217], v155 offset:23552
	global_load_lds_dwordx4 v[218:219], off
	s_add_i32 m0, s66, 0x2000
	s_add_u32 s66, s10, 0x80000
	v_lshl_add_u64 v[220:221], s[10:11], 0, v[128:129]
	s_addc_u32 s67, s11, 0
	s_add_i32 s68, s60, s34
	global_load_lds_dwordx4 v[220:221], off
	v_lshl_add_u64 v[222:223], s[66:67], 0, v[132:133]
	s_mov_b32 m0, s68
	s_nop 0
	global_load_lds_dwordx4 v[222:223], off
	v_lshl_add_u64 v[222:223], s[66:67], 0, v[128:129]
	s_add_i32 m0, s68, 0x2000
	s_nop 0
	global_load_lds_dwordx4 v[222:223], off
	s_waitcnt vmcnt(6)
	s_waitcnt lgkmcnt(0)
	s_barrier
; #define PG8_STAGE(bufoff, gbase, voff) do { _Pragma("unroll") for (int _i = 0; _i < 2; ++_i) \
;         __builtin_amdgcn_global_load_lds((const unsigned*)((const char*)(gbase) + (voff)[_i]), (PG8_LAS unsigned*)(lds + (bufoff) + ldsw + _i * 8192), 16, 0, 0); } while (0)
; #define PG8_LDA(dst, b, h) do { _Pragma("unroll") for (int m = 0; m < 4; ++m) _Pragma("unroll") for (int k = 0; k < 2; ++k) dst[m][k] = *(const PG8_LAS bf16x8*)(lds + PG8_SA(b, h) + aoff + m * 2048 + k * 1024); } while (0)
; #define PG8_LDB(dst, b, h) do { _Pragma("unroll") for (int n = 0; n < 2; ++n) _Pragma("unroll") for (int k = 0; k < 2; ++k) dst[n][k] = *(const PG8_LAS bf16x8*)(lds + PG8_SB(b, h) + boff + n * 2048 + k * 1024); } while (0)
; #define PG8_MMA(ai, bj, At, Bt) do { __builtin_amdgcn_s_setprio(1); _Pragma("unroll") for (int m = 0; m < 4; ++m) _Pragma("unroll") for (int n = 0; n < 2; ++n) _Pragma("unroll") for (int k = 0; k < 2; ++k) \
;         acc[ai][bj][m][n] = __builtin_amdgcn_mfma_f32_16x16x32_bf16(Bt[n][k], At[m][k], acc[ai][bj][m][n], 0, 0, 0); __builtin_amdgcn_s_setprio(0); } while (0)
; #define PG8_WAIT_V(n) asm volatile("s_waitcnt vmcnt(" #n ")" ::: "memory")
; #define PG8_WAIT_L(n) asm volatile("s_waitcnt lgkmcnt(" #n ")" ::: "memory")
; #define PG8_BAR __builtin_amdgcn_s_barrier()
; #define PG8_SCHED __builtin_amdgcn_sched_barrier(0)
; template <class Epi, class Sched, bool ALIGN_EPI = false, bool SP2 = false>
; __device__ __forceinline__ void gemm_phase(PG8_LAS unsigned char* lds, const Gemm g, const Sched& S, const Epi& E, const int wid  ) {
;     ...
;             PG8_WAIT_V(8); PG8_WAIT_L(0); PG8_BAR; PG8_MMA(1, 0, At, B0); PG8_MMA(1, 1, At, B1); PG8_BAR; PG8_SCHED;
;             PG8_LDB(B0, 1, 0); PG8_LDB(B1, 1, 1); PG8_SCHED; PG8_LDA(At, 1, 0); PG8_STAGE(PG8_SA(0, 1), a2 + hstep, voffA);
	s_setprio 1
	s_waitcnt lgkmcnt(0)
	v_mfma_f32_16x16x32_bf16 v[60:63], v[144:147], v[186:189], v[60:63]
	v_mfma_f32_16x16x32_bf16 v[56:59], v[162:165], v[186:189], v[56:59]
	v_mfma_f32_16x16x32_bf16 v[44:47], v[144:147], v[194:197], v[44:47]
	v_mfma_f32_16x16x32_bf16 v[40:43], v[162:165], v[194:197], v[40:43]
	v_mfma_f32_16x16x32_bf16 v[28:31], v[144:147], v[202:205], v[28:31]
	v_mfma_f32_16x16x32_bf16 v[24:27], v[162:165], v[202:205], v[24:27]
	v_mfma_f32_16x16x32_bf16 v[12:15], v[144:147], v[210:213], v[12:15]
	v_mfma_f32_16x16x32_bf16 v[8:11], v[162:165], v[210:213], v[8:11]
	v_mfma_f32_16x16x32_bf16 v[60:63], v[158:161], v[190:193], v[60:63]
	v_mfma_f32_16x16x32_bf16 v[56:59], v[166:169], v[190:193], v[56:59]
	v_mfma_f32_16x16x32_bf16 v[44:47], v[158:161], v[198:201], v[44:47]
	v_mfma_f32_16x16x32_bf16 v[40:43], v[166:169], v[198:201], v[40:43]
	v_mfma_f32_16x16x32_bf16 v[28:31], v[158:161], v[206:209], v[28:31]
	v_mfma_f32_16x16x32_bf16 v[24:27], v[166:169], v[206:209], v[24:27]
	v_mfma_f32_16x16x32_bf16 v[12:15], v[158:161], v[214:217], v[12:15]
	v_mfma_f32_16x16x32_bf16 v[8:11], v[166:169], v[214:217], v[8:11]
	s_setprio 0
	s_setprio 1
	v_mfma_f32_16x16x32_bf16 v[52:55], v[170:173], v[186:189], v[52:55]
	v_mfma_f32_16x16x32_bf16 v[48:51], v[178:181], v[186:189], v[48:51]
	v_mfma_f32_16x16x32_bf16 v[36:39], v[170:173], v[194:197], v[36:39]
	v_mfma_f32_16x16x32_bf16 v[32:35], v[178:181], v[194:197], v[32:35]
	v_mfma_f32_16x16x32_bf16 v[20:23], v[170:173], v[202:205], v[20:23]
	v_mfma_f32_16x16x32_bf16 v[16:19], v[178:181], v[202:205], v[16:19]
	v_mfma_f32_16x16x32_bf16 v[4:7], v[170:173], v[210:213], v[4:7]
	v_mfma_f32_16x16x32_bf16 v[0:3], v[178:181], v[210:213], v[0:3]
	v_mfma_f32_16x16x32_bf16 v[52:55], v[174:177], v[190:193], v[52:55]
	v_mfma_f32_16x16x32_bf16 v[48:51], v[182:185], v[190:193], v[48:51]
	v_mfma_f32_16x16x32_bf16 v[36:39], v[174:177], v[198:201], v[36:39]
	v_mfma_f32_16x16x32_bf16 v[32:35], v[182:185], v[198:201], v[32:35]
	v_mfma_f32_16x16x32_bf16 v[20:23], v[174:177], v[206:209], v[20:23]
	v_mfma_f32_16x16x32_bf16 v[16:19], v[182:185], v[206:209], v[16:19]
	v_mfma_f32_16x16x32_bf16 v[4:7], v[174:177], v[214:217], v[4:7]
	v_mfma_f32_16x16x32_bf16 v[0:3], v[182:185], v[214:217], v[0:3]
	s_setprio 0
	s_barrier
	s_add_i32 s66, 0, 0x18000
	v_add_u32_e32 v148, s66, v151
	s_add_i32 s67, 0, 0x1c000
	ds_read_b128 v[144:147], v148
	ds_read_b128 v[158:161], v148 offset:1024
	ds_read_b128 v[162:165], v148 offset:2048
	ds_read_b128 v[166:169], v148 offset:3072
	v_add_u32_e32 v148, s67, v151
	ds_read_b128 v[170:173], v148
	ds_read_b128 v[174:177], v148 offset:1024
	ds_read_b128 v[178:181], v148 offset:2048
	ds_read_b128 v[182:185], v148 offset:3072
	v_lshl_add_u64 v[222:223], s[12:13], 0, v[134:135]
	s_mov_b32 m0, s51
	v_lshl_add_u64 v[224:225], s[12:13], 0, v[130:131]
	global_load_lds_dwordx4 v[222:223], off
	s_mov_b32 m0, s52
	s_nop 0
	global_load_lds_dwordx4 v[224:225], off
	s_add_u32 s12, s12, 0x80000
	s_addc_u32 s13, s13, 0
	s_mov_b32 m0, s53
	v_lshl_add_u64 v[226:227], s[12:13], 0, v[134:135]
	ds_read_b128 v[186:189], v155 offset:32768
	ds_read_b128 v[190:193], v155 offset:33792
	ds_read_b128 v[194:197], v155 offset:34816
	ds_read_b128 v[198:201], v155 offset:35840
	ds_read_b128 v[202:205], v155 offset:36864
	ds_read_b128 v[206:209], v155 offset:37888
	ds_read_b128 v[210:213], v155 offset:38912
	ds_read_b128 v[214:217], v155 offset:39936
	global_load_lds_dwordx4 v[226:227], off
	v_lshl_add_u64 v[226:227], s[12:13], 0, v[130:131]
	s_mov_b32 m0, s54
	s_nop 0
	global_load_lds_dwordx4 v[226:227], off
	s_waitcnt vmcnt(8)
	s_waitcnt lgkmcnt(0)
	s_barrier
; #define PG8_STAGE(bufoff, gbase, voff) do { _Pragma("unroll") for (int _i = 0; _i < 2; ++_i) \
;         __builtin_amdgcn_global_load_lds((const unsigned*)((const char*)(gbase) + (voff)[_i]), (PG8_LAS unsigned*)(lds + (bufoff) + ldsw + _i * 8192), 16, 0, 0); } while (0)
; #define PG8_LDA(dst, b, h) do { _Pragma("unroll") for (int m = 0; m < 4; ++m) _Pragma("unroll") for (int k = 0; k < 2; ++k) dst[m][k] = *(const PG8_LAS bf16x8*)(lds + PG8_SA(b, h) + aoff + m * 2048 + k * 1024); } while (0)
; #define PG8_MMA(ai, bj, At, Bt) do { __builtin_amdgcn_s_setprio(1); _Pragma("unroll") for (int m = 0; m < 4; ++m) _Pragma("unroll") for (int n = 0; n < 2; ++n) _Pragma("unroll") for (int k = 0; k < 2; ++k) \
;         acc[ai][bj][m][n] = __builtin_amdgcn_mfma_f32_16x16x32_bf16(Bt[n][k], At[m][k], acc[ai][bj][m][n], 0, 0, 0); __builtin_amdgcn_s_setprio(0); } while (0)
; #define PG8_WAIT_V(n) asm volatile("s_waitcnt vmcnt(" #n ")" ::: "memory")
; #define PG8_WAIT_L(n) asm volatile("s_waitcnt lgkmcnt(" #n ")" ::: "memory")
; #define PG8_BAR __builtin_amdgcn_s_barrier()
; #define PG8_SCHED __builtin_amdgcn_sched_barrier(0)
; template <class Epi, class Sched, bool ALIGN_EPI = false, bool SP2 = false>
; __device__ __forceinline__ void gemm_phase(PG8_LAS unsigned char* lds, const Gemm g, const Sched& S, const Epi& E, const int wid  ) {
;     ...
;         for (int t = 0; t < nt; t += 2) {
;     ...
;             PG8_WAIT_V(8); PG8_WAIT_L(0); PG8_BAR; PG8_MMA(0, 0, At, B0); PG8_MMA(0, 1, At, B1); PG8_BAR; PG8_SCHED;
;             PG8_LDA(At, 1, 1); PG8_STAGE(PG8_SB(1, 0), b3, voffB); PG8_STAGE(PG8_SB(1, 1), b3 + hstep, voffB); PG8_STAGE(PG8_SA(1, 0), a3, voffA);
;             PG8_WAIT_V(8); PG8_WAIT_L(0); PG8_BAR; PG8_MMA(1, 0, At, B0); PG8_MMA(1, 1, At, B1); PG8_BAR; PG8_SCHED;
	s_setprio 1
	s_waitcnt lgkmcnt(0)
	v_mfma_f32_16x16x32_bf16 v[124:127], v[144:147], v[186:189], v[124:127]
	v_mfma_f32_16x16x32_bf16 v[120:123], v[162:165], v[186:189], v[120:123]
	v_mfma_f32_16x16x32_bf16 v[108:111], v[144:147], v[194:197], v[108:111]
	v_mfma_f32_16x16x32_bf16 v[104:107], v[162:165], v[194:197], v[104:107]
	v_mfma_f32_16x16x32_bf16 v[92:95], v[144:147], v[202:205], v[92:95]
	v_mfma_f32_16x16x32_bf16 v[88:91], v[162:165], v[202:205], v[88:91]
	v_mfma_f32_16x16x32_bf16 v[76:79], v[144:147], v[210:213], v[76:79]
	v_mfma_f32_16x16x32_bf16 v[72:75], v[162:165], v[210:213], v[72:75]
	v_mfma_f32_16x16x32_bf16 v[124:127], v[158:161], v[190:193], v[124:127]
	v_mfma_f32_16x16x32_bf16 v[120:123], v[166:169], v[190:193], v[120:123]
	v_mfma_f32_16x16x32_bf16 v[108:111], v[158:161], v[198:201], v[108:111]
	v_mfma_f32_16x16x32_bf16 v[104:107], v[166:169], v[198:201], v[104:107]
	v_mfma_f32_16x16x32_bf16 v[92:95], v[158:161], v[206:209], v[92:95]
	v_mfma_f32_16x16x32_bf16 v[88:91], v[166:169], v[206:209], v[88:91]
	v_mfma_f32_16x16x32_bf16 v[76:79], v[158:161], v[214:217], v[76:79]
	v_mfma_f32_16x16x32_bf16 v[72:75], v[166:169], v[214:217], v[72:75]
	s_setprio 0
	s_setprio 1
	v_mfma_f32_16x16x32_bf16 v[116:119], v[170:173], v[186:189], v[116:119]
	v_mfma_f32_16x16x32_bf16 v[112:115], v[178:181], v[186:189], v[112:115]
	v_mfma_f32_16x16x32_bf16 v[100:103], v[170:173], v[194:197], v[100:103]
	v_mfma_f32_16x16x32_bf16 v[96:99], v[178:181], v[194:197], v[96:99]
	v_mfma_f32_16x16x32_bf16 v[84:87], v[170:173], v[202:205], v[84:87]
	v_mfma_f32_16x16x32_bf16 v[80:83], v[178:181], v[202:205], v[80:83]
	v_mfma_f32_16x16x32_bf16 v[68:71], v[170:173], v[210:213], v[68:71]
	v_mfma_f32_16x16x32_bf16 v[64:67], v[178:181], v[210:213], v[64:67]
	v_mfma_f32_16x16x32_bf16 v[116:119], v[174:177], v[190:193], v[116:119]
	v_mfma_f32_16x16x32_bf16 v[112:115], v[182:185], v[190:193], v[112:115]
	v_mfma_f32_16x16x32_bf16 v[100:103], v[174:177], v[198:201], v[100:103]
	v_mfma_f32_16x16x32_bf16 v[96:99], v[182:185], v[198:201], v[96:99]
	v_mfma_f32_16x16x32_bf16 v[84:87], v[174:177], v[206:209], v[84:87]
	v_mfma_f32_16x16x32_bf16 v[80:83], v[182:185], v[206:209], v[80:83]
	v_mfma_f32_16x16x32_bf16 v[68:71], v[174:177], v[214:217], v[68:71]
	v_mfma_f32_16x16x32_bf16 v[64:67], v[182:185], v[214:217], v[64:67]
	s_setprio 0
	s_barrier
	s_add_i32 s12, s66, s34
	v_lshl_add_u64 v[218:219], v[218:219], 0, s[38:39]
	s_mov_b32 m0, s12
	ds_read_b128 v[186:189], v155 offset:49152
	ds_read_b128 v[190:193], v155 offset:50176
	ds_read_b128 v[194:197], v155 offset:51200
	ds_read_b128 v[198:201], v155 offset:52224
	ds_read_b128 v[202:205], v155 offset:53248
	ds_read_b128 v[206:209], v155 offset:54272
	ds_read_b128 v[210:213], v155 offset:55296
	ds_read_b128 v[214:217], v155 offset:56320
	global_load_lds_dwordx4 v[218:219], off
	s_add_i32 m0, s12, 0x2000
	s_add_u32 s10, s10, 0x80080
	v_lshl_add_u64 v[218:219], v[220:221], 0, s[38:39]
	s_addc_u32 s11, s11, 0
	s_add_i32 s12, s67, s34
	global_load_lds_dwordx4 v[218:219], off
	v_lshl_add_u64 v[218:219], s[10:11], 0, v[132:133]
	s_mov_b32 m0, s12
	s_nop 0
	global_load_lds_dwordx4 v[218:219], off
	v_lshl_add_u64 v[218:219], s[10:11], 0, v[128:129]
	s_add_i32 m0, s12, 0x2000
	s_nop 0
	global_load_lds_dwordx4 v[218:219], off
	s_waitcnt vmcnt(6)
	s_waitcnt lgkmcnt(0)
	s_barrier
	s_setprio 1
	s_waitcnt lgkmcnt(0)
	v_mfma_f32_16x16x32_bf16 v[60:63], v[144:147], v[186:189], v[60:63]
	v_mfma_f32_16x16x32_bf16 v[56:59], v[162:165], v[186:189], v[56:59]
	v_mfma_f32_16x16x32_bf16 v[44:47], v[144:147], v[194:197], v[44:47]
	v_mfma_f32_16x16x32_bf16 v[40:43], v[162:165], v[194:197], v[40:43]
	v_mfma_f32_16x16x32_bf16 v[28:31], v[144:147], v[202:205], v[28:31]
	v_mfma_f32_16x16x32_bf16 v[24:27], v[162:165], v[202:205], v[24:27]
	v_mfma_f32_16x16x32_bf16 v[12:15], v[144:147], v[210:213], v[12:15]
	v_mfma_f32_16x16x32_bf16 v[8:11], v[162:165], v[210:213], v[8:11]
	v_mfma_f32_16x16x32_bf16 v[60:63], v[158:161], v[190:193], v[60:63]
	v_mfma_f32_16x16x32_bf16 v[56:59], v[166:169], v[190:193], v[56:59]
	v_mfma_f32_16x16x32_bf16 v[44:47], v[158:161], v[198:201], v[44:47]
	v_mfma_f32_16x16x32_bf16 v[40:43], v[166:169], v[198:201], v[40:43]
	v_mfma_f32_16x16x32_bf16 v[28:31], v[158:161], v[206:209], v[28:31]
	v_mfma_f32_16x16x32_bf16 v[24:27], v[166:169], v[206:209], v[24:27]
	v_mfma_f32_16x16x32_bf16 v[12:15], v[158:161], v[214:217], v[12:15]
	v_mfma_f32_16x16x32_bf16 v[8:11], v[166:169], v[214:217], v[8:11]
	s_setprio 0
	s_setprio 1
	v_mfma_f32_16x16x32_bf16 v[52:55], v[170:173], v[186:189], v[52:55]
	v_mfma_f32_16x16x32_bf16 v[48:51], v[178:181], v[186:189], v[48:51]
	v_mfma_f32_16x16x32_bf16 v[36:39], v[170:173], v[194:197], v[36:39]
	v_mfma_f32_16x16x32_bf16 v[32:35], v[178:181], v[194:197], v[32:35]
	v_mfma_f32_16x16x32_bf16 v[20:23], v[170:173], v[202:205], v[20:23]
	v_mfma_f32_16x16x32_bf16 v[16:19], v[178:181], v[202:205], v[16:19]
	v_mfma_f32_16x16x32_bf16 v[4:7], v[170:173], v[210:213], v[4:7]
	v_mfma_f32_16x16x32_bf16 v[0:3], v[178:181], v[210:213], v[0:3]
	v_mfma_f32_16x16x32_bf16 v[52:55], v[174:177], v[190:193], v[52:55]
	v_mfma_f32_16x16x32_bf16 v[48:51], v[182:185], v[190:193], v[48:51]
	v_mfma_f32_16x16x32_bf16 v[36:39], v[174:177], v[198:201], v[36:39]
	v_mfma_f32_16x16x32_bf16 v[32:35], v[182:185], v[198:201], v[32:35]
	v_mfma_f32_16x16x32_bf16 v[20:23], v[174:177], v[206:209], v[20:23]
	v_mfma_f32_16x16x32_bf16 v[16:19], v[182:185], v[206:209], v[16:19]
	v_mfma_f32_16x16x32_bf16 v[4:7], v[174:177], v[214:217], v[4:7]
	v_mfma_f32_16x16x32_bf16 v[0:3], v[182:185], v[214:217], v[0:3]
	s_setprio 0
	s_barrier
	s_add_i32 s65, s65, 2
	s_add_u32 s8, s8, 0x100
	s_addc_u32 s9, s9, 0
	s_add_u32 s63, s63, 0x100
	s_addc_u32 s64, s64, 0
	s_cmp_gt_u32 s65, 29
	s_cbranch_scc0 .LBB0_5761
	s_and_b64 vcc, exec, s[40:41]
	s_cbranch_vccz .LBB0_5764
	s_barrier

; #define PG8_STAGE(bufoff, gbase, voff) do { _Pragma("unroll") for (int _i = 0; _i < 2; ++_i) \
;         __builtin_amdgcn_global_load_lds((const unsigned*)((const char*)(gbase) + (voff)[_i]), (PG8_LAS unsigned*)(lds + (bufoff) + ldsw + _i * 8192), 16, 0, 0); } while (0)
; #define PG8_LDA(dst, b, h) do { _Pragma("unroll") for (int m = 0; m < 4; ++m) _Pragma("unroll") for (int k = 0; k < 2; ++k) dst[m][k] = *(const PG8_LAS bf16x8*)(lds + PG8_SA(b, h) + aoff + m * 2048 + k * 1024); } while (0)
; #define PG8_LDB(dst, b, h) do { _Pragma("unroll") for (int n = 0; n < 2; ++n) _Pragma("unroll") for (int k = 0; k < 2; ++k) dst[n][k] = *(const PG8_LAS bf16x8*)(lds + PG8_SB(b, h) + boff + n * 2048 + k * 1024); } while (0)
; #define PG8_MMA(ai, bj, At, Bt) do { __builtin_amdgcn_s_setprio(1); _Pragma("unroll") for (int m = 0; m < 4; ++m) _Pragma("unroll") for (int n = 0; n < 2; ++n) _Pragma("unroll") for (int k = 0; k < 2; ++k) \
;         acc[ai][bj][m][n] = __builtin_amdgcn_mfma_f32_16x16x32_bf16(Bt[n][k], At[m][k], acc[ai][bj][m][n], 0, 0, 0); __builtin_amdgcn_s_setprio(0); } while (0)
; #define PG8_WAIT_V(n) asm volatile("s_waitcnt vmcnt(" #n ")" ::: "memory")
; #define PG8_WAIT_L(n) asm volatile("s_waitcnt lgkmcnt(" #n ")" ::: "memory")
; #define PG8_BAR __builtin_amdgcn_s_barrier()
; #define PG8_SCHED __builtin_amdgcn_sched_barrier(0)
; template <class Epi, class Sched, bool ALIGN_EPI = false, bool SP2 = false>
; __device__ __forceinline__ void gemm_phase(PG8_LAS unsigned char* lds, const Gemm g, const Sched& S, const Epi& E, const int wid  ) {
;     ...
;             const bool last = (t == nt - 2);
;             const char* a1 = cA + (size_t)(t + 1) * kstep;
;             const char* a2 = last ? nA : cA + (size_t)(t + 2) * kstep; const char* b2 = last ? nB : cB + (size_t)(t + 2) * kstep;
;             const char* a3 = a2 + kstep; const char* b3 = b2 + kstep;
;     ...
;             PG8_LDB(B0, 0, 0); PG8_LDB(B1, 0, 1); PG8_SCHED; PG8_LDA(At, 0, 0); PG8_STAGE(PG8_SA(1, 1), a1 + hstep, voffA);
;             PG8_WAIT_V(8); PG8_WAIT_L(0); PG8_BAR; PG8_MMA(0, 0, At, B0); PG8_MMA(0, 1, At, B1); PG8_BAR; PG8_SCHED;
;             PG8_LDA(At, 0, 1); PG8_STAGE(PG8_SB(0, 0), b2, voffB); PG8_STAGE(PG8_SB(0, 1), b2 + hstep, voffB); PG8_STAGE(PG8_SA(0, 0), a2, voffA);
.LBB0_5850:
	s_add_u32 s100, s18, 0xffea0000
	s_addc_u32 s101, s19, -1
	ds_read_b128 v[144:147], v153
	ds_read_b128 v[156:159], v153 offset:1024
	ds_read_b128 v[160:163], v153 offset:2048
	ds_read_b128 v[164:167], v153 offset:3072
	ds_read_b128 v[168:171], v154
	ds_read_b128 v[172:175], v154 offset:1024
	ds_read_b128 v[176:179], v154 offset:2048
	ds_read_b128 v[180:183], v154 offset:3072
	s_add_u32 s20, s18, 0x100
	s_addc_u32 s21, s19, 0
	s_cmpk_eq_i32 s49, 0x54
	s_cselect_b32 s25, s5, s21
	s_cselect_b32 s24, s4, s20
	s_cselect_b32 s23, s17, s48
	s_cselect_b32 s22, s16, s47
	v_lshl_add_u64 v[218:219], s[100:101], 0, v[136:137]
	s_mov_b32 m0, s39
	v_lshl_add_u64 v[220:221], s[100:101], 0, v[138:139]
	global_load_lds_dwordx4 v[218:219], off
	s_mov_b32 m0, s40
	s_nop 0
	global_load_lds_dwordx4 v[220:221], off
	v_lshl_add_u64 v[148:149], s[18:19], 0, v[136:137]
	s_add_i32 m0, s34, 0xc000
	ds_read_b128 v[184:187], v155
	ds_read_b128 v[188:191], v155 offset:1024
	ds_read_b128 v[192:195], v155 offset:2048
	ds_read_b128 v[196:199], v155 offset:3072
	ds_read_b128 v[200:203], v155 offset:4096
	ds_read_b128 v[204:207], v155 offset:5120
	ds_read_b128 v[208:211], v155 offset:6144
	ds_read_b128 v[212:215], v155 offset:7168
	global_load_lds_dwordx4 v[148:149], off
	v_lshl_add_u64 v[148:149], s[18:19], 0, v[138:139]
	s_add_i32 m0, s34, 0xe000
	s_nop 0
	global_load_lds_dwordx4 v[148:149], off
	s_waitcnt vmcnt(8)
	s_waitcnt lgkmcnt(0)
	s_barrier
	s_setprio 1
	s_waitcnt lgkmcnt(0)
	v_mfma_f32_16x16x32_bf16 v[124:127], v[144:147], v[184:187], v[124:127]
	v_mfma_f32_16x16x32_bf16 v[120:123], v[160:163], v[184:187], v[120:123]
	v_mfma_f32_16x16x32_bf16 v[112:115], v[144:147], v[192:195], v[112:115]
	v_mfma_f32_16x16x32_bf16 v[104:107], v[160:163], v[192:195], v[104:107]
	v_mfma_f32_16x16x32_bf16 v[96:99], v[144:147], v[200:203], v[96:99]
	v_mfma_f32_16x16x32_bf16 v[88:91], v[160:163], v[200:203], v[88:91]
	v_mfma_f32_16x16x32_bf16 v[80:83], v[144:147], v[208:211], v[80:83]
	v_mfma_f32_16x16x32_bf16 v[72:75], v[160:163], v[208:211], v[72:75]
	v_mfma_f32_16x16x32_bf16 v[124:127], v[156:159], v[188:191], v[124:127]
	v_mfma_f32_16x16x32_bf16 v[120:123], v[164:167], v[188:191], v[120:123]
	v_mfma_f32_16x16x32_bf16 v[112:115], v[156:159], v[196:199], v[112:115]
	v_mfma_f32_16x16x32_bf16 v[104:107], v[164:167], v[196:199], v[104:107]
	v_mfma_f32_16x16x32_bf16 v[96:99], v[156:159], v[204:207], v[96:99]
	v_mfma_f32_16x16x32_bf16 v[88:91], v[164:167], v[204:207], v[88:91]
	v_mfma_f32_16x16x32_bf16 v[80:83], v[156:159], v[212:215], v[80:83]
	v_mfma_f32_16x16x32_bf16 v[72:75], v[164:167], v[212:215], v[72:75]
	s_setprio 0
	s_setprio 1
	v_mfma_f32_16x16x32_bf16 v[116:119], v[168:171], v[184:187], v[116:119]
	v_mfma_f32_16x16x32_bf16 v[108:111], v[176:179], v[184:187], v[108:111]
	v_mfma_f32_16x16x32_bf16 v[100:103], v[168:171], v[192:195], v[100:103]
	v_mfma_f32_16x16x32_bf16 v[92:95], v[176:179], v[192:195], v[92:95]
	v_mfma_f32_16x16x32_bf16 v[84:87], v[168:171], v[200:203], v[84:87]
	v_mfma_f32_16x16x32_bf16 v[76:79], v[176:179], v[200:203], v[76:79]
	v_mfma_f32_16x16x32_bf16 v[68:71], v[168:171], v[208:211], v[68:71]
	v_mfma_f32_16x16x32_bf16 v[64:67], v[176:179], v[208:211], v[64:67]
	v_mfma_f32_16x16x32_bf16 v[116:119], v[172:175], v[188:191], v[116:119]
	v_mfma_f32_16x16x32_bf16 v[108:111], v[180:183], v[188:191], v[108:111]
	v_mfma_f32_16x16x32_bf16 v[100:103], v[172:175], v[196:199], v[100:103]
	v_mfma_f32_16x16x32_bf16 v[92:95], v[180:183], v[196:199], v[92:95]
	v_mfma_f32_16x16x32_bf16 v[84:87], v[172:175], v[204:207], v[84:87]
	v_mfma_f32_16x16x32_bf16 v[76:79], v[180:183], v[204:207], v[76:79]
	v_mfma_f32_16x16x32_bf16 v[68:71], v[172:175], v[212:215], v[68:71]
	v_mfma_f32_16x16x32_bf16 v[64:67], v[180:183], v[212:215], v[64:67]
	s_setprio 0
	s_barrier
	s_add_i32 s18, s41, s31
	v_lshl_add_u64 v[148:149], s[22:23], 0, v[130:131]
	s_mov_b32 m0, s18
	ds_read_b128 v[184:187], v155 offset:16384
	ds_read_b128 v[188:191], v155 offset:17408
	ds_read_b128 v[192:195], v155 offset:18432
	ds_read_b128 v[196:199], v155 offset:19456
	ds_read_b128 v[200:203], v155 offset:20480
	ds_read_b128 v[204:207], v155 offset:21504
	ds_read_b128 v[208:211], v155 offset:22528
	ds_read_b128 v[212:215], v155 offset:23552
	global_load_lds_dwordx4 v[148:149], off
	s_add_i32 m0, s18, 0x2000
	s_add_u32 s18, s22, 0x160000
	v_lshl_add_u64 v[216:217], s[22:23], 0, v[134:135]
	s_addc_u32 s19, s23, 0
	s_add_i32 s50, s42, s31
	global_load_lds_dwordx4 v[216:217], off
	v_lshl_add_u64 v[218:219], s[18:19], 0, v[130:131]
	s_mov_b32 m0, s50
	s_nop 0
	global_load_lds_dwordx4 v[218:219], off
	v_lshl_add_u64 v[218:219], s[18:19], 0, v[134:135]
	s_add_i32 m0, s50, 0x2000
	s_nop 0
	global_load_lds_dwordx4 v[218:219], off
	s_waitcnt vmcnt(6)
	s_waitcnt lgkmcnt(0)
	s_barrier
; #define PG8_STAGE(bufoff, gbase, voff) do { _Pragma("unroll") for (int _i = 0; _i < 2; ++_i) \
;         __builtin_amdgcn_global_load_lds((const unsigned*)((const char*)(gbase) + (voff)[_i]), (PG8_LAS unsigned*)(lds + (bufoff) + ldsw + _i * 8192), 16, 0, 0); } while (0)
; #define PG8_LDA(dst, b, h) do { _Pragma("unroll") for (int m = 0; m < 4; ++m) _Pragma("unroll") for (int k = 0; k < 2; ++k) dst[m][k] = *(const PG8_LAS bf16x8*)(lds + PG8_SA(b, h) + aoff + m * 2048 + k * 1024); } while (0)
; #define PG8_LDB(dst, b, h) do { _Pragma("unroll") for (int n = 0; n < 2; ++n) _Pragma("unroll") for (int k = 0; k < 2; ++k) dst[n][k] = *(const PG8_LAS bf16x8*)(lds + PG8_SB(b, h) + boff + n * 2048 + k * 1024); } while (0)
; #define PG8_MMA(ai, bj, At, Bt) do { __builtin_amdgcn_s_setprio(1); _Pragma("unroll") for (int m = 0; m < 4; ++m) _Pragma("unroll") for (int n = 0; n < 2; ++n) _Pragma("unroll") for (int k = 0; k < 2; ++k) \
;         acc[ai][bj][m][n] = __builtin_amdgcn_mfma_f32_16x16x32_bf16(Bt[n][k], At[m][k], acc[ai][bj][m][n], 0, 0, 0); __builtin_amdgcn_s_setprio(0); } while (0)
; #define PG8_WAIT_V(n) asm volatile("s_waitcnt vmcnt(" #n ")" ::: "memory")
; #define PG8_WAIT_L(n) asm volatile("s_waitcnt lgkmcnt(" #n ")" ::: "memory")
; #define PG8_BAR __builtin_amdgcn_s_barrier()
; #define PG8_SCHED __builtin_amdgcn_sched_barrier(0)
; template <class Epi, class Sched, bool ALIGN_EPI = false, bool SP2 = false>
; __device__ __forceinline__ void gemm_phase(PG8_LAS unsigned char* lds, const Gemm g, const Sched& S, const Epi& E, const int wid  ) {
;     ...
;             PG8_WAIT_V(8); PG8_WAIT_L(0); PG8_BAR; PG8_MMA(1, 0, At, B0); PG8_MMA(1, 1, At, B1); PG8_BAR; PG8_SCHED;
;             PG8_LDB(B0, 1, 0); PG8_LDB(B1, 1, 1); PG8_SCHED; PG8_LDA(At, 1, 0); PG8_STAGE(PG8_SA(0, 1), a2 + hstep, voffA);
;             PG8_WAIT_V(8); PG8_WAIT_L(0); PG8_BAR; PG8_MMA(0, 0, At, B0); PG8_MMA(0, 1, At, B1); PG8_BAR; PG8_SCHED;
	s_setprio 1
	s_waitcnt lgkmcnt(0)
	v_mfma_f32_16x16x32_bf16 v[60:63], v[144:147], v[184:187], v[60:63]
	v_mfma_f32_16x16x32_bf16 v[56:59], v[160:163], v[184:187], v[56:59]
	v_mfma_f32_16x16x32_bf16 v[48:51], v[144:147], v[192:195], v[48:51]
	v_mfma_f32_16x16x32_bf16 v[40:43], v[160:163], v[192:195], v[40:43]
	v_mfma_f32_16x16x32_bf16 v[32:35], v[144:147], v[200:203], v[32:35]
	v_mfma_f32_16x16x32_bf16 v[24:27], v[160:163], v[200:203], v[24:27]
	v_mfma_f32_16x16x32_bf16 v[16:19], v[144:147], v[208:211], v[16:19]
	v_mfma_f32_16x16x32_bf16 v[8:11], v[160:163], v[208:211], v[8:11]
	v_mfma_f32_16x16x32_bf16 v[60:63], v[156:159], v[188:191], v[60:63]
	v_mfma_f32_16x16x32_bf16 v[56:59], v[164:167], v[188:191], v[56:59]
	v_mfma_f32_16x16x32_bf16 v[48:51], v[156:159], v[196:199], v[48:51]
	v_mfma_f32_16x16x32_bf16 v[40:43], v[164:167], v[196:199], v[40:43]
	v_mfma_f32_16x16x32_bf16 v[32:35], v[156:159], v[204:207], v[32:35]
	v_mfma_f32_16x16x32_bf16 v[24:27], v[164:167], v[204:207], v[24:27]
	v_mfma_f32_16x16x32_bf16 v[16:19], v[156:159], v[212:215], v[16:19]
	v_mfma_f32_16x16x32_bf16 v[8:11], v[164:167], v[212:215], v[8:11]
	s_setprio 0
	s_setprio 1
	v_mfma_f32_16x16x32_bf16 v[52:55], v[168:171], v[184:187], v[52:55]
	v_mfma_f32_16x16x32_bf16 v[44:47], v[176:179], v[184:187], v[44:47]
	v_mfma_f32_16x16x32_bf16 v[36:39], v[168:171], v[192:195], v[36:39]
	v_mfma_f32_16x16x32_bf16 v[28:31], v[176:179], v[192:195], v[28:31]
	v_mfma_f32_16x16x32_bf16 v[20:23], v[168:171], v[200:203], v[20:23]
	v_mfma_f32_16x16x32_bf16 v[12:15], v[176:179], v[200:203], v[12:15]
	v_mfma_f32_16x16x32_bf16 v[4:7], v[168:171], v[208:211], v[4:7]
	v_mfma_f32_16x16x32_bf16 v[0:3], v[176:179], v[208:211], v[0:3]
	v_mfma_f32_16x16x32_bf16 v[52:55], v[172:175], v[188:191], v[52:55]
	v_mfma_f32_16x16x32_bf16 v[44:47], v[180:183], v[188:191], v[44:47]
	v_mfma_f32_16x16x32_bf16 v[36:39], v[172:175], v[196:199], v[36:39]
	v_mfma_f32_16x16x32_bf16 v[28:31], v[180:183], v[196:199], v[28:31]
	v_mfma_f32_16x16x32_bf16 v[20:23], v[172:175], v[204:207], v[20:23]
	v_mfma_f32_16x16x32_bf16 v[12:15], v[180:183], v[204:207], v[12:15]
	v_mfma_f32_16x16x32_bf16 v[4:7], v[172:175], v[212:215], v[4:7]
	v_mfma_f32_16x16x32_bf16 v[0:3], v[180:183], v[212:215], v[0:3]
	s_setprio 0
	s_barrier
	s_add_i32 s50, 0, 0x18000
	s_add_i32 s51, 0, 0x1c000
	v_add_u32_e32 v164, s50, v151
	v_add_u32_e32 v180, s51, v151
	ds_read_b128 v[144:147], v164
	ds_read_b128 v[156:159], v164 offset:1024
	ds_read_b128 v[160:163], v164 offset:2048
	ds_read_b128 v[164:167], v164 offset:3072
	ds_read_b128 v[168:171], v180
	ds_read_b128 v[172:175], v180 offset:1024
	ds_read_b128 v[176:179], v180 offset:2048
	ds_read_b128 v[180:183], v180 offset:3072
	v_lshl_add_u64 v[218:219], s[24:25], 0, v[128:129]
	s_mov_b32 m0, s34
	v_lshl_add_u64 v[220:221], s[24:25], 0, v[132:133]
	global_load_lds_dwordx4 v[218:219], off
	s_mov_b32 m0, s35
	s_nop 0
	global_load_lds_dwordx4 v[220:221], off
	s_add_u32 s18, s24, 0x160000
	s_addc_u32 s19, s25, 0
	s_mov_b32 m0, s36
	v_lshl_add_u64 v[222:223], s[18:19], 0, v[128:129]
	ds_read_b128 v[184:187], v155 offset:32768
	ds_read_b128 v[188:191], v155 offset:33792
	ds_read_b128 v[192:195], v155 offset:34816
	ds_read_b128 v[196:199], v155 offset:35840
	ds_read_b128 v[200:203], v155 offset:36864
	ds_read_b128 v[204:207], v155 offset:37888
	ds_read_b128 v[208:211], v155 offset:38912
	ds_read_b128 v[212:215], v155 offset:39936
	global_load_lds_dwordx4 v[222:223], off
	v_lshl_add_u64 v[222:223], s[18:19], 0, v[132:133]
	s_mov_b32 m0, s37
	s_nop 0
	global_load_lds_dwordx4 v[222:223], off
	s_waitcnt vmcnt(8)
	s_waitcnt lgkmcnt(0)
	s_barrier
; #define PG8_STAGE(bufoff, gbase, voff) do { _Pragma("unroll") for (int _i = 0; _i < 2; ++_i) \
;         __builtin_amdgcn_global_load_lds((const unsigned*)((const char*)(gbase) + (voff)[_i]), (PG8_LAS unsigned*)(lds + (bufoff) + ldsw + _i * 8192), 16, 0, 0); } while (0)
; #define PG8_LDA(dst, b, h) do { _Pragma("unroll") for (int m = 0; m < 4; ++m) _Pragma("unroll") for (int k = 0; k < 2; ++k) dst[m][k] = *(const PG8_LAS bf16x8*)(lds + PG8_SA(b, h) + aoff + m * 2048 + k * 1024); } while (0)
; #define PG8_MMA(ai, bj, At, Bt) do { __builtin_amdgcn_s_setprio(1); _Pragma("unroll") for (int m = 0; m < 4; ++m) _Pragma("unroll") for (int n = 0; n < 2; ++n) _Pragma("unroll") for (int k = 0; k < 2; ++k) \
;         acc[ai][bj][m][n] = __builtin_amdgcn_mfma_f32_16x16x32_bf16(Bt[n][k], At[m][k], acc[ai][bj][m][n], 0, 0, 0); __builtin_amdgcn_s_setprio(0); } while (0)
; #define PG8_WAIT_V(n) asm volatile("s_waitcnt vmcnt(" #n ")" ::: "memory")
; #define PG8_WAIT_L(n) asm volatile("s_waitcnt lgkmcnt(" #n ")" ::: "memory")
; #define PG8_BAR __builtin_amdgcn_s_barrier()
; #define PG8_SCHED __builtin_amdgcn_sched_barrier(0)
; template <class Epi, class Sched, bool ALIGN_EPI = false, bool SP2 = false>
; __device__ __forceinline__ void gemm_phase(PG8_LAS unsigned char* lds, const Gemm g, const Sched& S, const Epi& E, const int wid  ) {
;     ...
;         for (int t = 0; t < nt; t += 2) {
;             const bool last = (t == nt - 2);
;     ...
;             PG8_WAIT_V(8); PG8_WAIT_L(0); PG8_BAR; PG8_MMA(0, 0, At, B0); PG8_MMA(0, 1, At, B1); PG8_BAR; PG8_SCHED;
;             PG8_LDA(At, 1, 1); PG8_STAGE(PG8_SB(1, 0), b3, voffB); PG8_STAGE(PG8_SB(1, 1), b3 + hstep, voffB); PG8_STAGE(PG8_SA(1, 0), a3, voffA);
;             PG8_WAIT_V(8); PG8_WAIT_L(0); PG8_BAR; PG8_MMA(1, 0, At, B0); PG8_MMA(1, 1, At, B1); PG8_BAR; PG8_SCHED;
	s_setprio 1
	s_waitcnt lgkmcnt(0)
	v_mfma_f32_16x16x32_bf16 v[124:127], v[144:147], v[184:187], v[124:127]
	v_mfma_f32_16x16x32_bf16 v[120:123], v[160:163], v[184:187], v[120:123]
	v_mfma_f32_16x16x32_bf16 v[112:115], v[144:147], v[192:195], v[112:115]
	v_mfma_f32_16x16x32_bf16 v[104:107], v[160:163], v[192:195], v[104:107]
	v_mfma_f32_16x16x32_bf16 v[96:99], v[144:147], v[200:203], v[96:99]
	v_mfma_f32_16x16x32_bf16 v[88:91], v[160:163], v[200:203], v[88:91]
	v_mfma_f32_16x16x32_bf16 v[80:83], v[144:147], v[208:211], v[80:83]
	v_mfma_f32_16x16x32_bf16 v[72:75], v[160:163], v[208:211], v[72:75]
	v_mfma_f32_16x16x32_bf16 v[124:127], v[156:159], v[188:191], v[124:127]
	v_mfma_f32_16x16x32_bf16 v[120:123], v[164:167], v[188:191], v[120:123]
	v_mfma_f32_16x16x32_bf16 v[112:115], v[156:159], v[196:199], v[112:115]
	v_mfma_f32_16x16x32_bf16 v[104:107], v[164:167], v[196:199], v[104:107]
	v_mfma_f32_16x16x32_bf16 v[96:99], v[156:159], v[204:207], v[96:99]
	v_mfma_f32_16x16x32_bf16 v[88:91], v[164:167], v[204:207], v[88:91]
	v_mfma_f32_16x16x32_bf16 v[80:83], v[156:159], v[212:215], v[80:83]
	v_mfma_f32_16x16x32_bf16 v[72:75], v[164:167], v[212:215], v[72:75]
	s_setprio 0
	s_setprio 1
	v_mfma_f32_16x16x32_bf16 v[116:119], v[168:171], v[184:187], v[116:119]
	v_mfma_f32_16x16x32_bf16 v[108:111], v[176:179], v[184:187], v[108:111]
	v_mfma_f32_16x16x32_bf16 v[100:103], v[168:171], v[192:195], v[100:103]
	v_mfma_f32_16x16x32_bf16 v[92:95], v[176:179], v[192:195], v[92:95]
	v_mfma_f32_16x16x32_bf16 v[84:87], v[168:171], v[200:203], v[84:87]
	v_mfma_f32_16x16x32_bf16 v[76:79], v[176:179], v[200:203], v[76:79]
	v_mfma_f32_16x16x32_bf16 v[68:71], v[168:171], v[208:211], v[68:71]
	v_mfma_f32_16x16x32_bf16 v[64:67], v[176:179], v[208:211], v[64:67]
	v_mfma_f32_16x16x32_bf16 v[116:119], v[172:175], v[188:191], v[116:119]
	v_mfma_f32_16x16x32_bf16 v[108:111], v[180:183], v[188:191], v[108:111]
	v_mfma_f32_16x16x32_bf16 v[100:103], v[172:175], v[196:199], v[100:103]
	v_mfma_f32_16x16x32_bf16 v[92:95], v[180:183], v[196:199], v[92:95]
	v_mfma_f32_16x16x32_bf16 v[84:87], v[172:175], v[204:207], v[84:87]
	v_mfma_f32_16x16x32_bf16 v[76:79], v[180:183], v[204:207], v[76:79]
	v_mfma_f32_16x16x32_bf16 v[68:71], v[172:175], v[212:215], v[68:71]
	v_mfma_f32_16x16x32_bf16 v[64:67], v[180:183], v[212:215], v[64:67]
	s_setprio 0
	s_barrier
	s_add_i32 s18, s50, s31
	v_lshl_add_u64 v[148:149], v[148:149], 0, s[12:13]
	s_mov_b32 m0, s18
	ds_read_b128 v[184:187], v155 offset:49152
	ds_read_b128 v[188:191], v155 offset:50176
	ds_read_b128 v[192:195], v155 offset:51200
	ds_read_b128 v[196:199], v155 offset:52224
	ds_read_b128 v[200:203], v155 offset:53248
	ds_read_b128 v[204:207], v155 offset:54272
	ds_read_b128 v[208:211], v155 offset:55296
	ds_read_b128 v[212:215], v155 offset:56320
	global_load_lds_dwordx4 v[148:149], off
	s_add_i32 m0, s18, 0x2000
	s_add_u32 s18, s22, 0x160080
	v_lshl_add_u64 v[148:149], v[216:217], 0, s[12:13]
	s_addc_u32 s19, s23, 0
	s_add_i32 s22, s51, s31
	global_load_lds_dwordx4 v[148:149], off
	v_lshl_add_u64 v[148:149], s[18:19], 0, v[130:131]
	s_mov_b32 m0, s22
	s_nop 0
	global_load_lds_dwordx4 v[148:149], off
	v_lshl_add_u64 v[148:149], s[18:19], 0, v[134:135]
	s_add_i32 m0, s22, 0x2000
	s_nop 0
	global_load_lds_dwordx4 v[148:149], off
	s_waitcnt vmcnt(6)
	s_waitcnt lgkmcnt(0)
	s_barrier
	s_setprio 1
	s_waitcnt lgkmcnt(0)
	v_mfma_f32_16x16x32_bf16 v[60:63], v[144:147], v[184:187], v[60:63]
	v_mfma_f32_16x16x32_bf16 v[56:59], v[160:163], v[184:187], v[56:59]
	v_mfma_f32_16x16x32_bf16 v[48:51], v[144:147], v[192:195], v[48:51]
	v_mfma_f32_16x16x32_bf16 v[40:43], v[160:163], v[192:195], v[40:43]
	v_mfma_f32_16x16x32_bf16 v[32:35], v[144:147], v[200:203], v[32:35]
	v_mfma_f32_16x16x32_bf16 v[24:27], v[160:163], v[200:203], v[24:27]
	v_mfma_f32_16x16x32_bf16 v[16:19], v[144:147], v[208:211], v[16:19]
	v_mfma_f32_16x16x32_bf16 v[8:11], v[160:163], v[208:211], v[8:11]
	v_mfma_f32_16x16x32_bf16 v[60:63], v[156:159], v[188:191], v[60:63]
	v_mfma_f32_16x16x32_bf16 v[56:59], v[164:167], v[188:191], v[56:59]
	v_mfma_f32_16x16x32_bf16 v[48:51], v[156:159], v[196:199], v[48:51]
	v_mfma_f32_16x16x32_bf16 v[40:43], v[164:167], v[196:199], v[40:43]
	v_mfma_f32_16x16x32_bf16 v[32:35], v[156:159], v[204:207], v[32:35]
	v_mfma_f32_16x16x32_bf16 v[24:27], v[164:167], v[204:207], v[24:27]
	v_mfma_f32_16x16x32_bf16 v[16:19], v[156:159], v[212:215], v[16:19]
	v_mfma_f32_16x16x32_bf16 v[8:11], v[164:167], v[212:215], v[8:11]
	s_setprio 0
	s_setprio 1
	v_mfma_f32_16x16x32_bf16 v[52:55], v[168:171], v[184:187], v[52:55]
	v_mfma_f32_16x16x32_bf16 v[44:47], v[176:179], v[184:187], v[44:47]
	v_mfma_f32_16x16x32_bf16 v[36:39], v[168:171], v[192:195], v[36:39]
	v_mfma_f32_16x16x32_bf16 v[28:31], v[176:179], v[192:195], v[28:31]
	v_mfma_f32_16x16x32_bf16 v[20:23], v[168:171], v[200:203], v[20:23]
	v_mfma_f32_16x16x32_bf16 v[12:15], v[176:179], v[200:203], v[12:15]
	v_mfma_f32_16x16x32_bf16 v[4:7], v[168:171], v[208:211], v[4:7]
	v_mfma_f32_16x16x32_bf16 v[0:3], v[176:179], v[208:211], v[0:3]
	v_mfma_f32_16x16x32_bf16 v[52:55], v[172:175], v[188:191], v[52:55]
	v_mfma_f32_16x16x32_bf16 v[44:47], v[180:183], v[188:191], v[44:47]
	v_mfma_f32_16x16x32_bf16 v[36:39], v[172:175], v[196:199], v[36:39]
	v_mfma_f32_16x16x32_bf16 v[28:31], v[180:183], v[196:199], v[28:31]
	v_mfma_f32_16x16x32_bf16 v[20:23], v[172:175], v[204:207], v[20:23]
	v_mfma_f32_16x16x32_bf16 v[12:15], v[180:183], v[204:207], v[12:15]
	v_mfma_f32_16x16x32_bf16 v[4:7], v[172:175], v[212:215], v[4:7]
	v_mfma_f32_16x16x32_bf16 v[0:3], v[180:183], v[212:215], v[0:3]
	s_setprio 0
	s_barrier
	s_add_i32 s49, s49, 2
	s_add_u32 s47, s47, 0x100
	s_addc_u32 s48, s48, 0
	s_cmpk_gt_u32 s49, 0x55
	s_mov_b64 s[18:19], s[20:21]
	s_cbranch_scc0 .LBB0_5850
	s_and_b64 vcc, exec, s[14:15]
	s_cbranch_vccz .LBB0_5853
	s_barrier

; __global__ void __launch_bounds__(NTHR, 2) mk_fwd(Args args) {
	.amdhsa_kernel _Z6mk_fwd4Args
		.amdhsa_group_segment_fixed_size 0
		.amdhsa_private_segment_fixed_size 0
		.amdhsa_kernarg_size 456
		.amdhsa_user_sgpr_count 2
		.amdhsa_user_sgpr_dispatch_ptr 0
		.amdhsa_user_sgpr_queue_ptr 0
		.amdhsa_user_sgpr_kernarg_segment_ptr 1
		.amdhsa_user_sgpr_dispatch_id 0
		.amdhsa_user_sgpr_kernarg_preload_length 0
		.amdhsa_user_sgpr_kernarg_preload_offset 0
		.amdhsa_user_sgpr_private_segment_size 0
		.amdhsa_uses_dynamic_stack 0
		.amdhsa_enable_private_segment 0
		.amdhsa_system_sgpr_workgroup_id_x 1
		.amdhsa_system_sgpr_workgroup_id_y 0
		.amdhsa_system_sgpr_workgroup_id_z 0
		.amdhsa_system_sgpr_workgroup_info 0
		.amdhsa_system_vgpr_workitem_id 0
		.amdhsa_next_free_vgpr 252
		.amdhsa_next_free_sgpr 102
		.amdhsa_accum_offset 252
		.amdhsa_reserve_vcc 1
		.amdhsa_float_round_mode_32 0
		.amdhsa_float_round_mode_16_64 0
		.amdhsa_float_denorm_mode_32 3
		.amdhsa_float_denorm_mode_16_64 3
		.amdhsa_dx10_clamp 1
		.amdhsa_ieee_mode 1
		.amdhsa_fp16_overflow 0
		.amdhsa_tg_split 0
		.amdhsa_exception_fp_ieee_invalid_op 0
		.amdhsa_exception_fp_denorm_src 0
		.amdhsa_exception_fp_ieee_div_zero 0
		.amdhsa_exception_fp_ieee_overflow 0
		.amdhsa_exception_fp_ieee_underflow 0
		.amdhsa_exception_fp_ieee_inexact 0
		.amdhsa_exception_int_div_zero 0
	.end_amdhsa_kernel

; __global__ void __launch_bounds__(NTHR, 2) mk_fwd(Args args) {
amdhsa.kernels:
  - .agpr_count:     0
    .args:
      - .offset:         0
        .size:           200
        .value_kind:     by_value
      - .offset:         200
        .size:           4
        .value_kind:     hidden_block_count_x
      - .offset:         204
        .size:           4
        .value_kind:     hidden_block_count_y
      - .offset:         208
        .size:           4
        .value_kind:     hidden_block_count_z
      - .offset:         212
        .size:           2
        .value_kind:     hidden_group_size_x
      - .offset:         214
        .size:           2
        .value_kind:     hidden_group_size_y
      - .offset:         216
        .size:           2
        .value_kind:     hidden_group_size_z
      - .offset:         218
        .size:           2
        .value_kind:     hidden_remainder_x
      - .offset:         220
        .size:           2
        .value_kind:     hidden_remainder_y
      - .offset:         222
        .size:           2
        .value_kind:     hidden_remainder_z
      - .offset:         240
        .size:           8
        .value_kind:     hidden_global_offset_x
      - .offset:         248
        .size:           8
        .value_kind:     hidden_global_offset_y
      - .offset:         256
        .size:           8
        .value_kind:     hidden_global_offset_z
      - .offset:         264
        .size:           2
        .value_kind:     hidden_grid_dims
      - .offset:         320
        .size:           4
        .value_kind:     hidden_dynamic_lds_size
    .group_segment_fixed_size: 0
    .kernarg_segment_align: 8
    .kernarg_segment_size: 456
    .language:       OpenCL C
    .language_version:
      - 2
      - 0
    .max_flat_workgroup_size: 512
    .name:           _Z6mk_fwd4Args
    .private_segment_fixed_size: 0
    .sgpr_count:     108
    .sgpr_spill_count: 153
    .symbol:         _Z6mk_fwd4Args.kd
    .uniform_work_group_size: 1
    .uses_dynamic_stack: false
    .vgpr_count:     252
    .vgpr_spill_count: 0
    .wavefront_size: 64
